# hand-written adaLN norm phases (all 8 rows of a wave in flight, dwordx4, DPP reduce); original kept as fallback
# baseline (speedup 1.0000x reference)
.LBB0_551:
	v_readlane_b32 s4, v250, 12
	s_cmp_lt_i32 s4, 5
	s_cselect_b64 s[0:1], -1, 0
	s_and_b64 s[2:3], s[0:1], s[2:3]
	s_andn2_b64 vcc, exec, s[2:3]
	v_readlane_b32 s5, v250, 13
	v_readlane_b32 s6, v250, 14
	v_readlane_b32 s7, v250, 15
	s_cbranch_vccnz .LBB0_563
	v_and_b32_e32 v1, 63, v0
	v_lshlrev_b32_e32 v2, 5, v1
	v_add_u32_e32 v3, 0x1000, v2
	v_lshlrev_b32_e32 v1, 4, v1
	v_mov_b32_e32 v4, 0x2416c
	ds_read_b32 v5, v4
	ds_read_b32 v6, v4 offset:4
	v_readfirstlane_b32 s0, v0
	s_lshr_b32 s1, s0, 6
	s_waitcnt lgkmcnt(0)
	v_readfirstlane_b32 s4, v5
	v_readfirstlane_b32 s5, v6
	s_cmp_lt_i32 s4, 1
	s_cbranch_scc1 .Lnorm_fb_0
	s_add_i32 s4, s4, -1
	s_lshl_b32 s18, s4, 8
	s_lshl_b32 s19, s5, 3
	s_add_i32 s18, s18, s19
	s_add_i32 s18, s18, s1
	s_lshr_b32 s19, s4, 4
	s_lshl_b32 s20, s18, 12
	s_add_u32 s6, s88, 0x45c00000
	s_addc_u32 s7, s89, 0
	s_add_u32 s6, s6, s20
	s_addc_u32 s7, s7, 0
	s_add_u32 s10, s88, 0x13e00000
	s_addc_u32 s11, s89, 0
	s_add_u32 s10, s10, s20
	s_addc_u32 s11, s11, 0
	s_add_u32 s12, s44, 0x2000
	s_addc_u32 s13, s45, 0
	s_mul_i32 s21, s19, 0x12000
	s_add_u32 s14, s88, 0x106000
	s_addc_u32 s15, s89, 0
	s_add_u32 s14, s14, s21
	s_addc_u32 s15, s15, 0
	s_add_u32 s16, s88, 0x108000
	s_addc_u32 s17, s89, 0
	s_add_u32 s16, s16, s21
	s_addc_u32 s17, s17, 0
	global_load_dwordx4 v[72:75], v2, s[12:13] offset:0
	global_load_dwordx4 v[76:79], v2, s[12:13] offset:16
	global_load_dwordx4 v[80:83], v2, s[12:13] offset:2048
	global_load_dwordx4 v[84:87], v2, s[12:13] offset:2064
	global_load_dwordx4 v[88:91], v3, s[12:13] offset:0
	global_load_dwordx4 v[92:95], v3, s[12:13] offset:16
	global_load_dwordx4 v[96:99], v3, s[12:13] offset:2048
	global_load_dwordx4 v[100:103], v3, s[12:13] offset:2064
	global_load_dwordx4 v[8:11], v2, s[16:17] offset:0
	global_load_dwordx4 v[12:15], v2, s[16:17] offset:16
	global_load_dwordx4 v[16:19], v2, s[16:17] offset:2048
	global_load_dwordx4 v[20:23], v2, s[16:17] offset:2064
	global_load_dwordx4 v[24:27], v3, s[16:17] offset:0
	global_load_dwordx4 v[28:31], v3, s[16:17] offset:16
	global_load_dwordx4 v[32:35], v3, s[16:17] offset:2048
	global_load_dwordx4 v[36:39], v3, s[16:17] offset:2064
	global_load_dwordx4 v[40:43], v2, s[14:15] offset:0
	global_load_dwordx4 v[44:47], v2, s[14:15] offset:16
	global_load_dwordx4 v[48:51], v2, s[14:15] offset:2048
	global_load_dwordx4 v[52:55], v2, s[14:15] offset:2064
	global_load_dwordx4 v[56:59], v3, s[14:15] offset:0
	global_load_dwordx4 v[60:63], v3, s[14:15] offset:16
	global_load_dwordx4 v[64:67], v3, s[14:15] offset:2048
	global_load_dwordx4 v[68:71], v3, s[14:15] offset:2064
	s_add_u32 s8, s6, 0x0
	s_addc_u32 s9, s7, 0
	global_load_dwordx4 v[104:107], v1, s[8:9] offset:0 nt
	global_load_dwordx4 v[108:111], v1, s[8:9] offset:1024 nt
	global_load_dwordx4 v[112:115], v1, s[8:9] offset:2048 nt
	global_load_dwordx4 v[116:119], v1, s[8:9] offset:3072 nt
	s_add_u32 s8, s6, 0x20000
	s_addc_u32 s9, s7, 0
	global_load_dwordx4 v[120:123], v1, s[8:9] offset:0 nt
	global_load_dwordx4 v[124:127], v1, s[8:9] offset:1024 nt
	global_load_dwordx4 v[128:131], v1, s[8:9] offset:2048 nt
	global_load_dwordx4 v[132:135], v1, s[8:9] offset:3072 nt
	s_add_u32 s8, s6, 0x40000
	s_addc_u32 s9, s7, 0
	global_load_dwordx4 v[136:139], v1, s[8:9] offset:0 nt
	global_load_dwordx4 v[140:143], v1, s[8:9] offset:1024 nt
	global_load_dwordx4 v[144:147], v1, s[8:9] offset:2048 nt
	global_load_dwordx4 v[148:151], v1, s[8:9] offset:3072 nt
	s_add_u32 s8, s6, 0x60000
	s_addc_u32 s9, s7, 0
	global_load_dwordx4 v[152:155], v1, s[8:9] offset:0 nt
	global_load_dwordx4 v[156:159], v1, s[8:9] offset:1024 nt
	global_load_dwordx4 v[160:163], v1, s[8:9] offset:2048 nt
	global_load_dwordx4 v[164:167], v1, s[8:9] offset:3072 nt
	s_add_u32 s8, s6, 0x80000
	s_addc_u32 s9, s7, 0
	global_load_dwordx4 v[168:171], v1, s[8:9] offset:0 nt
	global_load_dwordx4 v[172:175], v1, s[8:9] offset:1024 nt
	global_load_dwordx4 v[176:179], v1, s[8:9] offset:2048 nt
	global_load_dwordx4 v[180:183], v1, s[8:9] offset:3072 nt
	s_add_u32 s8, s6, 0xa0000
	s_addc_u32 s9, s7, 0
	global_load_dwordx4 v[184:187], v1, s[8:9] offset:0 nt
	global_load_dwordx4 v[188:191], v1, s[8:9] offset:1024 nt
	global_load_dwordx4 v[192:195], v1, s[8:9] offset:2048 nt
	global_load_dwordx4 v[196:199], v1, s[8:9] offset:3072 nt
	s_add_u32 s8, s6, 0xc0000
	s_addc_u32 s9, s7, 0
	global_load_dwordx4 v[200:203], v1, s[8:9] offset:0 nt
	global_load_dwordx4 v[204:207], v1, s[8:9] offset:1024 nt
	global_load_dwordx4 v[208:211], v1, s[8:9] offset:2048 nt
	global_load_dwordx4 v[212:215], v1, s[8:9] offset:3072 nt
	s_add_u32 s8, s6, 0xe0000
	s_addc_u32 s9, s7, 0
	global_load_dwordx4 v[216:219], v1, s[8:9] offset:0 nt
	global_load_dwordx4 v[220:223], v1, s[8:9] offset:1024 nt
	global_load_dwordx4 v[224:227], v1, s[8:9] offset:2048 nt
	global_load_dwordx4 v[228:231], v1, s[8:9] offset:3072 nt
	s_waitcnt vmcnt(32)
	v_pk_add_f32 v[8:9], v[8:9], 1.0 op_sel_hi:[1,0]
	v_pk_add_f32 v[10:11], v[10:11], 1.0 op_sel_hi:[1,0]
	v_pk_add_f32 v[12:13], v[12:13], 1.0 op_sel_hi:[1,0]
	v_pk_add_f32 v[14:15], v[14:15], 1.0 op_sel_hi:[1,0]
	v_pk_add_f32 v[16:17], v[16:17], 1.0 op_sel_hi:[1,0]
	v_pk_add_f32 v[18:19], v[18:19], 1.0 op_sel_hi:[1,0]
	v_pk_add_f32 v[20:21], v[20:21], 1.0 op_sel_hi:[1,0]
	v_pk_add_f32 v[22:23], v[22:23], 1.0 op_sel_hi:[1,0]
	v_pk_add_f32 v[24:25], v[24:25], 1.0 op_sel_hi:[1,0]
	v_pk_add_f32 v[26:27], v[26:27], 1.0 op_sel_hi:[1,0]
	v_pk_add_f32 v[28:29], v[28:29], 1.0 op_sel_hi:[1,0]
	v_pk_add_f32 v[30:31], v[30:31], 1.0 op_sel_hi:[1,0]
	v_pk_add_f32 v[32:33], v[32:33], 1.0 op_sel_hi:[1,0]
	v_pk_add_f32 v[34:35], v[34:35], 1.0 op_sel_hi:[1,0]
	v_pk_add_f32 v[36:37], v[36:37], 1.0 op_sel_hi:[1,0]
	v_pk_add_f32 v[38:39], v[38:39], 1.0 op_sel_hi:[1,0]
	v_pk_mul_f32 v[8:9], v[72:73], v[8:9]
	v_pk_mul_f32 v[10:11], v[74:75], v[10:11]
	v_pk_mul_f32 v[12:13], v[76:77], v[12:13]
	v_pk_mul_f32 v[14:15], v[78:79], v[14:15]
	v_pk_mul_f32 v[16:17], v[80:81], v[16:17]
	v_pk_mul_f32 v[18:19], v[82:83], v[18:19]
	v_pk_mul_f32 v[20:21], v[84:85], v[20:21]
	v_pk_mul_f32 v[22:23], v[86:87], v[22:23]
	v_pk_mul_f32 v[24:25], v[88:89], v[24:25]
	v_pk_mul_f32 v[26:27], v[90:91], v[26:27]
	v_pk_mul_f32 v[28:29], v[92:93], v[28:29]
	v_pk_mul_f32 v[30:31], v[94:95], v[30:31]
	v_pk_mul_f32 v[32:33], v[96:97], v[32:33]
	v_pk_mul_f32 v[34:35], v[98:99], v[34:35]
	v_pk_mul_f32 v[36:37], v[100:101], v[36:37]
	v_pk_mul_f32 v[38:39], v[102:103], v[38:39]
	v_mov_b32_e32 v248, 0x260
	s_waitcnt vmcnt(28)
	v_cvt_f32_f16_e32 v72, v104
	v_cvt_f32_f16_sdwa v73, v104 dst_sel:DWORD dst_unused:UNUSED_PAD src0_sel:WORD_1
	v_cvt_f32_f16_e32 v74, v105
	v_cvt_f32_f16_sdwa v75, v105 dst_sel:DWORD dst_unused:UNUSED_PAD src0_sel:WORD_1
	v_cvt_f32_f16_e32 v76, v106
	v_cvt_f32_f16_sdwa v77, v106 dst_sel:DWORD dst_unused:UNUSED_PAD src0_sel:WORD_1
	v_cvt_f32_f16_e32 v78, v107
	v_cvt_f32_f16_sdwa v79, v107 dst_sel:DWORD dst_unused:UNUSED_PAD src0_sel:WORD_1
	v_cvt_f32_f16_e32 v80, v108
	v_cvt_f32_f16_sdwa v81, v108 dst_sel:DWORD dst_unused:UNUSED_PAD src0_sel:WORD_1
	v_cvt_f32_f16_e32 v82, v109
	v_cvt_f32_f16_sdwa v83, v109 dst_sel:DWORD dst_unused:UNUSED_PAD src0_sel:WORD_1
	v_cvt_f32_f16_e32 v84, v110
	v_cvt_f32_f16_sdwa v85, v110 dst_sel:DWORD dst_unused:UNUSED_PAD src0_sel:WORD_1
	v_cvt_f32_f16_e32 v86, v111
	v_cvt_f32_f16_sdwa v87, v111 dst_sel:DWORD dst_unused:UNUSED_PAD src0_sel:WORD_1
	v_cvt_f32_f16_e32 v88, v112
	v_cvt_f32_f16_sdwa v89, v112 dst_sel:DWORD dst_unused:UNUSED_PAD src0_sel:WORD_1
	v_cvt_f32_f16_e32 v90, v113
	v_cvt_f32_f16_sdwa v91, v113 dst_sel:DWORD dst_unused:UNUSED_PAD src0_sel:WORD_1
	v_cvt_f32_f16_e32 v92, v114
	v_cvt_f32_f16_sdwa v93, v114 dst_sel:DWORD dst_unused:UNUSED_PAD src0_sel:WORD_1
	v_cvt_f32_f16_e32 v94, v115
	v_cvt_f32_f16_sdwa v95, v115 dst_sel:DWORD dst_unused:UNUSED_PAD src0_sel:WORD_1
	v_cvt_f32_f16_e32 v96, v116
	v_cvt_f32_f16_sdwa v97, v116 dst_sel:DWORD dst_unused:UNUSED_PAD src0_sel:WORD_1
	v_cvt_f32_f16_e32 v98, v117
	v_cvt_f32_f16_sdwa v99, v117 dst_sel:DWORD dst_unused:UNUSED_PAD src0_sel:WORD_1
	v_cvt_f32_f16_e32 v100, v118
	v_cvt_f32_f16_sdwa v101, v118 dst_sel:DWORD dst_unused:UNUSED_PAD src0_sel:WORD_1
	v_cvt_f32_f16_e32 v102, v119
	v_cvt_f32_f16_sdwa v103, v119 dst_sel:DWORD dst_unused:UNUSED_PAD src0_sel:WORD_1
	v_pk_mul_f32 v[232:233], v[72:73], v[72:73]
	v_pk_mul_f32 v[234:235], v[74:75], v[74:75]
	v_pk_mul_f32 v[236:237], v[76:77], v[76:77]
	v_pk_mul_f32 v[238:239], v[78:79], v[78:79]
	v_pk_fma_f32 v[232:233], v[80:81], v[80:81], v[232:233]
	v_pk_fma_f32 v[234:235], v[82:83], v[82:83], v[234:235]
	v_pk_fma_f32 v[236:237], v[84:85], v[84:85], v[236:237]
	v_pk_fma_f32 v[238:239], v[86:87], v[86:87], v[238:239]
	v_pk_fma_f32 v[232:233], v[88:89], v[88:89], v[232:233]
	v_pk_fma_f32 v[234:235], v[90:91], v[90:91], v[234:235]
	v_pk_fma_f32 v[236:237], v[92:93], v[92:93], v[236:237]
	v_pk_fma_f32 v[238:239], v[94:95], v[94:95], v[238:239]
	v_pk_fma_f32 v[232:233], v[96:97], v[96:97], v[232:233]
	v_pk_fma_f32 v[234:235], v[98:99], v[98:99], v[234:235]
	v_pk_fma_f32 v[236:237], v[100:101], v[100:101], v[236:237]
	v_pk_fma_f32 v[238:239], v[102:103], v[102:103], v[238:239]
	v_pk_add_f32 v[232:233], v[232:233], v[234:235]
	v_pk_add_f32 v[236:237], v[236:237], v[238:239]
	v_pk_add_f32 v[232:233], v[232:233], v[236:237]
	v_add_f32_e32 v240, v232, v233
	s_nop 1
	v_add_f32_dpp v240, v240, v240 quad_perm:[1,0,3,2] row_mask:0xf bank_mask:0xf
	s_nop 1
	v_add_f32_dpp v240, v240, v240 quad_perm:[2,3,0,1] row_mask:0xf bank_mask:0xf
	s_nop 1
	v_add_f32_dpp v240, v240, v240 row_half_mirror row_mask:0xf bank_mask:0xf
	s_nop 1
	v_add_f32_dpp v240, v240, v240 row_mirror row_mask:0xf bank_mask:0xf
	s_nop 1
	v_readlane_b32 s0, v240, 0
	v_readlane_b32 s1, v240, 16
	v_readlane_b32 s4, v240, 32
	v_readlane_b32 s5, v240, 48
	v_mov_b32_e32 v249, 0x358637bd
	s_nop 1
	v_mov_b32_e32 v240, s0
	v_add_f32_e32 v240, s1, v240
	v_add_f32_e32 v240, s4, v240
	v_add_f32_e32 v240, s5, v240
	v_fmamk_f32 v240, v240, 0x3a000000, v249
	s_mov_b32 s0, 0xf800000
	v_mul_f32_e32 v241, 0x4f800000, v240
	v_cmp_gt_f32_e32 vcc, s0, v240
	s_nop 1
	v_cndmask_b32_e32 v240, v240, v241, vcc
	v_sqrt_f32_e32 v241, v240
	s_nop 0
	v_add_u32_e32 v242, -1, v241
	v_fma_f32 v243, -v242, v241, v240
	v_cmp_ge_f32_e64 s[0:1], 0, v243
	v_add_u32_e32 v243, 1, v241
	s_nop 0
	v_cndmask_b32_e64 v242, v241, v242, s[0:1]
	v_fma_f32 v241, -v243, v241, v240
	v_cmp_lt_f32_e64 s[0:1], 0, v241
	s_nop 1
	v_cndmask_b32_e64 v241, v242, v243, s[0:1]
	v_mul_f32_e32 v242, 0x37800000, v241
	v_cndmask_b32_e32 v241, v241, v242, vcc
	v_cmp_class_f32_e32 vcc, v240, v248
	s_nop 1
	v_cndmask_b32_e32 v240, v241, v240, vcc
	v_div_scale_f32 v241, s[0:1], v240, v240, 1.0
	v_rcp_f32_e32 v242, v241
	s_nop 0
	v_fma_f32 v243, -v241, v242, 1.0
	v_fmac_f32_e32 v242, v243, v242
	v_div_scale_f32 v243, vcc, 1.0, v240, 1.0
	v_mul_f32_e32 v244, v243, v242
	v_fma_f32 v247, -v241, v244, v243
	v_fmac_f32_e32 v244, v247, v242
	v_fma_f32 v241, -v241, v244, v243
	s_nop 1
	v_div_fmas_f32 v241, v241, v242, v244
	v_div_fixup_f32 v246, v241, v240, 1.0
	v_pk_mul_f32 v[72:73], v[72:73], v[246:247] op_sel_hi:[1,0]
	v_pk_mul_f32 v[74:75], v[74:75], v[246:247] op_sel_hi:[1,0]
	v_pk_mul_f32 v[76:77], v[76:77], v[246:247] op_sel_hi:[1,0]
	v_pk_mul_f32 v[78:79], v[78:79], v[246:247] op_sel_hi:[1,0]
	v_pk_mul_f32 v[80:81], v[80:81], v[246:247] op_sel_hi:[1,0]
	v_pk_mul_f32 v[82:83], v[82:83], v[246:247] op_sel_hi:[1,0]
	v_pk_mul_f32 v[84:85], v[84:85], v[246:247] op_sel_hi:[1,0]
	v_pk_mul_f32 v[86:87], v[86:87], v[246:247] op_sel_hi:[1,0]
	v_pk_mul_f32 v[88:89], v[88:89], v[246:247] op_sel_hi:[1,0]
	v_pk_mul_f32 v[90:91], v[90:91], v[246:247] op_sel_hi:[1,0]
	v_pk_mul_f32 v[92:93], v[92:93], v[246:247] op_sel_hi:[1,0]
	v_pk_mul_f32 v[94:95], v[94:95], v[246:247] op_sel_hi:[1,0]
	v_pk_mul_f32 v[96:97], v[96:97], v[246:247] op_sel_hi:[1,0]
	v_pk_mul_f32 v[98:99], v[98:99], v[246:247] op_sel_hi:[1,0]
	v_pk_mul_f32 v[100:101], v[100:101], v[246:247] op_sel_hi:[1,0]
	v_pk_mul_f32 v[102:103], v[102:103], v[246:247] op_sel_hi:[1,0]
	s_add_u32 s8, s10, 0x0
	s_addc_u32 s9, s11, 0
	v_pk_fma_f32 v[72:73], v[8:9], v[72:73], v[40:41]
	v_cvt_pk_bf16_f32 v232, v72, v73
	v_pk_fma_f32 v[74:75], v[10:11], v[74:75], v[42:43]
	v_cvt_pk_bf16_f32 v233, v74, v75
	v_pk_fma_f32 v[76:77], v[12:13], v[76:77], v[44:45]
	v_cvt_pk_bf16_f32 v234, v76, v77
	v_pk_fma_f32 v[78:79], v[14:15], v[78:79], v[46:47]
	v_cvt_pk_bf16_f32 v235, v78, v79
	global_store_dwordx4 v1, v[232:235], s[8:9] offset:0
	v_pk_fma_f32 v[80:81], v[16:17], v[80:81], v[48:49]
	v_cvt_pk_bf16_f32 v236, v80, v81
	v_pk_fma_f32 v[82:83], v[18:19], v[82:83], v[50:51]
	v_cvt_pk_bf16_f32 v237, v82, v83
	v_pk_fma_f32 v[84:85], v[20:21], v[84:85], v[52:53]
	v_cvt_pk_bf16_f32 v238, v84, v85
	v_pk_fma_f32 v[86:87], v[22:23], v[86:87], v[54:55]
	v_cvt_pk_bf16_f32 v239, v86, v87
	global_store_dwordx4 v1, v[236:239], s[8:9] offset:1024
	v_pk_fma_f32 v[88:89], v[24:25], v[88:89], v[56:57]
	v_cvt_pk_bf16_f32 v232, v88, v89
	v_pk_fma_f32 v[90:91], v[26:27], v[90:91], v[58:59]
	v_cvt_pk_bf16_f32 v233, v90, v91
	v_pk_fma_f32 v[92:93], v[28:29], v[92:93], v[60:61]
	v_cvt_pk_bf16_f32 v234, v92, v93
	v_pk_fma_f32 v[94:95], v[30:31], v[94:95], v[62:63]
	v_cvt_pk_bf16_f32 v235, v94, v95
	global_store_dwordx4 v1, v[232:235], s[8:9] offset:2048
	v_pk_fma_f32 v[96:97], v[32:33], v[96:97], v[64:65]
	v_cvt_pk_bf16_f32 v236, v96, v97
	v_pk_fma_f32 v[98:99], v[34:35], v[98:99], v[66:67]
	v_cvt_pk_bf16_f32 v237, v98, v99
	v_pk_fma_f32 v[100:101], v[36:37], v[100:101], v[68:69]
	v_cvt_pk_bf16_f32 v238, v100, v101
	v_pk_fma_f32 v[102:103], v[38:39], v[102:103], v[70:71]
	v_cvt_pk_bf16_f32 v239, v102, v103
	global_store_dwordx4 v1, v[236:239], s[8:9] offset:3072
	s_waitcnt vmcnt(28)
	v_cvt_f32_f16_e32 v72, v120
	v_cvt_f32_f16_sdwa v73, v120 dst_sel:DWORD dst_unused:UNUSED_PAD src0_sel:WORD_1
	v_cvt_f32_f16_e32 v74, v121
	v_cvt_f32_f16_sdwa v75, v121 dst_sel:DWORD dst_unused:UNUSED_PAD src0_sel:WORD_1
	v_cvt_f32_f16_e32 v76, v122
	v_cvt_f32_f16_sdwa v77, v122 dst_sel:DWORD dst_unused:UNUSED_PAD src0_sel:WORD_1
	v_cvt_f32_f16_e32 v78, v123
	v_cvt_f32_f16_sdwa v79, v123 dst_sel:DWORD dst_unused:UNUSED_PAD src0_sel:WORD_1
	v_cvt_f32_f16_e32 v80, v124
	v_cvt_f32_f16_sdwa v81, v124 dst_sel:DWORD dst_unused:UNUSED_PAD src0_sel:WORD_1
	v_cvt_f32_f16_e32 v82, v125
	v_cvt_f32_f16_sdwa v83, v125 dst_sel:DWORD dst_unused:UNUSED_PAD src0_sel:WORD_1
	v_cvt_f32_f16_e32 v84, v126
	v_cvt_f32_f16_sdwa v85, v126 dst_sel:DWORD dst_unused:UNUSED_PAD src0_sel:WORD_1
	v_cvt_f32_f16_e32 v86, v127
	v_cvt_f32_f16_sdwa v87, v127 dst_sel:DWORD dst_unused:UNUSED_PAD src0_sel:WORD_1
	v_cvt_f32_f16_e32 v88, v128
	v_cvt_f32_f16_sdwa v89, v128 dst_sel:DWORD dst_unused:UNUSED_PAD src0_sel:WORD_1
	v_cvt_f32_f16_e32 v90, v129
	v_cvt_f32_f16_sdwa v91, v129 dst_sel:DWORD dst_unused:UNUSED_PAD src0_sel:WORD_1
	v_cvt_f32_f16_e32 v92, v130
	v_cvt_f32_f16_sdwa v93, v130 dst_sel:DWORD dst_unused:UNUSED_PAD src0_sel:WORD_1
	v_cvt_f32_f16_e32 v94, v131
	v_cvt_f32_f16_sdwa v95, v131 dst_sel:DWORD dst_unused:UNUSED_PAD src0_sel:WORD_1
	v_cvt_f32_f16_e32 v96, v132
	v_cvt_f32_f16_sdwa v97, v132 dst_sel:DWORD dst_unused:UNUSED_PAD src0_sel:WORD_1
	v_cvt_f32_f16_e32 v98, v133
	v_cvt_f32_f16_sdwa v99, v133 dst_sel:DWORD dst_unused:UNUSED_PAD src0_sel:WORD_1
	v_cvt_f32_f16_e32 v100, v134
	v_cvt_f32_f16_sdwa v101, v134 dst_sel:DWORD dst_unused:UNUSED_PAD src0_sel:WORD_1
	v_cvt_f32_f16_e32 v102, v135
	v_cvt_f32_f16_sdwa v103, v135 dst_sel:DWORD dst_unused:UNUSED_PAD src0_sel:WORD_1
	v_pk_mul_f32 v[232:233], v[72:73], v[72:73]
	v_pk_mul_f32 v[234:235], v[74:75], v[74:75]
	v_pk_mul_f32 v[236:237], v[76:77], v[76:77]
	v_pk_mul_f32 v[238:239], v[78:79], v[78:79]
	v_pk_fma_f32 v[232:233], v[80:81], v[80:81], v[232:233]
	v_pk_fma_f32 v[234:235], v[82:83], v[82:83], v[234:235]
	v_pk_fma_f32 v[236:237], v[84:85], v[84:85], v[236:237]
	v_pk_fma_f32 v[238:239], v[86:87], v[86:87], v[238:239]
	v_pk_fma_f32 v[232:233], v[88:89], v[88:89], v[232:233]
	v_pk_fma_f32 v[234:235], v[90:91], v[90:91], v[234:235]
	v_pk_fma_f32 v[236:237], v[92:93], v[92:93], v[236:237]
	v_pk_fma_f32 v[238:239], v[94:95], v[94:95], v[238:239]
	v_pk_fma_f32 v[232:233], v[96:97], v[96:97], v[232:233]
	v_pk_fma_f32 v[234:235], v[98:99], v[98:99], v[234:235]
	v_pk_fma_f32 v[236:237], v[100:101], v[100:101], v[236:237]
	v_pk_fma_f32 v[238:239], v[102:103], v[102:103], v[238:239]
	v_pk_add_f32 v[232:233], v[232:233], v[234:235]
	v_pk_add_f32 v[236:237], v[236:237], v[238:239]
	v_pk_add_f32 v[232:233], v[232:233], v[236:237]
	v_add_f32_e32 v240, v232, v233
	s_nop 1
	v_add_f32_dpp v240, v240, v240 quad_perm:[1,0,3,2] row_mask:0xf bank_mask:0xf
	s_nop 1
	v_add_f32_dpp v240, v240, v240 quad_perm:[2,3,0,1] row_mask:0xf bank_mask:0xf
	s_nop 1
	v_add_f32_dpp v240, v240, v240 row_half_mirror row_mask:0xf bank_mask:0xf
	s_nop 1
	v_add_f32_dpp v240, v240, v240 row_mirror row_mask:0xf bank_mask:0xf
	s_nop 1
	v_readlane_b32 s0, v240, 0
	v_readlane_b32 s1, v240, 16
	v_readlane_b32 s4, v240, 32
	v_readlane_b32 s5, v240, 48
	v_mov_b32_e32 v249, 0x358637bd
	s_nop 1
	v_mov_b32_e32 v240, s0
	v_add_f32_e32 v240, s1, v240
	v_add_f32_e32 v240, s4, v240
	v_add_f32_e32 v240, s5, v240
	v_fmamk_f32 v240, v240, 0x3a000000, v249
	s_mov_b32 s0, 0xf800000
	v_mul_f32_e32 v241, 0x4f800000, v240
	v_cmp_gt_f32_e32 vcc, s0, v240
	s_nop 1
	v_cndmask_b32_e32 v240, v240, v241, vcc
	v_sqrt_f32_e32 v241, v240
	s_nop 0
	v_add_u32_e32 v242, -1, v241
	v_fma_f32 v243, -v242, v241, v240
	v_cmp_ge_f32_e64 s[0:1], 0, v243
	v_add_u32_e32 v243, 1, v241
	s_nop 0
	v_cndmask_b32_e64 v242, v241, v242, s[0:1]
	v_fma_f32 v241, -v243, v241, v240
	v_cmp_lt_f32_e64 s[0:1], 0, v241
	s_nop 1
	v_cndmask_b32_e64 v241, v242, v243, s[0:1]
	v_mul_f32_e32 v242, 0x37800000, v241
	v_cndmask_b32_e32 v241, v241, v242, vcc
	v_cmp_class_f32_e32 vcc, v240, v248
	s_nop 1
	v_cndmask_b32_e32 v240, v241, v240, vcc
	v_div_scale_f32 v241, s[0:1], v240, v240, 1.0
	v_rcp_f32_e32 v242, v241
	s_nop 0
	v_fma_f32 v243, -v241, v242, 1.0
	v_fmac_f32_e32 v242, v243, v242
	v_div_scale_f32 v243, vcc, 1.0, v240, 1.0
	v_mul_f32_e32 v244, v243, v242
	v_fma_f32 v247, -v241, v244, v243
	v_fmac_f32_e32 v244, v247, v242
	v_fma_f32 v241, -v241, v244, v243
	s_nop 1
	v_div_fmas_f32 v241, v241, v242, v244
	v_div_fixup_f32 v246, v241, v240, 1.0
	v_pk_mul_f32 v[72:73], v[72:73], v[246:247] op_sel_hi:[1,0]
	v_pk_mul_f32 v[74:75], v[74:75], v[246:247] op_sel_hi:[1,0]
	v_pk_mul_f32 v[76:77], v[76:77], v[246:247] op_sel_hi:[1,0]
	v_pk_mul_f32 v[78:79], v[78:79], v[246:247] op_sel_hi:[1,0]
	v_pk_mul_f32 v[80:81], v[80:81], v[246:247] op_sel_hi:[1,0]
	v_pk_mul_f32 v[82:83], v[82:83], v[246:247] op_sel_hi:[1,0]
	v_pk_mul_f32 v[84:85], v[84:85], v[246:247] op_sel_hi:[1,0]
	v_pk_mul_f32 v[86:87], v[86:87], v[246:247] op_sel_hi:[1,0]
	v_pk_mul_f32 v[88:89], v[88:89], v[246:247] op_sel_hi:[1,0]
	v_pk_mul_f32 v[90:91], v[90:91], v[246:247] op_sel_hi:[1,0]
	v_pk_mul_f32 v[92:93], v[92:93], v[246:247] op_sel_hi:[1,0]
	v_pk_mul_f32 v[94:95], v[94:95], v[246:247] op_sel_hi:[1,0]
	v_pk_mul_f32 v[96:97], v[96:97], v[246:247] op_sel_hi:[1,0]
	v_pk_mul_f32 v[98:99], v[98:99], v[246:247] op_sel_hi:[1,0]
	v_pk_mul_f32 v[100:101], v[100:101], v[246:247] op_sel_hi:[1,0]
	v_pk_mul_f32 v[102:103], v[102:103], v[246:247] op_sel_hi:[1,0]
	s_add_u32 s8, s10, 0x20000
	s_addc_u32 s9, s11, 0
	v_pk_fma_f32 v[72:73], v[8:9], v[72:73], v[40:41]
	v_cvt_pk_bf16_f32 v232, v72, v73
	v_pk_fma_f32 v[74:75], v[10:11], v[74:75], v[42:43]
	v_cvt_pk_bf16_f32 v233, v74, v75
	v_pk_fma_f32 v[76:77], v[12:13], v[76:77], v[44:45]
	v_cvt_pk_bf16_f32 v234, v76, v77
	v_pk_fma_f32 v[78:79], v[14:15], v[78:79], v[46:47]
	v_cvt_pk_bf16_f32 v235, v78, v79
	global_store_dwordx4 v1, v[232:235], s[8:9] offset:0
	v_pk_fma_f32 v[80:81], v[16:17], v[80:81], v[48:49]
	v_cvt_pk_bf16_f32 v236, v80, v81
	v_pk_fma_f32 v[82:83], v[18:19], v[82:83], v[50:51]
	v_cvt_pk_bf16_f32 v237, v82, v83
	v_pk_fma_f32 v[84:85], v[20:21], v[84:85], v[52:53]
	v_cvt_pk_bf16_f32 v238, v84, v85
	v_pk_fma_f32 v[86:87], v[22:23], v[86:87], v[54:55]
	v_cvt_pk_bf16_f32 v239, v86, v87
	global_store_dwordx4 v1, v[236:239], s[8:9] offset:1024
	v_pk_fma_f32 v[88:89], v[24:25], v[88:89], v[56:57]
	v_cvt_pk_bf16_f32 v232, v88, v89
	v_pk_fma_f32 v[90:91], v[26:27], v[90:91], v[58:59]
	v_cvt_pk_bf16_f32 v233, v90, v91
	v_pk_fma_f32 v[92:93], v[28:29], v[92:93], v[60:61]
	v_cvt_pk_bf16_f32 v234, v92, v93
	v_pk_fma_f32 v[94:95], v[30:31], v[94:95], v[62:63]
	v_cvt_pk_bf16_f32 v235, v94, v95
	global_store_dwordx4 v1, v[232:235], s[8:9] offset:2048
	v_pk_fma_f32 v[96:97], v[32:33], v[96:97], v[64:65]
	v_cvt_pk_bf16_f32 v236, v96, v97
	v_pk_fma_f32 v[98:99], v[34:35], v[98:99], v[66:67]
	v_cvt_pk_bf16_f32 v237, v98, v99
	v_pk_fma_f32 v[100:101], v[36:37], v[100:101], v[68:69]
	v_cvt_pk_bf16_f32 v238, v100, v101
	v_pk_fma_f32 v[102:103], v[38:39], v[102:103], v[70:71]
	v_cvt_pk_bf16_f32 v239, v102, v103
	global_store_dwordx4 v1, v[236:239], s[8:9] offset:3072
	s_waitcnt vmcnt(28)
	v_cvt_f32_f16_e32 v72, v136
	v_cvt_f32_f16_sdwa v73, v136 dst_sel:DWORD dst_unused:UNUSED_PAD src0_sel:WORD_1
	v_cvt_f32_f16_e32 v74, v137
	v_cvt_f32_f16_sdwa v75, v137 dst_sel:DWORD dst_unused:UNUSED_PAD src0_sel:WORD_1
	v_cvt_f32_f16_e32 v76, v138
	v_cvt_f32_f16_sdwa v77, v138 dst_sel:DWORD dst_unused:UNUSED_PAD src0_sel:WORD_1
	v_cvt_f32_f16_e32 v78, v139
	v_cvt_f32_f16_sdwa v79, v139 dst_sel:DWORD dst_unused:UNUSED_PAD src0_sel:WORD_1
	v_cvt_f32_f16_e32 v80, v140
	v_cvt_f32_f16_sdwa v81, v140 dst_sel:DWORD dst_unused:UNUSED_PAD src0_sel:WORD_1
	v_cvt_f32_f16_e32 v82, v141
	v_cvt_f32_f16_sdwa v83, v141 dst_sel:DWORD dst_unused:UNUSED_PAD src0_sel:WORD_1
	v_cvt_f32_f16_e32 v84, v142
	v_cvt_f32_f16_sdwa v85, v142 dst_sel:DWORD dst_unused:UNUSED_PAD src0_sel:WORD_1
	v_cvt_f32_f16_e32 v86, v143
	v_cvt_f32_f16_sdwa v87, v143 dst_sel:DWORD dst_unused:UNUSED_PAD src0_sel:WORD_1
	v_cvt_f32_f16_e32 v88, v144
	v_cvt_f32_f16_sdwa v89, v144 dst_sel:DWORD dst_unused:UNUSED_PAD src0_sel:WORD_1
	v_cvt_f32_f16_e32 v90, v145
	v_cvt_f32_f16_sdwa v91, v145 dst_sel:DWORD dst_unused:UNUSED_PAD src0_sel:WORD_1
	v_cvt_f32_f16_e32 v92, v146
	v_cvt_f32_f16_sdwa v93, v146 dst_sel:DWORD dst_unused:UNUSED_PAD src0_sel:WORD_1
	v_cvt_f32_f16_e32 v94, v147
	v_cvt_f32_f16_sdwa v95, v147 dst_sel:DWORD dst_unused:UNUSED_PAD src0_sel:WORD_1
	v_cvt_f32_f16_e32 v96, v148
	v_cvt_f32_f16_sdwa v97, v148 dst_sel:DWORD dst_unused:UNUSED_PAD src0_sel:WORD_1
	v_cvt_f32_f16_e32 v98, v149
	v_cvt_f32_f16_sdwa v99, v149 dst_sel:DWORD dst_unused:UNUSED_PAD src0_sel:WORD_1
	v_cvt_f32_f16_e32 v100, v150
	v_cvt_f32_f16_sdwa v101, v150 dst_sel:DWORD dst_unused:UNUSED_PAD src0_sel:WORD_1
	v_cvt_f32_f16_e32 v102, v151
	v_cvt_f32_f16_sdwa v103, v151 dst_sel:DWORD dst_unused:UNUSED_PAD src0_sel:WORD_1
	v_pk_mul_f32 v[232:233], v[72:73], v[72:73]
	v_pk_mul_f32 v[234:235], v[74:75], v[74:75]
	v_pk_mul_f32 v[236:237], v[76:77], v[76:77]
	v_pk_mul_f32 v[238:239], v[78:79], v[78:79]
	v_pk_fma_f32 v[232:233], v[80:81], v[80:81], v[232:233]
	v_pk_fma_f32 v[234:235], v[82:83], v[82:83], v[234:235]
	v_pk_fma_f32 v[236:237], v[84:85], v[84:85], v[236:237]
	v_pk_fma_f32 v[238:239], v[86:87], v[86:87], v[238:239]
	v_pk_fma_f32 v[232:233], v[88:89], v[88:89], v[232:233]
	v_pk_fma_f32 v[234:235], v[90:91], v[90:91], v[234:235]
	v_pk_fma_f32 v[236:237], v[92:93], v[92:93], v[236:237]
	v_pk_fma_f32 v[238:239], v[94:95], v[94:95], v[238:239]
	v_pk_fma_f32 v[232:233], v[96:97], v[96:97], v[232:233]
	v_pk_fma_f32 v[234:235], v[98:99], v[98:99], v[234:235]
	v_pk_fma_f32 v[236:237], v[100:101], v[100:101], v[236:237]
	v_pk_fma_f32 v[238:239], v[102:103], v[102:103], v[238:239]
	v_pk_add_f32 v[232:233], v[232:233], v[234:235]
	v_pk_add_f32 v[236:237], v[236:237], v[238:239]
	v_pk_add_f32 v[232:233], v[232:233], v[236:237]
	v_add_f32_e32 v240, v232, v233
	s_nop 1
	v_add_f32_dpp v240, v240, v240 quad_perm:[1,0,3,2] row_mask:0xf bank_mask:0xf
	s_nop 1
	v_add_f32_dpp v240, v240, v240 quad_perm:[2,3,0,1] row_mask:0xf bank_mask:0xf
	s_nop 1
	v_add_f32_dpp v240, v240, v240 row_half_mirror row_mask:0xf bank_mask:0xf
	s_nop 1
	v_add_f32_dpp v240, v240, v240 row_mirror row_mask:0xf bank_mask:0xf
	s_nop 1
	v_readlane_b32 s0, v240, 0
	v_readlane_b32 s1, v240, 16
	v_readlane_b32 s4, v240, 32
	v_readlane_b32 s5, v240, 48
	v_mov_b32_e32 v249, 0x358637bd
	s_nop 1
	v_mov_b32_e32 v240, s0
	v_add_f32_e32 v240, s1, v240
	v_add_f32_e32 v240, s4, v240
	v_add_f32_e32 v240, s5, v240
	v_fmamk_f32 v240, v240, 0x3a000000, v249
	s_mov_b32 s0, 0xf800000
	v_mul_f32_e32 v241, 0x4f800000, v240
	v_cmp_gt_f32_e32 vcc, s0, v240
	s_nop 1
	v_cndmask_b32_e32 v240, v240, v241, vcc
	v_sqrt_f32_e32 v241, v240
	s_nop 0
	v_add_u32_e32 v242, -1, v241
	v_fma_f32 v243, -v242, v241, v240
	v_cmp_ge_f32_e64 s[0:1], 0, v243
	v_add_u32_e32 v243, 1, v241
	s_nop 0
	v_cndmask_b32_e64 v242, v241, v242, s[0:1]
	v_fma_f32 v241, -v243, v241, v240
	v_cmp_lt_f32_e64 s[0:1], 0, v241
	s_nop 1
	v_cndmask_b32_e64 v241, v242, v243, s[0:1]
	v_mul_f32_e32 v242, 0x37800000, v241
	v_cndmask_b32_e32 v241, v241, v242, vcc
	v_cmp_class_f32_e32 vcc, v240, v248
	s_nop 1
	v_cndmask_b32_e32 v240, v241, v240, vcc
	v_div_scale_f32 v241, s[0:1], v240, v240, 1.0
	v_rcp_f32_e32 v242, v241
	s_nop 0
	v_fma_f32 v243, -v241, v242, 1.0
	v_fmac_f32_e32 v242, v243, v242
	v_div_scale_f32 v243, vcc, 1.0, v240, 1.0
	v_mul_f32_e32 v244, v243, v242
	v_fma_f32 v247, -v241, v244, v243
	v_fmac_f32_e32 v244, v247, v242
	v_fma_f32 v241, -v241, v244, v243
	s_nop 1
	v_div_fmas_f32 v241, v241, v242, v244
	v_div_fixup_f32 v246, v241, v240, 1.0
	v_pk_mul_f32 v[72:73], v[72:73], v[246:247] op_sel_hi:[1,0]
	v_pk_mul_f32 v[74:75], v[74:75], v[246:247] op_sel_hi:[1,0]
	v_pk_mul_f32 v[76:77], v[76:77], v[246:247] op_sel_hi:[1,0]
	v_pk_mul_f32 v[78:79], v[78:79], v[246:247] op_sel_hi:[1,0]
	v_pk_mul_f32 v[80:81], v[80:81], v[246:247] op_sel_hi:[1,0]
	v_pk_mul_f32 v[82:83], v[82:83], v[246:247] op_sel_hi:[1,0]
	v_pk_mul_f32 v[84:85], v[84:85], v[246:247] op_sel_hi:[1,0]
	v_pk_mul_f32 v[86:87], v[86:87], v[246:247] op_sel_hi:[1,0]
	v_pk_mul_f32 v[88:89], v[88:89], v[246:247] op_sel_hi:[1,0]
	v_pk_mul_f32 v[90:91], v[90:91], v[246:247] op_sel_hi:[1,0]
	v_pk_mul_f32 v[92:93], v[92:93], v[246:247] op_sel_hi:[1,0]
	v_pk_mul_f32 v[94:95], v[94:95], v[246:247] op_sel_hi:[1,0]
	v_pk_mul_f32 v[96:97], v[96:97], v[246:247] op_sel_hi:[1,0]
	v_pk_mul_f32 v[98:99], v[98:99], v[246:247] op_sel_hi:[1,0]
	v_pk_mul_f32 v[100:101], v[100:101], v[246:247] op_sel_hi:[1,0]
	v_pk_mul_f32 v[102:103], v[102:103], v[246:247] op_sel_hi:[1,0]
	s_add_u32 s8, s10, 0x40000
	s_addc_u32 s9, s11, 0
	v_pk_fma_f32 v[72:73], v[8:9], v[72:73], v[40:41]
	v_cvt_pk_bf16_f32 v232, v72, v73
	v_pk_fma_f32 v[74:75], v[10:11], v[74:75], v[42:43]
	v_cvt_pk_bf16_f32 v233, v74, v75
	v_pk_fma_f32 v[76:77], v[12:13], v[76:77], v[44:45]
	v_cvt_pk_bf16_f32 v234, v76, v77
	v_pk_fma_f32 v[78:79], v[14:15], v[78:79], v[46:47]
	v_cvt_pk_bf16_f32 v235, v78, v79
	global_store_dwordx4 v1, v[232:235], s[8:9] offset:0
	v_pk_fma_f32 v[80:81], v[16:17], v[80:81], v[48:49]
	v_cvt_pk_bf16_f32 v236, v80, v81
	v_pk_fma_f32 v[82:83], v[18:19], v[82:83], v[50:51]
	v_cvt_pk_bf16_f32 v237, v82, v83
	v_pk_fma_f32 v[84:85], v[20:21], v[84:85], v[52:53]
	v_cvt_pk_bf16_f32 v238, v84, v85
	v_pk_fma_f32 v[86:87], v[22:23], v[86:87], v[54:55]
	v_cvt_pk_bf16_f32 v239, v86, v87
	global_store_dwordx4 v1, v[236:239], s[8:9] offset:1024
	v_pk_fma_f32 v[88:89], v[24:25], v[88:89], v[56:57]
	v_cvt_pk_bf16_f32 v232, v88, v89
	v_pk_fma_f32 v[90:91], v[26:27], v[90:91], v[58:59]
	v_cvt_pk_bf16_f32 v233, v90, v91
	v_pk_fma_f32 v[92:93], v[28:29], v[92:93], v[60:61]
	v_cvt_pk_bf16_f32 v234, v92, v93
	v_pk_fma_f32 v[94:95], v[30:31], v[94:95], v[62:63]
	v_cvt_pk_bf16_f32 v235, v94, v95
	global_store_dwordx4 v1, v[232:235], s[8:9] offset:2048
	v_pk_fma_f32 v[96:97], v[32:33], v[96:97], v[64:65]
	v_cvt_pk_bf16_f32 v236, v96, v97
	v_pk_fma_f32 v[98:99], v[34:35], v[98:99], v[66:67]
	v_cvt_pk_bf16_f32 v237, v98, v99
	v_pk_fma_f32 v[100:101], v[36:37], v[100:101], v[68:69]
	v_cvt_pk_bf16_f32 v238, v100, v101
	v_pk_fma_f32 v[102:103], v[38:39], v[102:103], v[70:71]
	v_cvt_pk_bf16_f32 v239, v102, v103
	global_store_dwordx4 v1, v[236:239], s[8:9] offset:3072
	s_waitcnt vmcnt(28)
	v_cvt_f32_f16_e32 v72, v152
	v_cvt_f32_f16_sdwa v73, v152 dst_sel:DWORD dst_unused:UNUSED_PAD src0_sel:WORD_1
	v_cvt_f32_f16_e32 v74, v153
	v_cvt_f32_f16_sdwa v75, v153 dst_sel:DWORD dst_unused:UNUSED_PAD src0_sel:WORD_1
	v_cvt_f32_f16_e32 v76, v154
	v_cvt_f32_f16_sdwa v77, v154 dst_sel:DWORD dst_unused:UNUSED_PAD src0_sel:WORD_1
	v_cvt_f32_f16_e32 v78, v155
	v_cvt_f32_f16_sdwa v79, v155 dst_sel:DWORD dst_unused:UNUSED_PAD src0_sel:WORD_1
	v_cvt_f32_f16_e32 v80, v156
	v_cvt_f32_f16_sdwa v81, v156 dst_sel:DWORD dst_unused:UNUSED_PAD src0_sel:WORD_1
	v_cvt_f32_f16_e32 v82, v157
	v_cvt_f32_f16_sdwa v83, v157 dst_sel:DWORD dst_unused:UNUSED_PAD src0_sel:WORD_1
	v_cvt_f32_f16_e32 v84, v158
	v_cvt_f32_f16_sdwa v85, v158 dst_sel:DWORD dst_unused:UNUSED_PAD src0_sel:WORD_1
	v_cvt_f32_f16_e32 v86, v159
	v_cvt_f32_f16_sdwa v87, v159 dst_sel:DWORD dst_unused:UNUSED_PAD src0_sel:WORD_1
	v_cvt_f32_f16_e32 v88, v160
	v_cvt_f32_f16_sdwa v89, v160 dst_sel:DWORD dst_unused:UNUSED_PAD src0_sel:WORD_1
	v_cvt_f32_f16_e32 v90, v161
	v_cvt_f32_f16_sdwa v91, v161 dst_sel:DWORD dst_unused:UNUSED_PAD src0_sel:WORD_1
	v_cvt_f32_f16_e32 v92, v162
	v_cvt_f32_f16_sdwa v93, v162 dst_sel:DWORD dst_unused:UNUSED_PAD src0_sel:WORD_1
	v_cvt_f32_f16_e32 v94, v163
	v_cvt_f32_f16_sdwa v95, v163 dst_sel:DWORD dst_unused:UNUSED_PAD src0_sel:WORD_1
	v_cvt_f32_f16_e32 v96, v164
	v_cvt_f32_f16_sdwa v97, v164 dst_sel:DWORD dst_unused:UNUSED_PAD src0_sel:WORD_1
	v_cvt_f32_f16_e32 v98, v165
	v_cvt_f32_f16_sdwa v99, v165 dst_sel:DWORD dst_unused:UNUSED_PAD src0_sel:WORD_1
	v_cvt_f32_f16_e32 v100, v166
	v_cvt_f32_f16_sdwa v101, v166 dst_sel:DWORD dst_unused:UNUSED_PAD src0_sel:WORD_1
	v_cvt_f32_f16_e32 v102, v167
	v_cvt_f32_f16_sdwa v103, v167 dst_sel:DWORD dst_unused:UNUSED_PAD src0_sel:WORD_1
	v_pk_mul_f32 v[232:233], v[72:73], v[72:73]
	v_pk_mul_f32 v[234:235], v[74:75], v[74:75]
	v_pk_mul_f32 v[236:237], v[76:77], v[76:77]
	v_pk_mul_f32 v[238:239], v[78:79], v[78:79]
	v_pk_fma_f32 v[232:233], v[80:81], v[80:81], v[232:233]
	v_pk_fma_f32 v[234:235], v[82:83], v[82:83], v[234:235]
	v_pk_fma_f32 v[236:237], v[84:85], v[84:85], v[236:237]
	v_pk_fma_f32 v[238:239], v[86:87], v[86:87], v[238:239]
	v_pk_fma_f32 v[232:233], v[88:89], v[88:89], v[232:233]
	v_pk_fma_f32 v[234:235], v[90:91], v[90:91], v[234:235]
	v_pk_fma_f32 v[236:237], v[92:93], v[92:93], v[236:237]
	v_pk_fma_f32 v[238:239], v[94:95], v[94:95], v[238:239]
	v_pk_fma_f32 v[232:233], v[96:97], v[96:97], v[232:233]
	v_pk_fma_f32 v[234:235], v[98:99], v[98:99], v[234:235]
	v_pk_fma_f32 v[236:237], v[100:101], v[100:101], v[236:237]
	v_pk_fma_f32 v[238:239], v[102:103], v[102:103], v[238:239]
	v_pk_add_f32 v[232:233], v[232:233], v[234:235]
	v_pk_add_f32 v[236:237], v[236:237], v[238:239]
	v_pk_add_f32 v[232:233], v[232:233], v[236:237]
	v_add_f32_e32 v240, v232, v233
	s_nop 1
	v_add_f32_dpp v240, v240, v240 quad_perm:[1,0,3,2] row_mask:0xf bank_mask:0xf
	s_nop 1
	v_add_f32_dpp v240, v240, v240 quad_perm:[2,3,0,1] row_mask:0xf bank_mask:0xf
	s_nop 1
	v_add_f32_dpp v240, v240, v240 row_half_mirror row_mask:0xf bank_mask:0xf
	s_nop 1
	v_add_f32_dpp v240, v240, v240 row_mirror row_mask:0xf bank_mask:0xf
	s_nop 1
	v_readlane_b32 s0, v240, 0
	v_readlane_b32 s1, v240, 16
	v_readlane_b32 s4, v240, 32
	v_readlane_b32 s5, v240, 48
	v_mov_b32_e32 v249, 0x358637bd
	s_nop 1
	v_mov_b32_e32 v240, s0
	v_add_f32_e32 v240, s1, v240
	v_add_f32_e32 v240, s4, v240
	v_add_f32_e32 v240, s5, v240
	v_fmamk_f32 v240, v240, 0x3a000000, v249
	s_mov_b32 s0, 0xf800000
	v_mul_f32_e32 v241, 0x4f800000, v240
	v_cmp_gt_f32_e32 vcc, s0, v240
	s_nop 1
	v_cndmask_b32_e32 v240, v240, v241, vcc
	v_sqrt_f32_e32 v241, v240
	s_nop 0
	v_add_u32_e32 v242, -1, v241
	v_fma_f32 v243, -v242, v241, v240
	v_cmp_ge_f32_e64 s[0:1], 0, v243
	v_add_u32_e32 v243, 1, v241
	s_nop 0
	v_cndmask_b32_e64 v242, v241, v242, s[0:1]
	v_fma_f32 v241, -v243, v241, v240
	v_cmp_lt_f32_e64 s[0:1], 0, v241
	s_nop 1
	v_cndmask_b32_e64 v241, v242, v243, s[0:1]
	v_mul_f32_e32 v242, 0x37800000, v241
	v_cndmask_b32_e32 v241, v241, v242, vcc
	v_cmp_class_f32_e32 vcc, v240, v248
	s_nop 1
	v_cndmask_b32_e32 v240, v241, v240, vcc
	v_div_scale_f32 v241, s[0:1], v240, v240, 1.0
	v_rcp_f32_e32 v242, v241
	s_nop 0
	v_fma_f32 v243, -v241, v242, 1.0
	v_fmac_f32_e32 v242, v243, v242
	v_div_scale_f32 v243, vcc, 1.0, v240, 1.0
	v_mul_f32_e32 v244, v243, v242
	v_fma_f32 v247, -v241, v244, v243
	v_fmac_f32_e32 v244, v247, v242
	v_fma_f32 v241, -v241, v244, v243
	s_nop 1
	v_div_fmas_f32 v241, v241, v242, v244
	v_div_fixup_f32 v246, v241, v240, 1.0
	v_pk_mul_f32 v[72:73], v[72:73], v[246:247] op_sel_hi:[1,0]
	v_pk_mul_f32 v[74:75], v[74:75], v[246:247] op_sel_hi:[1,0]
	v_pk_mul_f32 v[76:77], v[76:77], v[246:247] op_sel_hi:[1,0]
	v_pk_mul_f32 v[78:79], v[78:79], v[246:247] op_sel_hi:[1,0]
	v_pk_mul_f32 v[80:81], v[80:81], v[246:247] op_sel_hi:[1,0]
	v_pk_mul_f32 v[82:83], v[82:83], v[246:247] op_sel_hi:[1,0]
	v_pk_mul_f32 v[84:85], v[84:85], v[246:247] op_sel_hi:[1,0]
	v_pk_mul_f32 v[86:87], v[86:87], v[246:247] op_sel_hi:[1,0]
	v_pk_mul_f32 v[88:89], v[88:89], v[246:247] op_sel_hi:[1,0]
	v_pk_mul_f32 v[90:91], v[90:91], v[246:247] op_sel_hi:[1,0]
	v_pk_mul_f32 v[92:93], v[92:93], v[246:247] op_sel_hi:[1,0]
	v_pk_mul_f32 v[94:95], v[94:95], v[246:247] op_sel_hi:[1,0]
	v_pk_mul_f32 v[96:97], v[96:97], v[246:247] op_sel_hi:[1,0]
	v_pk_mul_f32 v[98:99], v[98:99], v[246:247] op_sel_hi:[1,0]
	v_pk_mul_f32 v[100:101], v[100:101], v[246:247] op_sel_hi:[1,0]
	v_pk_mul_f32 v[102:103], v[102:103], v[246:247] op_sel_hi:[1,0]
	s_add_u32 s8, s10, 0x60000
	s_addc_u32 s9, s11, 0
	v_pk_fma_f32 v[72:73], v[8:9], v[72:73], v[40:41]
	v_cvt_pk_bf16_f32 v232, v72, v73
	v_pk_fma_f32 v[74:75], v[10:11], v[74:75], v[42:43]
	v_cvt_pk_bf16_f32 v233, v74, v75
	v_pk_fma_f32 v[76:77], v[12:13], v[76:77], v[44:45]
	v_cvt_pk_bf16_f32 v234, v76, v77
	v_pk_fma_f32 v[78:79], v[14:15], v[78:79], v[46:47]
	v_cvt_pk_bf16_f32 v235, v78, v79
	global_store_dwordx4 v1, v[232:235], s[8:9] offset:0
	v_pk_fma_f32 v[80:81], v[16:17], v[80:81], v[48:49]
	v_cvt_pk_bf16_f32 v236, v80, v81
	v_pk_fma_f32 v[82:83], v[18:19], v[82:83], v[50:51]
	v_cvt_pk_bf16_f32 v237, v82, v83
	v_pk_fma_f32 v[84:85], v[20:21], v[84:85], v[52:53]
	v_cvt_pk_bf16_f32 v238, v84, v85
	v_pk_fma_f32 v[86:87], v[22:23], v[86:87], v[54:55]
	v_cvt_pk_bf16_f32 v239, v86, v87
	global_store_dwordx4 v1, v[236:239], s[8:9] offset:1024
	v_pk_fma_f32 v[88:89], v[24:25], v[88:89], v[56:57]
	v_cvt_pk_bf16_f32 v232, v88, v89
	v_pk_fma_f32 v[90:91], v[26:27], v[90:91], v[58:59]
	v_cvt_pk_bf16_f32 v233, v90, v91
	v_pk_fma_f32 v[92:93], v[28:29], v[92:93], v[60:61]
	v_cvt_pk_bf16_f32 v234, v92, v93
	v_pk_fma_f32 v[94:95], v[30:31], v[94:95], v[62:63]
	v_cvt_pk_bf16_f32 v235, v94, v95
	global_store_dwordx4 v1, v[232:235], s[8:9] offset:2048
	v_pk_fma_f32 v[96:97], v[32:33], v[96:97], v[64:65]
	v_cvt_pk_bf16_f32 v236, v96, v97
	v_pk_fma_f32 v[98:99], v[34:35], v[98:99], v[66:67]
	v_cvt_pk_bf16_f32 v237, v98, v99
	v_pk_fma_f32 v[100:101], v[36:37], v[100:101], v[68:69]
	v_cvt_pk_bf16_f32 v238, v100, v101
	v_pk_fma_f32 v[102:103], v[38:39], v[102:103], v[70:71]
	v_cvt_pk_bf16_f32 v239, v102, v103
	global_store_dwordx4 v1, v[236:239], s[8:9] offset:3072
	s_waitcnt vmcnt(28)
	v_cvt_f32_f16_e32 v72, v168
	v_cvt_f32_f16_sdwa v73, v168 dst_sel:DWORD dst_unused:UNUSED_PAD src0_sel:WORD_1
	v_cvt_f32_f16_e32 v74, v169
	v_cvt_f32_f16_sdwa v75, v169 dst_sel:DWORD dst_unused:UNUSED_PAD src0_sel:WORD_1
	v_cvt_f32_f16_e32 v76, v170
	v_cvt_f32_f16_sdwa v77, v170 dst_sel:DWORD dst_unused:UNUSED_PAD src0_sel:WORD_1
	v_cvt_f32_f16_e32 v78, v171
	v_cvt_f32_f16_sdwa v79, v171 dst_sel:DWORD dst_unused:UNUSED_PAD src0_sel:WORD_1
	v_cvt_f32_f16_e32 v80, v172
	v_cvt_f32_f16_sdwa v81, v172 dst_sel:DWORD dst_unused:UNUSED_PAD src0_sel:WORD_1
	v_cvt_f32_f16_e32 v82, v173
	v_cvt_f32_f16_sdwa v83, v173 dst_sel:DWORD dst_unused:UNUSED_PAD src0_sel:WORD_1
	v_cvt_f32_f16_e32 v84, v174
	v_cvt_f32_f16_sdwa v85, v174 dst_sel:DWORD dst_unused:UNUSED_PAD src0_sel:WORD_1
	v_cvt_f32_f16_e32 v86, v175
	v_cvt_f32_f16_sdwa v87, v175 dst_sel:DWORD dst_unused:UNUSED_PAD src0_sel:WORD_1
	v_cvt_f32_f16_e32 v88, v176
	v_cvt_f32_f16_sdwa v89, v176 dst_sel:DWORD dst_unused:UNUSED_PAD src0_sel:WORD_1
	v_cvt_f32_f16_e32 v90, v177
	v_cvt_f32_f16_sdwa v91, v177 dst_sel:DWORD dst_unused:UNUSED_PAD src0_sel:WORD_1
	v_cvt_f32_f16_e32 v92, v178
	v_cvt_f32_f16_sdwa v93, v178 dst_sel:DWORD dst_unused:UNUSED_PAD src0_sel:WORD_1
	v_cvt_f32_f16_e32 v94, v179
	v_cvt_f32_f16_sdwa v95, v179 dst_sel:DWORD dst_unused:UNUSED_PAD src0_sel:WORD_1
	v_cvt_f32_f16_e32 v96, v180
	v_cvt_f32_f16_sdwa v97, v180 dst_sel:DWORD dst_unused:UNUSED_PAD src0_sel:WORD_1
	v_cvt_f32_f16_e32 v98, v181
	v_cvt_f32_f16_sdwa v99, v181 dst_sel:DWORD dst_unused:UNUSED_PAD src0_sel:WORD_1
	v_cvt_f32_f16_e32 v100, v182
	v_cvt_f32_f16_sdwa v101, v182 dst_sel:DWORD dst_unused:UNUSED_PAD src0_sel:WORD_1
	v_cvt_f32_f16_e32 v102, v183
	v_cvt_f32_f16_sdwa v103, v183 dst_sel:DWORD dst_unused:UNUSED_PAD src0_sel:WORD_1
	v_pk_mul_f32 v[232:233], v[72:73], v[72:73]
	v_pk_mul_f32 v[234:235], v[74:75], v[74:75]
	v_pk_mul_f32 v[236:237], v[76:77], v[76:77]
	v_pk_mul_f32 v[238:239], v[78:79], v[78:79]
	v_pk_fma_f32 v[232:233], v[80:81], v[80:81], v[232:233]
	v_pk_fma_f32 v[234:235], v[82:83], v[82:83], v[234:235]
	v_pk_fma_f32 v[236:237], v[84:85], v[84:85], v[236:237]
	v_pk_fma_f32 v[238:239], v[86:87], v[86:87], v[238:239]
	v_pk_fma_f32 v[232:233], v[88:89], v[88:89], v[232:233]
	v_pk_fma_f32 v[234:235], v[90:91], v[90:91], v[234:235]
	v_pk_fma_f32 v[236:237], v[92:93], v[92:93], v[236:237]
	v_pk_fma_f32 v[238:239], v[94:95], v[94:95], v[238:239]
	v_pk_fma_f32 v[232:233], v[96:97], v[96:97], v[232:233]
	v_pk_fma_f32 v[234:235], v[98:99], v[98:99], v[234:235]
	v_pk_fma_f32 v[236:237], v[100:101], v[100:101], v[236:237]
	v_pk_fma_f32 v[238:239], v[102:103], v[102:103], v[238:239]
	v_pk_add_f32 v[232:233], v[232:233], v[234:235]
	v_pk_add_f32 v[236:237], v[236:237], v[238:239]
	v_pk_add_f32 v[232:233], v[232:233], v[236:237]
	v_add_f32_e32 v240, v232, v233
	s_nop 1
	v_add_f32_dpp v240, v240, v240 quad_perm:[1,0,3,2] row_mask:0xf bank_mask:0xf
	s_nop 1
	v_add_f32_dpp v240, v240, v240 quad_perm:[2,3,0,1] row_mask:0xf bank_mask:0xf
	s_nop 1
	v_add_f32_dpp v240, v240, v240 row_half_mirror row_mask:0xf bank_mask:0xf
	s_nop 1
	v_add_f32_dpp v240, v240, v240 row_mirror row_mask:0xf bank_mask:0xf
	s_nop 1
	v_readlane_b32 s0, v240, 0
	v_readlane_b32 s1, v240, 16
	v_readlane_b32 s4, v240, 32
	v_readlane_b32 s5, v240, 48
	v_mov_b32_e32 v249, 0x358637bd
	s_nop 1
	v_mov_b32_e32 v240, s0
	v_add_f32_e32 v240, s1, v240
	v_add_f32_e32 v240, s4, v240
	v_add_f32_e32 v240, s5, v240
	v_fmamk_f32 v240, v240, 0x3a000000, v249
	s_mov_b32 s0, 0xf800000
	v_mul_f32_e32 v241, 0x4f800000, v240
	v_cmp_gt_f32_e32 vcc, s0, v240
	s_nop 1
	v_cndmask_b32_e32 v240, v240, v241, vcc
	v_sqrt_f32_e32 v241, v240
	s_nop 0
	v_add_u32_e32 v242, -1, v241
	v_fma_f32 v243, -v242, v241, v240
	v_cmp_ge_f32_e64 s[0:1], 0, v243
	v_add_u32_e32 v243, 1, v241
	s_nop 0
	v_cndmask_b32_e64 v242, v241, v242, s[0:1]
	v_fma_f32 v241, -v243, v241, v240
	v_cmp_lt_f32_e64 s[0:1], 0, v241
	s_nop 1
	v_cndmask_b32_e64 v241, v242, v243, s[0:1]
	v_mul_f32_e32 v242, 0x37800000, v241
	v_cndmask_b32_e32 v241, v241, v242, vcc
	v_cmp_class_f32_e32 vcc, v240, v248
	s_nop 1
	v_cndmask_b32_e32 v240, v241, v240, vcc
	v_div_scale_f32 v241, s[0:1], v240, v240, 1.0
	v_rcp_f32_e32 v242, v241
	s_nop 0
	v_fma_f32 v243, -v241, v242, 1.0
	v_fmac_f32_e32 v242, v243, v242
	v_div_scale_f32 v243, vcc, 1.0, v240, 1.0
	v_mul_f32_e32 v244, v243, v242
	v_fma_f32 v247, -v241, v244, v243
	v_fmac_f32_e32 v244, v247, v242
	v_fma_f32 v241, -v241, v244, v243
	s_nop 1
	v_div_fmas_f32 v241, v241, v242, v244
	v_div_fixup_f32 v246, v241, v240, 1.0
	v_pk_mul_f32 v[72:73], v[72:73], v[246:247] op_sel_hi:[1,0]
	v_pk_mul_f32 v[74:75], v[74:75], v[246:247] op_sel_hi:[1,0]
	v_pk_mul_f32 v[76:77], v[76:77], v[246:247] op_sel_hi:[1,0]
	v_pk_mul_f32 v[78:79], v[78:79], v[246:247] op_sel_hi:[1,0]
	v_pk_mul_f32 v[80:81], v[80:81], v[246:247] op_sel_hi:[1,0]
	v_pk_mul_f32 v[82:83], v[82:83], v[246:247] op_sel_hi:[1,0]
	v_pk_mul_f32 v[84:85], v[84:85], v[246:247] op_sel_hi:[1,0]
	v_pk_mul_f32 v[86:87], v[86:87], v[246:247] op_sel_hi:[1,0]
	v_pk_mul_f32 v[88:89], v[88:89], v[246:247] op_sel_hi:[1,0]
	v_pk_mul_f32 v[90:91], v[90:91], v[246:247] op_sel_hi:[1,0]
	v_pk_mul_f32 v[92:93], v[92:93], v[246:247] op_sel_hi:[1,0]
	v_pk_mul_f32 v[94:95], v[94:95], v[246:247] op_sel_hi:[1,0]
	v_pk_mul_f32 v[96:97], v[96:97], v[246:247] op_sel_hi:[1,0]
	v_pk_mul_f32 v[98:99], v[98:99], v[246:247] op_sel_hi:[1,0]
	v_pk_mul_f32 v[100:101], v[100:101], v[246:247] op_sel_hi:[1,0]
	v_pk_mul_f32 v[102:103], v[102:103], v[246:247] op_sel_hi:[1,0]
	s_add_u32 s8, s10, 0x80000
	s_addc_u32 s9, s11, 0
	v_pk_fma_f32 v[72:73], v[8:9], v[72:73], v[40:41]
	v_cvt_pk_bf16_f32 v232, v72, v73
	v_pk_fma_f32 v[74:75], v[10:11], v[74:75], v[42:43]
	v_cvt_pk_bf16_f32 v233, v74, v75
	v_pk_fma_f32 v[76:77], v[12:13], v[76:77], v[44:45]
	v_cvt_pk_bf16_f32 v234, v76, v77
	v_pk_fma_f32 v[78:79], v[14:15], v[78:79], v[46:47]
	v_cvt_pk_bf16_f32 v235, v78, v79
	global_store_dwordx4 v1, v[232:235], s[8:9] offset:0
	v_pk_fma_f32 v[80:81], v[16:17], v[80:81], v[48:49]
	v_cvt_pk_bf16_f32 v236, v80, v81
	v_pk_fma_f32 v[82:83], v[18:19], v[82:83], v[50:51]
	v_cvt_pk_bf16_f32 v237, v82, v83
	v_pk_fma_f32 v[84:85], v[20:21], v[84:85], v[52:53]
	v_cvt_pk_bf16_f32 v238, v84, v85
	v_pk_fma_f32 v[86:87], v[22:23], v[86:87], v[54:55]
	v_cvt_pk_bf16_f32 v239, v86, v87
	global_store_dwordx4 v1, v[236:239], s[8:9] offset:1024
	v_pk_fma_f32 v[88:89], v[24:25], v[88:89], v[56:57]
	v_cvt_pk_bf16_f32 v232, v88, v89
	v_pk_fma_f32 v[90:91], v[26:27], v[90:91], v[58:59]
	v_cvt_pk_bf16_f32 v233, v90, v91
	v_pk_fma_f32 v[92:93], v[28:29], v[92:93], v[60:61]
	v_cvt_pk_bf16_f32 v234, v92, v93
	v_pk_fma_f32 v[94:95], v[30:31], v[94:95], v[62:63]
	v_cvt_pk_bf16_f32 v235, v94, v95
	global_store_dwordx4 v1, v[232:235], s[8:9] offset:2048
	v_pk_fma_f32 v[96:97], v[32:33], v[96:97], v[64:65]
	v_cvt_pk_bf16_f32 v236, v96, v97
	v_pk_fma_f32 v[98:99], v[34:35], v[98:99], v[66:67]
	v_cvt_pk_bf16_f32 v237, v98, v99
	v_pk_fma_f32 v[100:101], v[36:37], v[100:101], v[68:69]
	v_cvt_pk_bf16_f32 v238, v100, v101
	v_pk_fma_f32 v[102:103], v[38:39], v[102:103], v[70:71]
	v_cvt_pk_bf16_f32 v239, v102, v103
	global_store_dwordx4 v1, v[236:239], s[8:9] offset:3072
	s_waitcnt vmcnt(28)
	v_cvt_f32_f16_e32 v72, v184
	v_cvt_f32_f16_sdwa v73, v184 dst_sel:DWORD dst_unused:UNUSED_PAD src0_sel:WORD_1
	v_cvt_f32_f16_e32 v74, v185
	v_cvt_f32_f16_sdwa v75, v185 dst_sel:DWORD dst_unused:UNUSED_PAD src0_sel:WORD_1
	v_cvt_f32_f16_e32 v76, v186
	v_cvt_f32_f16_sdwa v77, v186 dst_sel:DWORD dst_unused:UNUSED_PAD src0_sel:WORD_1
	v_cvt_f32_f16_e32 v78, v187
	v_cvt_f32_f16_sdwa v79, v187 dst_sel:DWORD dst_unused:UNUSED_PAD src0_sel:WORD_1
	v_cvt_f32_f16_e32 v80, v188
	v_cvt_f32_f16_sdwa v81, v188 dst_sel:DWORD dst_unused:UNUSED_PAD src0_sel:WORD_1
	v_cvt_f32_f16_e32 v82, v189
	v_cvt_f32_f16_sdwa v83, v189 dst_sel:DWORD dst_unused:UNUSED_PAD src0_sel:WORD_1
	v_cvt_f32_f16_e32 v84, v190
	v_cvt_f32_f16_sdwa v85, v190 dst_sel:DWORD dst_unused:UNUSED_PAD src0_sel:WORD_1
	v_cvt_f32_f16_e32 v86, v191
	v_cvt_f32_f16_sdwa v87, v191 dst_sel:DWORD dst_unused:UNUSED_PAD src0_sel:WORD_1
	v_cvt_f32_f16_e32 v88, v192
	v_cvt_f32_f16_sdwa v89, v192 dst_sel:DWORD dst_unused:UNUSED_PAD src0_sel:WORD_1
	v_cvt_f32_f16_e32 v90, v193
	v_cvt_f32_f16_sdwa v91, v193 dst_sel:DWORD dst_unused:UNUSED_PAD src0_sel:WORD_1
	v_cvt_f32_f16_e32 v92, v194
	v_cvt_f32_f16_sdwa v93, v194 dst_sel:DWORD dst_unused:UNUSED_PAD src0_sel:WORD_1
	v_cvt_f32_f16_e32 v94, v195
	v_cvt_f32_f16_sdwa v95, v195 dst_sel:DWORD dst_unused:UNUSED_PAD src0_sel:WORD_1
	v_cvt_f32_f16_e32 v96, v196
	v_cvt_f32_f16_sdwa v97, v196 dst_sel:DWORD dst_unused:UNUSED_PAD src0_sel:WORD_1
	v_cvt_f32_f16_e32 v98, v197
	v_cvt_f32_f16_sdwa v99, v197 dst_sel:DWORD dst_unused:UNUSED_PAD src0_sel:WORD_1
	v_cvt_f32_f16_e32 v100, v198
	v_cvt_f32_f16_sdwa v101, v198 dst_sel:DWORD dst_unused:UNUSED_PAD src0_sel:WORD_1
	v_cvt_f32_f16_e32 v102, v199
	v_cvt_f32_f16_sdwa v103, v199 dst_sel:DWORD dst_unused:UNUSED_PAD src0_sel:WORD_1
	v_pk_mul_f32 v[232:233], v[72:73], v[72:73]
	v_pk_mul_f32 v[234:235], v[74:75], v[74:75]
	v_pk_mul_f32 v[236:237], v[76:77], v[76:77]
	v_pk_mul_f32 v[238:239], v[78:79], v[78:79]
	v_pk_fma_f32 v[232:233], v[80:81], v[80:81], v[232:233]
	v_pk_fma_f32 v[234:235], v[82:83], v[82:83], v[234:235]
	v_pk_fma_f32 v[236:237], v[84:85], v[84:85], v[236:237]
	v_pk_fma_f32 v[238:239], v[86:87], v[86:87], v[238:239]
	v_pk_fma_f32 v[232:233], v[88:89], v[88:89], v[232:233]
	v_pk_fma_f32 v[234:235], v[90:91], v[90:91], v[234:235]
	v_pk_fma_f32 v[236:237], v[92:93], v[92:93], v[236:237]
	v_pk_fma_f32 v[238:239], v[94:95], v[94:95], v[238:239]
	v_pk_fma_f32 v[232:233], v[96:97], v[96:97], v[232:233]
	v_pk_fma_f32 v[234:235], v[98:99], v[98:99], v[234:235]
	v_pk_fma_f32 v[236:237], v[100:101], v[100:101], v[236:237]
	v_pk_fma_f32 v[238:239], v[102:103], v[102:103], v[238:239]
	v_pk_add_f32 v[232:233], v[232:233], v[234:235]
	v_pk_add_f32 v[236:237], v[236:237], v[238:239]
	v_pk_add_f32 v[232:233], v[232:233], v[236:237]
	v_add_f32_e32 v240, v232, v233
	s_nop 1
	v_add_f32_dpp v240, v240, v240 quad_perm:[1,0,3,2] row_mask:0xf bank_mask:0xf
	s_nop 1
	v_add_f32_dpp v240, v240, v240 quad_perm:[2,3,0,1] row_mask:0xf bank_mask:0xf
	s_nop 1
	v_add_f32_dpp v240, v240, v240 row_half_mirror row_mask:0xf bank_mask:0xf
	s_nop 1
	v_add_f32_dpp v240, v240, v240 row_mirror row_mask:0xf bank_mask:0xf
	s_nop 1
	v_readlane_b32 s0, v240, 0
	v_readlane_b32 s1, v240, 16
	v_readlane_b32 s4, v240, 32
	v_readlane_b32 s5, v240, 48
	v_mov_b32_e32 v249, 0x358637bd
	s_nop 1
	v_mov_b32_e32 v240, s0
	v_add_f32_e32 v240, s1, v240
	v_add_f32_e32 v240, s4, v240
	v_add_f32_e32 v240, s5, v240
	v_fmamk_f32 v240, v240, 0x3a000000, v249
	s_mov_b32 s0, 0xf800000
	v_mul_f32_e32 v241, 0x4f800000, v240
	v_cmp_gt_f32_e32 vcc, s0, v240
	s_nop 1
	v_cndmask_b32_e32 v240, v240, v241, vcc
	v_sqrt_f32_e32 v241, v240
	s_nop 0
	v_add_u32_e32 v242, -1, v241
	v_fma_f32 v243, -v242, v241, v240
	v_cmp_ge_f32_e64 s[0:1], 0, v243
	v_add_u32_e32 v243, 1, v241
	s_nop 0
	v_cndmask_b32_e64 v242, v241, v242, s[0:1]
	v_fma_f32 v241, -v243, v241, v240
	v_cmp_lt_f32_e64 s[0:1], 0, v241
	s_nop 1
	v_cndmask_b32_e64 v241, v242, v243, s[0:1]
	v_mul_f32_e32 v242, 0x37800000, v241
	v_cndmask_b32_e32 v241, v241, v242, vcc
	v_cmp_class_f32_e32 vcc, v240, v248
	s_nop 1
	v_cndmask_b32_e32 v240, v241, v240, vcc
	v_div_scale_f32 v241, s[0:1], v240, v240, 1.0
	v_rcp_f32_e32 v242, v241
	s_nop 0
	v_fma_f32 v243, -v241, v242, 1.0
	v_fmac_f32_e32 v242, v243, v242
	v_div_scale_f32 v243, vcc, 1.0, v240, 1.0
	v_mul_f32_e32 v244, v243, v242
	v_fma_f32 v247, -v241, v244, v243
	v_fmac_f32_e32 v244, v247, v242
	v_fma_f32 v241, -v241, v244, v243
	s_nop 1
	v_div_fmas_f32 v241, v241, v242, v244
	v_div_fixup_f32 v246, v241, v240, 1.0
	v_pk_mul_f32 v[72:73], v[72:73], v[246:247] op_sel_hi:[1,0]
	v_pk_mul_f32 v[74:75], v[74:75], v[246:247] op_sel_hi:[1,0]
	v_pk_mul_f32 v[76:77], v[76:77], v[246:247] op_sel_hi:[1,0]
	v_pk_mul_f32 v[78:79], v[78:79], v[246:247] op_sel_hi:[1,0]
	v_pk_mul_f32 v[80:81], v[80:81], v[246:247] op_sel_hi:[1,0]
	v_pk_mul_f32 v[82:83], v[82:83], v[246:247] op_sel_hi:[1,0]
	v_pk_mul_f32 v[84:85], v[84:85], v[246:247] op_sel_hi:[1,0]
	v_pk_mul_f32 v[86:87], v[86:87], v[246:247] op_sel_hi:[1,0]
	v_pk_mul_f32 v[88:89], v[88:89], v[246:247] op_sel_hi:[1,0]
	v_pk_mul_f32 v[90:91], v[90:91], v[246:247] op_sel_hi:[1,0]
	v_pk_mul_f32 v[92:93], v[92:93], v[246:247] op_sel_hi:[1,0]
	v_pk_mul_f32 v[94:95], v[94:95], v[246:247] op_sel_hi:[1,0]
	v_pk_mul_f32 v[96:97], v[96:97], v[246:247] op_sel_hi:[1,0]
	v_pk_mul_f32 v[98:99], v[98:99], v[246:247] op_sel_hi:[1,0]
	v_pk_mul_f32 v[100:101], v[100:101], v[246:247] op_sel_hi:[1,0]
	v_pk_mul_f32 v[102:103], v[102:103], v[246:247] op_sel_hi:[1,0]
	s_add_u32 s8, s10, 0xa0000
	s_addc_u32 s9, s11, 0
	v_pk_fma_f32 v[72:73], v[8:9], v[72:73], v[40:41]
	v_cvt_pk_bf16_f32 v232, v72, v73
	v_pk_fma_f32 v[74:75], v[10:11], v[74:75], v[42:43]
	v_cvt_pk_bf16_f32 v233, v74, v75
	v_pk_fma_f32 v[76:77], v[12:13], v[76:77], v[44:45]
	v_cvt_pk_bf16_f32 v234, v76, v77
	v_pk_fma_f32 v[78:79], v[14:15], v[78:79], v[46:47]
	v_cvt_pk_bf16_f32 v235, v78, v79
	global_store_dwordx4 v1, v[232:235], s[8:9] offset:0
	v_pk_fma_f32 v[80:81], v[16:17], v[80:81], v[48:49]
	v_cvt_pk_bf16_f32 v236, v80, v81
	v_pk_fma_f32 v[82:83], v[18:19], v[82:83], v[50:51]
	v_cvt_pk_bf16_f32 v237, v82, v83
	v_pk_fma_f32 v[84:85], v[20:21], v[84:85], v[52:53]
	v_cvt_pk_bf16_f32 v238, v84, v85
	v_pk_fma_f32 v[86:87], v[22:23], v[86:87], v[54:55]
	v_cvt_pk_bf16_f32 v239, v86, v87
	global_store_dwordx4 v1, v[236:239], s[8:9] offset:1024
	v_pk_fma_f32 v[88:89], v[24:25], v[88:89], v[56:57]
	v_cvt_pk_bf16_f32 v232, v88, v89
	v_pk_fma_f32 v[90:91], v[26:27], v[90:91], v[58:59]
	v_cvt_pk_bf16_f32 v233, v90, v91
	v_pk_fma_f32 v[92:93], v[28:29], v[92:93], v[60:61]
	v_cvt_pk_bf16_f32 v234, v92, v93
	v_pk_fma_f32 v[94:95], v[30:31], v[94:95], v[62:63]
	v_cvt_pk_bf16_f32 v235, v94, v95
	global_store_dwordx4 v1, v[232:235], s[8:9] offset:2048
	v_pk_fma_f32 v[96:97], v[32:33], v[96:97], v[64:65]
	v_cvt_pk_bf16_f32 v236, v96, v97
	v_pk_fma_f32 v[98:99], v[34:35], v[98:99], v[66:67]
	v_cvt_pk_bf16_f32 v237, v98, v99
	v_pk_fma_f32 v[100:101], v[36:37], v[100:101], v[68:69]
	v_cvt_pk_bf16_f32 v238, v100, v101
	v_pk_fma_f32 v[102:103], v[38:39], v[102:103], v[70:71]
	v_cvt_pk_bf16_f32 v239, v102, v103
	global_store_dwordx4 v1, v[236:239], s[8:9] offset:3072
	s_waitcnt vmcnt(28)
	v_cvt_f32_f16_e32 v72, v200
	v_cvt_f32_f16_sdwa v73, v200 dst_sel:DWORD dst_unused:UNUSED_PAD src0_sel:WORD_1
	v_cvt_f32_f16_e32 v74, v201
	v_cvt_f32_f16_sdwa v75, v201 dst_sel:DWORD dst_unused:UNUSED_PAD src0_sel:WORD_1
	v_cvt_f32_f16_e32 v76, v202
	v_cvt_f32_f16_sdwa v77, v202 dst_sel:DWORD dst_unused:UNUSED_PAD src0_sel:WORD_1
	v_cvt_f32_f16_e32 v78, v203
	v_cvt_f32_f16_sdwa v79, v203 dst_sel:DWORD dst_unused:UNUSED_PAD src0_sel:WORD_1
	v_cvt_f32_f16_e32 v80, v204
	v_cvt_f32_f16_sdwa v81, v204 dst_sel:DWORD dst_unused:UNUSED_PAD src0_sel:WORD_1
	v_cvt_f32_f16_e32 v82, v205
	v_cvt_f32_f16_sdwa v83, v205 dst_sel:DWORD dst_unused:UNUSED_PAD src0_sel:WORD_1
	v_cvt_f32_f16_e32 v84, v206
	v_cvt_f32_f16_sdwa v85, v206 dst_sel:DWORD dst_unused:UNUSED_PAD src0_sel:WORD_1
	v_cvt_f32_f16_e32 v86, v207
	v_cvt_f32_f16_sdwa v87, v207 dst_sel:DWORD dst_unused:UNUSED_PAD src0_sel:WORD_1
	v_cvt_f32_f16_e32 v88, v208
	v_cvt_f32_f16_sdwa v89, v208 dst_sel:DWORD dst_unused:UNUSED_PAD src0_sel:WORD_1
	v_cvt_f32_f16_e32 v90, v209
	v_cvt_f32_f16_sdwa v91, v209 dst_sel:DWORD dst_unused:UNUSED_PAD src0_sel:WORD_1
	v_cvt_f32_f16_e32 v92, v210
	v_cvt_f32_f16_sdwa v93, v210 dst_sel:DWORD dst_unused:UNUSED_PAD src0_sel:WORD_1
	v_cvt_f32_f16_e32 v94, v211
	v_cvt_f32_f16_sdwa v95, v211 dst_sel:DWORD dst_unused:UNUSED_PAD src0_sel:WORD_1
	v_cvt_f32_f16_e32 v96, v212
	v_cvt_f32_f16_sdwa v97, v212 dst_sel:DWORD dst_unused:UNUSED_PAD src0_sel:WORD_1
	v_cvt_f32_f16_e32 v98, v213
	v_cvt_f32_f16_sdwa v99, v213 dst_sel:DWORD dst_unused:UNUSED_PAD src0_sel:WORD_1
	v_cvt_f32_f16_e32 v100, v214
	v_cvt_f32_f16_sdwa v101, v214 dst_sel:DWORD dst_unused:UNUSED_PAD src0_sel:WORD_1
	v_cvt_f32_f16_e32 v102, v215
	v_cvt_f32_f16_sdwa v103, v215 dst_sel:DWORD dst_unused:UNUSED_PAD src0_sel:WORD_1
	v_pk_mul_f32 v[232:233], v[72:73], v[72:73]
	v_pk_mul_f32 v[234:235], v[74:75], v[74:75]
	v_pk_mul_f32 v[236:237], v[76:77], v[76:77]
	v_pk_mul_f32 v[238:239], v[78:79], v[78:79]
	v_pk_fma_f32 v[232:233], v[80:81], v[80:81], v[232:233]
	v_pk_fma_f32 v[234:235], v[82:83], v[82:83], v[234:235]
	v_pk_fma_f32 v[236:237], v[84:85], v[84:85], v[236:237]
	v_pk_fma_f32 v[238:239], v[86:87], v[86:87], v[238:239]
	v_pk_fma_f32 v[232:233], v[88:89], v[88:89], v[232:233]
	v_pk_fma_f32 v[234:235], v[90:91], v[90:91], v[234:235]
	v_pk_fma_f32 v[236:237], v[92:93], v[92:93], v[236:237]
	v_pk_fma_f32 v[238:239], v[94:95], v[94:95], v[238:239]
	v_pk_fma_f32 v[232:233], v[96:97], v[96:97], v[232:233]
	v_pk_fma_f32 v[234:235], v[98:99], v[98:99], v[234:235]
	v_pk_fma_f32 v[236:237], v[100:101], v[100:101], v[236:237]
	v_pk_fma_f32 v[238:239], v[102:103], v[102:103], v[238:239]
	v_pk_add_f32 v[232:233], v[232:233], v[234:235]
	v_pk_add_f32 v[236:237], v[236:237], v[238:239]
	v_pk_add_f32 v[232:233], v[232:233], v[236:237]
	v_add_f32_e32 v240, v232, v233
	s_nop 1
	v_add_f32_dpp v240, v240, v240 quad_perm:[1,0,3,2] row_mask:0xf bank_mask:0xf
	s_nop 1
	v_add_f32_dpp v240, v240, v240 quad_perm:[2,3,0,1] row_mask:0xf bank_mask:0xf
	s_nop 1
	v_add_f32_dpp v240, v240, v240 row_half_mirror row_mask:0xf bank_mask:0xf
	s_nop 1
	v_add_f32_dpp v240, v240, v240 row_mirror row_mask:0xf bank_mask:0xf
	s_nop 1
	v_readlane_b32 s0, v240, 0
	v_readlane_b32 s1, v240, 16
	v_readlane_b32 s4, v240, 32
	v_readlane_b32 s5, v240, 48
	v_mov_b32_e32 v249, 0x358637bd
	s_nop 1
	v_mov_b32_e32 v240, s0
	v_add_f32_e32 v240, s1, v240
	v_add_f32_e32 v240, s4, v240
	v_add_f32_e32 v240, s5, v240
	v_fmamk_f32 v240, v240, 0x3a000000, v249
	s_mov_b32 s0, 0xf800000
	v_mul_f32_e32 v241, 0x4f800000, v240
	v_cmp_gt_f32_e32 vcc, s0, v240
	s_nop 1
	v_cndmask_b32_e32 v240, v240, v241, vcc
	v_sqrt_f32_e32 v241, v240
	s_nop 0
	v_add_u32_e32 v242, -1, v241
	v_fma_f32 v243, -v242, v241, v240
	v_cmp_ge_f32_e64 s[0:1], 0, v243
	v_add_u32_e32 v243, 1, v241
	s_nop 0
	v_cndmask_b32_e64 v242, v241, v242, s[0:1]
	v_fma_f32 v241, -v243, v241, v240
	v_cmp_lt_f32_e64 s[0:1], 0, v241
	s_nop 1
	v_cndmask_b32_e64 v241, v242, v243, s[0:1]
	v_mul_f32_e32 v242, 0x37800000, v241
	v_cndmask_b32_e32 v241, v241, v242, vcc
	v_cmp_class_f32_e32 vcc, v240, v248
	s_nop 1
	v_cndmask_b32_e32 v240, v241, v240, vcc
	v_div_scale_f32 v241, s[0:1], v240, v240, 1.0
	v_rcp_f32_e32 v242, v241
	s_nop 0
	v_fma_f32 v243, -v241, v242, 1.0
	v_fmac_f32_e32 v242, v243, v242
	v_div_scale_f32 v243, vcc, 1.0, v240, 1.0
	v_mul_f32_e32 v244, v243, v242
	v_fma_f32 v247, -v241, v244, v243
	v_fmac_f32_e32 v244, v247, v242
	v_fma_f32 v241, -v241, v244, v243
	s_nop 1
	v_div_fmas_f32 v241, v241, v242, v244
	v_div_fixup_f32 v246, v241, v240, 1.0
	v_pk_mul_f32 v[72:73], v[72:73], v[246:247] op_sel_hi:[1,0]
	v_pk_mul_f32 v[74:75], v[74:75], v[246:247] op_sel_hi:[1,0]
	v_pk_mul_f32 v[76:77], v[76:77], v[246:247] op_sel_hi:[1,0]
	v_pk_mul_f32 v[78:79], v[78:79], v[246:247] op_sel_hi:[1,0]
	v_pk_mul_f32 v[80:81], v[80:81], v[246:247] op_sel_hi:[1,0]
	v_pk_mul_f32 v[82:83], v[82:83], v[246:247] op_sel_hi:[1,0]
	v_pk_mul_f32 v[84:85], v[84:85], v[246:247] op_sel_hi:[1,0]
	v_pk_mul_f32 v[86:87], v[86:87], v[246:247] op_sel_hi:[1,0]
	v_pk_mul_f32 v[88:89], v[88:89], v[246:247] op_sel_hi:[1,0]
	v_pk_mul_f32 v[90:91], v[90:91], v[246:247] op_sel_hi:[1,0]
	v_pk_mul_f32 v[92:93], v[92:93], v[246:247] op_sel_hi:[1,0]
	v_pk_mul_f32 v[94:95], v[94:95], v[246:247] op_sel_hi:[1,0]
	v_pk_mul_f32 v[96:97], v[96:97], v[246:247] op_sel_hi:[1,0]
	v_pk_mul_f32 v[98:99], v[98:99], v[246:247] op_sel_hi:[1,0]
	v_pk_mul_f32 v[100:101], v[100:101], v[246:247] op_sel_hi:[1,0]
	v_pk_mul_f32 v[102:103], v[102:103], v[246:247] op_sel_hi:[1,0]
	s_add_u32 s8, s10, 0xc0000
	s_addc_u32 s9, s11, 0
	v_pk_fma_f32 v[72:73], v[8:9], v[72:73], v[40:41]
	v_cvt_pk_bf16_f32 v232, v72, v73
	v_pk_fma_f32 v[74:75], v[10:11], v[74:75], v[42:43]
	v_cvt_pk_bf16_f32 v233, v74, v75
	v_pk_fma_f32 v[76:77], v[12:13], v[76:77], v[44:45]
	v_cvt_pk_bf16_f32 v234, v76, v77
	v_pk_fma_f32 v[78:79], v[14:15], v[78:79], v[46:47]
	v_cvt_pk_bf16_f32 v235, v78, v79
	global_store_dwordx4 v1, v[232:235], s[8:9] offset:0
	v_pk_fma_f32 v[80:81], v[16:17], v[80:81], v[48:49]
	v_cvt_pk_bf16_f32 v236, v80, v81
	v_pk_fma_f32 v[82:83], v[18:19], v[82:83], v[50:51]
	v_cvt_pk_bf16_f32 v237, v82, v83
	v_pk_fma_f32 v[84:85], v[20:21], v[84:85], v[52:53]
	v_cvt_pk_bf16_f32 v238, v84, v85
	v_pk_fma_f32 v[86:87], v[22:23], v[86:87], v[54:55]
	v_cvt_pk_bf16_f32 v239, v86, v87
	global_store_dwordx4 v1, v[236:239], s[8:9] offset:1024
	v_pk_fma_f32 v[88:89], v[24:25], v[88:89], v[56:57]
	v_cvt_pk_bf16_f32 v232, v88, v89
	v_pk_fma_f32 v[90:91], v[26:27], v[90:91], v[58:59]
	v_cvt_pk_bf16_f32 v233, v90, v91
	v_pk_fma_f32 v[92:93], v[28:29], v[92:93], v[60:61]
	v_cvt_pk_bf16_f32 v234, v92, v93
	v_pk_fma_f32 v[94:95], v[30:31], v[94:95], v[62:63]
	v_cvt_pk_bf16_f32 v235, v94, v95
	global_store_dwordx4 v1, v[232:235], s[8:9] offset:2048
	v_pk_fma_f32 v[96:97], v[32:33], v[96:97], v[64:65]
	v_cvt_pk_bf16_f32 v236, v96, v97
	v_pk_fma_f32 v[98:99], v[34:35], v[98:99], v[66:67]
	v_cvt_pk_bf16_f32 v237, v98, v99
	v_pk_fma_f32 v[100:101], v[36:37], v[100:101], v[68:69]
	v_cvt_pk_bf16_f32 v238, v100, v101
	v_pk_fma_f32 v[102:103], v[38:39], v[102:103], v[70:71]
	v_cvt_pk_bf16_f32 v239, v102, v103
	global_store_dwordx4 v1, v[236:239], s[8:9] offset:3072
	s_waitcnt vmcnt(28)
	v_cvt_f32_f16_e32 v72, v216
	v_cvt_f32_f16_sdwa v73, v216 dst_sel:DWORD dst_unused:UNUSED_PAD src0_sel:WORD_1
	v_cvt_f32_f16_e32 v74, v217
	v_cvt_f32_f16_sdwa v75, v217 dst_sel:DWORD dst_unused:UNUSED_PAD src0_sel:WORD_1
	v_cvt_f32_f16_e32 v76, v218
	v_cvt_f32_f16_sdwa v77, v218 dst_sel:DWORD dst_unused:UNUSED_PAD src0_sel:WORD_1
	v_cvt_f32_f16_e32 v78, v219
	v_cvt_f32_f16_sdwa v79, v219 dst_sel:DWORD dst_unused:UNUSED_PAD src0_sel:WORD_1
	v_cvt_f32_f16_e32 v80, v220
	v_cvt_f32_f16_sdwa v81, v220 dst_sel:DWORD dst_unused:UNUSED_PAD src0_sel:WORD_1
	v_cvt_f32_f16_e32 v82, v221
	v_cvt_f32_f16_sdwa v83, v221 dst_sel:DWORD dst_unused:UNUSED_PAD src0_sel:WORD_1
	v_cvt_f32_f16_e32 v84, v222
	v_cvt_f32_f16_sdwa v85, v222 dst_sel:DWORD dst_unused:UNUSED_PAD src0_sel:WORD_1
	v_cvt_f32_f16_e32 v86, v223
	v_cvt_f32_f16_sdwa v87, v223 dst_sel:DWORD dst_unused:UNUSED_PAD src0_sel:WORD_1
	v_cvt_f32_f16_e32 v88, v224
	v_cvt_f32_f16_sdwa v89, v224 dst_sel:DWORD dst_unused:UNUSED_PAD src0_sel:WORD_1
	v_cvt_f32_f16_e32 v90, v225
	v_cvt_f32_f16_sdwa v91, v225 dst_sel:DWORD dst_unused:UNUSED_PAD src0_sel:WORD_1
	v_cvt_f32_f16_e32 v92, v226
	v_cvt_f32_f16_sdwa v93, v226 dst_sel:DWORD dst_unused:UNUSED_PAD src0_sel:WORD_1
	v_cvt_f32_f16_e32 v94, v227
	v_cvt_f32_f16_sdwa v95, v227 dst_sel:DWORD dst_unused:UNUSED_PAD src0_sel:WORD_1
	v_cvt_f32_f16_e32 v96, v228
	v_cvt_f32_f16_sdwa v97, v228 dst_sel:DWORD dst_unused:UNUSED_PAD src0_sel:WORD_1
	v_cvt_f32_f16_e32 v98, v229
	v_cvt_f32_f16_sdwa v99, v229 dst_sel:DWORD dst_unused:UNUSED_PAD src0_sel:WORD_1
	v_cvt_f32_f16_e32 v100, v230
	v_cvt_f32_f16_sdwa v101, v230 dst_sel:DWORD dst_unused:UNUSED_PAD src0_sel:WORD_1
	v_cvt_f32_f16_e32 v102, v231
	v_cvt_f32_f16_sdwa v103, v231 dst_sel:DWORD dst_unused:UNUSED_PAD src0_sel:WORD_1
	v_pk_mul_f32 v[232:233], v[72:73], v[72:73]
	v_pk_mul_f32 v[234:235], v[74:75], v[74:75]
	v_pk_mul_f32 v[236:237], v[76:77], v[76:77]
	v_pk_mul_f32 v[238:239], v[78:79], v[78:79]
	v_pk_fma_f32 v[232:233], v[80:81], v[80:81], v[232:233]
	v_pk_fma_f32 v[234:235], v[82:83], v[82:83], v[234:235]
	v_pk_fma_f32 v[236:237], v[84:85], v[84:85], v[236:237]
	v_pk_fma_f32 v[238:239], v[86:87], v[86:87], v[238:239]
	v_pk_fma_f32 v[232:233], v[88:89], v[88:89], v[232:233]
	v_pk_fma_f32 v[234:235], v[90:91], v[90:91], v[234:235]
	v_pk_fma_f32 v[236:237], v[92:93], v[92:93], v[236:237]
	v_pk_fma_f32 v[238:239], v[94:95], v[94:95], v[238:239]
	v_pk_fma_f32 v[232:233], v[96:97], v[96:97], v[232:233]
	v_pk_fma_f32 v[234:235], v[98:99], v[98:99], v[234:235]
	v_pk_fma_f32 v[236:237], v[100:101], v[100:101], v[236:237]
	v_pk_fma_f32 v[238:239], v[102:103], v[102:103], v[238:239]
	v_pk_add_f32 v[232:233], v[232:233], v[234:235]
	v_pk_add_f32 v[236:237], v[236:237], v[238:239]
	v_pk_add_f32 v[232:233], v[232:233], v[236:237]
	v_add_f32_e32 v240, v232, v233
	s_nop 1
	v_add_f32_dpp v240, v240, v240 quad_perm:[1,0,3,2] row_mask:0xf bank_mask:0xf
	s_nop 1
	v_add_f32_dpp v240, v240, v240 quad_perm:[2,3,0,1] row_mask:0xf bank_mask:0xf
	s_nop 1
	v_add_f32_dpp v240, v240, v240 row_half_mirror row_mask:0xf bank_mask:0xf
	s_nop 1
	v_add_f32_dpp v240, v240, v240 row_mirror row_mask:0xf bank_mask:0xf
	s_nop 1
	v_readlane_b32 s0, v240, 0
	v_readlane_b32 s1, v240, 16
	v_readlane_b32 s4, v240, 32
	v_readlane_b32 s5, v240, 48
	v_mov_b32_e32 v249, 0x358637bd
	s_nop 1
	v_mov_b32_e32 v240, s0
	v_add_f32_e32 v240, s1, v240
	v_add_f32_e32 v240, s4, v240
	v_add_f32_e32 v240, s5, v240
	v_fmamk_f32 v240, v240, 0x3a000000, v249
	s_mov_b32 s0, 0xf800000
	v_mul_f32_e32 v241, 0x4f800000, v240
	v_cmp_gt_f32_e32 vcc, s0, v240
	s_nop 1
	v_cndmask_b32_e32 v240, v240, v241, vcc
	v_sqrt_f32_e32 v241, v240
	s_nop 0
	v_add_u32_e32 v242, -1, v241
	v_fma_f32 v243, -v242, v241, v240
	v_cmp_ge_f32_e64 s[0:1], 0, v243
	v_add_u32_e32 v243, 1, v241
	s_nop 0
	v_cndmask_b32_e64 v242, v241, v242, s[0:1]
	v_fma_f32 v241, -v243, v241, v240
	v_cmp_lt_f32_e64 s[0:1], 0, v241
	s_nop 1
	v_cndmask_b32_e64 v241, v242, v243, s[0:1]
	v_mul_f32_e32 v242, 0x37800000, v241
	v_cndmask_b32_e32 v241, v241, v242, vcc
	v_cmp_class_f32_e32 vcc, v240, v248
	s_nop 1
	v_cndmask_b32_e32 v240, v241, v240, vcc
	v_div_scale_f32 v241, s[0:1], v240, v240, 1.0
	v_rcp_f32_e32 v242, v241
	s_nop 0
	v_fma_f32 v243, -v241, v242, 1.0
	v_fmac_f32_e32 v242, v243, v242
	v_div_scale_f32 v243, vcc, 1.0, v240, 1.0
	v_mul_f32_e32 v244, v243, v242
	v_fma_f32 v247, -v241, v244, v243
	v_fmac_f32_e32 v244, v247, v242
	v_fma_f32 v241, -v241, v244, v243
	s_nop 1
	v_div_fmas_f32 v241, v241, v242, v244
	v_div_fixup_f32 v246, v241, v240, 1.0
	v_pk_mul_f32 v[72:73], v[72:73], v[246:247] op_sel_hi:[1,0]
	v_pk_mul_f32 v[74:75], v[74:75], v[246:247] op_sel_hi:[1,0]
	v_pk_mul_f32 v[76:77], v[76:77], v[246:247] op_sel_hi:[1,0]
	v_pk_mul_f32 v[78:79], v[78:79], v[246:247] op_sel_hi:[1,0]
	v_pk_mul_f32 v[80:81], v[80:81], v[246:247] op_sel_hi:[1,0]
	v_pk_mul_f32 v[82:83], v[82:83], v[246:247] op_sel_hi:[1,0]
	v_pk_mul_f32 v[84:85], v[84:85], v[246:247] op_sel_hi:[1,0]
	v_pk_mul_f32 v[86:87], v[86:87], v[246:247] op_sel_hi:[1,0]
	v_pk_mul_f32 v[88:89], v[88:89], v[246:247] op_sel_hi:[1,0]
	v_pk_mul_f32 v[90:91], v[90:91], v[246:247] op_sel_hi:[1,0]
	v_pk_mul_f32 v[92:93], v[92:93], v[246:247] op_sel_hi:[1,0]
	v_pk_mul_f32 v[94:95], v[94:95], v[246:247] op_sel_hi:[1,0]
	v_pk_mul_f32 v[96:97], v[96:97], v[246:247] op_sel_hi:[1,0]
	v_pk_mul_f32 v[98:99], v[98:99], v[246:247] op_sel_hi:[1,0]
	v_pk_mul_f32 v[100:101], v[100:101], v[246:247] op_sel_hi:[1,0]
	v_pk_mul_f32 v[102:103], v[102:103], v[246:247] op_sel_hi:[1,0]
	s_add_u32 s8, s10, 0xe0000
	s_addc_u32 s9, s11, 0
	v_pk_fma_f32 v[72:73], v[8:9], v[72:73], v[40:41]
	v_cvt_pk_bf16_f32 v232, v72, v73
	v_pk_fma_f32 v[74:75], v[10:11], v[74:75], v[42:43]
	v_cvt_pk_bf16_f32 v233, v74, v75
	v_pk_fma_f32 v[76:77], v[12:13], v[76:77], v[44:45]
	v_cvt_pk_bf16_f32 v234, v76, v77
	v_pk_fma_f32 v[78:79], v[14:15], v[78:79], v[46:47]
	v_cvt_pk_bf16_f32 v235, v78, v79
	global_store_dwordx4 v1, v[232:235], s[8:9] offset:0
	v_pk_fma_f32 v[80:81], v[16:17], v[80:81], v[48:49]
	v_cvt_pk_bf16_f32 v236, v80, v81
	v_pk_fma_f32 v[82:83], v[18:19], v[82:83], v[50:51]
	v_cvt_pk_bf16_f32 v237, v82, v83
	v_pk_fma_f32 v[84:85], v[20:21], v[84:85], v[52:53]
	v_cvt_pk_bf16_f32 v238, v84, v85
	v_pk_fma_f32 v[86:87], v[22:23], v[86:87], v[54:55]
	v_cvt_pk_bf16_f32 v239, v86, v87
	global_store_dwordx4 v1, v[236:239], s[8:9] offset:1024
	v_pk_fma_f32 v[88:89], v[24:25], v[88:89], v[56:57]
	v_cvt_pk_bf16_f32 v232, v88, v89
	v_pk_fma_f32 v[90:91], v[26:27], v[90:91], v[58:59]
	v_cvt_pk_bf16_f32 v233, v90, v91
	v_pk_fma_f32 v[92:93], v[28:29], v[92:93], v[60:61]
	v_cvt_pk_bf16_f32 v234, v92, v93
	v_pk_fma_f32 v[94:95], v[30:31], v[94:95], v[62:63]
	v_cvt_pk_bf16_f32 v235, v94, v95
	global_store_dwordx4 v1, v[232:235], s[8:9] offset:2048
	v_pk_fma_f32 v[96:97], v[32:33], v[96:97], v[64:65]
	v_cvt_pk_bf16_f32 v236, v96, v97
	v_pk_fma_f32 v[98:99], v[34:35], v[98:99], v[66:67]
	v_cvt_pk_bf16_f32 v237, v98, v99
	v_pk_fma_f32 v[100:101], v[36:37], v[100:101], v[68:69]
	v_cvt_pk_bf16_f32 v238, v100, v101
	v_pk_fma_f32 v[102:103], v[38:39], v[102:103], v[70:71]
	v_cvt_pk_bf16_f32 v239, v102, v103
	global_store_dwordx4 v1, v[236:239], s[8:9] offset:3072
	s_branch .LBB0_563
.Lnorm_fb_0:
	s_mov_b64 s[6:7], s[88:89]
	v_mov_b32_e32 v1, v0
	s_mov_b32 s0, s72
	s_add_i32 s0, 0, 0x2416c
	v_mov_b32_e32 v2, s0
	s_add_i32 s0, 0, 0x24170
	ds_read_b32 v2, v2
	s_waitcnt vmcnt(30)
	v_mov_b32_e32 v3, s0
	ds_read_b32 v3, v3
	v_readfirstlane_b32 s0, v1
	s_ashr_i32 s1, s0, 6
	s_waitcnt lgkmcnt(1)
	v_readfirstlane_b32 s5, v2
	s_cmp_lt_i32 s5, 1
	s_waitcnt lgkmcnt(0)
	v_readfirstlane_b32 s10, v3
	s_cbranch_scc0 .LBB0_554
	s_lshl_b32 s0, s72, 3
	s_add_i32 s0, s1, s0
	s_lshl_b32 s4, s38, 3
	s_movk_i32 s14, 0x4000
	s_cbranch_execz .LBB0_555
	s_branch .LBB0_556

.LBB0_1131:
	v_readlane_b32 s4, v250, 12
	s_cmp_lt_i32 s4, 10
	s_cselect_b64 s[0:1], -1, 0
	s_and_b64 s[2:3], s[0:1], s[2:3]
	s_andn2_b64 vcc, exec, s[2:3]
	v_readlane_b32 s5, v250, 13
	v_readlane_b32 s6, v250, 14
	v_readlane_b32 s7, v250, 15
	s_cbranch_vccnz .LBB0_1143
	v_and_b32_e32 v1, 63, v0
	v_lshlrev_b32_e32 v2, 5, v1
	v_add_u32_e32 v3, 0x1000, v2
	v_lshlrev_b32_e32 v1, 4, v1
	v_mov_b32_e32 v4, 0x2416c
	ds_read_b32 v5, v4
	ds_read_b32 v6, v4 offset:4
	v_readfirstlane_b32 s0, v0
	s_lshr_b32 s1, s0, 6
	s_waitcnt lgkmcnt(0)
	v_readfirstlane_b32 s4, v5
	v_readfirstlane_b32 s5, v6
	s_cmp_lt_i32 s4, 1
	s_cbranch_scc1 .Lnorm_fb_1
	s_add_i32 s4, s4, -1
	s_lshl_b32 s18, s4, 8
	s_lshl_b32 s19, s5, 3
	s_add_i32 s18, s18, s19
	s_add_i32 s18, s18, s1
	s_lshr_b32 s19, s4, 4
	s_lshl_b32 s20, s18, 12
	s_add_u32 s6, s88, 0x45c00000
	s_addc_u32 s7, s89, 0
	s_add_u32 s6, s6, s20
	s_addc_u32 s7, s7, 0
	s_add_u32 s10, s88, 0x13e00000
	s_addc_u32 s11, s89, 0
	s_add_u32 s10, s10, s20
	s_addc_u32 s11, s11, 0
	s_add_u32 s12, s44, 0x4000
	s_addc_u32 s13, s45, 0
	s_mul_i32 s21, s19, 0x12000
	s_add_u32 s14, s88, 0x10c000
	s_addc_u32 s15, s89, 0
	s_add_u32 s14, s14, s21
	s_addc_u32 s15, s15, 0
	s_add_u32 s16, s88, 0x10e000
	s_addc_u32 s17, s89, 0
	s_add_u32 s16, s16, s21
	s_addc_u32 s17, s17, 0
	global_load_dwordx4 v[72:75], v2, s[12:13] offset:0
	global_load_dwordx4 v[76:79], v2, s[12:13] offset:16
	global_load_dwordx4 v[80:83], v2, s[12:13] offset:2048
	global_load_dwordx4 v[84:87], v2, s[12:13] offset:2064
	global_load_dwordx4 v[88:91], v3, s[12:13] offset:0
	global_load_dwordx4 v[92:95], v3, s[12:13] offset:16
	global_load_dwordx4 v[96:99], v3, s[12:13] offset:2048
	global_load_dwordx4 v[100:103], v3, s[12:13] offset:2064
	global_load_dwordx4 v[8:11], v2, s[16:17] offset:0
	global_load_dwordx4 v[12:15], v2, s[16:17] offset:16
	global_load_dwordx4 v[16:19], v2, s[16:17] offset:2048
	global_load_dwordx4 v[20:23], v2, s[16:17] offset:2064
	global_load_dwordx4 v[24:27], v3, s[16:17] offset:0
	global_load_dwordx4 v[28:31], v3, s[16:17] offset:16
	global_load_dwordx4 v[32:35], v3, s[16:17] offset:2048
	global_load_dwordx4 v[36:39], v3, s[16:17] offset:2064
	global_load_dwordx4 v[40:43], v2, s[14:15] offset:0
	global_load_dwordx4 v[44:47], v2, s[14:15] offset:16
	global_load_dwordx4 v[48:51], v2, s[14:15] offset:2048
	global_load_dwordx4 v[52:55], v2, s[14:15] offset:2064
	global_load_dwordx4 v[56:59], v3, s[14:15] offset:0
	global_load_dwordx4 v[60:63], v3, s[14:15] offset:16
	global_load_dwordx4 v[64:67], v3, s[14:15] offset:2048
	global_load_dwordx4 v[68:71], v3, s[14:15] offset:2064
	s_add_u32 s8, s6, 0x0
	s_addc_u32 s9, s7, 0
	global_load_dwordx4 v[104:107], v1, s[8:9] offset:0 nt
	global_load_dwordx4 v[108:111], v1, s[8:9] offset:1024 nt
	global_load_dwordx4 v[112:115], v1, s[8:9] offset:2048 nt
	global_load_dwordx4 v[116:119], v1, s[8:9] offset:3072 nt
	s_add_u32 s8, s6, 0x20000
	s_addc_u32 s9, s7, 0
	global_load_dwordx4 v[120:123], v1, s[8:9] offset:0 nt
	global_load_dwordx4 v[124:127], v1, s[8:9] offset:1024 nt
	global_load_dwordx4 v[128:131], v1, s[8:9] offset:2048 nt
	global_load_dwordx4 v[132:135], v1, s[8:9] offset:3072 nt
	s_add_u32 s8, s6, 0x40000
	s_addc_u32 s9, s7, 0
	global_load_dwordx4 v[136:139], v1, s[8:9] offset:0 nt
	global_load_dwordx4 v[140:143], v1, s[8:9] offset:1024 nt
	global_load_dwordx4 v[144:147], v1, s[8:9] offset:2048 nt
	global_load_dwordx4 v[148:151], v1, s[8:9] offset:3072 nt
	s_add_u32 s8, s6, 0x60000
	s_addc_u32 s9, s7, 0
	global_load_dwordx4 v[152:155], v1, s[8:9] offset:0 nt
	global_load_dwordx4 v[156:159], v1, s[8:9] offset:1024 nt
	global_load_dwordx4 v[160:163], v1, s[8:9] offset:2048 nt
	global_load_dwordx4 v[164:167], v1, s[8:9] offset:3072 nt
	s_add_u32 s8, s6, 0x80000
	s_addc_u32 s9, s7, 0
	global_load_dwordx4 v[168:171], v1, s[8:9] offset:0 nt
	global_load_dwordx4 v[172:175], v1, s[8:9] offset:1024 nt
	global_load_dwordx4 v[176:179], v1, s[8:9] offset:2048 nt
	global_load_dwordx4 v[180:183], v1, s[8:9] offset:3072 nt
	s_add_u32 s8, s6, 0xa0000
	s_addc_u32 s9, s7, 0
	global_load_dwordx4 v[184:187], v1, s[8:9] offset:0 nt
	global_load_dwordx4 v[188:191], v1, s[8:9] offset:1024 nt
	global_load_dwordx4 v[192:195], v1, s[8:9] offset:2048 nt
	global_load_dwordx4 v[196:199], v1, s[8:9] offset:3072 nt
	s_add_u32 s8, s6, 0xc0000
	s_addc_u32 s9, s7, 0
	global_load_dwordx4 v[200:203], v1, s[8:9] offset:0 nt
	global_load_dwordx4 v[204:207], v1, s[8:9] offset:1024 nt
	global_load_dwordx4 v[208:211], v1, s[8:9] offset:2048 nt
	global_load_dwordx4 v[212:215], v1, s[8:9] offset:3072 nt
	s_add_u32 s8, s6, 0xe0000
	s_addc_u32 s9, s7, 0
	global_load_dwordx4 v[216:219], v1, s[8:9] offset:0 nt
	global_load_dwordx4 v[220:223], v1, s[8:9] offset:1024 nt
	global_load_dwordx4 v[224:227], v1, s[8:9] offset:2048 nt
	global_load_dwordx4 v[228:231], v1, s[8:9] offset:3072 nt
	s_waitcnt vmcnt(32)
	v_pk_add_f32 v[8:9], v[8:9], 1.0 op_sel_hi:[1,0]
	v_pk_add_f32 v[10:11], v[10:11], 1.0 op_sel_hi:[1,0]
	v_pk_add_f32 v[12:13], v[12:13], 1.0 op_sel_hi:[1,0]
	v_pk_add_f32 v[14:15], v[14:15], 1.0 op_sel_hi:[1,0]
	v_pk_add_f32 v[16:17], v[16:17], 1.0 op_sel_hi:[1,0]
	v_pk_add_f32 v[18:19], v[18:19], 1.0 op_sel_hi:[1,0]
	v_pk_add_f32 v[20:21], v[20:21], 1.0 op_sel_hi:[1,0]
	v_pk_add_f32 v[22:23], v[22:23], 1.0 op_sel_hi:[1,0]
	v_pk_add_f32 v[24:25], v[24:25], 1.0 op_sel_hi:[1,0]
	v_pk_add_f32 v[26:27], v[26:27], 1.0 op_sel_hi:[1,0]
	v_pk_add_f32 v[28:29], v[28:29], 1.0 op_sel_hi:[1,0]
	v_pk_add_f32 v[30:31], v[30:31], 1.0 op_sel_hi:[1,0]
	v_pk_add_f32 v[32:33], v[32:33], 1.0 op_sel_hi:[1,0]
	v_pk_add_f32 v[34:35], v[34:35], 1.0 op_sel_hi:[1,0]
	v_pk_add_f32 v[36:37], v[36:37], 1.0 op_sel_hi:[1,0]
	v_pk_add_f32 v[38:39], v[38:39], 1.0 op_sel_hi:[1,0]
	v_pk_mul_f32 v[8:9], v[72:73], v[8:9]
	v_pk_mul_f32 v[10:11], v[74:75], v[10:11]
	v_pk_mul_f32 v[12:13], v[76:77], v[12:13]
	v_pk_mul_f32 v[14:15], v[78:79], v[14:15]
	v_pk_mul_f32 v[16:17], v[80:81], v[16:17]
	v_pk_mul_f32 v[18:19], v[82:83], v[18:19]
	v_pk_mul_f32 v[20:21], v[84:85], v[20:21]
	v_pk_mul_f32 v[22:23], v[86:87], v[22:23]
	v_pk_mul_f32 v[24:25], v[88:89], v[24:25]
	v_pk_mul_f32 v[26:27], v[90:91], v[26:27]
	v_pk_mul_f32 v[28:29], v[92:93], v[28:29]
	v_pk_mul_f32 v[30:31], v[94:95], v[30:31]
	v_pk_mul_f32 v[32:33], v[96:97], v[32:33]
	v_pk_mul_f32 v[34:35], v[98:99], v[34:35]
	v_pk_mul_f32 v[36:37], v[100:101], v[36:37]
	v_pk_mul_f32 v[38:39], v[102:103], v[38:39]
	v_mov_b32_e32 v248, 0x260
	s_waitcnt vmcnt(28)
	v_cvt_f32_f16_e32 v72, v104
	v_cvt_f32_f16_sdwa v73, v104 dst_sel:DWORD dst_unused:UNUSED_PAD src0_sel:WORD_1
	v_cvt_f32_f16_e32 v74, v105
	v_cvt_f32_f16_sdwa v75, v105 dst_sel:DWORD dst_unused:UNUSED_PAD src0_sel:WORD_1
	v_cvt_f32_f16_e32 v76, v106
	v_cvt_f32_f16_sdwa v77, v106 dst_sel:DWORD dst_unused:UNUSED_PAD src0_sel:WORD_1
	v_cvt_f32_f16_e32 v78, v107
	v_cvt_f32_f16_sdwa v79, v107 dst_sel:DWORD dst_unused:UNUSED_PAD src0_sel:WORD_1
	v_cvt_f32_f16_e32 v80, v108
	v_cvt_f32_f16_sdwa v81, v108 dst_sel:DWORD dst_unused:UNUSED_PAD src0_sel:WORD_1
	v_cvt_f32_f16_e32 v82, v109
	v_cvt_f32_f16_sdwa v83, v109 dst_sel:DWORD dst_unused:UNUSED_PAD src0_sel:WORD_1
	v_cvt_f32_f16_e32 v84, v110
	v_cvt_f32_f16_sdwa v85, v110 dst_sel:DWORD dst_unused:UNUSED_PAD src0_sel:WORD_1
	v_cvt_f32_f16_e32 v86, v111
	v_cvt_f32_f16_sdwa v87, v111 dst_sel:DWORD dst_unused:UNUSED_PAD src0_sel:WORD_1
	v_cvt_f32_f16_e32 v88, v112
	v_cvt_f32_f16_sdwa v89, v112 dst_sel:DWORD dst_unused:UNUSED_PAD src0_sel:WORD_1
	v_cvt_f32_f16_e32 v90, v113
	v_cvt_f32_f16_sdwa v91, v113 dst_sel:DWORD dst_unused:UNUSED_PAD src0_sel:WORD_1
	v_cvt_f32_f16_e32 v92, v114
	v_cvt_f32_f16_sdwa v93, v114 dst_sel:DWORD dst_unused:UNUSED_PAD src0_sel:WORD_1
	v_cvt_f32_f16_e32 v94, v115
	v_cvt_f32_f16_sdwa v95, v115 dst_sel:DWORD dst_unused:UNUSED_PAD src0_sel:WORD_1
	v_cvt_f32_f16_e32 v96, v116
	v_cvt_f32_f16_sdwa v97, v116 dst_sel:DWORD dst_unused:UNUSED_PAD src0_sel:WORD_1
	v_cvt_f32_f16_e32 v98, v117
	v_cvt_f32_f16_sdwa v99, v117 dst_sel:DWORD dst_unused:UNUSED_PAD src0_sel:WORD_1
	v_cvt_f32_f16_e32 v100, v118
	v_cvt_f32_f16_sdwa v101, v118 dst_sel:DWORD dst_unused:UNUSED_PAD src0_sel:WORD_1
	v_cvt_f32_f16_e32 v102, v119
	v_cvt_f32_f16_sdwa v103, v119 dst_sel:DWORD dst_unused:UNUSED_PAD src0_sel:WORD_1
	v_pk_mul_f32 v[232:233], v[72:73], v[72:73]
	v_pk_mul_f32 v[234:235], v[74:75], v[74:75]
	v_pk_mul_f32 v[236:237], v[76:77], v[76:77]
	v_pk_mul_f32 v[238:239], v[78:79], v[78:79]
	v_pk_fma_f32 v[232:233], v[80:81], v[80:81], v[232:233]
	v_pk_fma_f32 v[234:235], v[82:83], v[82:83], v[234:235]
	v_pk_fma_f32 v[236:237], v[84:85], v[84:85], v[236:237]
	v_pk_fma_f32 v[238:239], v[86:87], v[86:87], v[238:239]
	v_pk_fma_f32 v[232:233], v[88:89], v[88:89], v[232:233]
	v_pk_fma_f32 v[234:235], v[90:91], v[90:91], v[234:235]
	v_pk_fma_f32 v[236:237], v[92:93], v[92:93], v[236:237]
	v_pk_fma_f32 v[238:239], v[94:95], v[94:95], v[238:239]
	v_pk_fma_f32 v[232:233], v[96:97], v[96:97], v[232:233]
	v_pk_fma_f32 v[234:235], v[98:99], v[98:99], v[234:235]
	v_pk_fma_f32 v[236:237], v[100:101], v[100:101], v[236:237]
	v_pk_fma_f32 v[238:239], v[102:103], v[102:103], v[238:239]
	v_pk_add_f32 v[232:233], v[232:233], v[234:235]
	v_pk_add_f32 v[236:237], v[236:237], v[238:239]
	v_pk_add_f32 v[232:233], v[232:233], v[236:237]
	v_add_f32_e32 v240, v232, v233
	s_nop 1
	v_add_f32_dpp v240, v240, v240 quad_perm:[1,0,3,2] row_mask:0xf bank_mask:0xf
	s_nop 1
	v_add_f32_dpp v240, v240, v240 quad_perm:[2,3,0,1] row_mask:0xf bank_mask:0xf
	s_nop 1
	v_add_f32_dpp v240, v240, v240 row_half_mirror row_mask:0xf bank_mask:0xf
	s_nop 1
	v_add_f32_dpp v240, v240, v240 row_mirror row_mask:0xf bank_mask:0xf
	s_nop 1
	v_readlane_b32 s0, v240, 0
	v_readlane_b32 s1, v240, 16
	v_readlane_b32 s4, v240, 32
	v_readlane_b32 s5, v240, 48
	v_mov_b32_e32 v249, 0x358637bd
	s_nop 1
	v_mov_b32_e32 v240, s0
	v_add_f32_e32 v240, s1, v240
	v_add_f32_e32 v240, s4, v240
	v_add_f32_e32 v240, s5, v240
	v_fmamk_f32 v240, v240, 0x3a000000, v249
	s_mov_b32 s0, 0xf800000
	v_mul_f32_e32 v241, 0x4f800000, v240
	v_cmp_gt_f32_e32 vcc, s0, v240
	s_nop 1
	v_cndmask_b32_e32 v240, v240, v241, vcc
	v_sqrt_f32_e32 v241, v240
	s_nop 0
	v_add_u32_e32 v242, -1, v241
	v_fma_f32 v243, -v242, v241, v240
	v_cmp_ge_f32_e64 s[0:1], 0, v243
	v_add_u32_e32 v243, 1, v241
	s_nop 0
	v_cndmask_b32_e64 v242, v241, v242, s[0:1]
	v_fma_f32 v241, -v243, v241, v240
	v_cmp_lt_f32_e64 s[0:1], 0, v241
	s_nop 1
	v_cndmask_b32_e64 v241, v242, v243, s[0:1]
	v_mul_f32_e32 v242, 0x37800000, v241
	v_cndmask_b32_e32 v241, v241, v242, vcc
	v_cmp_class_f32_e32 vcc, v240, v248
	s_nop 1
	v_cndmask_b32_e32 v240, v241, v240, vcc
	v_div_scale_f32 v241, s[0:1], v240, v240, 1.0
	v_rcp_f32_e32 v242, v241
	s_nop 0
	v_fma_f32 v243, -v241, v242, 1.0
	v_fmac_f32_e32 v242, v243, v242
	v_div_scale_f32 v243, vcc, 1.0, v240, 1.0
	v_mul_f32_e32 v244, v243, v242
	v_fma_f32 v247, -v241, v244, v243
	v_fmac_f32_e32 v244, v247, v242
	v_fma_f32 v241, -v241, v244, v243
	s_nop 1
	v_div_fmas_f32 v241, v241, v242, v244
	v_div_fixup_f32 v246, v241, v240, 1.0
	v_pk_mul_f32 v[72:73], v[72:73], v[246:247] op_sel_hi:[1,0]
	v_pk_mul_f32 v[74:75], v[74:75], v[246:247] op_sel_hi:[1,0]
	v_pk_mul_f32 v[76:77], v[76:77], v[246:247] op_sel_hi:[1,0]
	v_pk_mul_f32 v[78:79], v[78:79], v[246:247] op_sel_hi:[1,0]
	v_pk_mul_f32 v[80:81], v[80:81], v[246:247] op_sel_hi:[1,0]
	v_pk_mul_f32 v[82:83], v[82:83], v[246:247] op_sel_hi:[1,0]
	v_pk_mul_f32 v[84:85], v[84:85], v[246:247] op_sel_hi:[1,0]
	v_pk_mul_f32 v[86:87], v[86:87], v[246:247] op_sel_hi:[1,0]
	v_pk_mul_f32 v[88:89], v[88:89], v[246:247] op_sel_hi:[1,0]
	v_pk_mul_f32 v[90:91], v[90:91], v[246:247] op_sel_hi:[1,0]
	v_pk_mul_f32 v[92:93], v[92:93], v[246:247] op_sel_hi:[1,0]
	v_pk_mul_f32 v[94:95], v[94:95], v[246:247] op_sel_hi:[1,0]
	v_pk_mul_f32 v[96:97], v[96:97], v[246:247] op_sel_hi:[1,0]
	v_pk_mul_f32 v[98:99], v[98:99], v[246:247] op_sel_hi:[1,0]
	v_pk_mul_f32 v[100:101], v[100:101], v[246:247] op_sel_hi:[1,0]
	v_pk_mul_f32 v[102:103], v[102:103], v[246:247] op_sel_hi:[1,0]
	s_add_u32 s8, s10, 0x0
	s_addc_u32 s9, s11, 0
	v_pk_fma_f32 v[72:73], v[8:9], v[72:73], v[40:41]
	v_cvt_pk_bf16_f32 v232, v72, v73
	v_pk_fma_f32 v[74:75], v[10:11], v[74:75], v[42:43]
	v_cvt_pk_bf16_f32 v233, v74, v75
	v_pk_fma_f32 v[76:77], v[12:13], v[76:77], v[44:45]
	v_cvt_pk_bf16_f32 v234, v76, v77
	v_pk_fma_f32 v[78:79], v[14:15], v[78:79], v[46:47]
	v_cvt_pk_bf16_f32 v235, v78, v79
	global_store_dwordx4 v1, v[232:235], s[8:9] offset:0
	v_pk_fma_f32 v[80:81], v[16:17], v[80:81], v[48:49]
	v_cvt_pk_bf16_f32 v236, v80, v81
	v_pk_fma_f32 v[82:83], v[18:19], v[82:83], v[50:51]
	v_cvt_pk_bf16_f32 v237, v82, v83
	v_pk_fma_f32 v[84:85], v[20:21], v[84:85], v[52:53]
	v_cvt_pk_bf16_f32 v238, v84, v85
	v_pk_fma_f32 v[86:87], v[22:23], v[86:87], v[54:55]
	v_cvt_pk_bf16_f32 v239, v86, v87
	global_store_dwordx4 v1, v[236:239], s[8:9] offset:1024
	v_pk_fma_f32 v[88:89], v[24:25], v[88:89], v[56:57]
	v_cvt_pk_bf16_f32 v232, v88, v89
	v_pk_fma_f32 v[90:91], v[26:27], v[90:91], v[58:59]
	v_cvt_pk_bf16_f32 v233, v90, v91
	v_pk_fma_f32 v[92:93], v[28:29], v[92:93], v[60:61]
	v_cvt_pk_bf16_f32 v234, v92, v93
	v_pk_fma_f32 v[94:95], v[30:31], v[94:95], v[62:63]
	v_cvt_pk_bf16_f32 v235, v94, v95
	global_store_dwordx4 v1, v[232:235], s[8:9] offset:2048
	v_pk_fma_f32 v[96:97], v[32:33], v[96:97], v[64:65]
	v_cvt_pk_bf16_f32 v236, v96, v97
	v_pk_fma_f32 v[98:99], v[34:35], v[98:99], v[66:67]
	v_cvt_pk_bf16_f32 v237, v98, v99
	v_pk_fma_f32 v[100:101], v[36:37], v[100:101], v[68:69]
	v_cvt_pk_bf16_f32 v238, v100, v101
	v_pk_fma_f32 v[102:103], v[38:39], v[102:103], v[70:71]
	v_cvt_pk_bf16_f32 v239, v102, v103
	global_store_dwordx4 v1, v[236:239], s[8:9] offset:3072
	s_waitcnt vmcnt(28)
	v_cvt_f32_f16_e32 v72, v120
	v_cvt_f32_f16_sdwa v73, v120 dst_sel:DWORD dst_unused:UNUSED_PAD src0_sel:WORD_1
	v_cvt_f32_f16_e32 v74, v121
	v_cvt_f32_f16_sdwa v75, v121 dst_sel:DWORD dst_unused:UNUSED_PAD src0_sel:WORD_1
	v_cvt_f32_f16_e32 v76, v122
	v_cvt_f32_f16_sdwa v77, v122 dst_sel:DWORD dst_unused:UNUSED_PAD src0_sel:WORD_1
	v_cvt_f32_f16_e32 v78, v123
	v_cvt_f32_f16_sdwa v79, v123 dst_sel:DWORD dst_unused:UNUSED_PAD src0_sel:WORD_1
	v_cvt_f32_f16_e32 v80, v124
	v_cvt_f32_f16_sdwa v81, v124 dst_sel:DWORD dst_unused:UNUSED_PAD src0_sel:WORD_1
	v_cvt_f32_f16_e32 v82, v125
	v_cvt_f32_f16_sdwa v83, v125 dst_sel:DWORD dst_unused:UNUSED_PAD src0_sel:WORD_1
	v_cvt_f32_f16_e32 v84, v126
	v_cvt_f32_f16_sdwa v85, v126 dst_sel:DWORD dst_unused:UNUSED_PAD src0_sel:WORD_1
	v_cvt_f32_f16_e32 v86, v127
	v_cvt_f32_f16_sdwa v87, v127 dst_sel:DWORD dst_unused:UNUSED_PAD src0_sel:WORD_1
	v_cvt_f32_f16_e32 v88, v128
	v_cvt_f32_f16_sdwa v89, v128 dst_sel:DWORD dst_unused:UNUSED_PAD src0_sel:WORD_1
	v_cvt_f32_f16_e32 v90, v129
	v_cvt_f32_f16_sdwa v91, v129 dst_sel:DWORD dst_unused:UNUSED_PAD src0_sel:WORD_1
	v_cvt_f32_f16_e32 v92, v130
	v_cvt_f32_f16_sdwa v93, v130 dst_sel:DWORD dst_unused:UNUSED_PAD src0_sel:WORD_1
	v_cvt_f32_f16_e32 v94, v131
	v_cvt_f32_f16_sdwa v95, v131 dst_sel:DWORD dst_unused:UNUSED_PAD src0_sel:WORD_1
	v_cvt_f32_f16_e32 v96, v132
	v_cvt_f32_f16_sdwa v97, v132 dst_sel:DWORD dst_unused:UNUSED_PAD src0_sel:WORD_1
	v_cvt_f32_f16_e32 v98, v133
	v_cvt_f32_f16_sdwa v99, v133 dst_sel:DWORD dst_unused:UNUSED_PAD src0_sel:WORD_1
	v_cvt_f32_f16_e32 v100, v134
	v_cvt_f32_f16_sdwa v101, v134 dst_sel:DWORD dst_unused:UNUSED_PAD src0_sel:WORD_1
	v_cvt_f32_f16_e32 v102, v135
	v_cvt_f32_f16_sdwa v103, v135 dst_sel:DWORD dst_unused:UNUSED_PAD src0_sel:WORD_1
	v_pk_mul_f32 v[232:233], v[72:73], v[72:73]
	v_pk_mul_f32 v[234:235], v[74:75], v[74:75]
	v_pk_mul_f32 v[236:237], v[76:77], v[76:77]
	v_pk_mul_f32 v[238:239], v[78:79], v[78:79]
	v_pk_fma_f32 v[232:233], v[80:81], v[80:81], v[232:233]
	v_pk_fma_f32 v[234:235], v[82:83], v[82:83], v[234:235]
	v_pk_fma_f32 v[236:237], v[84:85], v[84:85], v[236:237]
	v_pk_fma_f32 v[238:239], v[86:87], v[86:87], v[238:239]
	v_pk_fma_f32 v[232:233], v[88:89], v[88:89], v[232:233]
	v_pk_fma_f32 v[234:235], v[90:91], v[90:91], v[234:235]
	v_pk_fma_f32 v[236:237], v[92:93], v[92:93], v[236:237]
	v_pk_fma_f32 v[238:239], v[94:95], v[94:95], v[238:239]
	v_pk_fma_f32 v[232:233], v[96:97], v[96:97], v[232:233]
	v_pk_fma_f32 v[234:235], v[98:99], v[98:99], v[234:235]
	v_pk_fma_f32 v[236:237], v[100:101], v[100:101], v[236:237]
	v_pk_fma_f32 v[238:239], v[102:103], v[102:103], v[238:239]
	v_pk_add_f32 v[232:233], v[232:233], v[234:235]
	v_pk_add_f32 v[236:237], v[236:237], v[238:239]
	v_pk_add_f32 v[232:233], v[232:233], v[236:237]
	v_add_f32_e32 v240, v232, v233
	s_nop 1
	v_add_f32_dpp v240, v240, v240 quad_perm:[1,0,3,2] row_mask:0xf bank_mask:0xf
	s_nop 1
	v_add_f32_dpp v240, v240, v240 quad_perm:[2,3,0,1] row_mask:0xf bank_mask:0xf
	s_nop 1
	v_add_f32_dpp v240, v240, v240 row_half_mirror row_mask:0xf bank_mask:0xf
	s_nop 1
	v_add_f32_dpp v240, v240, v240 row_mirror row_mask:0xf bank_mask:0xf
	s_nop 1
	v_readlane_b32 s0, v240, 0
	v_readlane_b32 s1, v240, 16
	v_readlane_b32 s4, v240, 32
	v_readlane_b32 s5, v240, 48
	v_mov_b32_e32 v249, 0x358637bd
	s_nop 1
	v_mov_b32_e32 v240, s0
	v_add_f32_e32 v240, s1, v240
	v_add_f32_e32 v240, s4, v240
	v_add_f32_e32 v240, s5, v240
	v_fmamk_f32 v240, v240, 0x3a000000, v249
	s_mov_b32 s0, 0xf800000
	v_mul_f32_e32 v241, 0x4f800000, v240
	v_cmp_gt_f32_e32 vcc, s0, v240
	s_nop 1
	v_cndmask_b32_e32 v240, v240, v241, vcc
	v_sqrt_f32_e32 v241, v240
	s_nop 0
	v_add_u32_e32 v242, -1, v241
	v_fma_f32 v243, -v242, v241, v240
	v_cmp_ge_f32_e64 s[0:1], 0, v243
	v_add_u32_e32 v243, 1, v241
	s_nop 0
	v_cndmask_b32_e64 v242, v241, v242, s[0:1]
	v_fma_f32 v241, -v243, v241, v240
	v_cmp_lt_f32_e64 s[0:1], 0, v241
	s_nop 1
	v_cndmask_b32_e64 v241, v242, v243, s[0:1]
	v_mul_f32_e32 v242, 0x37800000, v241
	v_cndmask_b32_e32 v241, v241, v242, vcc
	v_cmp_class_f32_e32 vcc, v240, v248
	s_nop 1
	v_cndmask_b32_e32 v240, v241, v240, vcc
	v_div_scale_f32 v241, s[0:1], v240, v240, 1.0
	v_rcp_f32_e32 v242, v241
	s_nop 0
	v_fma_f32 v243, -v241, v242, 1.0
	v_fmac_f32_e32 v242, v243, v242
	v_div_scale_f32 v243, vcc, 1.0, v240, 1.0
	v_mul_f32_e32 v244, v243, v242
	v_fma_f32 v247, -v241, v244, v243
	v_fmac_f32_e32 v244, v247, v242
	v_fma_f32 v241, -v241, v244, v243
	s_nop 1
	v_div_fmas_f32 v241, v241, v242, v244
	v_div_fixup_f32 v246, v241, v240, 1.0
	v_pk_mul_f32 v[72:73], v[72:73], v[246:247] op_sel_hi:[1,0]
	v_pk_mul_f32 v[74:75], v[74:75], v[246:247] op_sel_hi:[1,0]
	v_pk_mul_f32 v[76:77], v[76:77], v[246:247] op_sel_hi:[1,0]
	v_pk_mul_f32 v[78:79], v[78:79], v[246:247] op_sel_hi:[1,0]
	v_pk_mul_f32 v[80:81], v[80:81], v[246:247] op_sel_hi:[1,0]
	v_pk_mul_f32 v[82:83], v[82:83], v[246:247] op_sel_hi:[1,0]
	v_pk_mul_f32 v[84:85], v[84:85], v[246:247] op_sel_hi:[1,0]
	v_pk_mul_f32 v[86:87], v[86:87], v[246:247] op_sel_hi:[1,0]
	v_pk_mul_f32 v[88:89], v[88:89], v[246:247] op_sel_hi:[1,0]
	v_pk_mul_f32 v[90:91], v[90:91], v[246:247] op_sel_hi:[1,0]
	v_pk_mul_f32 v[92:93], v[92:93], v[246:247] op_sel_hi:[1,0]
	v_pk_mul_f32 v[94:95], v[94:95], v[246:247] op_sel_hi:[1,0]
	v_pk_mul_f32 v[96:97], v[96:97], v[246:247] op_sel_hi:[1,0]
	v_pk_mul_f32 v[98:99], v[98:99], v[246:247] op_sel_hi:[1,0]
	v_pk_mul_f32 v[100:101], v[100:101], v[246:247] op_sel_hi:[1,0]
	v_pk_mul_f32 v[102:103], v[102:103], v[246:247] op_sel_hi:[1,0]
	s_add_u32 s8, s10, 0x20000
	s_addc_u32 s9, s11, 0
	v_pk_fma_f32 v[72:73], v[8:9], v[72:73], v[40:41]
	v_cvt_pk_bf16_f32 v232, v72, v73
	v_pk_fma_f32 v[74:75], v[10:11], v[74:75], v[42:43]
	v_cvt_pk_bf16_f32 v233, v74, v75
	v_pk_fma_f32 v[76:77], v[12:13], v[76:77], v[44:45]
	v_cvt_pk_bf16_f32 v234, v76, v77
	v_pk_fma_f32 v[78:79], v[14:15], v[78:79], v[46:47]
	v_cvt_pk_bf16_f32 v235, v78, v79
	global_store_dwordx4 v1, v[232:235], s[8:9] offset:0
	v_pk_fma_f32 v[80:81], v[16:17], v[80:81], v[48:49]
	v_cvt_pk_bf16_f32 v236, v80, v81
	v_pk_fma_f32 v[82:83], v[18:19], v[82:83], v[50:51]
	v_cvt_pk_bf16_f32 v237, v82, v83
	v_pk_fma_f32 v[84:85], v[20:21], v[84:85], v[52:53]
	v_cvt_pk_bf16_f32 v238, v84, v85
	v_pk_fma_f32 v[86:87], v[22:23], v[86:87], v[54:55]
	v_cvt_pk_bf16_f32 v239, v86, v87
	global_store_dwordx4 v1, v[236:239], s[8:9] offset:1024
	v_pk_fma_f32 v[88:89], v[24:25], v[88:89], v[56:57]
	v_cvt_pk_bf16_f32 v232, v88, v89
	v_pk_fma_f32 v[90:91], v[26:27], v[90:91], v[58:59]
	v_cvt_pk_bf16_f32 v233, v90, v91
	v_pk_fma_f32 v[92:93], v[28:29], v[92:93], v[60:61]
	v_cvt_pk_bf16_f32 v234, v92, v93
	v_pk_fma_f32 v[94:95], v[30:31], v[94:95], v[62:63]
	v_cvt_pk_bf16_f32 v235, v94, v95
	global_store_dwordx4 v1, v[232:235], s[8:9] offset:2048
	v_pk_fma_f32 v[96:97], v[32:33], v[96:97], v[64:65]
	v_cvt_pk_bf16_f32 v236, v96, v97
	v_pk_fma_f32 v[98:99], v[34:35], v[98:99], v[66:67]
	v_cvt_pk_bf16_f32 v237, v98, v99
	v_pk_fma_f32 v[100:101], v[36:37], v[100:101], v[68:69]
	v_cvt_pk_bf16_f32 v238, v100, v101
	v_pk_fma_f32 v[102:103], v[38:39], v[102:103], v[70:71]
	v_cvt_pk_bf16_f32 v239, v102, v103
	global_store_dwordx4 v1, v[236:239], s[8:9] offset:3072
	s_waitcnt vmcnt(28)
	v_cvt_f32_f16_e32 v72, v136
	v_cvt_f32_f16_sdwa v73, v136 dst_sel:DWORD dst_unused:UNUSED_PAD src0_sel:WORD_1
	v_cvt_f32_f16_e32 v74, v137
	v_cvt_f32_f16_sdwa v75, v137 dst_sel:DWORD dst_unused:UNUSED_PAD src0_sel:WORD_1
	v_cvt_f32_f16_e32 v76, v138
	v_cvt_f32_f16_sdwa v77, v138 dst_sel:DWORD dst_unused:UNUSED_PAD src0_sel:WORD_1
	v_cvt_f32_f16_e32 v78, v139
	v_cvt_f32_f16_sdwa v79, v139 dst_sel:DWORD dst_unused:UNUSED_PAD src0_sel:WORD_1
	v_cvt_f32_f16_e32 v80, v140
	v_cvt_f32_f16_sdwa v81, v140 dst_sel:DWORD dst_unused:UNUSED_PAD src0_sel:WORD_1
	v_cvt_f32_f16_e32 v82, v141
	v_cvt_f32_f16_sdwa v83, v141 dst_sel:DWORD dst_unused:UNUSED_PAD src0_sel:WORD_1
	v_cvt_f32_f16_e32 v84, v142
	v_cvt_f32_f16_sdwa v85, v142 dst_sel:DWORD dst_unused:UNUSED_PAD src0_sel:WORD_1
	v_cvt_f32_f16_e32 v86, v143
	v_cvt_f32_f16_sdwa v87, v143 dst_sel:DWORD dst_unused:UNUSED_PAD src0_sel:WORD_1
	v_cvt_f32_f16_e32 v88, v144
	v_cvt_f32_f16_sdwa v89, v144 dst_sel:DWORD dst_unused:UNUSED_PAD src0_sel:WORD_1
	v_cvt_f32_f16_e32 v90, v145
	v_cvt_f32_f16_sdwa v91, v145 dst_sel:DWORD dst_unused:UNUSED_PAD src0_sel:WORD_1
	v_cvt_f32_f16_e32 v92, v146
	v_cvt_f32_f16_sdwa v93, v146 dst_sel:DWORD dst_unused:UNUSED_PAD src0_sel:WORD_1
	v_cvt_f32_f16_e32 v94, v147
	v_cvt_f32_f16_sdwa v95, v147 dst_sel:DWORD dst_unused:UNUSED_PAD src0_sel:WORD_1
	v_cvt_f32_f16_e32 v96, v148
	v_cvt_f32_f16_sdwa v97, v148 dst_sel:DWORD dst_unused:UNUSED_PAD src0_sel:WORD_1
	v_cvt_f32_f16_e32 v98, v149
	v_cvt_f32_f16_sdwa v99, v149 dst_sel:DWORD dst_unused:UNUSED_PAD src0_sel:WORD_1
	v_cvt_f32_f16_e32 v100, v150
	v_cvt_f32_f16_sdwa v101, v150 dst_sel:DWORD dst_unused:UNUSED_PAD src0_sel:WORD_1
	v_cvt_f32_f16_e32 v102, v151
	v_cvt_f32_f16_sdwa v103, v151 dst_sel:DWORD dst_unused:UNUSED_PAD src0_sel:WORD_1
	v_pk_mul_f32 v[232:233], v[72:73], v[72:73]
	v_pk_mul_f32 v[234:235], v[74:75], v[74:75]
	v_pk_mul_f32 v[236:237], v[76:77], v[76:77]
	v_pk_mul_f32 v[238:239], v[78:79], v[78:79]
	v_pk_fma_f32 v[232:233], v[80:81], v[80:81], v[232:233]
	v_pk_fma_f32 v[234:235], v[82:83], v[82:83], v[234:235]
	v_pk_fma_f32 v[236:237], v[84:85], v[84:85], v[236:237]
	v_pk_fma_f32 v[238:239], v[86:87], v[86:87], v[238:239]
	v_pk_fma_f32 v[232:233], v[88:89], v[88:89], v[232:233]
	v_pk_fma_f32 v[234:235], v[90:91], v[90:91], v[234:235]
	v_pk_fma_f32 v[236:237], v[92:93], v[92:93], v[236:237]
	v_pk_fma_f32 v[238:239], v[94:95], v[94:95], v[238:239]
	v_pk_fma_f32 v[232:233], v[96:97], v[96:97], v[232:233]
	v_pk_fma_f32 v[234:235], v[98:99], v[98:99], v[234:235]
	v_pk_fma_f32 v[236:237], v[100:101], v[100:101], v[236:237]
	v_pk_fma_f32 v[238:239], v[102:103], v[102:103], v[238:239]
	v_pk_add_f32 v[232:233], v[232:233], v[234:235]
	v_pk_add_f32 v[236:237], v[236:237], v[238:239]
	v_pk_add_f32 v[232:233], v[232:233], v[236:237]
	v_add_f32_e32 v240, v232, v233
	s_nop 1
	v_add_f32_dpp v240, v240, v240 quad_perm:[1,0,3,2] row_mask:0xf bank_mask:0xf
	s_nop 1
	v_add_f32_dpp v240, v240, v240 quad_perm:[2,3,0,1] row_mask:0xf bank_mask:0xf
	s_nop 1
	v_add_f32_dpp v240, v240, v240 row_half_mirror row_mask:0xf bank_mask:0xf
	s_nop 1
	v_add_f32_dpp v240, v240, v240 row_mirror row_mask:0xf bank_mask:0xf
	s_nop 1
	v_readlane_b32 s0, v240, 0
	v_readlane_b32 s1, v240, 16
	v_readlane_b32 s4, v240, 32
	v_readlane_b32 s5, v240, 48
	v_mov_b32_e32 v249, 0x358637bd
	s_nop 1
	v_mov_b32_e32 v240, s0
	v_add_f32_e32 v240, s1, v240
	v_add_f32_e32 v240, s4, v240
	v_add_f32_e32 v240, s5, v240
	v_fmamk_f32 v240, v240, 0x3a000000, v249
	s_mov_b32 s0, 0xf800000
	v_mul_f32_e32 v241, 0x4f800000, v240
	v_cmp_gt_f32_e32 vcc, s0, v240
	s_nop 1
	v_cndmask_b32_e32 v240, v240, v241, vcc
	v_sqrt_f32_e32 v241, v240
	s_nop 0
	v_add_u32_e32 v242, -1, v241
	v_fma_f32 v243, -v242, v241, v240
	v_cmp_ge_f32_e64 s[0:1], 0, v243
	v_add_u32_e32 v243, 1, v241
	s_nop 0
	v_cndmask_b32_e64 v242, v241, v242, s[0:1]
	v_fma_f32 v241, -v243, v241, v240
	v_cmp_lt_f32_e64 s[0:1], 0, v241
	s_nop 1
	v_cndmask_b32_e64 v241, v242, v243, s[0:1]
	v_mul_f32_e32 v242, 0x37800000, v241
	v_cndmask_b32_e32 v241, v241, v242, vcc
	v_cmp_class_f32_e32 vcc, v240, v248
	s_nop 1
	v_cndmask_b32_e32 v240, v241, v240, vcc
	v_div_scale_f32 v241, s[0:1], v240, v240, 1.0
	v_rcp_f32_e32 v242, v241
	s_nop 0
	v_fma_f32 v243, -v241, v242, 1.0
	v_fmac_f32_e32 v242, v243, v242
	v_div_scale_f32 v243, vcc, 1.0, v240, 1.0
	v_mul_f32_e32 v244, v243, v242
	v_fma_f32 v247, -v241, v244, v243
	v_fmac_f32_e32 v244, v247, v242
	v_fma_f32 v241, -v241, v244, v243
	s_nop 1
	v_div_fmas_f32 v241, v241, v242, v244
	v_div_fixup_f32 v246, v241, v240, 1.0
	v_pk_mul_f32 v[72:73], v[72:73], v[246:247] op_sel_hi:[1,0]
	v_pk_mul_f32 v[74:75], v[74:75], v[246:247] op_sel_hi:[1,0]
	v_pk_mul_f32 v[76:77], v[76:77], v[246:247] op_sel_hi:[1,0]
	v_pk_mul_f32 v[78:79], v[78:79], v[246:247] op_sel_hi:[1,0]
	v_pk_mul_f32 v[80:81], v[80:81], v[246:247] op_sel_hi:[1,0]
	v_pk_mul_f32 v[82:83], v[82:83], v[246:247] op_sel_hi:[1,0]
	v_pk_mul_f32 v[84:85], v[84:85], v[246:247] op_sel_hi:[1,0]
	v_pk_mul_f32 v[86:87], v[86:87], v[246:247] op_sel_hi:[1,0]
	v_pk_mul_f32 v[88:89], v[88:89], v[246:247] op_sel_hi:[1,0]
	v_pk_mul_f32 v[90:91], v[90:91], v[246:247] op_sel_hi:[1,0]
	v_pk_mul_f32 v[92:93], v[92:93], v[246:247] op_sel_hi:[1,0]
	v_pk_mul_f32 v[94:95], v[94:95], v[246:247] op_sel_hi:[1,0]
	v_pk_mul_f32 v[96:97], v[96:97], v[246:247] op_sel_hi:[1,0]
	v_pk_mul_f32 v[98:99], v[98:99], v[246:247] op_sel_hi:[1,0]
	v_pk_mul_f32 v[100:101], v[100:101], v[246:247] op_sel_hi:[1,0]
	v_pk_mul_f32 v[102:103], v[102:103], v[246:247] op_sel_hi:[1,0]
	s_add_u32 s8, s10, 0x40000
	s_addc_u32 s9, s11, 0
	v_pk_fma_f32 v[72:73], v[8:9], v[72:73], v[40:41]
	v_cvt_pk_bf16_f32 v232, v72, v73
	v_pk_fma_f32 v[74:75], v[10:11], v[74:75], v[42:43]
	v_cvt_pk_bf16_f32 v233, v74, v75
	v_pk_fma_f32 v[76:77], v[12:13], v[76:77], v[44:45]
	v_cvt_pk_bf16_f32 v234, v76, v77
	v_pk_fma_f32 v[78:79], v[14:15], v[78:79], v[46:47]
	v_cvt_pk_bf16_f32 v235, v78, v79
	global_store_dwordx4 v1, v[232:235], s[8:9] offset:0
	v_pk_fma_f32 v[80:81], v[16:17], v[80:81], v[48:49]
	v_cvt_pk_bf16_f32 v236, v80, v81
	v_pk_fma_f32 v[82:83], v[18:19], v[82:83], v[50:51]
	v_cvt_pk_bf16_f32 v237, v82, v83
	v_pk_fma_f32 v[84:85], v[20:21], v[84:85], v[52:53]
	v_cvt_pk_bf16_f32 v238, v84, v85
	v_pk_fma_f32 v[86:87], v[22:23], v[86:87], v[54:55]
	v_cvt_pk_bf16_f32 v239, v86, v87
	global_store_dwordx4 v1, v[236:239], s[8:9] offset:1024
	v_pk_fma_f32 v[88:89], v[24:25], v[88:89], v[56:57]
	v_cvt_pk_bf16_f32 v232, v88, v89
	v_pk_fma_f32 v[90:91], v[26:27], v[90:91], v[58:59]
	v_cvt_pk_bf16_f32 v233, v90, v91
	v_pk_fma_f32 v[92:93], v[28:29], v[92:93], v[60:61]
	v_cvt_pk_bf16_f32 v234, v92, v93
	v_pk_fma_f32 v[94:95], v[30:31], v[94:95], v[62:63]
	v_cvt_pk_bf16_f32 v235, v94, v95
	global_store_dwordx4 v1, v[232:235], s[8:9] offset:2048
	v_pk_fma_f32 v[96:97], v[32:33], v[96:97], v[64:65]
	v_cvt_pk_bf16_f32 v236, v96, v97
	v_pk_fma_f32 v[98:99], v[34:35], v[98:99], v[66:67]
	v_cvt_pk_bf16_f32 v237, v98, v99
	v_pk_fma_f32 v[100:101], v[36:37], v[100:101], v[68:69]
	v_cvt_pk_bf16_f32 v238, v100, v101
	v_pk_fma_f32 v[102:103], v[38:39], v[102:103], v[70:71]
	v_cvt_pk_bf16_f32 v239, v102, v103
	global_store_dwordx4 v1, v[236:239], s[8:9] offset:3072
	s_waitcnt vmcnt(28)
	v_cvt_f32_f16_e32 v72, v152
	v_cvt_f32_f16_sdwa v73, v152 dst_sel:DWORD dst_unused:UNUSED_PAD src0_sel:WORD_1
	v_cvt_f32_f16_e32 v74, v153
	v_cvt_f32_f16_sdwa v75, v153 dst_sel:DWORD dst_unused:UNUSED_PAD src0_sel:WORD_1
	v_cvt_f32_f16_e32 v76, v154
	v_cvt_f32_f16_sdwa v77, v154 dst_sel:DWORD dst_unused:UNUSED_PAD src0_sel:WORD_1
	v_cvt_f32_f16_e32 v78, v155
	v_cvt_f32_f16_sdwa v79, v155 dst_sel:DWORD dst_unused:UNUSED_PAD src0_sel:WORD_1
	v_cvt_f32_f16_e32 v80, v156
	v_cvt_f32_f16_sdwa v81, v156 dst_sel:DWORD dst_unused:UNUSED_PAD src0_sel:WORD_1
	v_cvt_f32_f16_e32 v82, v157
	v_cvt_f32_f16_sdwa v83, v157 dst_sel:DWORD dst_unused:UNUSED_PAD src0_sel:WORD_1
	v_cvt_f32_f16_e32 v84, v158
	v_cvt_f32_f16_sdwa v85, v158 dst_sel:DWORD dst_unused:UNUSED_PAD src0_sel:WORD_1
	v_cvt_f32_f16_e32 v86, v159
	v_cvt_f32_f16_sdwa v87, v159 dst_sel:DWORD dst_unused:UNUSED_PAD src0_sel:WORD_1
	v_cvt_f32_f16_e32 v88, v160
	v_cvt_f32_f16_sdwa v89, v160 dst_sel:DWORD dst_unused:UNUSED_PAD src0_sel:WORD_1
	v_cvt_f32_f16_e32 v90, v161
	v_cvt_f32_f16_sdwa v91, v161 dst_sel:DWORD dst_unused:UNUSED_PAD src0_sel:WORD_1
	v_cvt_f32_f16_e32 v92, v162
	v_cvt_f32_f16_sdwa v93, v162 dst_sel:DWORD dst_unused:UNUSED_PAD src0_sel:WORD_1
	v_cvt_f32_f16_e32 v94, v163
	v_cvt_f32_f16_sdwa v95, v163 dst_sel:DWORD dst_unused:UNUSED_PAD src0_sel:WORD_1
	v_cvt_f32_f16_e32 v96, v164
	v_cvt_f32_f16_sdwa v97, v164 dst_sel:DWORD dst_unused:UNUSED_PAD src0_sel:WORD_1
	v_cvt_f32_f16_e32 v98, v165
	v_cvt_f32_f16_sdwa v99, v165 dst_sel:DWORD dst_unused:UNUSED_PAD src0_sel:WORD_1
	v_cvt_f32_f16_e32 v100, v166
	v_cvt_f32_f16_sdwa v101, v166 dst_sel:DWORD dst_unused:UNUSED_PAD src0_sel:WORD_1
	v_cvt_f32_f16_e32 v102, v167
	v_cvt_f32_f16_sdwa v103, v167 dst_sel:DWORD dst_unused:UNUSED_PAD src0_sel:WORD_1
	v_pk_mul_f32 v[232:233], v[72:73], v[72:73]
	v_pk_mul_f32 v[234:235], v[74:75], v[74:75]
	v_pk_mul_f32 v[236:237], v[76:77], v[76:77]
	v_pk_mul_f32 v[238:239], v[78:79], v[78:79]
	v_pk_fma_f32 v[232:233], v[80:81], v[80:81], v[232:233]
	v_pk_fma_f32 v[234:235], v[82:83], v[82:83], v[234:235]
	v_pk_fma_f32 v[236:237], v[84:85], v[84:85], v[236:237]
	v_pk_fma_f32 v[238:239], v[86:87], v[86:87], v[238:239]
	v_pk_fma_f32 v[232:233], v[88:89], v[88:89], v[232:233]
	v_pk_fma_f32 v[234:235], v[90:91], v[90:91], v[234:235]
	v_pk_fma_f32 v[236:237], v[92:93], v[92:93], v[236:237]
	v_pk_fma_f32 v[238:239], v[94:95], v[94:95], v[238:239]
	v_pk_fma_f32 v[232:233], v[96:97], v[96:97], v[232:233]
	v_pk_fma_f32 v[234:235], v[98:99], v[98:99], v[234:235]
	v_pk_fma_f32 v[236:237], v[100:101], v[100:101], v[236:237]
	v_pk_fma_f32 v[238:239], v[102:103], v[102:103], v[238:239]
	v_pk_add_f32 v[232:233], v[232:233], v[234:235]
	v_pk_add_f32 v[236:237], v[236:237], v[238:239]
	v_pk_add_f32 v[232:233], v[232:233], v[236:237]
	v_add_f32_e32 v240, v232, v233
	s_nop 1
	v_add_f32_dpp v240, v240, v240 quad_perm:[1,0,3,2] row_mask:0xf bank_mask:0xf
	s_nop 1
	v_add_f32_dpp v240, v240, v240 quad_perm:[2,3,0,1] row_mask:0xf bank_mask:0xf
	s_nop 1
	v_add_f32_dpp v240, v240, v240 row_half_mirror row_mask:0xf bank_mask:0xf
	s_nop 1
	v_add_f32_dpp v240, v240, v240 row_mirror row_mask:0xf bank_mask:0xf
	s_nop 1
	v_readlane_b32 s0, v240, 0
	v_readlane_b32 s1, v240, 16
	v_readlane_b32 s4, v240, 32
	v_readlane_b32 s5, v240, 48
	v_mov_b32_e32 v249, 0x358637bd
	s_nop 1
	v_mov_b32_e32 v240, s0
	v_add_f32_e32 v240, s1, v240
	v_add_f32_e32 v240, s4, v240
	v_add_f32_e32 v240, s5, v240
	v_fmamk_f32 v240, v240, 0x3a000000, v249
	s_mov_b32 s0, 0xf800000
	v_mul_f32_e32 v241, 0x4f800000, v240
	v_cmp_gt_f32_e32 vcc, s0, v240
	s_nop 1
	v_cndmask_b32_e32 v240, v240, v241, vcc
	v_sqrt_f32_e32 v241, v240
	s_nop 0
	v_add_u32_e32 v242, -1, v241
	v_fma_f32 v243, -v242, v241, v240
	v_cmp_ge_f32_e64 s[0:1], 0, v243
	v_add_u32_e32 v243, 1, v241
	s_nop 0
	v_cndmask_b32_e64 v242, v241, v242, s[0:1]
	v_fma_f32 v241, -v243, v241, v240
	v_cmp_lt_f32_e64 s[0:1], 0, v241
	s_nop 1
	v_cndmask_b32_e64 v241, v242, v243, s[0:1]
	v_mul_f32_e32 v242, 0x37800000, v241
	v_cndmask_b32_e32 v241, v241, v242, vcc
	v_cmp_class_f32_e32 vcc, v240, v248
	s_nop 1
	v_cndmask_b32_e32 v240, v241, v240, vcc
	v_div_scale_f32 v241, s[0:1], v240, v240, 1.0
	v_rcp_f32_e32 v242, v241
	s_nop 0
	v_fma_f32 v243, -v241, v242, 1.0
	v_fmac_f32_e32 v242, v243, v242
	v_div_scale_f32 v243, vcc, 1.0, v240, 1.0
	v_mul_f32_e32 v244, v243, v242
	v_fma_f32 v247, -v241, v244, v243
	v_fmac_f32_e32 v244, v247, v242
	v_fma_f32 v241, -v241, v244, v243
	s_nop 1
	v_div_fmas_f32 v241, v241, v242, v244
	v_div_fixup_f32 v246, v241, v240, 1.0
	v_pk_mul_f32 v[72:73], v[72:73], v[246:247] op_sel_hi:[1,0]
	v_pk_mul_f32 v[74:75], v[74:75], v[246:247] op_sel_hi:[1,0]
	v_pk_mul_f32 v[76:77], v[76:77], v[246:247] op_sel_hi:[1,0]
	v_pk_mul_f32 v[78:79], v[78:79], v[246:247] op_sel_hi:[1,0]
	v_pk_mul_f32 v[80:81], v[80:81], v[246:247] op_sel_hi:[1,0]
	v_pk_mul_f32 v[82:83], v[82:83], v[246:247] op_sel_hi:[1,0]
	v_pk_mul_f32 v[84:85], v[84:85], v[246:247] op_sel_hi:[1,0]
	v_pk_mul_f32 v[86:87], v[86:87], v[246:247] op_sel_hi:[1,0]
	v_pk_mul_f32 v[88:89], v[88:89], v[246:247] op_sel_hi:[1,0]
	v_pk_mul_f32 v[90:91], v[90:91], v[246:247] op_sel_hi:[1,0]
	v_pk_mul_f32 v[92:93], v[92:93], v[246:247] op_sel_hi:[1,0]
	v_pk_mul_f32 v[94:95], v[94:95], v[246:247] op_sel_hi:[1,0]
	v_pk_mul_f32 v[96:97], v[96:97], v[246:247] op_sel_hi:[1,0]
	v_pk_mul_f32 v[98:99], v[98:99], v[246:247] op_sel_hi:[1,0]
	v_pk_mul_f32 v[100:101], v[100:101], v[246:247] op_sel_hi:[1,0]
	v_pk_mul_f32 v[102:103], v[102:103], v[246:247] op_sel_hi:[1,0]
	s_add_u32 s8, s10, 0x60000
	s_addc_u32 s9, s11, 0
	v_pk_fma_f32 v[72:73], v[8:9], v[72:73], v[40:41]
	v_cvt_pk_bf16_f32 v232, v72, v73
	v_pk_fma_f32 v[74:75], v[10:11], v[74:75], v[42:43]
	v_cvt_pk_bf16_f32 v233, v74, v75
	v_pk_fma_f32 v[76:77], v[12:13], v[76:77], v[44:45]
	v_cvt_pk_bf16_f32 v234, v76, v77
	v_pk_fma_f32 v[78:79], v[14:15], v[78:79], v[46:47]
	v_cvt_pk_bf16_f32 v235, v78, v79
	global_store_dwordx4 v1, v[232:235], s[8:9] offset:0
	v_pk_fma_f32 v[80:81], v[16:17], v[80:81], v[48:49]
	v_cvt_pk_bf16_f32 v236, v80, v81
	v_pk_fma_f32 v[82:83], v[18:19], v[82:83], v[50:51]
	v_cvt_pk_bf16_f32 v237, v82, v83
	v_pk_fma_f32 v[84:85], v[20:21], v[84:85], v[52:53]
	v_cvt_pk_bf16_f32 v238, v84, v85
	v_pk_fma_f32 v[86:87], v[22:23], v[86:87], v[54:55]
	v_cvt_pk_bf16_f32 v239, v86, v87
	global_store_dwordx4 v1, v[236:239], s[8:9] offset:1024
	v_pk_fma_f32 v[88:89], v[24:25], v[88:89], v[56:57]
	v_cvt_pk_bf16_f32 v232, v88, v89
	v_pk_fma_f32 v[90:91], v[26:27], v[90:91], v[58:59]
	v_cvt_pk_bf16_f32 v233, v90, v91
	v_pk_fma_f32 v[92:93], v[28:29], v[92:93], v[60:61]
	v_cvt_pk_bf16_f32 v234, v92, v93
	v_pk_fma_f32 v[94:95], v[30:31], v[94:95], v[62:63]
	v_cvt_pk_bf16_f32 v235, v94, v95
	global_store_dwordx4 v1, v[232:235], s[8:9] offset:2048
	v_pk_fma_f32 v[96:97], v[32:33], v[96:97], v[64:65]
	v_cvt_pk_bf16_f32 v236, v96, v97
	v_pk_fma_f32 v[98:99], v[34:35], v[98:99], v[66:67]
	v_cvt_pk_bf16_f32 v237, v98, v99
	v_pk_fma_f32 v[100:101], v[36:37], v[100:101], v[68:69]
	v_cvt_pk_bf16_f32 v238, v100, v101
	v_pk_fma_f32 v[102:103], v[38:39], v[102:103], v[70:71]
	v_cvt_pk_bf16_f32 v239, v102, v103
	global_store_dwordx4 v1, v[236:239], s[8:9] offset:3072
	s_waitcnt vmcnt(28)
	v_cvt_f32_f16_e32 v72, v168
	v_cvt_f32_f16_sdwa v73, v168 dst_sel:DWORD dst_unused:UNUSED_PAD src0_sel:WORD_1
	v_cvt_f32_f16_e32 v74, v169
	v_cvt_f32_f16_sdwa v75, v169 dst_sel:DWORD dst_unused:UNUSED_PAD src0_sel:WORD_1
	v_cvt_f32_f16_e32 v76, v170
	v_cvt_f32_f16_sdwa v77, v170 dst_sel:DWORD dst_unused:UNUSED_PAD src0_sel:WORD_1
	v_cvt_f32_f16_e32 v78, v171
	v_cvt_f32_f16_sdwa v79, v171 dst_sel:DWORD dst_unused:UNUSED_PAD src0_sel:WORD_1
	v_cvt_f32_f16_e32 v80, v172
	v_cvt_f32_f16_sdwa v81, v172 dst_sel:DWORD dst_unused:UNUSED_PAD src0_sel:WORD_1
	v_cvt_f32_f16_e32 v82, v173
	v_cvt_f32_f16_sdwa v83, v173 dst_sel:DWORD dst_unused:UNUSED_PAD src0_sel:WORD_1
	v_cvt_f32_f16_e32 v84, v174
	v_cvt_f32_f16_sdwa v85, v174 dst_sel:DWORD dst_unused:UNUSED_PAD src0_sel:WORD_1
	v_cvt_f32_f16_e32 v86, v175
	v_cvt_f32_f16_sdwa v87, v175 dst_sel:DWORD dst_unused:UNUSED_PAD src0_sel:WORD_1
	v_cvt_f32_f16_e32 v88, v176
	v_cvt_f32_f16_sdwa v89, v176 dst_sel:DWORD dst_unused:UNUSED_PAD src0_sel:WORD_1
	v_cvt_f32_f16_e32 v90, v177
	v_cvt_f32_f16_sdwa v91, v177 dst_sel:DWORD dst_unused:UNUSED_PAD src0_sel:WORD_1
	v_cvt_f32_f16_e32 v92, v178
	v_cvt_f32_f16_sdwa v93, v178 dst_sel:DWORD dst_unused:UNUSED_PAD src0_sel:WORD_1
	v_cvt_f32_f16_e32 v94, v179
	v_cvt_f32_f16_sdwa v95, v179 dst_sel:DWORD dst_unused:UNUSED_PAD src0_sel:WORD_1
	v_cvt_f32_f16_e32 v96, v180
	v_cvt_f32_f16_sdwa v97, v180 dst_sel:DWORD dst_unused:UNUSED_PAD src0_sel:WORD_1
	v_cvt_f32_f16_e32 v98, v181
	v_cvt_f32_f16_sdwa v99, v181 dst_sel:DWORD dst_unused:UNUSED_PAD src0_sel:WORD_1
	v_cvt_f32_f16_e32 v100, v182
	v_cvt_f32_f16_sdwa v101, v182 dst_sel:DWORD dst_unused:UNUSED_PAD src0_sel:WORD_1
	v_cvt_f32_f16_e32 v102, v183
	v_cvt_f32_f16_sdwa v103, v183 dst_sel:DWORD dst_unused:UNUSED_PAD src0_sel:WORD_1
	v_pk_mul_f32 v[232:233], v[72:73], v[72:73]
	v_pk_mul_f32 v[234:235], v[74:75], v[74:75]
	v_pk_mul_f32 v[236:237], v[76:77], v[76:77]
	v_pk_mul_f32 v[238:239], v[78:79], v[78:79]
	v_pk_fma_f32 v[232:233], v[80:81], v[80:81], v[232:233]
	v_pk_fma_f32 v[234:235], v[82:83], v[82:83], v[234:235]
	v_pk_fma_f32 v[236:237], v[84:85], v[84:85], v[236:237]
	v_pk_fma_f32 v[238:239], v[86:87], v[86:87], v[238:239]
	v_pk_fma_f32 v[232:233], v[88:89], v[88:89], v[232:233]
	v_pk_fma_f32 v[234:235], v[90:91], v[90:91], v[234:235]
	v_pk_fma_f32 v[236:237], v[92:93], v[92:93], v[236:237]
	v_pk_fma_f32 v[238:239], v[94:95], v[94:95], v[238:239]
	v_pk_fma_f32 v[232:233], v[96:97], v[96:97], v[232:233]
	v_pk_fma_f32 v[234:235], v[98:99], v[98:99], v[234:235]
	v_pk_fma_f32 v[236:237], v[100:101], v[100:101], v[236:237]
	v_pk_fma_f32 v[238:239], v[102:103], v[102:103], v[238:239]
	v_pk_add_f32 v[232:233], v[232:233], v[234:235]
	v_pk_add_f32 v[236:237], v[236:237], v[238:239]
	v_pk_add_f32 v[232:233], v[232:233], v[236:237]
	v_add_f32_e32 v240, v232, v233
	s_nop 1
	v_add_f32_dpp v240, v240, v240 quad_perm:[1,0,3,2] row_mask:0xf bank_mask:0xf
	s_nop 1
	v_add_f32_dpp v240, v240, v240 quad_perm:[2,3,0,1] row_mask:0xf bank_mask:0xf
	s_nop 1
	v_add_f32_dpp v240, v240, v240 row_half_mirror row_mask:0xf bank_mask:0xf
	s_nop 1
	v_add_f32_dpp v240, v240, v240 row_mirror row_mask:0xf bank_mask:0xf
	s_nop 1
	v_readlane_b32 s0, v240, 0
	v_readlane_b32 s1, v240, 16
	v_readlane_b32 s4, v240, 32
	v_readlane_b32 s5, v240, 48
	v_mov_b32_e32 v249, 0x358637bd
	s_nop 1
	v_mov_b32_e32 v240, s0
	v_add_f32_e32 v240, s1, v240
	v_add_f32_e32 v240, s4, v240
	v_add_f32_e32 v240, s5, v240
	v_fmamk_f32 v240, v240, 0x3a000000, v249
	s_mov_b32 s0, 0xf800000
	v_mul_f32_e32 v241, 0x4f800000, v240
	v_cmp_gt_f32_e32 vcc, s0, v240
	s_nop 1
	v_cndmask_b32_e32 v240, v240, v241, vcc
	v_sqrt_f32_e32 v241, v240
	s_nop 0
	v_add_u32_e32 v242, -1, v241
	v_fma_f32 v243, -v242, v241, v240
	v_cmp_ge_f32_e64 s[0:1], 0, v243
	v_add_u32_e32 v243, 1, v241
	s_nop 0
	v_cndmask_b32_e64 v242, v241, v242, s[0:1]
	v_fma_f32 v241, -v243, v241, v240
	v_cmp_lt_f32_e64 s[0:1], 0, v241
	s_nop 1
	v_cndmask_b32_e64 v241, v242, v243, s[0:1]
	v_mul_f32_e32 v242, 0x37800000, v241
	v_cndmask_b32_e32 v241, v241, v242, vcc
	v_cmp_class_f32_e32 vcc, v240, v248
	s_nop 1
	v_cndmask_b32_e32 v240, v241, v240, vcc
	v_div_scale_f32 v241, s[0:1], v240, v240, 1.0
	v_rcp_f32_e32 v242, v241
	s_nop 0
	v_fma_f32 v243, -v241, v242, 1.0
	v_fmac_f32_e32 v242, v243, v242
	v_div_scale_f32 v243, vcc, 1.0, v240, 1.0
	v_mul_f32_e32 v244, v243, v242
	v_fma_f32 v247, -v241, v244, v243
	v_fmac_f32_e32 v244, v247, v242
	v_fma_f32 v241, -v241, v244, v243
	s_nop 1
	v_div_fmas_f32 v241, v241, v242, v244
	v_div_fixup_f32 v246, v241, v240, 1.0
	v_pk_mul_f32 v[72:73], v[72:73], v[246:247] op_sel_hi:[1,0]
	v_pk_mul_f32 v[74:75], v[74:75], v[246:247] op_sel_hi:[1,0]
	v_pk_mul_f32 v[76:77], v[76:77], v[246:247] op_sel_hi:[1,0]
	v_pk_mul_f32 v[78:79], v[78:79], v[246:247] op_sel_hi:[1,0]
	v_pk_mul_f32 v[80:81], v[80:81], v[246:247] op_sel_hi:[1,0]
	v_pk_mul_f32 v[82:83], v[82:83], v[246:247] op_sel_hi:[1,0]
	v_pk_mul_f32 v[84:85], v[84:85], v[246:247] op_sel_hi:[1,0]
	v_pk_mul_f32 v[86:87], v[86:87], v[246:247] op_sel_hi:[1,0]
	v_pk_mul_f32 v[88:89], v[88:89], v[246:247] op_sel_hi:[1,0]
	v_pk_mul_f32 v[90:91], v[90:91], v[246:247] op_sel_hi:[1,0]
	v_pk_mul_f32 v[92:93], v[92:93], v[246:247] op_sel_hi:[1,0]
	v_pk_mul_f32 v[94:95], v[94:95], v[246:247] op_sel_hi:[1,0]
	v_pk_mul_f32 v[96:97], v[96:97], v[246:247] op_sel_hi:[1,0]
	v_pk_mul_f32 v[98:99], v[98:99], v[246:247] op_sel_hi:[1,0]
	v_pk_mul_f32 v[100:101], v[100:101], v[246:247] op_sel_hi:[1,0]
	v_pk_mul_f32 v[102:103], v[102:103], v[246:247] op_sel_hi:[1,0]
	s_add_u32 s8, s10, 0x80000
	s_addc_u32 s9, s11, 0
	v_pk_fma_f32 v[72:73], v[8:9], v[72:73], v[40:41]
	v_cvt_pk_bf16_f32 v232, v72, v73
	v_pk_fma_f32 v[74:75], v[10:11], v[74:75], v[42:43]
	v_cvt_pk_bf16_f32 v233, v74, v75
	v_pk_fma_f32 v[76:77], v[12:13], v[76:77], v[44:45]
	v_cvt_pk_bf16_f32 v234, v76, v77
	v_pk_fma_f32 v[78:79], v[14:15], v[78:79], v[46:47]
	v_cvt_pk_bf16_f32 v235, v78, v79
	global_store_dwordx4 v1, v[232:235], s[8:9] offset:0
	v_pk_fma_f32 v[80:81], v[16:17], v[80:81], v[48:49]
	v_cvt_pk_bf16_f32 v236, v80, v81
	v_pk_fma_f32 v[82:83], v[18:19], v[82:83], v[50:51]
	v_cvt_pk_bf16_f32 v237, v82, v83
	v_pk_fma_f32 v[84:85], v[20:21], v[84:85], v[52:53]
	v_cvt_pk_bf16_f32 v238, v84, v85
	v_pk_fma_f32 v[86:87], v[22:23], v[86:87], v[54:55]
	v_cvt_pk_bf16_f32 v239, v86, v87
	global_store_dwordx4 v1, v[236:239], s[8:9] offset:1024
	v_pk_fma_f32 v[88:89], v[24:25], v[88:89], v[56:57]
	v_cvt_pk_bf16_f32 v232, v88, v89
	v_pk_fma_f32 v[90:91], v[26:27], v[90:91], v[58:59]
	v_cvt_pk_bf16_f32 v233, v90, v91
	v_pk_fma_f32 v[92:93], v[28:29], v[92:93], v[60:61]
	v_cvt_pk_bf16_f32 v234, v92, v93
	v_pk_fma_f32 v[94:95], v[30:31], v[94:95], v[62:63]
	v_cvt_pk_bf16_f32 v235, v94, v95
	global_store_dwordx4 v1, v[232:235], s[8:9] offset:2048
	v_pk_fma_f32 v[96:97], v[32:33], v[96:97], v[64:65]
	v_cvt_pk_bf16_f32 v236, v96, v97
	v_pk_fma_f32 v[98:99], v[34:35], v[98:99], v[66:67]
	v_cvt_pk_bf16_f32 v237, v98, v99
	v_pk_fma_f32 v[100:101], v[36:37], v[100:101], v[68:69]
	v_cvt_pk_bf16_f32 v238, v100, v101
	v_pk_fma_f32 v[102:103], v[38:39], v[102:103], v[70:71]
	v_cvt_pk_bf16_f32 v239, v102, v103
	global_store_dwordx4 v1, v[236:239], s[8:9] offset:3072
	s_waitcnt vmcnt(28)
	v_cvt_f32_f16_e32 v72, v184
	v_cvt_f32_f16_sdwa v73, v184 dst_sel:DWORD dst_unused:UNUSED_PAD src0_sel:WORD_1
	v_cvt_f32_f16_e32 v74, v185
	v_cvt_f32_f16_sdwa v75, v185 dst_sel:DWORD dst_unused:UNUSED_PAD src0_sel:WORD_1
	v_cvt_f32_f16_e32 v76, v186
	v_cvt_f32_f16_sdwa v77, v186 dst_sel:DWORD dst_unused:UNUSED_PAD src0_sel:WORD_1
	v_cvt_f32_f16_e32 v78, v187
	v_cvt_f32_f16_sdwa v79, v187 dst_sel:DWORD dst_unused:UNUSED_PAD src0_sel:WORD_1
	v_cvt_f32_f16_e32 v80, v188
	v_cvt_f32_f16_sdwa v81, v188 dst_sel:DWORD dst_unused:UNUSED_PAD src0_sel:WORD_1
	v_cvt_f32_f16_e32 v82, v189
	v_cvt_f32_f16_sdwa v83, v189 dst_sel:DWORD dst_unused:UNUSED_PAD src0_sel:WORD_1
	v_cvt_f32_f16_e32 v84, v190
	v_cvt_f32_f16_sdwa v85, v190 dst_sel:DWORD dst_unused:UNUSED_PAD src0_sel:WORD_1
	v_cvt_f32_f16_e32 v86, v191
	v_cvt_f32_f16_sdwa v87, v191 dst_sel:DWORD dst_unused:UNUSED_PAD src0_sel:WORD_1
	v_cvt_f32_f16_e32 v88, v192
	v_cvt_f32_f16_sdwa v89, v192 dst_sel:DWORD dst_unused:UNUSED_PAD src0_sel:WORD_1
	v_cvt_f32_f16_e32 v90, v193
	v_cvt_f32_f16_sdwa v91, v193 dst_sel:DWORD dst_unused:UNUSED_PAD src0_sel:WORD_1
	v_cvt_f32_f16_e32 v92, v194
	v_cvt_f32_f16_sdwa v93, v194 dst_sel:DWORD dst_unused:UNUSED_PAD src0_sel:WORD_1
	v_cvt_f32_f16_e32 v94, v195
	v_cvt_f32_f16_sdwa v95, v195 dst_sel:DWORD dst_unused:UNUSED_PAD src0_sel:WORD_1
	v_cvt_f32_f16_e32 v96, v196
	v_cvt_f32_f16_sdwa v97, v196 dst_sel:DWORD dst_unused:UNUSED_PAD src0_sel:WORD_1
	v_cvt_f32_f16_e32 v98, v197
	v_cvt_f32_f16_sdwa v99, v197 dst_sel:DWORD dst_unused:UNUSED_PAD src0_sel:WORD_1
	v_cvt_f32_f16_e32 v100, v198
	v_cvt_f32_f16_sdwa v101, v198 dst_sel:DWORD dst_unused:UNUSED_PAD src0_sel:WORD_1
	v_cvt_f32_f16_e32 v102, v199
	v_cvt_f32_f16_sdwa v103, v199 dst_sel:DWORD dst_unused:UNUSED_PAD src0_sel:WORD_1
	v_pk_mul_f32 v[232:233], v[72:73], v[72:73]
	v_pk_mul_f32 v[234:235], v[74:75], v[74:75]
	v_pk_mul_f32 v[236:237], v[76:77], v[76:77]
	v_pk_mul_f32 v[238:239], v[78:79], v[78:79]
	v_pk_fma_f32 v[232:233], v[80:81], v[80:81], v[232:233]
	v_pk_fma_f32 v[234:235], v[82:83], v[82:83], v[234:235]
	v_pk_fma_f32 v[236:237], v[84:85], v[84:85], v[236:237]
	v_pk_fma_f32 v[238:239], v[86:87], v[86:87], v[238:239]
	v_pk_fma_f32 v[232:233], v[88:89], v[88:89], v[232:233]
	v_pk_fma_f32 v[234:235], v[90:91], v[90:91], v[234:235]
	v_pk_fma_f32 v[236:237], v[92:93], v[92:93], v[236:237]
	v_pk_fma_f32 v[238:239], v[94:95], v[94:95], v[238:239]
	v_pk_fma_f32 v[232:233], v[96:97], v[96:97], v[232:233]
	v_pk_fma_f32 v[234:235], v[98:99], v[98:99], v[234:235]
	v_pk_fma_f32 v[236:237], v[100:101], v[100:101], v[236:237]
	v_pk_fma_f32 v[238:239], v[102:103], v[102:103], v[238:239]
	v_pk_add_f32 v[232:233], v[232:233], v[234:235]
	v_pk_add_f32 v[236:237], v[236:237], v[238:239]
	v_pk_add_f32 v[232:233], v[232:233], v[236:237]
	v_add_f32_e32 v240, v232, v233
	s_nop 1
	v_add_f32_dpp v240, v240, v240 quad_perm:[1,0,3,2] row_mask:0xf bank_mask:0xf
	s_nop 1
	v_add_f32_dpp v240, v240, v240 quad_perm:[2,3,0,1] row_mask:0xf bank_mask:0xf
	s_nop 1
	v_add_f32_dpp v240, v240, v240 row_half_mirror row_mask:0xf bank_mask:0xf
	s_nop 1
	v_add_f32_dpp v240, v240, v240 row_mirror row_mask:0xf bank_mask:0xf
	s_nop 1
	v_readlane_b32 s0, v240, 0
	v_readlane_b32 s1, v240, 16
	v_readlane_b32 s4, v240, 32
	v_readlane_b32 s5, v240, 48
	v_mov_b32_e32 v249, 0x358637bd
	s_nop 1
	v_mov_b32_e32 v240, s0
	v_add_f32_e32 v240, s1, v240
	v_add_f32_e32 v240, s4, v240
	v_add_f32_e32 v240, s5, v240
	v_fmamk_f32 v240, v240, 0x3a000000, v249
	s_mov_b32 s0, 0xf800000
	v_mul_f32_e32 v241, 0x4f800000, v240
	v_cmp_gt_f32_e32 vcc, s0, v240
	s_nop 1
	v_cndmask_b32_e32 v240, v240, v241, vcc
	v_sqrt_f32_e32 v241, v240
	s_nop 0
	v_add_u32_e32 v242, -1, v241
	v_fma_f32 v243, -v242, v241, v240
	v_cmp_ge_f32_e64 s[0:1], 0, v243
	v_add_u32_e32 v243, 1, v241
	s_nop 0
	v_cndmask_b32_e64 v242, v241, v242, s[0:1]
	v_fma_f32 v241, -v243, v241, v240
	v_cmp_lt_f32_e64 s[0:1], 0, v241
	s_nop 1
	v_cndmask_b32_e64 v241, v242, v243, s[0:1]
	v_mul_f32_e32 v242, 0x37800000, v241
	v_cndmask_b32_e32 v241, v241, v242, vcc
	v_cmp_class_f32_e32 vcc, v240, v248
	s_nop 1
	v_cndmask_b32_e32 v240, v241, v240, vcc
	v_div_scale_f32 v241, s[0:1], v240, v240, 1.0
	v_rcp_f32_e32 v242, v241
	s_nop 0
	v_fma_f32 v243, -v241, v242, 1.0
	v_fmac_f32_e32 v242, v243, v242
	v_div_scale_f32 v243, vcc, 1.0, v240, 1.0
	v_mul_f32_e32 v244, v243, v242
	v_fma_f32 v247, -v241, v244, v243
	v_fmac_f32_e32 v244, v247, v242
	v_fma_f32 v241, -v241, v244, v243
	s_nop 1
	v_div_fmas_f32 v241, v241, v242, v244
	v_div_fixup_f32 v246, v241, v240, 1.0
	v_pk_mul_f32 v[72:73], v[72:73], v[246:247] op_sel_hi:[1,0]
	v_pk_mul_f32 v[74:75], v[74:75], v[246:247] op_sel_hi:[1,0]
	v_pk_mul_f32 v[76:77], v[76:77], v[246:247] op_sel_hi:[1,0]
	v_pk_mul_f32 v[78:79], v[78:79], v[246:247] op_sel_hi:[1,0]
	v_pk_mul_f32 v[80:81], v[80:81], v[246:247] op_sel_hi:[1,0]
	v_pk_mul_f32 v[82:83], v[82:83], v[246:247] op_sel_hi:[1,0]
	v_pk_mul_f32 v[84:85], v[84:85], v[246:247] op_sel_hi:[1,0]
	v_pk_mul_f32 v[86:87], v[86:87], v[246:247] op_sel_hi:[1,0]
	v_pk_mul_f32 v[88:89], v[88:89], v[246:247] op_sel_hi:[1,0]
	v_pk_mul_f32 v[90:91], v[90:91], v[246:247] op_sel_hi:[1,0]
	v_pk_mul_f32 v[92:93], v[92:93], v[246:247] op_sel_hi:[1,0]
	v_pk_mul_f32 v[94:95], v[94:95], v[246:247] op_sel_hi:[1,0]
	v_pk_mul_f32 v[96:97], v[96:97], v[246:247] op_sel_hi:[1,0]
	v_pk_mul_f32 v[98:99], v[98:99], v[246:247] op_sel_hi:[1,0]
	v_pk_mul_f32 v[100:101], v[100:101], v[246:247] op_sel_hi:[1,0]
	v_pk_mul_f32 v[102:103], v[102:103], v[246:247] op_sel_hi:[1,0]
	s_add_u32 s8, s10, 0xa0000
	s_addc_u32 s9, s11, 0
	v_pk_fma_f32 v[72:73], v[8:9], v[72:73], v[40:41]
	v_cvt_pk_bf16_f32 v232, v72, v73
	v_pk_fma_f32 v[74:75], v[10:11], v[74:75], v[42:43]
	v_cvt_pk_bf16_f32 v233, v74, v75
	v_pk_fma_f32 v[76:77], v[12:13], v[76:77], v[44:45]
	v_cvt_pk_bf16_f32 v234, v76, v77
	v_pk_fma_f32 v[78:79], v[14:15], v[78:79], v[46:47]
	v_cvt_pk_bf16_f32 v235, v78, v79
	global_store_dwordx4 v1, v[232:235], s[8:9] offset:0
	v_pk_fma_f32 v[80:81], v[16:17], v[80:81], v[48:49]
	v_cvt_pk_bf16_f32 v236, v80, v81
	v_pk_fma_f32 v[82:83], v[18:19], v[82:83], v[50:51]
	v_cvt_pk_bf16_f32 v237, v82, v83
	v_pk_fma_f32 v[84:85], v[20:21], v[84:85], v[52:53]
	v_cvt_pk_bf16_f32 v238, v84, v85
	v_pk_fma_f32 v[86:87], v[22:23], v[86:87], v[54:55]
	v_cvt_pk_bf16_f32 v239, v86, v87
	global_store_dwordx4 v1, v[236:239], s[8:9] offset:1024
	v_pk_fma_f32 v[88:89], v[24:25], v[88:89], v[56:57]
	v_cvt_pk_bf16_f32 v232, v88, v89
	v_pk_fma_f32 v[90:91], v[26:27], v[90:91], v[58:59]
	v_cvt_pk_bf16_f32 v233, v90, v91
	v_pk_fma_f32 v[92:93], v[28:29], v[92:93], v[60:61]
	v_cvt_pk_bf16_f32 v234, v92, v93
	v_pk_fma_f32 v[94:95], v[30:31], v[94:95], v[62:63]
	v_cvt_pk_bf16_f32 v235, v94, v95
	global_store_dwordx4 v1, v[232:235], s[8:9] offset:2048
	v_pk_fma_f32 v[96:97], v[32:33], v[96:97], v[64:65]
	v_cvt_pk_bf16_f32 v236, v96, v97
	v_pk_fma_f32 v[98:99], v[34:35], v[98:99], v[66:67]
	v_cvt_pk_bf16_f32 v237, v98, v99
	v_pk_fma_f32 v[100:101], v[36:37], v[100:101], v[68:69]
	v_cvt_pk_bf16_f32 v238, v100, v101
	v_pk_fma_f32 v[102:103], v[38:39], v[102:103], v[70:71]
	v_cvt_pk_bf16_f32 v239, v102, v103
	global_store_dwordx4 v1, v[236:239], s[8:9] offset:3072
	s_waitcnt vmcnt(28)
	v_cvt_f32_f16_e32 v72, v200
	v_cvt_f32_f16_sdwa v73, v200 dst_sel:DWORD dst_unused:UNUSED_PAD src0_sel:WORD_1
	v_cvt_f32_f16_e32 v74, v201
	v_cvt_f32_f16_sdwa v75, v201 dst_sel:DWORD dst_unused:UNUSED_PAD src0_sel:WORD_1
	v_cvt_f32_f16_e32 v76, v202
	v_cvt_f32_f16_sdwa v77, v202 dst_sel:DWORD dst_unused:UNUSED_PAD src0_sel:WORD_1
	v_cvt_f32_f16_e32 v78, v203
	v_cvt_f32_f16_sdwa v79, v203 dst_sel:DWORD dst_unused:UNUSED_PAD src0_sel:WORD_1
	v_cvt_f32_f16_e32 v80, v204
	v_cvt_f32_f16_sdwa v81, v204 dst_sel:DWORD dst_unused:UNUSED_PAD src0_sel:WORD_1
	v_cvt_f32_f16_e32 v82, v205
	v_cvt_f32_f16_sdwa v83, v205 dst_sel:DWORD dst_unused:UNUSED_PAD src0_sel:WORD_1
	v_cvt_f32_f16_e32 v84, v206
	v_cvt_f32_f16_sdwa v85, v206 dst_sel:DWORD dst_unused:UNUSED_PAD src0_sel:WORD_1
	v_cvt_f32_f16_e32 v86, v207
	v_cvt_f32_f16_sdwa v87, v207 dst_sel:DWORD dst_unused:UNUSED_PAD src0_sel:WORD_1
	v_cvt_f32_f16_e32 v88, v208
	v_cvt_f32_f16_sdwa v89, v208 dst_sel:DWORD dst_unused:UNUSED_PAD src0_sel:WORD_1
	v_cvt_f32_f16_e32 v90, v209
	v_cvt_f32_f16_sdwa v91, v209 dst_sel:DWORD dst_unused:UNUSED_PAD src0_sel:WORD_1
	v_cvt_f32_f16_e32 v92, v210
	v_cvt_f32_f16_sdwa v93, v210 dst_sel:DWORD dst_unused:UNUSED_PAD src0_sel:WORD_1
	v_cvt_f32_f16_e32 v94, v211
	v_cvt_f32_f16_sdwa v95, v211 dst_sel:DWORD dst_unused:UNUSED_PAD src0_sel:WORD_1
	v_cvt_f32_f16_e32 v96, v212
	v_cvt_f32_f16_sdwa v97, v212 dst_sel:DWORD dst_unused:UNUSED_PAD src0_sel:WORD_1
	v_cvt_f32_f16_e32 v98, v213
	v_cvt_f32_f16_sdwa v99, v213 dst_sel:DWORD dst_unused:UNUSED_PAD src0_sel:WORD_1
	v_cvt_f32_f16_e32 v100, v214
	v_cvt_f32_f16_sdwa v101, v214 dst_sel:DWORD dst_unused:UNUSED_PAD src0_sel:WORD_1
	v_cvt_f32_f16_e32 v102, v215
	v_cvt_f32_f16_sdwa v103, v215 dst_sel:DWORD dst_unused:UNUSED_PAD src0_sel:WORD_1
	v_pk_mul_f32 v[232:233], v[72:73], v[72:73]
	v_pk_mul_f32 v[234:235], v[74:75], v[74:75]
	v_pk_mul_f32 v[236:237], v[76:77], v[76:77]
	v_pk_mul_f32 v[238:239], v[78:79], v[78:79]
	v_pk_fma_f32 v[232:233], v[80:81], v[80:81], v[232:233]
	v_pk_fma_f32 v[234:235], v[82:83], v[82:83], v[234:235]
	v_pk_fma_f32 v[236:237], v[84:85], v[84:85], v[236:237]
	v_pk_fma_f32 v[238:239], v[86:87], v[86:87], v[238:239]
	v_pk_fma_f32 v[232:233], v[88:89], v[88:89], v[232:233]
	v_pk_fma_f32 v[234:235], v[90:91], v[90:91], v[234:235]
	v_pk_fma_f32 v[236:237], v[92:93], v[92:93], v[236:237]
	v_pk_fma_f32 v[238:239], v[94:95], v[94:95], v[238:239]
	v_pk_fma_f32 v[232:233], v[96:97], v[96:97], v[232:233]
	v_pk_fma_f32 v[234:235], v[98:99], v[98:99], v[234:235]
	v_pk_fma_f32 v[236:237], v[100:101], v[100:101], v[236:237]
	v_pk_fma_f32 v[238:239], v[102:103], v[102:103], v[238:239]
	v_pk_add_f32 v[232:233], v[232:233], v[234:235]
	v_pk_add_f32 v[236:237], v[236:237], v[238:239]
	v_pk_add_f32 v[232:233], v[232:233], v[236:237]
	v_add_f32_e32 v240, v232, v233
	s_nop 1
	v_add_f32_dpp v240, v240, v240 quad_perm:[1,0,3,2] row_mask:0xf bank_mask:0xf
	s_nop 1
	v_add_f32_dpp v240, v240, v240 quad_perm:[2,3,0,1] row_mask:0xf bank_mask:0xf
	s_nop 1
	v_add_f32_dpp v240, v240, v240 row_half_mirror row_mask:0xf bank_mask:0xf
	s_nop 1
	v_add_f32_dpp v240, v240, v240 row_mirror row_mask:0xf bank_mask:0xf
	s_nop 1
	v_readlane_b32 s0, v240, 0
	v_readlane_b32 s1, v240, 16
	v_readlane_b32 s4, v240, 32
	v_readlane_b32 s5, v240, 48
	v_mov_b32_e32 v249, 0x358637bd
	s_nop 1
	v_mov_b32_e32 v240, s0
	v_add_f32_e32 v240, s1, v240
	v_add_f32_e32 v240, s4, v240
	v_add_f32_e32 v240, s5, v240
	v_fmamk_f32 v240, v240, 0x3a000000, v249
	s_mov_b32 s0, 0xf800000
	v_mul_f32_e32 v241, 0x4f800000, v240
	v_cmp_gt_f32_e32 vcc, s0, v240
	s_nop 1
	v_cndmask_b32_e32 v240, v240, v241, vcc
	v_sqrt_f32_e32 v241, v240
	s_nop 0
	v_add_u32_e32 v242, -1, v241
	v_fma_f32 v243, -v242, v241, v240
	v_cmp_ge_f32_e64 s[0:1], 0, v243
	v_add_u32_e32 v243, 1, v241
	s_nop 0
	v_cndmask_b32_e64 v242, v241, v242, s[0:1]
	v_fma_f32 v241, -v243, v241, v240
	v_cmp_lt_f32_e64 s[0:1], 0, v241
	s_nop 1
	v_cndmask_b32_e64 v241, v242, v243, s[0:1]
	v_mul_f32_e32 v242, 0x37800000, v241
	v_cndmask_b32_e32 v241, v241, v242, vcc
	v_cmp_class_f32_e32 vcc, v240, v248
	s_nop 1
	v_cndmask_b32_e32 v240, v241, v240, vcc
	v_div_scale_f32 v241, s[0:1], v240, v240, 1.0
	v_rcp_f32_e32 v242, v241
	s_nop 0
	v_fma_f32 v243, -v241, v242, 1.0
	v_fmac_f32_e32 v242, v243, v242
	v_div_scale_f32 v243, vcc, 1.0, v240, 1.0
	v_mul_f32_e32 v244, v243, v242
	v_fma_f32 v247, -v241, v244, v243
	v_fmac_f32_e32 v244, v247, v242
	v_fma_f32 v241, -v241, v244, v243
	s_nop 1
	v_div_fmas_f32 v241, v241, v242, v244
	v_div_fixup_f32 v246, v241, v240, 1.0
	v_pk_mul_f32 v[72:73], v[72:73], v[246:247] op_sel_hi:[1,0]
	v_pk_mul_f32 v[74:75], v[74:75], v[246:247] op_sel_hi:[1,0]
	v_pk_mul_f32 v[76:77], v[76:77], v[246:247] op_sel_hi:[1,0]
	v_pk_mul_f32 v[78:79], v[78:79], v[246:247] op_sel_hi:[1,0]
	v_pk_mul_f32 v[80:81], v[80:81], v[246:247] op_sel_hi:[1,0]
	v_pk_mul_f32 v[82:83], v[82:83], v[246:247] op_sel_hi:[1,0]
	v_pk_mul_f32 v[84:85], v[84:85], v[246:247] op_sel_hi:[1,0]
	v_pk_mul_f32 v[86:87], v[86:87], v[246:247] op_sel_hi:[1,0]
	v_pk_mul_f32 v[88:89], v[88:89], v[246:247] op_sel_hi:[1,0]
	v_pk_mul_f32 v[90:91], v[90:91], v[246:247] op_sel_hi:[1,0]
	v_pk_mul_f32 v[92:93], v[92:93], v[246:247] op_sel_hi:[1,0]
	v_pk_mul_f32 v[94:95], v[94:95], v[246:247] op_sel_hi:[1,0]
	v_pk_mul_f32 v[96:97], v[96:97], v[246:247] op_sel_hi:[1,0]
	v_pk_mul_f32 v[98:99], v[98:99], v[246:247] op_sel_hi:[1,0]
	v_pk_mul_f32 v[100:101], v[100:101], v[246:247] op_sel_hi:[1,0]
	v_pk_mul_f32 v[102:103], v[102:103], v[246:247] op_sel_hi:[1,0]
	s_add_u32 s8, s10, 0xc0000
	s_addc_u32 s9, s11, 0
	v_pk_fma_f32 v[72:73], v[8:9], v[72:73], v[40:41]
	v_cvt_pk_bf16_f32 v232, v72, v73
	v_pk_fma_f32 v[74:75], v[10:11], v[74:75], v[42:43]
	v_cvt_pk_bf16_f32 v233, v74, v75
	v_pk_fma_f32 v[76:77], v[12:13], v[76:77], v[44:45]
	v_cvt_pk_bf16_f32 v234, v76, v77
	v_pk_fma_f32 v[78:79], v[14:15], v[78:79], v[46:47]
	v_cvt_pk_bf16_f32 v235, v78, v79
	global_store_dwordx4 v1, v[232:235], s[8:9] offset:0
	v_pk_fma_f32 v[80:81], v[16:17], v[80:81], v[48:49]
	v_cvt_pk_bf16_f32 v236, v80, v81
	v_pk_fma_f32 v[82:83], v[18:19], v[82:83], v[50:51]
	v_cvt_pk_bf16_f32 v237, v82, v83
	v_pk_fma_f32 v[84:85], v[20:21], v[84:85], v[52:53]
	v_cvt_pk_bf16_f32 v238, v84, v85
	v_pk_fma_f32 v[86:87], v[22:23], v[86:87], v[54:55]
	v_cvt_pk_bf16_f32 v239, v86, v87
	global_store_dwordx4 v1, v[236:239], s[8:9] offset:1024
	v_pk_fma_f32 v[88:89], v[24:25], v[88:89], v[56:57]
	v_cvt_pk_bf16_f32 v232, v88, v89
	v_pk_fma_f32 v[90:91], v[26:27], v[90:91], v[58:59]
	v_cvt_pk_bf16_f32 v233, v90, v91
	v_pk_fma_f32 v[92:93], v[28:29], v[92:93], v[60:61]
	v_cvt_pk_bf16_f32 v234, v92, v93
	v_pk_fma_f32 v[94:95], v[30:31], v[94:95], v[62:63]
	v_cvt_pk_bf16_f32 v235, v94, v95
	global_store_dwordx4 v1, v[232:235], s[8:9] offset:2048
	v_pk_fma_f32 v[96:97], v[32:33], v[96:97], v[64:65]
	v_cvt_pk_bf16_f32 v236, v96, v97
	v_pk_fma_f32 v[98:99], v[34:35], v[98:99], v[66:67]
	v_cvt_pk_bf16_f32 v237, v98, v99
	v_pk_fma_f32 v[100:101], v[36:37], v[100:101], v[68:69]
	v_cvt_pk_bf16_f32 v238, v100, v101
	v_pk_fma_f32 v[102:103], v[38:39], v[102:103], v[70:71]
	v_cvt_pk_bf16_f32 v239, v102, v103
	global_store_dwordx4 v1, v[236:239], s[8:9] offset:3072
	s_waitcnt vmcnt(28)
	v_cvt_f32_f16_e32 v72, v216
	v_cvt_f32_f16_sdwa v73, v216 dst_sel:DWORD dst_unused:UNUSED_PAD src0_sel:WORD_1
	v_cvt_f32_f16_e32 v74, v217
	v_cvt_f32_f16_sdwa v75, v217 dst_sel:DWORD dst_unused:UNUSED_PAD src0_sel:WORD_1
	v_cvt_f32_f16_e32 v76, v218
	v_cvt_f32_f16_sdwa v77, v218 dst_sel:DWORD dst_unused:UNUSED_PAD src0_sel:WORD_1
	v_cvt_f32_f16_e32 v78, v219
	v_cvt_f32_f16_sdwa v79, v219 dst_sel:DWORD dst_unused:UNUSED_PAD src0_sel:WORD_1
	v_cvt_f32_f16_e32 v80, v220
	v_cvt_f32_f16_sdwa v81, v220 dst_sel:DWORD dst_unused:UNUSED_PAD src0_sel:WORD_1
	v_cvt_f32_f16_e32 v82, v221
	v_cvt_f32_f16_sdwa v83, v221 dst_sel:DWORD dst_unused:UNUSED_PAD src0_sel:WORD_1
	v_cvt_f32_f16_e32 v84, v222
	v_cvt_f32_f16_sdwa v85, v222 dst_sel:DWORD dst_unused:UNUSED_PAD src0_sel:WORD_1
	v_cvt_f32_f16_e32 v86, v223
	v_cvt_f32_f16_sdwa v87, v223 dst_sel:DWORD dst_unused:UNUSED_PAD src0_sel:WORD_1
	v_cvt_f32_f16_e32 v88, v224
	v_cvt_f32_f16_sdwa v89, v224 dst_sel:DWORD dst_unused:UNUSED_PAD src0_sel:WORD_1
	v_cvt_f32_f16_e32 v90, v225
	v_cvt_f32_f16_sdwa v91, v225 dst_sel:DWORD dst_unused:UNUSED_PAD src0_sel:WORD_1
	v_cvt_f32_f16_e32 v92, v226
	v_cvt_f32_f16_sdwa v93, v226 dst_sel:DWORD dst_unused:UNUSED_PAD src0_sel:WORD_1
	v_cvt_f32_f16_e32 v94, v227
	v_cvt_f32_f16_sdwa v95, v227 dst_sel:DWORD dst_unused:UNUSED_PAD src0_sel:WORD_1
	v_cvt_f32_f16_e32 v96, v228
	v_cvt_f32_f16_sdwa v97, v228 dst_sel:DWORD dst_unused:UNUSED_PAD src0_sel:WORD_1
	v_cvt_f32_f16_e32 v98, v229
	v_cvt_f32_f16_sdwa v99, v229 dst_sel:DWORD dst_unused:UNUSED_PAD src0_sel:WORD_1
	v_cvt_f32_f16_e32 v100, v230
	v_cvt_f32_f16_sdwa v101, v230 dst_sel:DWORD dst_unused:UNUSED_PAD src0_sel:WORD_1
	v_cvt_f32_f16_e32 v102, v231
	v_cvt_f32_f16_sdwa v103, v231 dst_sel:DWORD dst_unused:UNUSED_PAD src0_sel:WORD_1
	v_pk_mul_f32 v[232:233], v[72:73], v[72:73]
	v_pk_mul_f32 v[234:235], v[74:75], v[74:75]
	v_pk_mul_f32 v[236:237], v[76:77], v[76:77]
	v_pk_mul_f32 v[238:239], v[78:79], v[78:79]
	v_pk_fma_f32 v[232:233], v[80:81], v[80:81], v[232:233]
	v_pk_fma_f32 v[234:235], v[82:83], v[82:83], v[234:235]
	v_pk_fma_f32 v[236:237], v[84:85], v[84:85], v[236:237]
	v_pk_fma_f32 v[238:239], v[86:87], v[86:87], v[238:239]
	v_pk_fma_f32 v[232:233], v[88:89], v[88:89], v[232:233]
	v_pk_fma_f32 v[234:235], v[90:91], v[90:91], v[234:235]
	v_pk_fma_f32 v[236:237], v[92:93], v[92:93], v[236:237]
	v_pk_fma_f32 v[238:239], v[94:95], v[94:95], v[238:239]
	v_pk_fma_f32 v[232:233], v[96:97], v[96:97], v[232:233]
	v_pk_fma_f32 v[234:235], v[98:99], v[98:99], v[234:235]
	v_pk_fma_f32 v[236:237], v[100:101], v[100:101], v[236:237]
	v_pk_fma_f32 v[238:239], v[102:103], v[102:103], v[238:239]
	v_pk_add_f32 v[232:233], v[232:233], v[234:235]
	v_pk_add_f32 v[236:237], v[236:237], v[238:239]
	v_pk_add_f32 v[232:233], v[232:233], v[236:237]
	v_add_f32_e32 v240, v232, v233
	s_nop 1
	v_add_f32_dpp v240, v240, v240 quad_perm:[1,0,3,2] row_mask:0xf bank_mask:0xf
	s_nop 1
	v_add_f32_dpp v240, v240, v240 quad_perm:[2,3,0,1] row_mask:0xf bank_mask:0xf
	s_nop 1
	v_add_f32_dpp v240, v240, v240 row_half_mirror row_mask:0xf bank_mask:0xf
	s_nop 1
	v_add_f32_dpp v240, v240, v240 row_mirror row_mask:0xf bank_mask:0xf
	s_nop 1
	v_readlane_b32 s0, v240, 0
	v_readlane_b32 s1, v240, 16
	v_readlane_b32 s4, v240, 32
	v_readlane_b32 s5, v240, 48
	v_mov_b32_e32 v249, 0x358637bd
	s_nop 1
	v_mov_b32_e32 v240, s0
	v_add_f32_e32 v240, s1, v240
	v_add_f32_e32 v240, s4, v240
	v_add_f32_e32 v240, s5, v240
	v_fmamk_f32 v240, v240, 0x3a000000, v249
	s_mov_b32 s0, 0xf800000
	v_mul_f32_e32 v241, 0x4f800000, v240
	v_cmp_gt_f32_e32 vcc, s0, v240
	s_nop 1
	v_cndmask_b32_e32 v240, v240, v241, vcc
	v_sqrt_f32_e32 v241, v240
	s_nop 0
	v_add_u32_e32 v242, -1, v241
	v_fma_f32 v243, -v242, v241, v240
	v_cmp_ge_f32_e64 s[0:1], 0, v243
	v_add_u32_e32 v243, 1, v241
	s_nop 0
	v_cndmask_b32_e64 v242, v241, v242, s[0:1]
	v_fma_f32 v241, -v243, v241, v240
	v_cmp_lt_f32_e64 s[0:1], 0, v241
	s_nop 1
	v_cndmask_b32_e64 v241, v242, v243, s[0:1]
	v_mul_f32_e32 v242, 0x37800000, v241
	v_cndmask_b32_e32 v241, v241, v242, vcc
	v_cmp_class_f32_e32 vcc, v240, v248
	s_nop 1
	v_cndmask_b32_e32 v240, v241, v240, vcc
	v_div_scale_f32 v241, s[0:1], v240, v240, 1.0
	v_rcp_f32_e32 v242, v241
	s_nop 0
	v_fma_f32 v243, -v241, v242, 1.0
	v_fmac_f32_e32 v242, v243, v242
	v_div_scale_f32 v243, vcc, 1.0, v240, 1.0
	v_mul_f32_e32 v244, v243, v242
	v_fma_f32 v247, -v241, v244, v243
	v_fmac_f32_e32 v244, v247, v242
	v_fma_f32 v241, -v241, v244, v243
	s_nop 1
	v_div_fmas_f32 v241, v241, v242, v244
	v_div_fixup_f32 v246, v241, v240, 1.0
	v_pk_mul_f32 v[72:73], v[72:73], v[246:247] op_sel_hi:[1,0]
	v_pk_mul_f32 v[74:75], v[74:75], v[246:247] op_sel_hi:[1,0]
	v_pk_mul_f32 v[76:77], v[76:77], v[246:247] op_sel_hi:[1,0]
	v_pk_mul_f32 v[78:79], v[78:79], v[246:247] op_sel_hi:[1,0]
	v_pk_mul_f32 v[80:81], v[80:81], v[246:247] op_sel_hi:[1,0]
	v_pk_mul_f32 v[82:83], v[82:83], v[246:247] op_sel_hi:[1,0]
	v_pk_mul_f32 v[84:85], v[84:85], v[246:247] op_sel_hi:[1,0]
	v_pk_mul_f32 v[86:87], v[86:87], v[246:247] op_sel_hi:[1,0]
	v_pk_mul_f32 v[88:89], v[88:89], v[246:247] op_sel_hi:[1,0]
	v_pk_mul_f32 v[90:91], v[90:91], v[246:247] op_sel_hi:[1,0]
	v_pk_mul_f32 v[92:93], v[92:93], v[246:247] op_sel_hi:[1,0]
	v_pk_mul_f32 v[94:95], v[94:95], v[246:247] op_sel_hi:[1,0]
	v_pk_mul_f32 v[96:97], v[96:97], v[246:247] op_sel_hi:[1,0]
	v_pk_mul_f32 v[98:99], v[98:99], v[246:247] op_sel_hi:[1,0]
	v_pk_mul_f32 v[100:101], v[100:101], v[246:247] op_sel_hi:[1,0]
	v_pk_mul_f32 v[102:103], v[102:103], v[246:247] op_sel_hi:[1,0]
	s_add_u32 s8, s10, 0xe0000
	s_addc_u32 s9, s11, 0
	v_pk_fma_f32 v[72:73], v[8:9], v[72:73], v[40:41]
	v_cvt_pk_bf16_f32 v232, v72, v73
	v_pk_fma_f32 v[74:75], v[10:11], v[74:75], v[42:43]
	v_cvt_pk_bf16_f32 v233, v74, v75
	v_pk_fma_f32 v[76:77], v[12:13], v[76:77], v[44:45]
	v_cvt_pk_bf16_f32 v234, v76, v77
	v_pk_fma_f32 v[78:79], v[14:15], v[78:79], v[46:47]
	v_cvt_pk_bf16_f32 v235, v78, v79
	global_store_dwordx4 v1, v[232:235], s[8:9] offset:0
	v_pk_fma_f32 v[80:81], v[16:17], v[80:81], v[48:49]
	v_cvt_pk_bf16_f32 v236, v80, v81
	v_pk_fma_f32 v[82:83], v[18:19], v[82:83], v[50:51]
	v_cvt_pk_bf16_f32 v237, v82, v83
	v_pk_fma_f32 v[84:85], v[20:21], v[84:85], v[52:53]
	v_cvt_pk_bf16_f32 v238, v84, v85
	v_pk_fma_f32 v[86:87], v[22:23], v[86:87], v[54:55]
	v_cvt_pk_bf16_f32 v239, v86, v87
	global_store_dwordx4 v1, v[236:239], s[8:9] offset:1024
	v_pk_fma_f32 v[88:89], v[24:25], v[88:89], v[56:57]
	v_cvt_pk_bf16_f32 v232, v88, v89
	v_pk_fma_f32 v[90:91], v[26:27], v[90:91], v[58:59]
	v_cvt_pk_bf16_f32 v233, v90, v91
	v_pk_fma_f32 v[92:93], v[28:29], v[92:93], v[60:61]
	v_cvt_pk_bf16_f32 v234, v92, v93
	v_pk_fma_f32 v[94:95], v[30:31], v[94:95], v[62:63]
	v_cvt_pk_bf16_f32 v235, v94, v95
	global_store_dwordx4 v1, v[232:235], s[8:9] offset:2048
	v_pk_fma_f32 v[96:97], v[32:33], v[96:97], v[64:65]
	v_cvt_pk_bf16_f32 v236, v96, v97
	v_pk_fma_f32 v[98:99], v[34:35], v[98:99], v[66:67]
	v_cvt_pk_bf16_f32 v237, v98, v99
	v_pk_fma_f32 v[100:101], v[36:37], v[100:101], v[68:69]
	v_cvt_pk_bf16_f32 v238, v100, v101
	v_pk_fma_f32 v[102:103], v[38:39], v[102:103], v[70:71]
	v_cvt_pk_bf16_f32 v239, v102, v103
	global_store_dwordx4 v1, v[236:239], s[8:9] offset:3072
	s_branch .LBB0_1143

.LBB0_1435:
	v_readlane_b32 s4, v250, 12
	s_cmp_lt_i32 s4, 13
	s_cselect_b64 s[0:1], -1, 0
	s_and_b64 s[2:3], s[0:1], s[2:3]
	s_andn2_b64 vcc, exec, s[2:3]
	v_readlane_b32 s5, v250, 13
	v_readlane_b32 s6, v250, 14
	v_readlane_b32 s7, v250, 15
	s_cbranch_vccnz .LBB0_1447
	v_and_b32_e32 v1, 63, v0
	v_lshlrev_b32_e32 v2, 5, v1
	v_add_u32_e32 v3, 0x1000, v2
	v_lshlrev_b32_e32 v1, 4, v1
	v_mov_b32_e32 v4, 0x2416c
	ds_read_b32 v5, v4
	ds_read_b32 v6, v4 offset:4
	v_readfirstlane_b32 s0, v0
	s_lshr_b32 s1, s0, 6
	s_waitcnt lgkmcnt(0)
	v_readfirstlane_b32 s4, v5
	v_readfirstlane_b32 s5, v6
	s_cmp_lt_i32 s4, 1
	s_cbranch_scc1 .Lnorm_fb_2
	s_add_i32 s4, s4, -1
	s_lshl_b32 s18, s4, 8
	s_lshl_b32 s19, s5, 3
	s_add_i32 s18, s18, s19
	s_add_i32 s18, s18, s1
	s_lshr_b32 s19, s4, 4
	s_lshl_b32 s20, s18, 12
	s_add_u32 s6, s88, 0x45c00000
	s_addc_u32 s7, s89, 0
	s_add_u32 s6, s6, s20
	s_addc_u32 s7, s7, 0
	s_add_u32 s10, s88, 0x13e00000
	s_addc_u32 s11, s89, 0
	s_add_u32 s10, s10, s20
	s_addc_u32 s11, s11, 0
	s_add_u32 s12, s44, 0x6000
	s_addc_u32 s13, s45, 0
	s_mul_i32 s21, s19, 0x12000
	s_add_u32 s14, s88, 0x148000
	s_addc_u32 s15, s89, 0
	s_add_u32 s14, s14, s21
	s_addc_u32 s15, s15, 0
	s_add_u32 s16, s88, 0x14a000
	s_addc_u32 s17, s89, 0
	s_add_u32 s16, s16, s21
	s_addc_u32 s17, s17, 0
	s_add_u32 s22, s88, 0x17e00000
	s_addc_u32 s23, s89, 0
	s_add_u32 s22, s22, s20
	s_addc_u32 s23, s23, 0
	s_add_u32 s24, s62, 0x0
	s_addc_u32 s25, s63, 0
	s_mul_i32 s21, s19, 0x4000
	s_add_u32 s26, s88, 0x190000
	s_addc_u32 s27, s89, 0
	s_add_u32 s26, s26, s21
	s_addc_u32 s27, s27, 0
	s_add_u32 s28, s88, 0x192000
	s_addc_u32 s29, s89, 0
	s_add_u32 s28, s28, s21
	s_addc_u32 s29, s29, 0
	global_load_dwordx4 v[136:139], v2, s[12:13] offset:0
	global_load_dwordx4 v[140:143], v2, s[12:13] offset:16
	global_load_dwordx4 v[144:147], v2, s[12:13] offset:2048
	global_load_dwordx4 v[148:151], v2, s[12:13] offset:2064
	global_load_dwordx4 v[152:155], v3, s[12:13] offset:0
	global_load_dwordx4 v[156:159], v3, s[12:13] offset:16
	global_load_dwordx4 v[160:163], v3, s[12:13] offset:2048
	global_load_dwordx4 v[164:167], v3, s[12:13] offset:2064
	global_load_dwordx4 v[8:11], v2, s[16:17] offset:0
	global_load_dwordx4 v[12:15], v2, s[16:17] offset:16
	global_load_dwordx4 v[16:19], v2, s[16:17] offset:2048
	global_load_dwordx4 v[20:23], v2, s[16:17] offset:2064
	global_load_dwordx4 v[24:27], v3, s[16:17] offset:0
	global_load_dwordx4 v[28:31], v3, s[16:17] offset:16
	global_load_dwordx4 v[32:35], v3, s[16:17] offset:2048
	global_load_dwordx4 v[36:39], v3, s[16:17] offset:2064
	global_load_dwordx4 v[40:43], v2, s[14:15] offset:0
	global_load_dwordx4 v[44:47], v2, s[14:15] offset:16
	global_load_dwordx4 v[48:51], v2, s[14:15] offset:2048
	global_load_dwordx4 v[52:55], v2, s[14:15] offset:2064
	global_load_dwordx4 v[56:59], v3, s[14:15] offset:0
	global_load_dwordx4 v[60:63], v3, s[14:15] offset:16
	global_load_dwordx4 v[64:67], v3, s[14:15] offset:2048
	global_load_dwordx4 v[68:71], v3, s[14:15] offset:2064
	s_waitcnt vmcnt(0)
	v_pk_add_f32 v[8:9], v[8:9], 1.0 op_sel_hi:[1,0]
	v_pk_add_f32 v[10:11], v[10:11], 1.0 op_sel_hi:[1,0]
	v_pk_add_f32 v[12:13], v[12:13], 1.0 op_sel_hi:[1,0]
	v_pk_add_f32 v[14:15], v[14:15], 1.0 op_sel_hi:[1,0]
	v_pk_add_f32 v[16:17], v[16:17], 1.0 op_sel_hi:[1,0]
	v_pk_add_f32 v[18:19], v[18:19], 1.0 op_sel_hi:[1,0]
	v_pk_add_f32 v[20:21], v[20:21], 1.0 op_sel_hi:[1,0]
	v_pk_add_f32 v[22:23], v[22:23], 1.0 op_sel_hi:[1,0]
	v_pk_add_f32 v[24:25], v[24:25], 1.0 op_sel_hi:[1,0]
	v_pk_add_f32 v[26:27], v[26:27], 1.0 op_sel_hi:[1,0]
	v_pk_add_f32 v[28:29], v[28:29], 1.0 op_sel_hi:[1,0]
	v_pk_add_f32 v[30:31], v[30:31], 1.0 op_sel_hi:[1,0]
	v_pk_add_f32 v[32:33], v[32:33], 1.0 op_sel_hi:[1,0]
	v_pk_add_f32 v[34:35], v[34:35], 1.0 op_sel_hi:[1,0]
	v_pk_add_f32 v[36:37], v[36:37], 1.0 op_sel_hi:[1,0]
	v_pk_add_f32 v[38:39], v[38:39], 1.0 op_sel_hi:[1,0]
	v_pk_mul_f32 v[8:9], v[136:137], v[8:9]
	v_pk_mul_f32 v[10:11], v[138:139], v[10:11]
	v_pk_mul_f32 v[12:13], v[140:141], v[12:13]
	v_pk_mul_f32 v[14:15], v[142:143], v[14:15]
	v_pk_mul_f32 v[16:17], v[144:145], v[16:17]
	v_pk_mul_f32 v[18:19], v[146:147], v[18:19]
	v_pk_mul_f32 v[20:21], v[148:149], v[20:21]
	v_pk_mul_f32 v[22:23], v[150:151], v[22:23]
	v_pk_mul_f32 v[24:25], v[152:153], v[24:25]
	v_pk_mul_f32 v[26:27], v[154:155], v[26:27]
	v_pk_mul_f32 v[28:29], v[156:157], v[28:29]
	v_pk_mul_f32 v[30:31], v[158:159], v[30:31]
	v_pk_mul_f32 v[32:33], v[160:161], v[32:33]
	v_pk_mul_f32 v[34:35], v[162:163], v[34:35]
	v_pk_mul_f32 v[36:37], v[164:165], v[36:37]
	v_pk_mul_f32 v[38:39], v[166:167], v[38:39]
	global_load_dwordx4 v[136:139], v2, s[24:25] offset:0
	global_load_dwordx4 v[140:143], v2, s[24:25] offset:16
	global_load_dwordx4 v[144:147], v2, s[24:25] offset:2048
	global_load_dwordx4 v[148:151], v2, s[24:25] offset:2064
	global_load_dwordx4 v[152:155], v3, s[24:25] offset:0
	global_load_dwordx4 v[156:159], v3, s[24:25] offset:16
	global_load_dwordx4 v[160:163], v3, s[24:25] offset:2048
	global_load_dwordx4 v[164:167], v3, s[24:25] offset:2064
	global_load_dwordx4 v[72:75], v2, s[28:29] offset:0
	global_load_dwordx4 v[76:79], v2, s[28:29] offset:16
	global_load_dwordx4 v[80:83], v2, s[28:29] offset:2048
	global_load_dwordx4 v[84:87], v2, s[28:29] offset:2064
	global_load_dwordx4 v[88:91], v3, s[28:29] offset:0
	global_load_dwordx4 v[92:95], v3, s[28:29] offset:16
	global_load_dwordx4 v[96:99], v3, s[28:29] offset:2048
	global_load_dwordx4 v[100:103], v3, s[28:29] offset:2064
	global_load_dwordx4 v[104:107], v2, s[26:27] offset:0
	global_load_dwordx4 v[108:111], v2, s[26:27] offset:16
	global_load_dwordx4 v[112:115], v2, s[26:27] offset:2048
	global_load_dwordx4 v[116:119], v2, s[26:27] offset:2064
	global_load_dwordx4 v[120:123], v3, s[26:27] offset:0
	global_load_dwordx4 v[124:127], v3, s[26:27] offset:16
	global_load_dwordx4 v[128:131], v3, s[26:27] offset:2048
	global_load_dwordx4 v[132:135], v3, s[26:27] offset:2064
	s_add_u32 s8, s6, 0x0
	s_addc_u32 s9, s7, 0
	global_load_dwordx4 v[168:171], v1, s[8:9] offset:0 nt
	global_load_dwordx4 v[172:175], v1, s[8:9] offset:1024 nt
	global_load_dwordx4 v[176:179], v1, s[8:9] offset:2048 nt
	global_load_dwordx4 v[180:183], v1, s[8:9] offset:3072 nt
	s_add_u32 s8, s6, 0x20000
	s_addc_u32 s9, s7, 0
	global_load_dwordx4 v[184:187], v1, s[8:9] offset:0 nt
	global_load_dwordx4 v[188:191], v1, s[8:9] offset:1024 nt
	global_load_dwordx4 v[192:195], v1, s[8:9] offset:2048 nt
	global_load_dwordx4 v[196:199], v1, s[8:9] offset:3072 nt
	s_add_u32 s8, s6, 0x40000
	s_addc_u32 s9, s7, 0
	global_load_dwordx4 v[200:203], v1, s[8:9] offset:0 nt
	global_load_dwordx4 v[204:207], v1, s[8:9] offset:1024 nt
	global_load_dwordx4 v[208:211], v1, s[8:9] offset:2048 nt
	global_load_dwordx4 v[212:215], v1, s[8:9] offset:3072 nt
	s_add_u32 s8, s6, 0x60000
	s_addc_u32 s9, s7, 0
	global_load_dwordx4 v[216:219], v1, s[8:9] offset:0 nt
	global_load_dwordx4 v[220:223], v1, s[8:9] offset:1024 nt
	global_load_dwordx4 v[224:227], v1, s[8:9] offset:2048 nt
	global_load_dwordx4 v[228:231], v1, s[8:9] offset:3072 nt
	s_waitcnt vmcnt(16)
	v_pk_add_f32 v[72:73], v[72:73], 1.0 op_sel_hi:[1,0]
	v_pk_add_f32 v[74:75], v[74:75], 1.0 op_sel_hi:[1,0]
	v_pk_add_f32 v[76:77], v[76:77], 1.0 op_sel_hi:[1,0]
	v_pk_add_f32 v[78:79], v[78:79], 1.0 op_sel_hi:[1,0]
	v_pk_add_f32 v[80:81], v[80:81], 1.0 op_sel_hi:[1,0]
	v_pk_add_f32 v[82:83], v[82:83], 1.0 op_sel_hi:[1,0]
	v_pk_add_f32 v[84:85], v[84:85], 1.0 op_sel_hi:[1,0]
	v_pk_add_f32 v[86:87], v[86:87], 1.0 op_sel_hi:[1,0]
	v_pk_add_f32 v[88:89], v[88:89], 1.0 op_sel_hi:[1,0]
	v_pk_add_f32 v[90:91], v[90:91], 1.0 op_sel_hi:[1,0]
	v_pk_add_f32 v[92:93], v[92:93], 1.0 op_sel_hi:[1,0]
	v_pk_add_f32 v[94:95], v[94:95], 1.0 op_sel_hi:[1,0]
	v_pk_add_f32 v[96:97], v[96:97], 1.0 op_sel_hi:[1,0]
	v_pk_add_f32 v[98:99], v[98:99], 1.0 op_sel_hi:[1,0]
	v_pk_add_f32 v[100:101], v[100:101], 1.0 op_sel_hi:[1,0]
	v_pk_add_f32 v[102:103], v[102:103], 1.0 op_sel_hi:[1,0]
	v_pk_mul_f32 v[72:73], v[136:137], v[72:73]
	v_pk_mul_f32 v[74:75], v[138:139], v[74:75]
	v_pk_mul_f32 v[76:77], v[140:141], v[76:77]
	v_pk_mul_f32 v[78:79], v[142:143], v[78:79]
	v_pk_mul_f32 v[80:81], v[144:145], v[80:81]
	v_pk_mul_f32 v[82:83], v[146:147], v[82:83]
	v_pk_mul_f32 v[84:85], v[148:149], v[84:85]
	v_pk_mul_f32 v[86:87], v[150:151], v[86:87]
	v_pk_mul_f32 v[88:89], v[152:153], v[88:89]
	v_pk_mul_f32 v[90:91], v[154:155], v[90:91]
	v_pk_mul_f32 v[92:93], v[156:157], v[92:93]
	v_pk_mul_f32 v[94:95], v[158:159], v[94:95]
	v_pk_mul_f32 v[96:97], v[160:161], v[96:97]
	v_pk_mul_f32 v[98:99], v[162:163], v[98:99]
	v_pk_mul_f32 v[100:101], v[164:165], v[100:101]
	v_pk_mul_f32 v[102:103], v[166:167], v[102:103]
	v_mov_b32_e32 v248, 0x260
	s_waitcnt vmcnt(12)
	v_cvt_f32_f16_e32 v136, v168
	v_cvt_f32_f16_sdwa v137, v168 dst_sel:DWORD dst_unused:UNUSED_PAD src0_sel:WORD_1
	v_cvt_f32_f16_e32 v138, v169
	v_cvt_f32_f16_sdwa v139, v169 dst_sel:DWORD dst_unused:UNUSED_PAD src0_sel:WORD_1
	v_cvt_f32_f16_e32 v140, v170
	v_cvt_f32_f16_sdwa v141, v170 dst_sel:DWORD dst_unused:UNUSED_PAD src0_sel:WORD_1
	v_cvt_f32_f16_e32 v142, v171
	v_cvt_f32_f16_sdwa v143, v171 dst_sel:DWORD dst_unused:UNUSED_PAD src0_sel:WORD_1
	v_cvt_f32_f16_e32 v144, v172
	v_cvt_f32_f16_sdwa v145, v172 dst_sel:DWORD dst_unused:UNUSED_PAD src0_sel:WORD_1
	v_cvt_f32_f16_e32 v146, v173
	v_cvt_f32_f16_sdwa v147, v173 dst_sel:DWORD dst_unused:UNUSED_PAD src0_sel:WORD_1
	v_cvt_f32_f16_e32 v148, v174
	v_cvt_f32_f16_sdwa v149, v174 dst_sel:DWORD dst_unused:UNUSED_PAD src0_sel:WORD_1
	v_cvt_f32_f16_e32 v150, v175
	v_cvt_f32_f16_sdwa v151, v175 dst_sel:DWORD dst_unused:UNUSED_PAD src0_sel:WORD_1
	v_cvt_f32_f16_e32 v152, v176
	v_cvt_f32_f16_sdwa v153, v176 dst_sel:DWORD dst_unused:UNUSED_PAD src0_sel:WORD_1
	v_cvt_f32_f16_e32 v154, v177
	v_cvt_f32_f16_sdwa v155, v177 dst_sel:DWORD dst_unused:UNUSED_PAD src0_sel:WORD_1
	v_cvt_f32_f16_e32 v156, v178
	v_cvt_f32_f16_sdwa v157, v178 dst_sel:DWORD dst_unused:UNUSED_PAD src0_sel:WORD_1
	v_cvt_f32_f16_e32 v158, v179
	v_cvt_f32_f16_sdwa v159, v179 dst_sel:DWORD dst_unused:UNUSED_PAD src0_sel:WORD_1
	v_cvt_f32_f16_e32 v160, v180
	v_cvt_f32_f16_sdwa v161, v180 dst_sel:DWORD dst_unused:UNUSED_PAD src0_sel:WORD_1
	v_cvt_f32_f16_e32 v162, v181
	v_cvt_f32_f16_sdwa v163, v181 dst_sel:DWORD dst_unused:UNUSED_PAD src0_sel:WORD_1
	v_cvt_f32_f16_e32 v164, v182
	v_cvt_f32_f16_sdwa v165, v182 dst_sel:DWORD dst_unused:UNUSED_PAD src0_sel:WORD_1
	v_cvt_f32_f16_e32 v166, v183
	v_cvt_f32_f16_sdwa v167, v183 dst_sel:DWORD dst_unused:UNUSED_PAD src0_sel:WORD_1
	s_add_u32 s8, s6, 0x80000
	s_addc_u32 s9, s7, 0
	global_load_dwordx4 v[168:171], v1, s[8:9] offset:0 nt
	global_load_dwordx4 v[172:175], v1, s[8:9] offset:1024 nt
	global_load_dwordx4 v[176:179], v1, s[8:9] offset:2048 nt
	global_load_dwordx4 v[180:183], v1, s[8:9] offset:3072 nt
	v_pk_mul_f32 v[232:233], v[136:137], v[136:137]
	v_pk_mul_f32 v[234:235], v[138:139], v[138:139]
	v_pk_mul_f32 v[236:237], v[140:141], v[140:141]
	v_pk_mul_f32 v[238:239], v[142:143], v[142:143]
	v_pk_fma_f32 v[232:233], v[144:145], v[144:145], v[232:233]
	v_pk_fma_f32 v[234:235], v[146:147], v[146:147], v[234:235]
	v_pk_fma_f32 v[236:237], v[148:149], v[148:149], v[236:237]
	v_pk_fma_f32 v[238:239], v[150:151], v[150:151], v[238:239]
	v_pk_fma_f32 v[232:233], v[152:153], v[152:153], v[232:233]
	v_pk_fma_f32 v[234:235], v[154:155], v[154:155], v[234:235]
	v_pk_fma_f32 v[236:237], v[156:157], v[156:157], v[236:237]
	v_pk_fma_f32 v[238:239], v[158:159], v[158:159], v[238:239]
	v_pk_fma_f32 v[232:233], v[160:161], v[160:161], v[232:233]
	v_pk_fma_f32 v[234:235], v[162:163], v[162:163], v[234:235]
	v_pk_fma_f32 v[236:237], v[164:165], v[164:165], v[236:237]
	v_pk_fma_f32 v[238:239], v[166:167], v[166:167], v[238:239]
	v_pk_add_f32 v[232:233], v[232:233], v[234:235]
	v_pk_add_f32 v[236:237], v[236:237], v[238:239]
	v_pk_add_f32 v[232:233], v[232:233], v[236:237]
	v_add_f32_e32 v240, v232, v233
	s_nop 1
	v_add_f32_dpp v240, v240, v240 quad_perm:[1,0,3,2] row_mask:0xf bank_mask:0xf
	s_nop 1
	v_add_f32_dpp v240, v240, v240 quad_perm:[2,3,0,1] row_mask:0xf bank_mask:0xf
	s_nop 1
	v_add_f32_dpp v240, v240, v240 row_half_mirror row_mask:0xf bank_mask:0xf
	s_nop 1
	v_add_f32_dpp v240, v240, v240 row_mirror row_mask:0xf bank_mask:0xf
	s_nop 1
	v_readlane_b32 s0, v240, 0
	v_readlane_b32 s1, v240, 16
	v_readlane_b32 s4, v240, 32
	v_readlane_b32 s5, v240, 48
	v_mov_b32_e32 v249, 0x358637bd
	s_nop 1
	v_mov_b32_e32 v240, s0
	v_add_f32_e32 v240, s1, v240
	v_add_f32_e32 v240, s4, v240
	v_add_f32_e32 v240, s5, v240
	v_fmamk_f32 v240, v240, 0x3a000000, v249
	s_mov_b32 s0, 0xf800000
	v_mul_f32_e32 v241, 0x4f800000, v240
	v_cmp_gt_f32_e32 vcc, s0, v240
	s_nop 1
	v_cndmask_b32_e32 v240, v240, v241, vcc
	v_sqrt_f32_e32 v241, v240
	s_nop 0
	v_add_u32_e32 v242, -1, v241
	v_fma_f32 v243, -v242, v241, v240
	v_cmp_ge_f32_e64 s[0:1], 0, v243
	v_add_u32_e32 v243, 1, v241
	s_nop 0
	v_cndmask_b32_e64 v242, v241, v242, s[0:1]
	v_fma_f32 v241, -v243, v241, v240
	v_cmp_lt_f32_e64 s[0:1], 0, v241
	s_nop 1
	v_cndmask_b32_e64 v241, v242, v243, s[0:1]
	v_mul_f32_e32 v242, 0x37800000, v241
	v_cndmask_b32_e32 v241, v241, v242, vcc
	v_cmp_class_f32_e32 vcc, v240, v248
	s_nop 1
	v_cndmask_b32_e32 v240, v241, v240, vcc
	v_div_scale_f32 v241, s[0:1], v240, v240, 1.0
	v_rcp_f32_e32 v242, v241
	s_nop 0
	v_fma_f32 v243, -v241, v242, 1.0
	v_fmac_f32_e32 v242, v243, v242
	v_div_scale_f32 v243, vcc, 1.0, v240, 1.0
	v_mul_f32_e32 v244, v243, v242
	v_fma_f32 v247, -v241, v244, v243
	v_fmac_f32_e32 v244, v247, v242
	v_fma_f32 v241, -v241, v244, v243
	s_nop 1
	v_div_fmas_f32 v241, v241, v242, v244
	v_div_fixup_f32 v246, v241, v240, 1.0
	v_pk_mul_f32 v[136:137], v[136:137], v[246:247] op_sel_hi:[1,0]
	v_pk_mul_f32 v[138:139], v[138:139], v[246:247] op_sel_hi:[1,0]
	v_pk_mul_f32 v[140:141], v[140:141], v[246:247] op_sel_hi:[1,0]
	v_pk_mul_f32 v[142:143], v[142:143], v[246:247] op_sel_hi:[1,0]
	v_pk_mul_f32 v[144:145], v[144:145], v[246:247] op_sel_hi:[1,0]
	v_pk_mul_f32 v[146:147], v[146:147], v[246:247] op_sel_hi:[1,0]
	v_pk_mul_f32 v[148:149], v[148:149], v[246:247] op_sel_hi:[1,0]
	v_pk_mul_f32 v[150:151], v[150:151], v[246:247] op_sel_hi:[1,0]
	v_pk_mul_f32 v[152:153], v[152:153], v[246:247] op_sel_hi:[1,0]
	v_pk_mul_f32 v[154:155], v[154:155], v[246:247] op_sel_hi:[1,0]
	v_pk_mul_f32 v[156:157], v[156:157], v[246:247] op_sel_hi:[1,0]
	v_pk_mul_f32 v[158:159], v[158:159], v[246:247] op_sel_hi:[1,0]
	v_pk_mul_f32 v[160:161], v[160:161], v[246:247] op_sel_hi:[1,0]
	v_pk_mul_f32 v[162:163], v[162:163], v[246:247] op_sel_hi:[1,0]
	v_pk_mul_f32 v[164:165], v[164:165], v[246:247] op_sel_hi:[1,0]
	v_pk_mul_f32 v[166:167], v[166:167], v[246:247] op_sel_hi:[1,0]
	s_add_u32 s8, s10, 0x0
	s_addc_u32 s9, s11, 0
	v_pk_fma_f32 v[4:5], v[8:9], v[136:137], v[40:41]
	v_cvt_pk_bf16_f32 v232, v4, v5
	v_pk_fma_f32 v[4:5], v[10:11], v[138:139], v[42:43]
	v_cvt_pk_bf16_f32 v233, v4, v5
	v_pk_fma_f32 v[4:5], v[12:13], v[140:141], v[44:45]
	v_cvt_pk_bf16_f32 v234, v4, v5
	v_pk_fma_f32 v[4:5], v[14:15], v[142:143], v[46:47]
	v_cvt_pk_bf16_f32 v235, v4, v5
	global_store_dwordx4 v1, v[232:235], s[8:9] offset:0
	v_pk_fma_f32 v[4:5], v[16:17], v[144:145], v[48:49]
	v_cvt_pk_bf16_f32 v236, v4, v5
	v_pk_fma_f32 v[4:5], v[18:19], v[146:147], v[50:51]
	v_cvt_pk_bf16_f32 v237, v4, v5
	v_pk_fma_f32 v[4:5], v[20:21], v[148:149], v[52:53]
	v_cvt_pk_bf16_f32 v238, v4, v5
	v_pk_fma_f32 v[4:5], v[22:23], v[150:151], v[54:55]
	v_cvt_pk_bf16_f32 v239, v4, v5
	global_store_dwordx4 v1, v[236:239], s[8:9] offset:1024
	v_pk_fma_f32 v[4:5], v[24:25], v[152:153], v[56:57]
	v_cvt_pk_bf16_f32 v232, v4, v5
	v_pk_fma_f32 v[4:5], v[26:27], v[154:155], v[58:59]
	v_cvt_pk_bf16_f32 v233, v4, v5
	v_pk_fma_f32 v[4:5], v[28:29], v[156:157], v[60:61]
	v_cvt_pk_bf16_f32 v234, v4, v5
	v_pk_fma_f32 v[4:5], v[30:31], v[158:159], v[62:63]
	v_cvt_pk_bf16_f32 v235, v4, v5
	global_store_dwordx4 v1, v[232:235], s[8:9] offset:2048
	v_pk_fma_f32 v[4:5], v[32:33], v[160:161], v[64:65]
	v_cvt_pk_bf16_f32 v236, v4, v5
	v_pk_fma_f32 v[4:5], v[34:35], v[162:163], v[66:67]
	v_cvt_pk_bf16_f32 v237, v4, v5
	v_pk_fma_f32 v[4:5], v[36:37], v[164:165], v[68:69]
	v_cvt_pk_bf16_f32 v238, v4, v5
	v_pk_fma_f32 v[4:5], v[38:39], v[166:167], v[70:71]
	v_cvt_pk_bf16_f32 v239, v4, v5
	global_store_dwordx4 v1, v[236:239], s[8:9] offset:3072
	s_add_u32 s8, s22, 0x0
	s_addc_u32 s9, s23, 0
	v_pk_fma_f32 v[136:137], v[72:73], v[136:137], v[104:105]
	v_cvt_pk_bf16_f32 v232, v136, v137
	v_pk_fma_f32 v[138:139], v[74:75], v[138:139], v[106:107]
	v_cvt_pk_bf16_f32 v233, v138, v139
	v_pk_fma_f32 v[140:141], v[76:77], v[140:141], v[108:109]
	v_cvt_pk_bf16_f32 v234, v140, v141
	v_pk_fma_f32 v[142:143], v[78:79], v[142:143], v[110:111]
	v_cvt_pk_bf16_f32 v235, v142, v143
	global_store_dwordx4 v1, v[232:235], s[8:9] offset:0
	v_pk_fma_f32 v[144:145], v[80:81], v[144:145], v[112:113]
	v_cvt_pk_bf16_f32 v236, v144, v145
	v_pk_fma_f32 v[146:147], v[82:83], v[146:147], v[114:115]
	v_cvt_pk_bf16_f32 v237, v146, v147
	v_pk_fma_f32 v[148:149], v[84:85], v[148:149], v[116:117]
	v_cvt_pk_bf16_f32 v238, v148, v149
	v_pk_fma_f32 v[150:151], v[86:87], v[150:151], v[118:119]
	v_cvt_pk_bf16_f32 v239, v150, v151
	global_store_dwordx4 v1, v[236:239], s[8:9] offset:1024
	v_pk_fma_f32 v[152:153], v[88:89], v[152:153], v[120:121]
	v_cvt_pk_bf16_f32 v232, v152, v153
	v_pk_fma_f32 v[154:155], v[90:91], v[154:155], v[122:123]
	v_cvt_pk_bf16_f32 v233, v154, v155
	v_pk_fma_f32 v[156:157], v[92:93], v[156:157], v[124:125]
	v_cvt_pk_bf16_f32 v234, v156, v157
	v_pk_fma_f32 v[158:159], v[94:95], v[158:159], v[126:127]
	v_cvt_pk_bf16_f32 v235, v158, v159
	global_store_dwordx4 v1, v[232:235], s[8:9] offset:2048
	v_pk_fma_f32 v[160:161], v[96:97], v[160:161], v[128:129]
	v_cvt_pk_bf16_f32 v236, v160, v161
	v_pk_fma_f32 v[162:163], v[98:99], v[162:163], v[130:131]
	v_cvt_pk_bf16_f32 v237, v162, v163
	v_pk_fma_f32 v[164:165], v[100:101], v[164:165], v[132:133]
	v_cvt_pk_bf16_f32 v238, v164, v165
	v_pk_fma_f32 v[166:167], v[102:103], v[166:167], v[134:135]
	v_cvt_pk_bf16_f32 v239, v166, v167
	global_store_dwordx4 v1, v[236:239], s[8:9] offset:3072
	s_waitcnt vmcnt(20)
	v_cvt_f32_f16_e32 v136, v184
	v_cvt_f32_f16_sdwa v137, v184 dst_sel:DWORD dst_unused:UNUSED_PAD src0_sel:WORD_1
	v_cvt_f32_f16_e32 v138, v185
	v_cvt_f32_f16_sdwa v139, v185 dst_sel:DWORD dst_unused:UNUSED_PAD src0_sel:WORD_1
	v_cvt_f32_f16_e32 v140, v186
	v_cvt_f32_f16_sdwa v141, v186 dst_sel:DWORD dst_unused:UNUSED_PAD src0_sel:WORD_1
	v_cvt_f32_f16_e32 v142, v187
	v_cvt_f32_f16_sdwa v143, v187 dst_sel:DWORD dst_unused:UNUSED_PAD src0_sel:WORD_1
	v_cvt_f32_f16_e32 v144, v188
	v_cvt_f32_f16_sdwa v145, v188 dst_sel:DWORD dst_unused:UNUSED_PAD src0_sel:WORD_1
	v_cvt_f32_f16_e32 v146, v189
	v_cvt_f32_f16_sdwa v147, v189 dst_sel:DWORD dst_unused:UNUSED_PAD src0_sel:WORD_1
	v_cvt_f32_f16_e32 v148, v190
	v_cvt_f32_f16_sdwa v149, v190 dst_sel:DWORD dst_unused:UNUSED_PAD src0_sel:WORD_1
	v_cvt_f32_f16_e32 v150, v191
	v_cvt_f32_f16_sdwa v151, v191 dst_sel:DWORD dst_unused:UNUSED_PAD src0_sel:WORD_1
	v_cvt_f32_f16_e32 v152, v192
	v_cvt_f32_f16_sdwa v153, v192 dst_sel:DWORD dst_unused:UNUSED_PAD src0_sel:WORD_1
	v_cvt_f32_f16_e32 v154, v193
	v_cvt_f32_f16_sdwa v155, v193 dst_sel:DWORD dst_unused:UNUSED_PAD src0_sel:WORD_1
	v_cvt_f32_f16_e32 v156, v194
	v_cvt_f32_f16_sdwa v157, v194 dst_sel:DWORD dst_unused:UNUSED_PAD src0_sel:WORD_1
	v_cvt_f32_f16_e32 v158, v195
	v_cvt_f32_f16_sdwa v159, v195 dst_sel:DWORD dst_unused:UNUSED_PAD src0_sel:WORD_1
	v_cvt_f32_f16_e32 v160, v196
	v_cvt_f32_f16_sdwa v161, v196 dst_sel:DWORD dst_unused:UNUSED_PAD src0_sel:WORD_1
	v_cvt_f32_f16_e32 v162, v197
	v_cvt_f32_f16_sdwa v163, v197 dst_sel:DWORD dst_unused:UNUSED_PAD src0_sel:WORD_1
	v_cvt_f32_f16_e32 v164, v198
	v_cvt_f32_f16_sdwa v165, v198 dst_sel:DWORD dst_unused:UNUSED_PAD src0_sel:WORD_1
	v_cvt_f32_f16_e32 v166, v199
	v_cvt_f32_f16_sdwa v167, v199 dst_sel:DWORD dst_unused:UNUSED_PAD src0_sel:WORD_1
	s_add_u32 s8, s6, 0xa0000
	s_addc_u32 s9, s7, 0
	global_load_dwordx4 v[184:187], v1, s[8:9] offset:0 nt
	global_load_dwordx4 v[188:191], v1, s[8:9] offset:1024 nt
	global_load_dwordx4 v[192:195], v1, s[8:9] offset:2048 nt
	global_load_dwordx4 v[196:199], v1, s[8:9] offset:3072 nt
	v_pk_mul_f32 v[232:233], v[136:137], v[136:137]
	v_pk_mul_f32 v[234:235], v[138:139], v[138:139]
	v_pk_mul_f32 v[236:237], v[140:141], v[140:141]
	v_pk_mul_f32 v[238:239], v[142:143], v[142:143]
	v_pk_fma_f32 v[232:233], v[144:145], v[144:145], v[232:233]
	v_pk_fma_f32 v[234:235], v[146:147], v[146:147], v[234:235]
	v_pk_fma_f32 v[236:237], v[148:149], v[148:149], v[236:237]
	v_pk_fma_f32 v[238:239], v[150:151], v[150:151], v[238:239]
	v_pk_fma_f32 v[232:233], v[152:153], v[152:153], v[232:233]
	v_pk_fma_f32 v[234:235], v[154:155], v[154:155], v[234:235]
	v_pk_fma_f32 v[236:237], v[156:157], v[156:157], v[236:237]
	v_pk_fma_f32 v[238:239], v[158:159], v[158:159], v[238:239]
	v_pk_fma_f32 v[232:233], v[160:161], v[160:161], v[232:233]
	v_pk_fma_f32 v[234:235], v[162:163], v[162:163], v[234:235]
	v_pk_fma_f32 v[236:237], v[164:165], v[164:165], v[236:237]
	v_pk_fma_f32 v[238:239], v[166:167], v[166:167], v[238:239]
	v_pk_add_f32 v[232:233], v[232:233], v[234:235]
	v_pk_add_f32 v[236:237], v[236:237], v[238:239]
	v_pk_add_f32 v[232:233], v[232:233], v[236:237]
	v_add_f32_e32 v240, v232, v233
	s_nop 1
	v_add_f32_dpp v240, v240, v240 quad_perm:[1,0,3,2] row_mask:0xf bank_mask:0xf
	s_nop 1
	v_add_f32_dpp v240, v240, v240 quad_perm:[2,3,0,1] row_mask:0xf bank_mask:0xf
	s_nop 1
	v_add_f32_dpp v240, v240, v240 row_half_mirror row_mask:0xf bank_mask:0xf
	s_nop 1
	v_add_f32_dpp v240, v240, v240 row_mirror row_mask:0xf bank_mask:0xf
	s_nop 1
	v_readlane_b32 s0, v240, 0
	v_readlane_b32 s1, v240, 16
	v_readlane_b32 s4, v240, 32
	v_readlane_b32 s5, v240, 48
	v_mov_b32_e32 v249, 0x358637bd
	s_nop 1
	v_mov_b32_e32 v240, s0
	v_add_f32_e32 v240, s1, v240
	v_add_f32_e32 v240, s4, v240
	v_add_f32_e32 v240, s5, v240
	v_fmamk_f32 v240, v240, 0x3a000000, v249
	s_mov_b32 s0, 0xf800000
	v_mul_f32_e32 v241, 0x4f800000, v240
	v_cmp_gt_f32_e32 vcc, s0, v240
	s_nop 1
	v_cndmask_b32_e32 v240, v240, v241, vcc
	v_sqrt_f32_e32 v241, v240
	s_nop 0
	v_add_u32_e32 v242, -1, v241
	v_fma_f32 v243, -v242, v241, v240
	v_cmp_ge_f32_e64 s[0:1], 0, v243
	v_add_u32_e32 v243, 1, v241
	s_nop 0
	v_cndmask_b32_e64 v242, v241, v242, s[0:1]
	v_fma_f32 v241, -v243, v241, v240
	v_cmp_lt_f32_e64 s[0:1], 0, v241
	s_nop 1
	v_cndmask_b32_e64 v241, v242, v243, s[0:1]
	v_mul_f32_e32 v242, 0x37800000, v241
	v_cndmask_b32_e32 v241, v241, v242, vcc
	v_cmp_class_f32_e32 vcc, v240, v248
	s_nop 1
	v_cndmask_b32_e32 v240, v241, v240, vcc
	v_div_scale_f32 v241, s[0:1], v240, v240, 1.0
	v_rcp_f32_e32 v242, v241
	s_nop 0
	v_fma_f32 v243, -v241, v242, 1.0
	v_fmac_f32_e32 v242, v243, v242
	v_div_scale_f32 v243, vcc, 1.0, v240, 1.0
	v_mul_f32_e32 v244, v243, v242
	v_fma_f32 v247, -v241, v244, v243
	v_fmac_f32_e32 v244, v247, v242
	v_fma_f32 v241, -v241, v244, v243
	s_nop 1
	v_div_fmas_f32 v241, v241, v242, v244
	v_div_fixup_f32 v246, v241, v240, 1.0
	v_pk_mul_f32 v[136:137], v[136:137], v[246:247] op_sel_hi:[1,0]
	v_pk_mul_f32 v[138:139], v[138:139], v[246:247] op_sel_hi:[1,0]
	v_pk_mul_f32 v[140:141], v[140:141], v[246:247] op_sel_hi:[1,0]
	v_pk_mul_f32 v[142:143], v[142:143], v[246:247] op_sel_hi:[1,0]
	v_pk_mul_f32 v[144:145], v[144:145], v[246:247] op_sel_hi:[1,0]
	v_pk_mul_f32 v[146:147], v[146:147], v[246:247] op_sel_hi:[1,0]
	v_pk_mul_f32 v[148:149], v[148:149], v[246:247] op_sel_hi:[1,0]
	v_pk_mul_f32 v[150:151], v[150:151], v[246:247] op_sel_hi:[1,0]
	v_pk_mul_f32 v[152:153], v[152:153], v[246:247] op_sel_hi:[1,0]
	v_pk_mul_f32 v[154:155], v[154:155], v[246:247] op_sel_hi:[1,0]
	v_pk_mul_f32 v[156:157], v[156:157], v[246:247] op_sel_hi:[1,0]
	v_pk_mul_f32 v[158:159], v[158:159], v[246:247] op_sel_hi:[1,0]
	v_pk_mul_f32 v[160:161], v[160:161], v[246:247] op_sel_hi:[1,0]
	v_pk_mul_f32 v[162:163], v[162:163], v[246:247] op_sel_hi:[1,0]
	v_pk_mul_f32 v[164:165], v[164:165], v[246:247] op_sel_hi:[1,0]
	v_pk_mul_f32 v[166:167], v[166:167], v[246:247] op_sel_hi:[1,0]
	s_add_u32 s8, s10, 0x20000
	s_addc_u32 s9, s11, 0
	v_pk_fma_f32 v[4:5], v[8:9], v[136:137], v[40:41]
	v_cvt_pk_bf16_f32 v232, v4, v5
	v_pk_fma_f32 v[4:5], v[10:11], v[138:139], v[42:43]
	v_cvt_pk_bf16_f32 v233, v4, v5
	v_pk_fma_f32 v[4:5], v[12:13], v[140:141], v[44:45]
	v_cvt_pk_bf16_f32 v234, v4, v5
	v_pk_fma_f32 v[4:5], v[14:15], v[142:143], v[46:47]
	v_cvt_pk_bf16_f32 v235, v4, v5
	global_store_dwordx4 v1, v[232:235], s[8:9] offset:0
	v_pk_fma_f32 v[4:5], v[16:17], v[144:145], v[48:49]
	v_cvt_pk_bf16_f32 v236, v4, v5
	v_pk_fma_f32 v[4:5], v[18:19], v[146:147], v[50:51]
	v_cvt_pk_bf16_f32 v237, v4, v5
	v_pk_fma_f32 v[4:5], v[20:21], v[148:149], v[52:53]
	v_cvt_pk_bf16_f32 v238, v4, v5
	v_pk_fma_f32 v[4:5], v[22:23], v[150:151], v[54:55]
	v_cvt_pk_bf16_f32 v239, v4, v5
	global_store_dwordx4 v1, v[236:239], s[8:9] offset:1024
	v_pk_fma_f32 v[4:5], v[24:25], v[152:153], v[56:57]
	v_cvt_pk_bf16_f32 v232, v4, v5
	v_pk_fma_f32 v[4:5], v[26:27], v[154:155], v[58:59]
	v_cvt_pk_bf16_f32 v233, v4, v5
	v_pk_fma_f32 v[4:5], v[28:29], v[156:157], v[60:61]
	v_cvt_pk_bf16_f32 v234, v4, v5
	v_pk_fma_f32 v[4:5], v[30:31], v[158:159], v[62:63]
	v_cvt_pk_bf16_f32 v235, v4, v5
	global_store_dwordx4 v1, v[232:235], s[8:9] offset:2048
	v_pk_fma_f32 v[4:5], v[32:33], v[160:161], v[64:65]
	v_cvt_pk_bf16_f32 v236, v4, v5
	v_pk_fma_f32 v[4:5], v[34:35], v[162:163], v[66:67]
	v_cvt_pk_bf16_f32 v237, v4, v5
	v_pk_fma_f32 v[4:5], v[36:37], v[164:165], v[68:69]
	v_cvt_pk_bf16_f32 v238, v4, v5
	v_pk_fma_f32 v[4:5], v[38:39], v[166:167], v[70:71]
	v_cvt_pk_bf16_f32 v239, v4, v5
	global_store_dwordx4 v1, v[236:239], s[8:9] offset:3072
	s_add_u32 s8, s22, 0x20000
	s_addc_u32 s9, s23, 0
	v_pk_fma_f32 v[136:137], v[72:73], v[136:137], v[104:105]
	v_cvt_pk_bf16_f32 v232, v136, v137
	v_pk_fma_f32 v[138:139], v[74:75], v[138:139], v[106:107]
	v_cvt_pk_bf16_f32 v233, v138, v139
	v_pk_fma_f32 v[140:141], v[76:77], v[140:141], v[108:109]
	v_cvt_pk_bf16_f32 v234, v140, v141
	v_pk_fma_f32 v[142:143], v[78:79], v[142:143], v[110:111]
	v_cvt_pk_bf16_f32 v235, v142, v143
	global_store_dwordx4 v1, v[232:235], s[8:9] offset:0
	v_pk_fma_f32 v[144:145], v[80:81], v[144:145], v[112:113]
	v_cvt_pk_bf16_f32 v236, v144, v145
	v_pk_fma_f32 v[146:147], v[82:83], v[146:147], v[114:115]
	v_cvt_pk_bf16_f32 v237, v146, v147
	v_pk_fma_f32 v[148:149], v[84:85], v[148:149], v[116:117]
	v_cvt_pk_bf16_f32 v238, v148, v149
	v_pk_fma_f32 v[150:151], v[86:87], v[150:151], v[118:119]
	v_cvt_pk_bf16_f32 v239, v150, v151
	global_store_dwordx4 v1, v[236:239], s[8:9] offset:1024
	v_pk_fma_f32 v[152:153], v[88:89], v[152:153], v[120:121]
	v_cvt_pk_bf16_f32 v232, v152, v153
	v_pk_fma_f32 v[154:155], v[90:91], v[154:155], v[122:123]
	v_cvt_pk_bf16_f32 v233, v154, v155
	v_pk_fma_f32 v[156:157], v[92:93], v[156:157], v[124:125]
	v_cvt_pk_bf16_f32 v234, v156, v157
	v_pk_fma_f32 v[158:159], v[94:95], v[158:159], v[126:127]
	v_cvt_pk_bf16_f32 v235, v158, v159
	global_store_dwordx4 v1, v[232:235], s[8:9] offset:2048
	v_pk_fma_f32 v[160:161], v[96:97], v[160:161], v[128:129]
	v_cvt_pk_bf16_f32 v236, v160, v161
	v_pk_fma_f32 v[162:163], v[98:99], v[162:163], v[130:131]
	v_cvt_pk_bf16_f32 v237, v162, v163
	v_pk_fma_f32 v[164:165], v[100:101], v[164:165], v[132:133]
	v_cvt_pk_bf16_f32 v238, v164, v165
	v_pk_fma_f32 v[166:167], v[102:103], v[166:167], v[134:135]
	v_cvt_pk_bf16_f32 v239, v166, v167
	global_store_dwordx4 v1, v[236:239], s[8:9] offset:3072
	s_waitcnt vmcnt(28)
	v_cvt_f32_f16_e32 v136, v200
	v_cvt_f32_f16_sdwa v137, v200 dst_sel:DWORD dst_unused:UNUSED_PAD src0_sel:WORD_1
	v_cvt_f32_f16_e32 v138, v201
	v_cvt_f32_f16_sdwa v139, v201 dst_sel:DWORD dst_unused:UNUSED_PAD src0_sel:WORD_1
	v_cvt_f32_f16_e32 v140, v202
	v_cvt_f32_f16_sdwa v141, v202 dst_sel:DWORD dst_unused:UNUSED_PAD src0_sel:WORD_1
	v_cvt_f32_f16_e32 v142, v203
	v_cvt_f32_f16_sdwa v143, v203 dst_sel:DWORD dst_unused:UNUSED_PAD src0_sel:WORD_1
	v_cvt_f32_f16_e32 v144, v204
	v_cvt_f32_f16_sdwa v145, v204 dst_sel:DWORD dst_unused:UNUSED_PAD src0_sel:WORD_1
	v_cvt_f32_f16_e32 v146, v205
	v_cvt_f32_f16_sdwa v147, v205 dst_sel:DWORD dst_unused:UNUSED_PAD src0_sel:WORD_1
	v_cvt_f32_f16_e32 v148, v206
	v_cvt_f32_f16_sdwa v149, v206 dst_sel:DWORD dst_unused:UNUSED_PAD src0_sel:WORD_1
	v_cvt_f32_f16_e32 v150, v207
	v_cvt_f32_f16_sdwa v151, v207 dst_sel:DWORD dst_unused:UNUSED_PAD src0_sel:WORD_1
	v_cvt_f32_f16_e32 v152, v208
	v_cvt_f32_f16_sdwa v153, v208 dst_sel:DWORD dst_unused:UNUSED_PAD src0_sel:WORD_1
	v_cvt_f32_f16_e32 v154, v209
	v_cvt_f32_f16_sdwa v155, v209 dst_sel:DWORD dst_unused:UNUSED_PAD src0_sel:WORD_1
	v_cvt_f32_f16_e32 v156, v210
	v_cvt_f32_f16_sdwa v157, v210 dst_sel:DWORD dst_unused:UNUSED_PAD src0_sel:WORD_1
	v_cvt_f32_f16_e32 v158, v211
	v_cvt_f32_f16_sdwa v159, v211 dst_sel:DWORD dst_unused:UNUSED_PAD src0_sel:WORD_1
	v_cvt_f32_f16_e32 v160, v212
	v_cvt_f32_f16_sdwa v161, v212 dst_sel:DWORD dst_unused:UNUSED_PAD src0_sel:WORD_1
	v_cvt_f32_f16_e32 v162, v213
	v_cvt_f32_f16_sdwa v163, v213 dst_sel:DWORD dst_unused:UNUSED_PAD src0_sel:WORD_1
	v_cvt_f32_f16_e32 v164, v214
	v_cvt_f32_f16_sdwa v165, v214 dst_sel:DWORD dst_unused:UNUSED_PAD src0_sel:WORD_1
	v_cvt_f32_f16_e32 v166, v215
	v_cvt_f32_f16_sdwa v167, v215 dst_sel:DWORD dst_unused:UNUSED_PAD src0_sel:WORD_1
	s_add_u32 s8, s6, 0xc0000
	s_addc_u32 s9, s7, 0
	global_load_dwordx4 v[200:203], v1, s[8:9] offset:0 nt
	global_load_dwordx4 v[204:207], v1, s[8:9] offset:1024 nt
	global_load_dwordx4 v[208:211], v1, s[8:9] offset:2048 nt
	global_load_dwordx4 v[212:215], v1, s[8:9] offset:3072 nt
	v_pk_mul_f32 v[232:233], v[136:137], v[136:137]
	v_pk_mul_f32 v[234:235], v[138:139], v[138:139]
	v_pk_mul_f32 v[236:237], v[140:141], v[140:141]
	v_pk_mul_f32 v[238:239], v[142:143], v[142:143]
	v_pk_fma_f32 v[232:233], v[144:145], v[144:145], v[232:233]
	v_pk_fma_f32 v[234:235], v[146:147], v[146:147], v[234:235]
	v_pk_fma_f32 v[236:237], v[148:149], v[148:149], v[236:237]
	v_pk_fma_f32 v[238:239], v[150:151], v[150:151], v[238:239]
	v_pk_fma_f32 v[232:233], v[152:153], v[152:153], v[232:233]
	v_pk_fma_f32 v[234:235], v[154:155], v[154:155], v[234:235]
	v_pk_fma_f32 v[236:237], v[156:157], v[156:157], v[236:237]
	v_pk_fma_f32 v[238:239], v[158:159], v[158:159], v[238:239]
	v_pk_fma_f32 v[232:233], v[160:161], v[160:161], v[232:233]
	v_pk_fma_f32 v[234:235], v[162:163], v[162:163], v[234:235]
	v_pk_fma_f32 v[236:237], v[164:165], v[164:165], v[236:237]
	v_pk_fma_f32 v[238:239], v[166:167], v[166:167], v[238:239]
	v_pk_add_f32 v[232:233], v[232:233], v[234:235]
	v_pk_add_f32 v[236:237], v[236:237], v[238:239]
	v_pk_add_f32 v[232:233], v[232:233], v[236:237]
	v_add_f32_e32 v240, v232, v233
	s_nop 1
	v_add_f32_dpp v240, v240, v240 quad_perm:[1,0,3,2] row_mask:0xf bank_mask:0xf
	s_nop 1
	v_add_f32_dpp v240, v240, v240 quad_perm:[2,3,0,1] row_mask:0xf bank_mask:0xf
	s_nop 1
	v_add_f32_dpp v240, v240, v240 row_half_mirror row_mask:0xf bank_mask:0xf
	s_nop 1
	v_add_f32_dpp v240, v240, v240 row_mirror row_mask:0xf bank_mask:0xf
	s_nop 1
	v_readlane_b32 s0, v240, 0
	v_readlane_b32 s1, v240, 16
	v_readlane_b32 s4, v240, 32
	v_readlane_b32 s5, v240, 48
	v_mov_b32_e32 v249, 0x358637bd
	s_nop 1
	v_mov_b32_e32 v240, s0
	v_add_f32_e32 v240, s1, v240
	v_add_f32_e32 v240, s4, v240
	v_add_f32_e32 v240, s5, v240
	v_fmamk_f32 v240, v240, 0x3a000000, v249
	s_mov_b32 s0, 0xf800000
	v_mul_f32_e32 v241, 0x4f800000, v240
	v_cmp_gt_f32_e32 vcc, s0, v240
	s_nop 1
	v_cndmask_b32_e32 v240, v240, v241, vcc
	v_sqrt_f32_e32 v241, v240
	s_nop 0
	v_add_u32_e32 v242, -1, v241
	v_fma_f32 v243, -v242, v241, v240
	v_cmp_ge_f32_e64 s[0:1], 0, v243
	v_add_u32_e32 v243, 1, v241
	s_nop 0
	v_cndmask_b32_e64 v242, v241, v242, s[0:1]
	v_fma_f32 v241, -v243, v241, v240
	v_cmp_lt_f32_e64 s[0:1], 0, v241
	s_nop 1
	v_cndmask_b32_e64 v241, v242, v243, s[0:1]
	v_mul_f32_e32 v242, 0x37800000, v241
	v_cndmask_b32_e32 v241, v241, v242, vcc
	v_cmp_class_f32_e32 vcc, v240, v248
	s_nop 1
	v_cndmask_b32_e32 v240, v241, v240, vcc
	v_div_scale_f32 v241, s[0:1], v240, v240, 1.0
	v_rcp_f32_e32 v242, v241
	s_nop 0
	v_fma_f32 v243, -v241, v242, 1.0
	v_fmac_f32_e32 v242, v243, v242
	v_div_scale_f32 v243, vcc, 1.0, v240, 1.0
	v_mul_f32_e32 v244, v243, v242
	v_fma_f32 v247, -v241, v244, v243
	v_fmac_f32_e32 v244, v247, v242
	v_fma_f32 v241, -v241, v244, v243
	s_nop 1
	v_div_fmas_f32 v241, v241, v242, v244
	v_div_fixup_f32 v246, v241, v240, 1.0
	v_pk_mul_f32 v[136:137], v[136:137], v[246:247] op_sel_hi:[1,0]
	v_pk_mul_f32 v[138:139], v[138:139], v[246:247] op_sel_hi:[1,0]
	v_pk_mul_f32 v[140:141], v[140:141], v[246:247] op_sel_hi:[1,0]
	v_pk_mul_f32 v[142:143], v[142:143], v[246:247] op_sel_hi:[1,0]
	v_pk_mul_f32 v[144:145], v[144:145], v[246:247] op_sel_hi:[1,0]
	v_pk_mul_f32 v[146:147], v[146:147], v[246:247] op_sel_hi:[1,0]
	v_pk_mul_f32 v[148:149], v[148:149], v[246:247] op_sel_hi:[1,0]
	v_pk_mul_f32 v[150:151], v[150:151], v[246:247] op_sel_hi:[1,0]
	v_pk_mul_f32 v[152:153], v[152:153], v[246:247] op_sel_hi:[1,0]
	v_pk_mul_f32 v[154:155], v[154:155], v[246:247] op_sel_hi:[1,0]
	v_pk_mul_f32 v[156:157], v[156:157], v[246:247] op_sel_hi:[1,0]
	v_pk_mul_f32 v[158:159], v[158:159], v[246:247] op_sel_hi:[1,0]
	v_pk_mul_f32 v[160:161], v[160:161], v[246:247] op_sel_hi:[1,0]
	v_pk_mul_f32 v[162:163], v[162:163], v[246:247] op_sel_hi:[1,0]
	v_pk_mul_f32 v[164:165], v[164:165], v[246:247] op_sel_hi:[1,0]
	v_pk_mul_f32 v[166:167], v[166:167], v[246:247] op_sel_hi:[1,0]
	s_add_u32 s8, s10, 0x40000
	s_addc_u32 s9, s11, 0
	v_pk_fma_f32 v[4:5], v[8:9], v[136:137], v[40:41]
	v_cvt_pk_bf16_f32 v232, v4, v5
	v_pk_fma_f32 v[4:5], v[10:11], v[138:139], v[42:43]
	v_cvt_pk_bf16_f32 v233, v4, v5
	v_pk_fma_f32 v[4:5], v[12:13], v[140:141], v[44:45]
	v_cvt_pk_bf16_f32 v234, v4, v5
	v_pk_fma_f32 v[4:5], v[14:15], v[142:143], v[46:47]
	v_cvt_pk_bf16_f32 v235, v4, v5
	global_store_dwordx4 v1, v[232:235], s[8:9] offset:0
	v_pk_fma_f32 v[4:5], v[16:17], v[144:145], v[48:49]
	v_cvt_pk_bf16_f32 v236, v4, v5
	v_pk_fma_f32 v[4:5], v[18:19], v[146:147], v[50:51]
	v_cvt_pk_bf16_f32 v237, v4, v5
	v_pk_fma_f32 v[4:5], v[20:21], v[148:149], v[52:53]
	v_cvt_pk_bf16_f32 v238, v4, v5
	v_pk_fma_f32 v[4:5], v[22:23], v[150:151], v[54:55]
	v_cvt_pk_bf16_f32 v239, v4, v5
	global_store_dwordx4 v1, v[236:239], s[8:9] offset:1024
	v_pk_fma_f32 v[4:5], v[24:25], v[152:153], v[56:57]
	v_cvt_pk_bf16_f32 v232, v4, v5
	v_pk_fma_f32 v[4:5], v[26:27], v[154:155], v[58:59]
	v_cvt_pk_bf16_f32 v233, v4, v5
	v_pk_fma_f32 v[4:5], v[28:29], v[156:157], v[60:61]
	v_cvt_pk_bf16_f32 v234, v4, v5
	v_pk_fma_f32 v[4:5], v[30:31], v[158:159], v[62:63]
	v_cvt_pk_bf16_f32 v235, v4, v5
	global_store_dwordx4 v1, v[232:235], s[8:9] offset:2048
	v_pk_fma_f32 v[4:5], v[32:33], v[160:161], v[64:65]
	v_cvt_pk_bf16_f32 v236, v4, v5
	v_pk_fma_f32 v[4:5], v[34:35], v[162:163], v[66:67]
	v_cvt_pk_bf16_f32 v237, v4, v5
	v_pk_fma_f32 v[4:5], v[36:37], v[164:165], v[68:69]
	v_cvt_pk_bf16_f32 v238, v4, v5
	v_pk_fma_f32 v[4:5], v[38:39], v[166:167], v[70:71]
	v_cvt_pk_bf16_f32 v239, v4, v5
	global_store_dwordx4 v1, v[236:239], s[8:9] offset:3072
	s_add_u32 s8, s22, 0x40000
	s_addc_u32 s9, s23, 0
	v_pk_fma_f32 v[136:137], v[72:73], v[136:137], v[104:105]
	v_cvt_pk_bf16_f32 v232, v136, v137
	v_pk_fma_f32 v[138:139], v[74:75], v[138:139], v[106:107]
	v_cvt_pk_bf16_f32 v233, v138, v139
	v_pk_fma_f32 v[140:141], v[76:77], v[140:141], v[108:109]
	v_cvt_pk_bf16_f32 v234, v140, v141
	v_pk_fma_f32 v[142:143], v[78:79], v[142:143], v[110:111]
	v_cvt_pk_bf16_f32 v235, v142, v143
	global_store_dwordx4 v1, v[232:235], s[8:9] offset:0
	v_pk_fma_f32 v[144:145], v[80:81], v[144:145], v[112:113]
	v_cvt_pk_bf16_f32 v236, v144, v145
	v_pk_fma_f32 v[146:147], v[82:83], v[146:147], v[114:115]
	v_cvt_pk_bf16_f32 v237, v146, v147
	v_pk_fma_f32 v[148:149], v[84:85], v[148:149], v[116:117]
	v_cvt_pk_bf16_f32 v238, v148, v149
	v_pk_fma_f32 v[150:151], v[86:87], v[150:151], v[118:119]
	v_cvt_pk_bf16_f32 v239, v150, v151
	global_store_dwordx4 v1, v[236:239], s[8:9] offset:1024
	v_pk_fma_f32 v[152:153], v[88:89], v[152:153], v[120:121]
	v_cvt_pk_bf16_f32 v232, v152, v153
	v_pk_fma_f32 v[154:155], v[90:91], v[154:155], v[122:123]
	v_cvt_pk_bf16_f32 v233, v154, v155
	v_pk_fma_f32 v[156:157], v[92:93], v[156:157], v[124:125]
	v_cvt_pk_bf16_f32 v234, v156, v157
	v_pk_fma_f32 v[158:159], v[94:95], v[158:159], v[126:127]
	v_cvt_pk_bf16_f32 v235, v158, v159
	global_store_dwordx4 v1, v[232:235], s[8:9] offset:2048
	v_pk_fma_f32 v[160:161], v[96:97], v[160:161], v[128:129]
	v_cvt_pk_bf16_f32 v236, v160, v161
	v_pk_fma_f32 v[162:163], v[98:99], v[162:163], v[130:131]
	v_cvt_pk_bf16_f32 v237, v162, v163
	v_pk_fma_f32 v[164:165], v[100:101], v[164:165], v[132:133]
	v_cvt_pk_bf16_f32 v238, v164, v165
	v_pk_fma_f32 v[166:167], v[102:103], v[166:167], v[134:135]
	v_cvt_pk_bf16_f32 v239, v166, v167
	global_store_dwordx4 v1, v[236:239], s[8:9] offset:3072
	s_waitcnt vmcnt(36)
	v_cvt_f32_f16_e32 v136, v216
	v_cvt_f32_f16_sdwa v137, v216 dst_sel:DWORD dst_unused:UNUSED_PAD src0_sel:WORD_1
	v_cvt_f32_f16_e32 v138, v217
	v_cvt_f32_f16_sdwa v139, v217 dst_sel:DWORD dst_unused:UNUSED_PAD src0_sel:WORD_1
	v_cvt_f32_f16_e32 v140, v218
	v_cvt_f32_f16_sdwa v141, v218 dst_sel:DWORD dst_unused:UNUSED_PAD src0_sel:WORD_1
	v_cvt_f32_f16_e32 v142, v219
	v_cvt_f32_f16_sdwa v143, v219 dst_sel:DWORD dst_unused:UNUSED_PAD src0_sel:WORD_1
	v_cvt_f32_f16_e32 v144, v220
	v_cvt_f32_f16_sdwa v145, v220 dst_sel:DWORD dst_unused:UNUSED_PAD src0_sel:WORD_1
	v_cvt_f32_f16_e32 v146, v221
	v_cvt_f32_f16_sdwa v147, v221 dst_sel:DWORD dst_unused:UNUSED_PAD src0_sel:WORD_1
	v_cvt_f32_f16_e32 v148, v222
	v_cvt_f32_f16_sdwa v149, v222 dst_sel:DWORD dst_unused:UNUSED_PAD src0_sel:WORD_1
	v_cvt_f32_f16_e32 v150, v223
	v_cvt_f32_f16_sdwa v151, v223 dst_sel:DWORD dst_unused:UNUSED_PAD src0_sel:WORD_1
	v_cvt_f32_f16_e32 v152, v224
	v_cvt_f32_f16_sdwa v153, v224 dst_sel:DWORD dst_unused:UNUSED_PAD src0_sel:WORD_1
	v_cvt_f32_f16_e32 v154, v225
	v_cvt_f32_f16_sdwa v155, v225 dst_sel:DWORD dst_unused:UNUSED_PAD src0_sel:WORD_1
	v_cvt_f32_f16_e32 v156, v226
	v_cvt_f32_f16_sdwa v157, v226 dst_sel:DWORD dst_unused:UNUSED_PAD src0_sel:WORD_1
	v_cvt_f32_f16_e32 v158, v227
	v_cvt_f32_f16_sdwa v159, v227 dst_sel:DWORD dst_unused:UNUSED_PAD src0_sel:WORD_1
	v_cvt_f32_f16_e32 v160, v228
	v_cvt_f32_f16_sdwa v161, v228 dst_sel:DWORD dst_unused:UNUSED_PAD src0_sel:WORD_1
	v_cvt_f32_f16_e32 v162, v229
	v_cvt_f32_f16_sdwa v163, v229 dst_sel:DWORD dst_unused:UNUSED_PAD src0_sel:WORD_1
	v_cvt_f32_f16_e32 v164, v230
	v_cvt_f32_f16_sdwa v165, v230 dst_sel:DWORD dst_unused:UNUSED_PAD src0_sel:WORD_1
	v_cvt_f32_f16_e32 v166, v231
	v_cvt_f32_f16_sdwa v167, v231 dst_sel:DWORD dst_unused:UNUSED_PAD src0_sel:WORD_1
	s_add_u32 s8, s6, 0xe0000
	s_addc_u32 s9, s7, 0
	global_load_dwordx4 v[216:219], v1, s[8:9] offset:0 nt
	global_load_dwordx4 v[220:223], v1, s[8:9] offset:1024 nt
	global_load_dwordx4 v[224:227], v1, s[8:9] offset:2048 nt
	global_load_dwordx4 v[228:231], v1, s[8:9] offset:3072 nt
	v_pk_mul_f32 v[232:233], v[136:137], v[136:137]
	v_pk_mul_f32 v[234:235], v[138:139], v[138:139]
	v_pk_mul_f32 v[236:237], v[140:141], v[140:141]
	v_pk_mul_f32 v[238:239], v[142:143], v[142:143]
	v_pk_fma_f32 v[232:233], v[144:145], v[144:145], v[232:233]
	v_pk_fma_f32 v[234:235], v[146:147], v[146:147], v[234:235]
	v_pk_fma_f32 v[236:237], v[148:149], v[148:149], v[236:237]
	v_pk_fma_f32 v[238:239], v[150:151], v[150:151], v[238:239]
	v_pk_fma_f32 v[232:233], v[152:153], v[152:153], v[232:233]
	v_pk_fma_f32 v[234:235], v[154:155], v[154:155], v[234:235]
	v_pk_fma_f32 v[236:237], v[156:157], v[156:157], v[236:237]
	v_pk_fma_f32 v[238:239], v[158:159], v[158:159], v[238:239]
	v_pk_fma_f32 v[232:233], v[160:161], v[160:161], v[232:233]
	v_pk_fma_f32 v[234:235], v[162:163], v[162:163], v[234:235]
	v_pk_fma_f32 v[236:237], v[164:165], v[164:165], v[236:237]
	v_pk_fma_f32 v[238:239], v[166:167], v[166:167], v[238:239]
	v_pk_add_f32 v[232:233], v[232:233], v[234:235]
	v_pk_add_f32 v[236:237], v[236:237], v[238:239]
	v_pk_add_f32 v[232:233], v[232:233], v[236:237]
	v_add_f32_e32 v240, v232, v233
	s_nop 1
	v_add_f32_dpp v240, v240, v240 quad_perm:[1,0,3,2] row_mask:0xf bank_mask:0xf
	s_nop 1
	v_add_f32_dpp v240, v240, v240 quad_perm:[2,3,0,1] row_mask:0xf bank_mask:0xf
	s_nop 1
	v_add_f32_dpp v240, v240, v240 row_half_mirror row_mask:0xf bank_mask:0xf
	s_nop 1
	v_add_f32_dpp v240, v240, v240 row_mirror row_mask:0xf bank_mask:0xf
	s_nop 1
	v_readlane_b32 s0, v240, 0
	v_readlane_b32 s1, v240, 16
	v_readlane_b32 s4, v240, 32
	v_readlane_b32 s5, v240, 48
	v_mov_b32_e32 v249, 0x358637bd
	s_nop 1
	v_mov_b32_e32 v240, s0
	v_add_f32_e32 v240, s1, v240
	v_add_f32_e32 v240, s4, v240
	v_add_f32_e32 v240, s5, v240
	v_fmamk_f32 v240, v240, 0x3a000000, v249
	s_mov_b32 s0, 0xf800000
	v_mul_f32_e32 v241, 0x4f800000, v240
	v_cmp_gt_f32_e32 vcc, s0, v240
	s_nop 1
	v_cndmask_b32_e32 v240, v240, v241, vcc
	v_sqrt_f32_e32 v241, v240
	s_nop 0
	v_add_u32_e32 v242, -1, v241
	v_fma_f32 v243, -v242, v241, v240
	v_cmp_ge_f32_e64 s[0:1], 0, v243
	v_add_u32_e32 v243, 1, v241
	s_nop 0
	v_cndmask_b32_e64 v242, v241, v242, s[0:1]
	v_fma_f32 v241, -v243, v241, v240
	v_cmp_lt_f32_e64 s[0:1], 0, v241
	s_nop 1
	v_cndmask_b32_e64 v241, v242, v243, s[0:1]
	v_mul_f32_e32 v242, 0x37800000, v241
	v_cndmask_b32_e32 v241, v241, v242, vcc
	v_cmp_class_f32_e32 vcc, v240, v248
	s_nop 1
	v_cndmask_b32_e32 v240, v241, v240, vcc
	v_div_scale_f32 v241, s[0:1], v240, v240, 1.0
	v_rcp_f32_e32 v242, v241
	s_nop 0
	v_fma_f32 v243, -v241, v242, 1.0
	v_fmac_f32_e32 v242, v243, v242
	v_div_scale_f32 v243, vcc, 1.0, v240, 1.0
	v_mul_f32_e32 v244, v243, v242
	v_fma_f32 v247, -v241, v244, v243
	v_fmac_f32_e32 v244, v247, v242
	v_fma_f32 v241, -v241, v244, v243
	s_nop 1
	v_div_fmas_f32 v241, v241, v242, v244
	v_div_fixup_f32 v246, v241, v240, 1.0
	v_pk_mul_f32 v[136:137], v[136:137], v[246:247] op_sel_hi:[1,0]
	v_pk_mul_f32 v[138:139], v[138:139], v[246:247] op_sel_hi:[1,0]
	v_pk_mul_f32 v[140:141], v[140:141], v[246:247] op_sel_hi:[1,0]
	v_pk_mul_f32 v[142:143], v[142:143], v[246:247] op_sel_hi:[1,0]
	v_pk_mul_f32 v[144:145], v[144:145], v[246:247] op_sel_hi:[1,0]
	v_pk_mul_f32 v[146:147], v[146:147], v[246:247] op_sel_hi:[1,0]
	v_pk_mul_f32 v[148:149], v[148:149], v[246:247] op_sel_hi:[1,0]
	v_pk_mul_f32 v[150:151], v[150:151], v[246:247] op_sel_hi:[1,0]
	v_pk_mul_f32 v[152:153], v[152:153], v[246:247] op_sel_hi:[1,0]
	v_pk_mul_f32 v[154:155], v[154:155], v[246:247] op_sel_hi:[1,0]
	v_pk_mul_f32 v[156:157], v[156:157], v[246:247] op_sel_hi:[1,0]
	v_pk_mul_f32 v[158:159], v[158:159], v[246:247] op_sel_hi:[1,0]
	v_pk_mul_f32 v[160:161], v[160:161], v[246:247] op_sel_hi:[1,0]
	v_pk_mul_f32 v[162:163], v[162:163], v[246:247] op_sel_hi:[1,0]
	v_pk_mul_f32 v[164:165], v[164:165], v[246:247] op_sel_hi:[1,0]
	v_pk_mul_f32 v[166:167], v[166:167], v[246:247] op_sel_hi:[1,0]
	s_add_u32 s8, s10, 0x60000
	s_addc_u32 s9, s11, 0
	v_pk_fma_f32 v[4:5], v[8:9], v[136:137], v[40:41]
	v_cvt_pk_bf16_f32 v232, v4, v5
	v_pk_fma_f32 v[4:5], v[10:11], v[138:139], v[42:43]
	v_cvt_pk_bf16_f32 v233, v4, v5
	v_pk_fma_f32 v[4:5], v[12:13], v[140:141], v[44:45]
	v_cvt_pk_bf16_f32 v234, v4, v5
	v_pk_fma_f32 v[4:5], v[14:15], v[142:143], v[46:47]
	v_cvt_pk_bf16_f32 v235, v4, v5
	global_store_dwordx4 v1, v[232:235], s[8:9] offset:0
	v_pk_fma_f32 v[4:5], v[16:17], v[144:145], v[48:49]
	v_cvt_pk_bf16_f32 v236, v4, v5
	v_pk_fma_f32 v[4:5], v[18:19], v[146:147], v[50:51]
	v_cvt_pk_bf16_f32 v237, v4, v5
	v_pk_fma_f32 v[4:5], v[20:21], v[148:149], v[52:53]
	v_cvt_pk_bf16_f32 v238, v4, v5
	v_pk_fma_f32 v[4:5], v[22:23], v[150:151], v[54:55]
	v_cvt_pk_bf16_f32 v239, v4, v5
	global_store_dwordx4 v1, v[236:239], s[8:9] offset:1024
	v_pk_fma_f32 v[4:5], v[24:25], v[152:153], v[56:57]
	v_cvt_pk_bf16_f32 v232, v4, v5
	v_pk_fma_f32 v[4:5], v[26:27], v[154:155], v[58:59]
	v_cvt_pk_bf16_f32 v233, v4, v5
	v_pk_fma_f32 v[4:5], v[28:29], v[156:157], v[60:61]
	v_cvt_pk_bf16_f32 v234, v4, v5
	v_pk_fma_f32 v[4:5], v[30:31], v[158:159], v[62:63]
	v_cvt_pk_bf16_f32 v235, v4, v5
	global_store_dwordx4 v1, v[232:235], s[8:9] offset:2048
	v_pk_fma_f32 v[4:5], v[32:33], v[160:161], v[64:65]
	v_cvt_pk_bf16_f32 v236, v4, v5
	v_pk_fma_f32 v[4:5], v[34:35], v[162:163], v[66:67]
	v_cvt_pk_bf16_f32 v237, v4, v5
	v_pk_fma_f32 v[4:5], v[36:37], v[164:165], v[68:69]
	v_cvt_pk_bf16_f32 v238, v4, v5
	v_pk_fma_f32 v[4:5], v[38:39], v[166:167], v[70:71]
	v_cvt_pk_bf16_f32 v239, v4, v5
	global_store_dwordx4 v1, v[236:239], s[8:9] offset:3072
	s_add_u32 s8, s22, 0x60000
	s_addc_u32 s9, s23, 0
	v_pk_fma_f32 v[136:137], v[72:73], v[136:137], v[104:105]
	v_cvt_pk_bf16_f32 v232, v136, v137
	v_pk_fma_f32 v[138:139], v[74:75], v[138:139], v[106:107]
	v_cvt_pk_bf16_f32 v233, v138, v139
	v_pk_fma_f32 v[140:141], v[76:77], v[140:141], v[108:109]
	v_cvt_pk_bf16_f32 v234, v140, v141
	v_pk_fma_f32 v[142:143], v[78:79], v[142:143], v[110:111]
	v_cvt_pk_bf16_f32 v235, v142, v143
	global_store_dwordx4 v1, v[232:235], s[8:9] offset:0
	v_pk_fma_f32 v[144:145], v[80:81], v[144:145], v[112:113]
	v_cvt_pk_bf16_f32 v236, v144, v145
	v_pk_fma_f32 v[146:147], v[82:83], v[146:147], v[114:115]
	v_cvt_pk_bf16_f32 v237, v146, v147
	v_pk_fma_f32 v[148:149], v[84:85], v[148:149], v[116:117]
	v_cvt_pk_bf16_f32 v238, v148, v149
	v_pk_fma_f32 v[150:151], v[86:87], v[150:151], v[118:119]
	v_cvt_pk_bf16_f32 v239, v150, v151
	global_store_dwordx4 v1, v[236:239], s[8:9] offset:1024
	v_pk_fma_f32 v[152:153], v[88:89], v[152:153], v[120:121]
	v_cvt_pk_bf16_f32 v232, v152, v153
	v_pk_fma_f32 v[154:155], v[90:91], v[154:155], v[122:123]
	v_cvt_pk_bf16_f32 v233, v154, v155
	v_pk_fma_f32 v[156:157], v[92:93], v[156:157], v[124:125]
	v_cvt_pk_bf16_f32 v234, v156, v157
	v_pk_fma_f32 v[158:159], v[94:95], v[158:159], v[126:127]
	v_cvt_pk_bf16_f32 v235, v158, v159
	global_store_dwordx4 v1, v[232:235], s[8:9] offset:2048
	v_pk_fma_f32 v[160:161], v[96:97], v[160:161], v[128:129]
	v_cvt_pk_bf16_f32 v236, v160, v161
	v_pk_fma_f32 v[162:163], v[98:99], v[162:163], v[130:131]
	v_cvt_pk_bf16_f32 v237, v162, v163
	v_pk_fma_f32 v[164:165], v[100:101], v[164:165], v[132:133]
	v_cvt_pk_bf16_f32 v238, v164, v165
	v_pk_fma_f32 v[166:167], v[102:103], v[166:167], v[134:135]
	v_cvt_pk_bf16_f32 v239, v166, v167
	global_store_dwordx4 v1, v[236:239], s[8:9] offset:3072
	s_waitcnt vmcnt(44)
	v_cvt_f32_f16_e32 v136, v168
	v_cvt_f32_f16_sdwa v137, v168 dst_sel:DWORD dst_unused:UNUSED_PAD src0_sel:WORD_1
	v_cvt_f32_f16_e32 v138, v169
	v_cvt_f32_f16_sdwa v139, v169 dst_sel:DWORD dst_unused:UNUSED_PAD src0_sel:WORD_1
	v_cvt_f32_f16_e32 v140, v170
	v_cvt_f32_f16_sdwa v141, v170 dst_sel:DWORD dst_unused:UNUSED_PAD src0_sel:WORD_1
	v_cvt_f32_f16_e32 v142, v171
	v_cvt_f32_f16_sdwa v143, v171 dst_sel:DWORD dst_unused:UNUSED_PAD src0_sel:WORD_1
	v_cvt_f32_f16_e32 v144, v172
	v_cvt_f32_f16_sdwa v145, v172 dst_sel:DWORD dst_unused:UNUSED_PAD src0_sel:WORD_1
	v_cvt_f32_f16_e32 v146, v173
	v_cvt_f32_f16_sdwa v147, v173 dst_sel:DWORD dst_unused:UNUSED_PAD src0_sel:WORD_1
	v_cvt_f32_f16_e32 v148, v174
	v_cvt_f32_f16_sdwa v149, v174 dst_sel:DWORD dst_unused:UNUSED_PAD src0_sel:WORD_1
	v_cvt_f32_f16_e32 v150, v175
	v_cvt_f32_f16_sdwa v151, v175 dst_sel:DWORD dst_unused:UNUSED_PAD src0_sel:WORD_1
	v_cvt_f32_f16_e32 v152, v176
	v_cvt_f32_f16_sdwa v153, v176 dst_sel:DWORD dst_unused:UNUSED_PAD src0_sel:WORD_1
	v_cvt_f32_f16_e32 v154, v177
	v_cvt_f32_f16_sdwa v155, v177 dst_sel:DWORD dst_unused:UNUSED_PAD src0_sel:WORD_1
	v_cvt_f32_f16_e32 v156, v178
	v_cvt_f32_f16_sdwa v157, v178 dst_sel:DWORD dst_unused:UNUSED_PAD src0_sel:WORD_1
	v_cvt_f32_f16_e32 v158, v179
	v_cvt_f32_f16_sdwa v159, v179 dst_sel:DWORD dst_unused:UNUSED_PAD src0_sel:WORD_1
	v_cvt_f32_f16_e32 v160, v180
	v_cvt_f32_f16_sdwa v161, v180 dst_sel:DWORD dst_unused:UNUSED_PAD src0_sel:WORD_1
	v_cvt_f32_f16_e32 v162, v181
	v_cvt_f32_f16_sdwa v163, v181 dst_sel:DWORD dst_unused:UNUSED_PAD src0_sel:WORD_1
	v_cvt_f32_f16_e32 v164, v182
	v_cvt_f32_f16_sdwa v165, v182 dst_sel:DWORD dst_unused:UNUSED_PAD src0_sel:WORD_1
	v_cvt_f32_f16_e32 v166, v183
	v_cvt_f32_f16_sdwa v167, v183 dst_sel:DWORD dst_unused:UNUSED_PAD src0_sel:WORD_1
	v_pk_mul_f32 v[232:233], v[136:137], v[136:137]
	v_pk_mul_f32 v[234:235], v[138:139], v[138:139]
	v_pk_mul_f32 v[236:237], v[140:141], v[140:141]
	v_pk_mul_f32 v[238:239], v[142:143], v[142:143]
	v_pk_fma_f32 v[232:233], v[144:145], v[144:145], v[232:233]
	v_pk_fma_f32 v[234:235], v[146:147], v[146:147], v[234:235]
	v_pk_fma_f32 v[236:237], v[148:149], v[148:149], v[236:237]
	v_pk_fma_f32 v[238:239], v[150:151], v[150:151], v[238:239]
	v_pk_fma_f32 v[232:233], v[152:153], v[152:153], v[232:233]
	v_pk_fma_f32 v[234:235], v[154:155], v[154:155], v[234:235]
	v_pk_fma_f32 v[236:237], v[156:157], v[156:157], v[236:237]
	v_pk_fma_f32 v[238:239], v[158:159], v[158:159], v[238:239]
	v_pk_fma_f32 v[232:233], v[160:161], v[160:161], v[232:233]
	v_pk_fma_f32 v[234:235], v[162:163], v[162:163], v[234:235]
	v_pk_fma_f32 v[236:237], v[164:165], v[164:165], v[236:237]
	v_pk_fma_f32 v[238:239], v[166:167], v[166:167], v[238:239]
	v_pk_add_f32 v[232:233], v[232:233], v[234:235]
	v_pk_add_f32 v[236:237], v[236:237], v[238:239]
	v_pk_add_f32 v[232:233], v[232:233], v[236:237]
	v_add_f32_e32 v240, v232, v233
	s_nop 1
	v_add_f32_dpp v240, v240, v240 quad_perm:[1,0,3,2] row_mask:0xf bank_mask:0xf
	s_nop 1
	v_add_f32_dpp v240, v240, v240 quad_perm:[2,3,0,1] row_mask:0xf bank_mask:0xf
	s_nop 1
	v_add_f32_dpp v240, v240, v240 row_half_mirror row_mask:0xf bank_mask:0xf
	s_nop 1
	v_add_f32_dpp v240, v240, v240 row_mirror row_mask:0xf bank_mask:0xf
	s_nop 1
	v_readlane_b32 s0, v240, 0
	v_readlane_b32 s1, v240, 16
	v_readlane_b32 s4, v240, 32
	v_readlane_b32 s5, v240, 48
	v_mov_b32_e32 v249, 0x358637bd
	s_nop 1
	v_mov_b32_e32 v240, s0
	v_add_f32_e32 v240, s1, v240
	v_add_f32_e32 v240, s4, v240
	v_add_f32_e32 v240, s5, v240
	v_fmamk_f32 v240, v240, 0x3a000000, v249
	s_mov_b32 s0, 0xf800000
	v_mul_f32_e32 v241, 0x4f800000, v240
	v_cmp_gt_f32_e32 vcc, s0, v240
	s_nop 1
	v_cndmask_b32_e32 v240, v240, v241, vcc
	v_sqrt_f32_e32 v241, v240
	s_nop 0
	v_add_u32_e32 v242, -1, v241
	v_fma_f32 v243, -v242, v241, v240
	v_cmp_ge_f32_e64 s[0:1], 0, v243
	v_add_u32_e32 v243, 1, v241
	s_nop 0
	v_cndmask_b32_e64 v242, v241, v242, s[0:1]
	v_fma_f32 v241, -v243, v241, v240
	v_cmp_lt_f32_e64 s[0:1], 0, v241
	s_nop 1
	v_cndmask_b32_e64 v241, v242, v243, s[0:1]
	v_mul_f32_e32 v242, 0x37800000, v241
	v_cndmask_b32_e32 v241, v241, v242, vcc
	v_cmp_class_f32_e32 vcc, v240, v248
	s_nop 1
	v_cndmask_b32_e32 v240, v241, v240, vcc
	v_div_scale_f32 v241, s[0:1], v240, v240, 1.0
	v_rcp_f32_e32 v242, v241
	s_nop 0
	v_fma_f32 v243, -v241, v242, 1.0
	v_fmac_f32_e32 v242, v243, v242
	v_div_scale_f32 v243, vcc, 1.0, v240, 1.0
	v_mul_f32_e32 v244, v243, v242
	v_fma_f32 v247, -v241, v244, v243
	v_fmac_f32_e32 v244, v247, v242
	v_fma_f32 v241, -v241, v244, v243
	s_nop 1
	v_div_fmas_f32 v241, v241, v242, v244
	v_div_fixup_f32 v246, v241, v240, 1.0
	v_pk_mul_f32 v[136:137], v[136:137], v[246:247] op_sel_hi:[1,0]
	v_pk_mul_f32 v[138:139], v[138:139], v[246:247] op_sel_hi:[1,0]
	v_pk_mul_f32 v[140:141], v[140:141], v[246:247] op_sel_hi:[1,0]
	v_pk_mul_f32 v[142:143], v[142:143], v[246:247] op_sel_hi:[1,0]
	v_pk_mul_f32 v[144:145], v[144:145], v[246:247] op_sel_hi:[1,0]
	v_pk_mul_f32 v[146:147], v[146:147], v[246:247] op_sel_hi:[1,0]
	v_pk_mul_f32 v[148:149], v[148:149], v[246:247] op_sel_hi:[1,0]
	v_pk_mul_f32 v[150:151], v[150:151], v[246:247] op_sel_hi:[1,0]
	v_pk_mul_f32 v[152:153], v[152:153], v[246:247] op_sel_hi:[1,0]
	v_pk_mul_f32 v[154:155], v[154:155], v[246:247] op_sel_hi:[1,0]
	v_pk_mul_f32 v[156:157], v[156:157], v[246:247] op_sel_hi:[1,0]
	v_pk_mul_f32 v[158:159], v[158:159], v[246:247] op_sel_hi:[1,0]
	v_pk_mul_f32 v[160:161], v[160:161], v[246:247] op_sel_hi:[1,0]
	v_pk_mul_f32 v[162:163], v[162:163], v[246:247] op_sel_hi:[1,0]
	v_pk_mul_f32 v[164:165], v[164:165], v[246:247] op_sel_hi:[1,0]
	v_pk_mul_f32 v[166:167], v[166:167], v[246:247] op_sel_hi:[1,0]
	s_add_u32 s8, s10, 0x80000
	s_addc_u32 s9, s11, 0
	v_pk_fma_f32 v[4:5], v[8:9], v[136:137], v[40:41]
	v_cvt_pk_bf16_f32 v232, v4, v5
	v_pk_fma_f32 v[4:5], v[10:11], v[138:139], v[42:43]
	v_cvt_pk_bf16_f32 v233, v4, v5
	v_pk_fma_f32 v[4:5], v[12:13], v[140:141], v[44:45]
	v_cvt_pk_bf16_f32 v234, v4, v5
	v_pk_fma_f32 v[4:5], v[14:15], v[142:143], v[46:47]
	v_cvt_pk_bf16_f32 v235, v4, v5
	global_store_dwordx4 v1, v[232:235], s[8:9] offset:0
	v_pk_fma_f32 v[4:5], v[16:17], v[144:145], v[48:49]
	v_cvt_pk_bf16_f32 v236, v4, v5
	v_pk_fma_f32 v[4:5], v[18:19], v[146:147], v[50:51]
	v_cvt_pk_bf16_f32 v237, v4, v5
	v_pk_fma_f32 v[4:5], v[20:21], v[148:149], v[52:53]
	v_cvt_pk_bf16_f32 v238, v4, v5
	v_pk_fma_f32 v[4:5], v[22:23], v[150:151], v[54:55]
	v_cvt_pk_bf16_f32 v239, v4, v5
	global_store_dwordx4 v1, v[236:239], s[8:9] offset:1024
	v_pk_fma_f32 v[4:5], v[24:25], v[152:153], v[56:57]
	v_cvt_pk_bf16_f32 v232, v4, v5
	v_pk_fma_f32 v[4:5], v[26:27], v[154:155], v[58:59]
	v_cvt_pk_bf16_f32 v233, v4, v5
	v_pk_fma_f32 v[4:5], v[28:29], v[156:157], v[60:61]
	v_cvt_pk_bf16_f32 v234, v4, v5
	v_pk_fma_f32 v[4:5], v[30:31], v[158:159], v[62:63]
	v_cvt_pk_bf16_f32 v235, v4, v5
	global_store_dwordx4 v1, v[232:235], s[8:9] offset:2048
	v_pk_fma_f32 v[4:5], v[32:33], v[160:161], v[64:65]
	v_cvt_pk_bf16_f32 v236, v4, v5
	v_pk_fma_f32 v[4:5], v[34:35], v[162:163], v[66:67]
	v_cvt_pk_bf16_f32 v237, v4, v5
	v_pk_fma_f32 v[4:5], v[36:37], v[164:165], v[68:69]
	v_cvt_pk_bf16_f32 v238, v4, v5
	v_pk_fma_f32 v[4:5], v[38:39], v[166:167], v[70:71]
	v_cvt_pk_bf16_f32 v239, v4, v5
	global_store_dwordx4 v1, v[236:239], s[8:9] offset:3072
	s_add_u32 s8, s22, 0x80000
	s_addc_u32 s9, s23, 0
	v_pk_fma_f32 v[136:137], v[72:73], v[136:137], v[104:105]
	v_cvt_pk_bf16_f32 v232, v136, v137
	v_pk_fma_f32 v[138:139], v[74:75], v[138:139], v[106:107]
	v_cvt_pk_bf16_f32 v233, v138, v139
	v_pk_fma_f32 v[140:141], v[76:77], v[140:141], v[108:109]
	v_cvt_pk_bf16_f32 v234, v140, v141
	v_pk_fma_f32 v[142:143], v[78:79], v[142:143], v[110:111]
	v_cvt_pk_bf16_f32 v235, v142, v143
	global_store_dwordx4 v1, v[232:235], s[8:9] offset:0
	v_pk_fma_f32 v[144:145], v[80:81], v[144:145], v[112:113]
	v_cvt_pk_bf16_f32 v236, v144, v145
	v_pk_fma_f32 v[146:147], v[82:83], v[146:147], v[114:115]
	v_cvt_pk_bf16_f32 v237, v146, v147
	v_pk_fma_f32 v[148:149], v[84:85], v[148:149], v[116:117]
	v_cvt_pk_bf16_f32 v238, v148, v149
	v_pk_fma_f32 v[150:151], v[86:87], v[150:151], v[118:119]
	v_cvt_pk_bf16_f32 v239, v150, v151
	global_store_dwordx4 v1, v[236:239], s[8:9] offset:1024
	v_pk_fma_f32 v[152:153], v[88:89], v[152:153], v[120:121]
	v_cvt_pk_bf16_f32 v232, v152, v153
	v_pk_fma_f32 v[154:155], v[90:91], v[154:155], v[122:123]
	v_cvt_pk_bf16_f32 v233, v154, v155
	v_pk_fma_f32 v[156:157], v[92:93], v[156:157], v[124:125]
	v_cvt_pk_bf16_f32 v234, v156, v157
	v_pk_fma_f32 v[158:159], v[94:95], v[158:159], v[126:127]
	v_cvt_pk_bf16_f32 v235, v158, v159
	global_store_dwordx4 v1, v[232:235], s[8:9] offset:2048
	v_pk_fma_f32 v[160:161], v[96:97], v[160:161], v[128:129]
	v_cvt_pk_bf16_f32 v236, v160, v161
	v_pk_fma_f32 v[162:163], v[98:99], v[162:163], v[130:131]
	v_cvt_pk_bf16_f32 v237, v162, v163
	v_pk_fma_f32 v[164:165], v[100:101], v[164:165], v[132:133]
	v_cvt_pk_bf16_f32 v238, v164, v165
	v_pk_fma_f32 v[166:167], v[102:103], v[166:167], v[134:135]
	v_cvt_pk_bf16_f32 v239, v166, v167
	global_store_dwordx4 v1, v[236:239], s[8:9] offset:3072
	s_waitcnt vmcnt(40)
	v_cvt_f32_f16_e32 v136, v184
	v_cvt_f32_f16_sdwa v137, v184 dst_sel:DWORD dst_unused:UNUSED_PAD src0_sel:WORD_1
	v_cvt_f32_f16_e32 v138, v185
	v_cvt_f32_f16_sdwa v139, v185 dst_sel:DWORD dst_unused:UNUSED_PAD src0_sel:WORD_1
	v_cvt_f32_f16_e32 v140, v186
	v_cvt_f32_f16_sdwa v141, v186 dst_sel:DWORD dst_unused:UNUSED_PAD src0_sel:WORD_1
	v_cvt_f32_f16_e32 v142, v187
	v_cvt_f32_f16_sdwa v143, v187 dst_sel:DWORD dst_unused:UNUSED_PAD src0_sel:WORD_1
	v_cvt_f32_f16_e32 v144, v188
	v_cvt_f32_f16_sdwa v145, v188 dst_sel:DWORD dst_unused:UNUSED_PAD src0_sel:WORD_1
	v_cvt_f32_f16_e32 v146, v189
	v_cvt_f32_f16_sdwa v147, v189 dst_sel:DWORD dst_unused:UNUSED_PAD src0_sel:WORD_1
	v_cvt_f32_f16_e32 v148, v190
	v_cvt_f32_f16_sdwa v149, v190 dst_sel:DWORD dst_unused:UNUSED_PAD src0_sel:WORD_1
	v_cvt_f32_f16_e32 v150, v191
	v_cvt_f32_f16_sdwa v151, v191 dst_sel:DWORD dst_unused:UNUSED_PAD src0_sel:WORD_1
	v_cvt_f32_f16_e32 v152, v192
	v_cvt_f32_f16_sdwa v153, v192 dst_sel:DWORD dst_unused:UNUSED_PAD src0_sel:WORD_1
	v_cvt_f32_f16_e32 v154, v193
	v_cvt_f32_f16_sdwa v155, v193 dst_sel:DWORD dst_unused:UNUSED_PAD src0_sel:WORD_1
	v_cvt_f32_f16_e32 v156, v194
	v_cvt_f32_f16_sdwa v157, v194 dst_sel:DWORD dst_unused:UNUSED_PAD src0_sel:WORD_1
	v_cvt_f32_f16_e32 v158, v195
	v_cvt_f32_f16_sdwa v159, v195 dst_sel:DWORD dst_unused:UNUSED_PAD src0_sel:WORD_1
	v_cvt_f32_f16_e32 v160, v196
	v_cvt_f32_f16_sdwa v161, v196 dst_sel:DWORD dst_unused:UNUSED_PAD src0_sel:WORD_1
	v_cvt_f32_f16_e32 v162, v197
	v_cvt_f32_f16_sdwa v163, v197 dst_sel:DWORD dst_unused:UNUSED_PAD src0_sel:WORD_1
	v_cvt_f32_f16_e32 v164, v198
	v_cvt_f32_f16_sdwa v165, v198 dst_sel:DWORD dst_unused:UNUSED_PAD src0_sel:WORD_1
	v_cvt_f32_f16_e32 v166, v199
	v_cvt_f32_f16_sdwa v167, v199 dst_sel:DWORD dst_unused:UNUSED_PAD src0_sel:WORD_1
	v_pk_mul_f32 v[232:233], v[136:137], v[136:137]
	v_pk_mul_f32 v[234:235], v[138:139], v[138:139]
	v_pk_mul_f32 v[236:237], v[140:141], v[140:141]
	v_pk_mul_f32 v[238:239], v[142:143], v[142:143]
	v_pk_fma_f32 v[232:233], v[144:145], v[144:145], v[232:233]
	v_pk_fma_f32 v[234:235], v[146:147], v[146:147], v[234:235]
	v_pk_fma_f32 v[236:237], v[148:149], v[148:149], v[236:237]
	v_pk_fma_f32 v[238:239], v[150:151], v[150:151], v[238:239]
	v_pk_fma_f32 v[232:233], v[152:153], v[152:153], v[232:233]
	v_pk_fma_f32 v[234:235], v[154:155], v[154:155], v[234:235]
	v_pk_fma_f32 v[236:237], v[156:157], v[156:157], v[236:237]
	v_pk_fma_f32 v[238:239], v[158:159], v[158:159], v[238:239]
	v_pk_fma_f32 v[232:233], v[160:161], v[160:161], v[232:233]
	v_pk_fma_f32 v[234:235], v[162:163], v[162:163], v[234:235]
	v_pk_fma_f32 v[236:237], v[164:165], v[164:165], v[236:237]
	v_pk_fma_f32 v[238:239], v[166:167], v[166:167], v[238:239]
	v_pk_add_f32 v[232:233], v[232:233], v[234:235]
	v_pk_add_f32 v[236:237], v[236:237], v[238:239]
	v_pk_add_f32 v[232:233], v[232:233], v[236:237]
	v_add_f32_e32 v240, v232, v233
	s_nop 1
	v_add_f32_dpp v240, v240, v240 quad_perm:[1,0,3,2] row_mask:0xf bank_mask:0xf
	s_nop 1
	v_add_f32_dpp v240, v240, v240 quad_perm:[2,3,0,1] row_mask:0xf bank_mask:0xf
	s_nop 1
	v_add_f32_dpp v240, v240, v240 row_half_mirror row_mask:0xf bank_mask:0xf
	s_nop 1
	v_add_f32_dpp v240, v240, v240 row_mirror row_mask:0xf bank_mask:0xf
	s_nop 1
	v_readlane_b32 s0, v240, 0
	v_readlane_b32 s1, v240, 16
	v_readlane_b32 s4, v240, 32
	v_readlane_b32 s5, v240, 48
	v_mov_b32_e32 v249, 0x358637bd
	s_nop 1
	v_mov_b32_e32 v240, s0
	v_add_f32_e32 v240, s1, v240
	v_add_f32_e32 v240, s4, v240
	v_add_f32_e32 v240, s5, v240
	v_fmamk_f32 v240, v240, 0x3a000000, v249
	s_mov_b32 s0, 0xf800000
	v_mul_f32_e32 v241, 0x4f800000, v240
	v_cmp_gt_f32_e32 vcc, s0, v240
	s_nop 1
	v_cndmask_b32_e32 v240, v240, v241, vcc
	v_sqrt_f32_e32 v241, v240
	s_nop 0
	v_add_u32_e32 v242, -1, v241
	v_fma_f32 v243, -v242, v241, v240
	v_cmp_ge_f32_e64 s[0:1], 0, v243
	v_add_u32_e32 v243, 1, v241
	s_nop 0
	v_cndmask_b32_e64 v242, v241, v242, s[0:1]
	v_fma_f32 v241, -v243, v241, v240
	v_cmp_lt_f32_e64 s[0:1], 0, v241
	s_nop 1
	v_cndmask_b32_e64 v241, v242, v243, s[0:1]
	v_mul_f32_e32 v242, 0x37800000, v241
	v_cndmask_b32_e32 v241, v241, v242, vcc
	v_cmp_class_f32_e32 vcc, v240, v248
	s_nop 1
	v_cndmask_b32_e32 v240, v241, v240, vcc
	v_div_scale_f32 v241, s[0:1], v240, v240, 1.0
	v_rcp_f32_e32 v242, v241
	s_nop 0
	v_fma_f32 v243, -v241, v242, 1.0
	v_fmac_f32_e32 v242, v243, v242
	v_div_scale_f32 v243, vcc, 1.0, v240, 1.0
	v_mul_f32_e32 v244, v243, v242
	v_fma_f32 v247, -v241, v244, v243
	v_fmac_f32_e32 v244, v247, v242
	v_fma_f32 v241, -v241, v244, v243
	s_nop 1
	v_div_fmas_f32 v241, v241, v242, v244
	v_div_fixup_f32 v246, v241, v240, 1.0
	v_pk_mul_f32 v[136:137], v[136:137], v[246:247] op_sel_hi:[1,0]
	v_pk_mul_f32 v[138:139], v[138:139], v[246:247] op_sel_hi:[1,0]
	v_pk_mul_f32 v[140:141], v[140:141], v[246:247] op_sel_hi:[1,0]
	v_pk_mul_f32 v[142:143], v[142:143], v[246:247] op_sel_hi:[1,0]
	v_pk_mul_f32 v[144:145], v[144:145], v[246:247] op_sel_hi:[1,0]
	v_pk_mul_f32 v[146:147], v[146:147], v[246:247] op_sel_hi:[1,0]
	v_pk_mul_f32 v[148:149], v[148:149], v[246:247] op_sel_hi:[1,0]
	v_pk_mul_f32 v[150:151], v[150:151], v[246:247] op_sel_hi:[1,0]
	v_pk_mul_f32 v[152:153], v[152:153], v[246:247] op_sel_hi:[1,0]
	v_pk_mul_f32 v[154:155], v[154:155], v[246:247] op_sel_hi:[1,0]
	v_pk_mul_f32 v[156:157], v[156:157], v[246:247] op_sel_hi:[1,0]
	v_pk_mul_f32 v[158:159], v[158:159], v[246:247] op_sel_hi:[1,0]
	v_pk_mul_f32 v[160:161], v[160:161], v[246:247] op_sel_hi:[1,0]
	v_pk_mul_f32 v[162:163], v[162:163], v[246:247] op_sel_hi:[1,0]
	v_pk_mul_f32 v[164:165], v[164:165], v[246:247] op_sel_hi:[1,0]
	v_pk_mul_f32 v[166:167], v[166:167], v[246:247] op_sel_hi:[1,0]
	s_add_u32 s8, s10, 0xa0000
	s_addc_u32 s9, s11, 0
	v_pk_fma_f32 v[4:5], v[8:9], v[136:137], v[40:41]
	v_cvt_pk_bf16_f32 v232, v4, v5
	v_pk_fma_f32 v[4:5], v[10:11], v[138:139], v[42:43]
	v_cvt_pk_bf16_f32 v233, v4, v5
	v_pk_fma_f32 v[4:5], v[12:13], v[140:141], v[44:45]
	v_cvt_pk_bf16_f32 v234, v4, v5
	v_pk_fma_f32 v[4:5], v[14:15], v[142:143], v[46:47]
	v_cvt_pk_bf16_f32 v235, v4, v5
	global_store_dwordx4 v1, v[232:235], s[8:9] offset:0
	v_pk_fma_f32 v[4:5], v[16:17], v[144:145], v[48:49]
	v_cvt_pk_bf16_f32 v236, v4, v5
	v_pk_fma_f32 v[4:5], v[18:19], v[146:147], v[50:51]
	v_cvt_pk_bf16_f32 v237, v4, v5
	v_pk_fma_f32 v[4:5], v[20:21], v[148:149], v[52:53]
	v_cvt_pk_bf16_f32 v238, v4, v5
	v_pk_fma_f32 v[4:5], v[22:23], v[150:151], v[54:55]
	v_cvt_pk_bf16_f32 v239, v4, v5
	global_store_dwordx4 v1, v[236:239], s[8:9] offset:1024
	v_pk_fma_f32 v[4:5], v[24:25], v[152:153], v[56:57]
	v_cvt_pk_bf16_f32 v232, v4, v5
	v_pk_fma_f32 v[4:5], v[26:27], v[154:155], v[58:59]
	v_cvt_pk_bf16_f32 v233, v4, v5
	v_pk_fma_f32 v[4:5], v[28:29], v[156:157], v[60:61]
	v_cvt_pk_bf16_f32 v234, v4, v5
	v_pk_fma_f32 v[4:5], v[30:31], v[158:159], v[62:63]
	v_cvt_pk_bf16_f32 v235, v4, v5
	global_store_dwordx4 v1, v[232:235], s[8:9] offset:2048
	v_pk_fma_f32 v[4:5], v[32:33], v[160:161], v[64:65]
	v_cvt_pk_bf16_f32 v236, v4, v5
	v_pk_fma_f32 v[4:5], v[34:35], v[162:163], v[66:67]
	v_cvt_pk_bf16_f32 v237, v4, v5
	v_pk_fma_f32 v[4:5], v[36:37], v[164:165], v[68:69]
	v_cvt_pk_bf16_f32 v238, v4, v5
	v_pk_fma_f32 v[4:5], v[38:39], v[166:167], v[70:71]
	v_cvt_pk_bf16_f32 v239, v4, v5
	global_store_dwordx4 v1, v[236:239], s[8:9] offset:3072
	s_add_u32 s8, s22, 0xa0000
	s_addc_u32 s9, s23, 0
	v_pk_fma_f32 v[136:137], v[72:73], v[136:137], v[104:105]
	v_cvt_pk_bf16_f32 v232, v136, v137
	v_pk_fma_f32 v[138:139], v[74:75], v[138:139], v[106:107]
	v_cvt_pk_bf16_f32 v233, v138, v139
	v_pk_fma_f32 v[140:141], v[76:77], v[140:141], v[108:109]
	v_cvt_pk_bf16_f32 v234, v140, v141
	v_pk_fma_f32 v[142:143], v[78:79], v[142:143], v[110:111]
	v_cvt_pk_bf16_f32 v235, v142, v143
	global_store_dwordx4 v1, v[232:235], s[8:9] offset:0
	v_pk_fma_f32 v[144:145], v[80:81], v[144:145], v[112:113]
	v_cvt_pk_bf16_f32 v236, v144, v145
	v_pk_fma_f32 v[146:147], v[82:83], v[146:147], v[114:115]
	v_cvt_pk_bf16_f32 v237, v146, v147
	v_pk_fma_f32 v[148:149], v[84:85], v[148:149], v[116:117]
	v_cvt_pk_bf16_f32 v238, v148, v149
	v_pk_fma_f32 v[150:151], v[86:87], v[150:151], v[118:119]
	v_cvt_pk_bf16_f32 v239, v150, v151
	global_store_dwordx4 v1, v[236:239], s[8:9] offset:1024
	v_pk_fma_f32 v[152:153], v[88:89], v[152:153], v[120:121]
	v_cvt_pk_bf16_f32 v232, v152, v153
	v_pk_fma_f32 v[154:155], v[90:91], v[154:155], v[122:123]
	v_cvt_pk_bf16_f32 v233, v154, v155
	v_pk_fma_f32 v[156:157], v[92:93], v[156:157], v[124:125]
	v_cvt_pk_bf16_f32 v234, v156, v157
	v_pk_fma_f32 v[158:159], v[94:95], v[158:159], v[126:127]
	v_cvt_pk_bf16_f32 v235, v158, v159
	global_store_dwordx4 v1, v[232:235], s[8:9] offset:2048
	v_pk_fma_f32 v[160:161], v[96:97], v[160:161], v[128:129]
	v_cvt_pk_bf16_f32 v236, v160, v161
	v_pk_fma_f32 v[162:163], v[98:99], v[162:163], v[130:131]
	v_cvt_pk_bf16_f32 v237, v162, v163
	v_pk_fma_f32 v[164:165], v[100:101], v[164:165], v[132:133]
	v_cvt_pk_bf16_f32 v238, v164, v165
	v_pk_fma_f32 v[166:167], v[102:103], v[166:167], v[134:135]
	v_cvt_pk_bf16_f32 v239, v166, v167
	global_store_dwordx4 v1, v[236:239], s[8:9] offset:3072
	s_waitcnt vmcnt(36)
	v_cvt_f32_f16_e32 v136, v200
	v_cvt_f32_f16_sdwa v137, v200 dst_sel:DWORD dst_unused:UNUSED_PAD src0_sel:WORD_1
	v_cvt_f32_f16_e32 v138, v201
	v_cvt_f32_f16_sdwa v139, v201 dst_sel:DWORD dst_unused:UNUSED_PAD src0_sel:WORD_1
	v_cvt_f32_f16_e32 v140, v202
	v_cvt_f32_f16_sdwa v141, v202 dst_sel:DWORD dst_unused:UNUSED_PAD src0_sel:WORD_1
	v_cvt_f32_f16_e32 v142, v203
	v_cvt_f32_f16_sdwa v143, v203 dst_sel:DWORD dst_unused:UNUSED_PAD src0_sel:WORD_1
	v_cvt_f32_f16_e32 v144, v204
	v_cvt_f32_f16_sdwa v145, v204 dst_sel:DWORD dst_unused:UNUSED_PAD src0_sel:WORD_1
	v_cvt_f32_f16_e32 v146, v205
	v_cvt_f32_f16_sdwa v147, v205 dst_sel:DWORD dst_unused:UNUSED_PAD src0_sel:WORD_1
	v_cvt_f32_f16_e32 v148, v206
	v_cvt_f32_f16_sdwa v149, v206 dst_sel:DWORD dst_unused:UNUSED_PAD src0_sel:WORD_1
	v_cvt_f32_f16_e32 v150, v207
	v_cvt_f32_f16_sdwa v151, v207 dst_sel:DWORD dst_unused:UNUSED_PAD src0_sel:WORD_1
	v_cvt_f32_f16_e32 v152, v208
	v_cvt_f32_f16_sdwa v153, v208 dst_sel:DWORD dst_unused:UNUSED_PAD src0_sel:WORD_1
	v_cvt_f32_f16_e32 v154, v209
	v_cvt_f32_f16_sdwa v155, v209 dst_sel:DWORD dst_unused:UNUSED_PAD src0_sel:WORD_1
	v_cvt_f32_f16_e32 v156, v210
	v_cvt_f32_f16_sdwa v157, v210 dst_sel:DWORD dst_unused:UNUSED_PAD src0_sel:WORD_1
	v_cvt_f32_f16_e32 v158, v211
	v_cvt_f32_f16_sdwa v159, v211 dst_sel:DWORD dst_unused:UNUSED_PAD src0_sel:WORD_1
	v_cvt_f32_f16_e32 v160, v212
	v_cvt_f32_f16_sdwa v161, v212 dst_sel:DWORD dst_unused:UNUSED_PAD src0_sel:WORD_1
	v_cvt_f32_f16_e32 v162, v213
	v_cvt_f32_f16_sdwa v163, v213 dst_sel:DWORD dst_unused:UNUSED_PAD src0_sel:WORD_1
	v_cvt_f32_f16_e32 v164, v214
	v_cvt_f32_f16_sdwa v165, v214 dst_sel:DWORD dst_unused:UNUSED_PAD src0_sel:WORD_1
	v_cvt_f32_f16_e32 v166, v215
	v_cvt_f32_f16_sdwa v167, v215 dst_sel:DWORD dst_unused:UNUSED_PAD src0_sel:WORD_1
	v_pk_mul_f32 v[232:233], v[136:137], v[136:137]
	v_pk_mul_f32 v[234:235], v[138:139], v[138:139]
	v_pk_mul_f32 v[236:237], v[140:141], v[140:141]
	v_pk_mul_f32 v[238:239], v[142:143], v[142:143]
	v_pk_fma_f32 v[232:233], v[144:145], v[144:145], v[232:233]
	v_pk_fma_f32 v[234:235], v[146:147], v[146:147], v[234:235]
	v_pk_fma_f32 v[236:237], v[148:149], v[148:149], v[236:237]
	v_pk_fma_f32 v[238:239], v[150:151], v[150:151], v[238:239]
	v_pk_fma_f32 v[232:233], v[152:153], v[152:153], v[232:233]
	v_pk_fma_f32 v[234:235], v[154:155], v[154:155], v[234:235]
	v_pk_fma_f32 v[236:237], v[156:157], v[156:157], v[236:237]
	v_pk_fma_f32 v[238:239], v[158:159], v[158:159], v[238:239]
	v_pk_fma_f32 v[232:233], v[160:161], v[160:161], v[232:233]
	v_pk_fma_f32 v[234:235], v[162:163], v[162:163], v[234:235]
	v_pk_fma_f32 v[236:237], v[164:165], v[164:165], v[236:237]
	v_pk_fma_f32 v[238:239], v[166:167], v[166:167], v[238:239]
	v_pk_add_f32 v[232:233], v[232:233], v[234:235]
	v_pk_add_f32 v[236:237], v[236:237], v[238:239]
	v_pk_add_f32 v[232:233], v[232:233], v[236:237]
	v_add_f32_e32 v240, v232, v233
	s_nop 1
	v_add_f32_dpp v240, v240, v240 quad_perm:[1,0,3,2] row_mask:0xf bank_mask:0xf
	s_nop 1
	v_add_f32_dpp v240, v240, v240 quad_perm:[2,3,0,1] row_mask:0xf bank_mask:0xf
	s_nop 1
	v_add_f32_dpp v240, v240, v240 row_half_mirror row_mask:0xf bank_mask:0xf
	s_nop 1
	v_add_f32_dpp v240, v240, v240 row_mirror row_mask:0xf bank_mask:0xf
	s_nop 1
	v_readlane_b32 s0, v240, 0
	v_readlane_b32 s1, v240, 16
	v_readlane_b32 s4, v240, 32
	v_readlane_b32 s5, v240, 48
	v_mov_b32_e32 v249, 0x358637bd
	s_nop 1
	v_mov_b32_e32 v240, s0
	v_add_f32_e32 v240, s1, v240
	v_add_f32_e32 v240, s4, v240
	v_add_f32_e32 v240, s5, v240
	v_fmamk_f32 v240, v240, 0x3a000000, v249
	s_mov_b32 s0, 0xf800000
	v_mul_f32_e32 v241, 0x4f800000, v240
	v_cmp_gt_f32_e32 vcc, s0, v240
	s_nop 1
	v_cndmask_b32_e32 v240, v240, v241, vcc
	v_sqrt_f32_e32 v241, v240
	s_nop 0
	v_add_u32_e32 v242, -1, v241
	v_fma_f32 v243, -v242, v241, v240
	v_cmp_ge_f32_e64 s[0:1], 0, v243
	v_add_u32_e32 v243, 1, v241
	s_nop 0
	v_cndmask_b32_e64 v242, v241, v242, s[0:1]
	v_fma_f32 v241, -v243, v241, v240
	v_cmp_lt_f32_e64 s[0:1], 0, v241
	s_nop 1
	v_cndmask_b32_e64 v241, v242, v243, s[0:1]
	v_mul_f32_e32 v242, 0x37800000, v241
	v_cndmask_b32_e32 v241, v241, v242, vcc
	v_cmp_class_f32_e32 vcc, v240, v248
	s_nop 1
	v_cndmask_b32_e32 v240, v241, v240, vcc
	v_div_scale_f32 v241, s[0:1], v240, v240, 1.0
	v_rcp_f32_e32 v242, v241
	s_nop 0
	v_fma_f32 v243, -v241, v242, 1.0
	v_fmac_f32_e32 v242, v243, v242
	v_div_scale_f32 v243, vcc, 1.0, v240, 1.0
	v_mul_f32_e32 v244, v243, v242
	v_fma_f32 v247, -v241, v244, v243
	v_fmac_f32_e32 v244, v247, v242
	v_fma_f32 v241, -v241, v244, v243
	s_nop 1
	v_div_fmas_f32 v241, v241, v242, v244
	v_div_fixup_f32 v246, v241, v240, 1.0
	v_pk_mul_f32 v[136:137], v[136:137], v[246:247] op_sel_hi:[1,0]
	v_pk_mul_f32 v[138:139], v[138:139], v[246:247] op_sel_hi:[1,0]
	v_pk_mul_f32 v[140:141], v[140:141], v[246:247] op_sel_hi:[1,0]
	v_pk_mul_f32 v[142:143], v[142:143], v[246:247] op_sel_hi:[1,0]
	v_pk_mul_f32 v[144:145], v[144:145], v[246:247] op_sel_hi:[1,0]
	v_pk_mul_f32 v[146:147], v[146:147], v[246:247] op_sel_hi:[1,0]
	v_pk_mul_f32 v[148:149], v[148:149], v[246:247] op_sel_hi:[1,0]
	v_pk_mul_f32 v[150:151], v[150:151], v[246:247] op_sel_hi:[1,0]
	v_pk_mul_f32 v[152:153], v[152:153], v[246:247] op_sel_hi:[1,0]
	v_pk_mul_f32 v[154:155], v[154:155], v[246:247] op_sel_hi:[1,0]
	v_pk_mul_f32 v[156:157], v[156:157], v[246:247] op_sel_hi:[1,0]
	v_pk_mul_f32 v[158:159], v[158:159], v[246:247] op_sel_hi:[1,0]
	v_pk_mul_f32 v[160:161], v[160:161], v[246:247] op_sel_hi:[1,0]
	v_pk_mul_f32 v[162:163], v[162:163], v[246:247] op_sel_hi:[1,0]
	v_pk_mul_f32 v[164:165], v[164:165], v[246:247] op_sel_hi:[1,0]
	v_pk_mul_f32 v[166:167], v[166:167], v[246:247] op_sel_hi:[1,0]
	s_add_u32 s8, s10, 0xc0000
	s_addc_u32 s9, s11, 0
	v_pk_fma_f32 v[4:5], v[8:9], v[136:137], v[40:41]
	v_cvt_pk_bf16_f32 v232, v4, v5
	v_pk_fma_f32 v[4:5], v[10:11], v[138:139], v[42:43]
	v_cvt_pk_bf16_f32 v233, v4, v5
	v_pk_fma_f32 v[4:5], v[12:13], v[140:141], v[44:45]
	v_cvt_pk_bf16_f32 v234, v4, v5
	v_pk_fma_f32 v[4:5], v[14:15], v[142:143], v[46:47]
	v_cvt_pk_bf16_f32 v235, v4, v5
	global_store_dwordx4 v1, v[232:235], s[8:9] offset:0
	v_pk_fma_f32 v[4:5], v[16:17], v[144:145], v[48:49]
	v_cvt_pk_bf16_f32 v236, v4, v5
	v_pk_fma_f32 v[4:5], v[18:19], v[146:147], v[50:51]
	v_cvt_pk_bf16_f32 v237, v4, v5
	v_pk_fma_f32 v[4:5], v[20:21], v[148:149], v[52:53]
	v_cvt_pk_bf16_f32 v238, v4, v5
	v_pk_fma_f32 v[4:5], v[22:23], v[150:151], v[54:55]
	v_cvt_pk_bf16_f32 v239, v4, v5
	global_store_dwordx4 v1, v[236:239], s[8:9] offset:1024
	v_pk_fma_f32 v[4:5], v[24:25], v[152:153], v[56:57]
	v_cvt_pk_bf16_f32 v232, v4, v5
	v_pk_fma_f32 v[4:5], v[26:27], v[154:155], v[58:59]
	v_cvt_pk_bf16_f32 v233, v4, v5
	v_pk_fma_f32 v[4:5], v[28:29], v[156:157], v[60:61]
	v_cvt_pk_bf16_f32 v234, v4, v5
	v_pk_fma_f32 v[4:5], v[30:31], v[158:159], v[62:63]
	v_cvt_pk_bf16_f32 v235, v4, v5
	global_store_dwordx4 v1, v[232:235], s[8:9] offset:2048
	v_pk_fma_f32 v[4:5], v[32:33], v[160:161], v[64:65]
	v_cvt_pk_bf16_f32 v236, v4, v5
	v_pk_fma_f32 v[4:5], v[34:35], v[162:163], v[66:67]
	v_cvt_pk_bf16_f32 v237, v4, v5
	v_pk_fma_f32 v[4:5], v[36:37], v[164:165], v[68:69]
	v_cvt_pk_bf16_f32 v238, v4, v5
	v_pk_fma_f32 v[4:5], v[38:39], v[166:167], v[70:71]
	v_cvt_pk_bf16_f32 v239, v4, v5
	global_store_dwordx4 v1, v[236:239], s[8:9] offset:3072
	s_add_u32 s8, s22, 0xc0000
	s_addc_u32 s9, s23, 0
	v_pk_fma_f32 v[136:137], v[72:73], v[136:137], v[104:105]
	v_cvt_pk_bf16_f32 v232, v136, v137
	v_pk_fma_f32 v[138:139], v[74:75], v[138:139], v[106:107]
	v_cvt_pk_bf16_f32 v233, v138, v139
	v_pk_fma_f32 v[140:141], v[76:77], v[140:141], v[108:109]
	v_cvt_pk_bf16_f32 v234, v140, v141
	v_pk_fma_f32 v[142:143], v[78:79], v[142:143], v[110:111]
	v_cvt_pk_bf16_f32 v235, v142, v143
	global_store_dwordx4 v1, v[232:235], s[8:9] offset:0
	v_pk_fma_f32 v[144:145], v[80:81], v[144:145], v[112:113]
	v_cvt_pk_bf16_f32 v236, v144, v145
	v_pk_fma_f32 v[146:147], v[82:83], v[146:147], v[114:115]
	v_cvt_pk_bf16_f32 v237, v146, v147
	v_pk_fma_f32 v[148:149], v[84:85], v[148:149], v[116:117]
	v_cvt_pk_bf16_f32 v238, v148, v149
	v_pk_fma_f32 v[150:151], v[86:87], v[150:151], v[118:119]
	v_cvt_pk_bf16_f32 v239, v150, v151
	global_store_dwordx4 v1, v[236:239], s[8:9] offset:1024
	v_pk_fma_f32 v[152:153], v[88:89], v[152:153], v[120:121]
	v_cvt_pk_bf16_f32 v232, v152, v153
	v_pk_fma_f32 v[154:155], v[90:91], v[154:155], v[122:123]
	v_cvt_pk_bf16_f32 v233, v154, v155
	v_pk_fma_f32 v[156:157], v[92:93], v[156:157], v[124:125]
	v_cvt_pk_bf16_f32 v234, v156, v157
	v_pk_fma_f32 v[158:159], v[94:95], v[158:159], v[126:127]
	v_cvt_pk_bf16_f32 v235, v158, v159
	global_store_dwordx4 v1, v[232:235], s[8:9] offset:2048
	v_pk_fma_f32 v[160:161], v[96:97], v[160:161], v[128:129]
	v_cvt_pk_bf16_f32 v236, v160, v161
	v_pk_fma_f32 v[162:163], v[98:99], v[162:163], v[130:131]
	v_cvt_pk_bf16_f32 v237, v162, v163
	v_pk_fma_f32 v[164:165], v[100:101], v[164:165], v[132:133]
	v_cvt_pk_bf16_f32 v238, v164, v165
	v_pk_fma_f32 v[166:167], v[102:103], v[166:167], v[134:135]
	v_cvt_pk_bf16_f32 v239, v166, v167
	global_store_dwordx4 v1, v[236:239], s[8:9] offset:3072
	s_waitcnt vmcnt(32)
	v_cvt_f32_f16_e32 v136, v216
	v_cvt_f32_f16_sdwa v137, v216 dst_sel:DWORD dst_unused:UNUSED_PAD src0_sel:WORD_1
	v_cvt_f32_f16_e32 v138, v217
	v_cvt_f32_f16_sdwa v139, v217 dst_sel:DWORD dst_unused:UNUSED_PAD src0_sel:WORD_1
	v_cvt_f32_f16_e32 v140, v218
	v_cvt_f32_f16_sdwa v141, v218 dst_sel:DWORD dst_unused:UNUSED_PAD src0_sel:WORD_1
	v_cvt_f32_f16_e32 v142, v219
	v_cvt_f32_f16_sdwa v143, v219 dst_sel:DWORD dst_unused:UNUSED_PAD src0_sel:WORD_1
	v_cvt_f32_f16_e32 v144, v220
	v_cvt_f32_f16_sdwa v145, v220 dst_sel:DWORD dst_unused:UNUSED_PAD src0_sel:WORD_1
	v_cvt_f32_f16_e32 v146, v221
	v_cvt_f32_f16_sdwa v147, v221 dst_sel:DWORD dst_unused:UNUSED_PAD src0_sel:WORD_1
	v_cvt_f32_f16_e32 v148, v222
	v_cvt_f32_f16_sdwa v149, v222 dst_sel:DWORD dst_unused:UNUSED_PAD src0_sel:WORD_1
	v_cvt_f32_f16_e32 v150, v223
	v_cvt_f32_f16_sdwa v151, v223 dst_sel:DWORD dst_unused:UNUSED_PAD src0_sel:WORD_1
	v_cvt_f32_f16_e32 v152, v224
	v_cvt_f32_f16_sdwa v153, v224 dst_sel:DWORD dst_unused:UNUSED_PAD src0_sel:WORD_1
	v_cvt_f32_f16_e32 v154, v225
	v_cvt_f32_f16_sdwa v155, v225 dst_sel:DWORD dst_unused:UNUSED_PAD src0_sel:WORD_1
	v_cvt_f32_f16_e32 v156, v226
	v_cvt_f32_f16_sdwa v157, v226 dst_sel:DWORD dst_unused:UNUSED_PAD src0_sel:WORD_1
	v_cvt_f32_f16_e32 v158, v227
	v_cvt_f32_f16_sdwa v159, v227 dst_sel:DWORD dst_unused:UNUSED_PAD src0_sel:WORD_1
	v_cvt_f32_f16_e32 v160, v228
	v_cvt_f32_f16_sdwa v161, v228 dst_sel:DWORD dst_unused:UNUSED_PAD src0_sel:WORD_1
	v_cvt_f32_f16_e32 v162, v229
	v_cvt_f32_f16_sdwa v163, v229 dst_sel:DWORD dst_unused:UNUSED_PAD src0_sel:WORD_1
	v_cvt_f32_f16_e32 v164, v230
	v_cvt_f32_f16_sdwa v165, v230 dst_sel:DWORD dst_unused:UNUSED_PAD src0_sel:WORD_1
	v_cvt_f32_f16_e32 v166, v231
	v_cvt_f32_f16_sdwa v167, v231 dst_sel:DWORD dst_unused:UNUSED_PAD src0_sel:WORD_1
	v_pk_mul_f32 v[232:233], v[136:137], v[136:137]
	v_pk_mul_f32 v[234:235], v[138:139], v[138:139]
	v_pk_mul_f32 v[236:237], v[140:141], v[140:141]
	v_pk_mul_f32 v[238:239], v[142:143], v[142:143]
	v_pk_fma_f32 v[232:233], v[144:145], v[144:145], v[232:233]
	v_pk_fma_f32 v[234:235], v[146:147], v[146:147], v[234:235]
	v_pk_fma_f32 v[236:237], v[148:149], v[148:149], v[236:237]
	v_pk_fma_f32 v[238:239], v[150:151], v[150:151], v[238:239]
	v_pk_fma_f32 v[232:233], v[152:153], v[152:153], v[232:233]
	v_pk_fma_f32 v[234:235], v[154:155], v[154:155], v[234:235]
	v_pk_fma_f32 v[236:237], v[156:157], v[156:157], v[236:237]
	v_pk_fma_f32 v[238:239], v[158:159], v[158:159], v[238:239]
	v_pk_fma_f32 v[232:233], v[160:161], v[160:161], v[232:233]
	v_pk_fma_f32 v[234:235], v[162:163], v[162:163], v[234:235]
	v_pk_fma_f32 v[236:237], v[164:165], v[164:165], v[236:237]
	v_pk_fma_f32 v[238:239], v[166:167], v[166:167], v[238:239]
	v_pk_add_f32 v[232:233], v[232:233], v[234:235]
	v_pk_add_f32 v[236:237], v[236:237], v[238:239]
	v_pk_add_f32 v[232:233], v[232:233], v[236:237]
	v_add_f32_e32 v240, v232, v233
	s_nop 1
	v_add_f32_dpp v240, v240, v240 quad_perm:[1,0,3,2] row_mask:0xf bank_mask:0xf
	s_nop 1
	v_add_f32_dpp v240, v240, v240 quad_perm:[2,3,0,1] row_mask:0xf bank_mask:0xf
	s_nop 1
	v_add_f32_dpp v240, v240, v240 row_half_mirror row_mask:0xf bank_mask:0xf
	s_nop 1
	v_add_f32_dpp v240, v240, v240 row_mirror row_mask:0xf bank_mask:0xf
	s_nop 1
	v_readlane_b32 s0, v240, 0
	v_readlane_b32 s1, v240, 16
	v_readlane_b32 s4, v240, 32
	v_readlane_b32 s5, v240, 48
	v_mov_b32_e32 v249, 0x358637bd
	s_nop 1
	v_mov_b32_e32 v240, s0
	v_add_f32_e32 v240, s1, v240
	v_add_f32_e32 v240, s4, v240
	v_add_f32_e32 v240, s5, v240
	v_fmamk_f32 v240, v240, 0x3a000000, v249
	s_mov_b32 s0, 0xf800000
	v_mul_f32_e32 v241, 0x4f800000, v240
	v_cmp_gt_f32_e32 vcc, s0, v240
	s_nop 1
	v_cndmask_b32_e32 v240, v240, v241, vcc
	v_sqrt_f32_e32 v241, v240
	s_nop 0
	v_add_u32_e32 v242, -1, v241
	v_fma_f32 v243, -v242, v241, v240
	v_cmp_ge_f32_e64 s[0:1], 0, v243
	v_add_u32_e32 v243, 1, v241
	s_nop 0
	v_cndmask_b32_e64 v242, v241, v242, s[0:1]
	v_fma_f32 v241, -v243, v241, v240
	v_cmp_lt_f32_e64 s[0:1], 0, v241
	s_nop 1
	v_cndmask_b32_e64 v241, v242, v243, s[0:1]
	v_mul_f32_e32 v242, 0x37800000, v241
	v_cndmask_b32_e32 v241, v241, v242, vcc
	v_cmp_class_f32_e32 vcc, v240, v248
	s_nop 1
	v_cndmask_b32_e32 v240, v241, v240, vcc
	v_div_scale_f32 v241, s[0:1], v240, v240, 1.0
	v_rcp_f32_e32 v242, v241
	s_nop 0
	v_fma_f32 v243, -v241, v242, 1.0
	v_fmac_f32_e32 v242, v243, v242
	v_div_scale_f32 v243, vcc, 1.0, v240, 1.0
	v_mul_f32_e32 v244, v243, v242
	v_fma_f32 v247, -v241, v244, v243
	v_fmac_f32_e32 v244, v247, v242
	v_fma_f32 v241, -v241, v244, v243
	s_nop 1
	v_div_fmas_f32 v241, v241, v242, v244
	v_div_fixup_f32 v246, v241, v240, 1.0
	v_pk_mul_f32 v[136:137], v[136:137], v[246:247] op_sel_hi:[1,0]
	v_pk_mul_f32 v[138:139], v[138:139], v[246:247] op_sel_hi:[1,0]
	v_pk_mul_f32 v[140:141], v[140:141], v[246:247] op_sel_hi:[1,0]
	v_pk_mul_f32 v[142:143], v[142:143], v[246:247] op_sel_hi:[1,0]
	v_pk_mul_f32 v[144:145], v[144:145], v[246:247] op_sel_hi:[1,0]
	v_pk_mul_f32 v[146:147], v[146:147], v[246:247] op_sel_hi:[1,0]
	v_pk_mul_f32 v[148:149], v[148:149], v[246:247] op_sel_hi:[1,0]
	v_pk_mul_f32 v[150:151], v[150:151], v[246:247] op_sel_hi:[1,0]
	v_pk_mul_f32 v[152:153], v[152:153], v[246:247] op_sel_hi:[1,0]
	v_pk_mul_f32 v[154:155], v[154:155], v[246:247] op_sel_hi:[1,0]
	v_pk_mul_f32 v[156:157], v[156:157], v[246:247] op_sel_hi:[1,0]
	v_pk_mul_f32 v[158:159], v[158:159], v[246:247] op_sel_hi:[1,0]
	v_pk_mul_f32 v[160:161], v[160:161], v[246:247] op_sel_hi:[1,0]
	v_pk_mul_f32 v[162:163], v[162:163], v[246:247] op_sel_hi:[1,0]
	v_pk_mul_f32 v[164:165], v[164:165], v[246:247] op_sel_hi:[1,0]
	v_pk_mul_f32 v[166:167], v[166:167], v[246:247] op_sel_hi:[1,0]
	s_add_u32 s8, s10, 0xe0000
	s_addc_u32 s9, s11, 0
	v_pk_fma_f32 v[4:5], v[8:9], v[136:137], v[40:41]
	v_cvt_pk_bf16_f32 v232, v4, v5
	v_pk_fma_f32 v[4:5], v[10:11], v[138:139], v[42:43]
	v_cvt_pk_bf16_f32 v233, v4, v5
	v_pk_fma_f32 v[4:5], v[12:13], v[140:141], v[44:45]
	v_cvt_pk_bf16_f32 v234, v4, v5
	v_pk_fma_f32 v[4:5], v[14:15], v[142:143], v[46:47]
	v_cvt_pk_bf16_f32 v235, v4, v5
	global_store_dwordx4 v1, v[232:235], s[8:9] offset:0
	v_pk_fma_f32 v[4:5], v[16:17], v[144:145], v[48:49]
	v_cvt_pk_bf16_f32 v236, v4, v5
	v_pk_fma_f32 v[4:5], v[18:19], v[146:147], v[50:51]
	v_cvt_pk_bf16_f32 v237, v4, v5
	v_pk_fma_f32 v[4:5], v[20:21], v[148:149], v[52:53]
	v_cvt_pk_bf16_f32 v238, v4, v5
	v_pk_fma_f32 v[4:5], v[22:23], v[150:151], v[54:55]
	v_cvt_pk_bf16_f32 v239, v4, v5
	global_store_dwordx4 v1, v[236:239], s[8:9] offset:1024
	v_pk_fma_f32 v[4:5], v[24:25], v[152:153], v[56:57]
	v_cvt_pk_bf16_f32 v232, v4, v5
	v_pk_fma_f32 v[4:5], v[26:27], v[154:155], v[58:59]
	v_cvt_pk_bf16_f32 v233, v4, v5
	v_pk_fma_f32 v[4:5], v[28:29], v[156:157], v[60:61]
	v_cvt_pk_bf16_f32 v234, v4, v5
	v_pk_fma_f32 v[4:5], v[30:31], v[158:159], v[62:63]
	v_cvt_pk_bf16_f32 v235, v4, v5
	global_store_dwordx4 v1, v[232:235], s[8:9] offset:2048
	v_pk_fma_f32 v[4:5], v[32:33], v[160:161], v[64:65]
	v_cvt_pk_bf16_f32 v236, v4, v5
	v_pk_fma_f32 v[4:5], v[34:35], v[162:163], v[66:67]
	v_cvt_pk_bf16_f32 v237, v4, v5
	v_pk_fma_f32 v[4:5], v[36:37], v[164:165], v[68:69]
	v_cvt_pk_bf16_f32 v238, v4, v5
	v_pk_fma_f32 v[4:5], v[38:39], v[166:167], v[70:71]
	v_cvt_pk_bf16_f32 v239, v4, v5
	global_store_dwordx4 v1, v[236:239], s[8:9] offset:3072
	s_add_u32 s8, s22, 0xe0000
	s_addc_u32 s9, s23, 0
	v_pk_fma_f32 v[136:137], v[72:73], v[136:137], v[104:105]
	v_cvt_pk_bf16_f32 v232, v136, v137
	v_pk_fma_f32 v[138:139], v[74:75], v[138:139], v[106:107]
	v_cvt_pk_bf16_f32 v233, v138, v139
	v_pk_fma_f32 v[140:141], v[76:77], v[140:141], v[108:109]
	v_cvt_pk_bf16_f32 v234, v140, v141
	v_pk_fma_f32 v[142:143], v[78:79], v[142:143], v[110:111]
	v_cvt_pk_bf16_f32 v235, v142, v143
	global_store_dwordx4 v1, v[232:235], s[8:9] offset:0
	v_pk_fma_f32 v[144:145], v[80:81], v[144:145], v[112:113]
	v_cvt_pk_bf16_f32 v236, v144, v145
	v_pk_fma_f32 v[146:147], v[82:83], v[146:147], v[114:115]
	v_cvt_pk_bf16_f32 v237, v146, v147
	v_pk_fma_f32 v[148:149], v[84:85], v[148:149], v[116:117]
	v_cvt_pk_bf16_f32 v238, v148, v149
	v_pk_fma_f32 v[150:151], v[86:87], v[150:151], v[118:119]
	v_cvt_pk_bf16_f32 v239, v150, v151
	global_store_dwordx4 v1, v[236:239], s[8:9] offset:1024
	v_pk_fma_f32 v[152:153], v[88:89], v[152:153], v[120:121]
	v_cvt_pk_bf16_f32 v232, v152, v153
	v_pk_fma_f32 v[154:155], v[90:91], v[154:155], v[122:123]
	v_cvt_pk_bf16_f32 v233, v154, v155
	v_pk_fma_f32 v[156:157], v[92:93], v[156:157], v[124:125]
	v_cvt_pk_bf16_f32 v234, v156, v157
	v_pk_fma_f32 v[158:159], v[94:95], v[158:159], v[126:127]
	v_cvt_pk_bf16_f32 v235, v158, v159
	global_store_dwordx4 v1, v[232:235], s[8:9] offset:2048
	v_pk_fma_f32 v[160:161], v[96:97], v[160:161], v[128:129]
	v_cvt_pk_bf16_f32 v236, v160, v161
	v_pk_fma_f32 v[162:163], v[98:99], v[162:163], v[130:131]
	v_cvt_pk_bf16_f32 v237, v162, v163
	v_pk_fma_f32 v[164:165], v[100:101], v[164:165], v[132:133]
	v_cvt_pk_bf16_f32 v238, v164, v165
	v_pk_fma_f32 v[166:167], v[102:103], v[166:167], v[134:135]
	v_cvt_pk_bf16_f32 v239, v166, v167
	global_store_dwordx4 v1, v[236:239], s[8:9] offset:3072
	s_branch .LBB0_1447
.Lnorm_fb_2:
	s_mov_b64 s[6:7], s[88:89]
	v_mov_b32_e32 v1, v0
	s_mov_b32 s0, s72
	s_add_i32 s0, 0, 0x2416c
	v_mov_b32_e32 v2, s0
	s_add_i32 s0, 0, 0x24170
	ds_read_b32 v2, v2
	s_waitcnt vmcnt(30)
	v_mov_b32_e32 v3, s0
	ds_read_b32 v3, v3
	v_readfirstlane_b32 s0, v1
	s_ashr_i32 s1, s0, 6
	s_waitcnt lgkmcnt(1)
	v_readfirstlane_b32 s5, v2
	s_cmp_lt_i32 s5, 1
	s_waitcnt lgkmcnt(0)
	v_readfirstlane_b32 s10, v3
	s_cbranch_scc0 .LBB0_1438
	s_lshl_b32 s0, s72, 3
	s_add_i32 s0, s1, s0
	s_lshl_b32 s4, s38, 3
	s_movk_i32 s20, 0x4000
	s_cbranch_execz .LBB0_1439
	s_branch .LBB0_1440

.LBB0_2030:
	v_readlane_b32 s4, v250, 12
	s_cmp_lt_i32 s4, 17
	s_cselect_b64 s[0:1], -1, 0
	s_and_b64 s[2:3], s[0:1], s[2:3]
	s_andn2_b64 vcc, exec, s[2:3]
	v_readlane_b32 s5, v250, 13
	v_readlane_b32 s6, v250, 14
	v_readlane_b32 s7, v250, 15
	s_cbranch_vccnz .LBB0_2042
	v_and_b32_e32 v1, 63, v0
	v_lshlrev_b32_e32 v2, 5, v1
	v_add_u32_e32 v3, 0x1000, v2
	v_lshlrev_b32_e32 v1, 4, v1
	v_mov_b32_e32 v4, 0x2416c
	ds_read_b32 v5, v4
	ds_read_b32 v6, v4 offset:4
	v_readfirstlane_b32 s0, v0
	s_lshr_b32 s1, s0, 6
	s_waitcnt lgkmcnt(0)
	v_readfirstlane_b32 s4, v5
	v_readfirstlane_b32 s5, v6
	s_cmp_lt_i32 s4, 1
	s_cbranch_scc1 .Lnorm_fb_3
	s_add_i32 s4, s4, -1
	s_lshl_b32 s18, s4, 8
	s_lshl_b32 s19, s5, 3
	s_add_i32 s18, s18, s19
	s_add_i32 s18, s18, s1
	s_lshr_b32 s19, s4, 4
	s_lshl_b32 s20, s18, 12
	s_add_u32 s6, s88, 0x45c00000
	s_addc_u32 s7, s89, 0
	s_add_u32 s6, s6, s20
	s_addc_u32 s7, s7, 0
	s_add_u32 s10, s88, 0x13e00000
	s_addc_u32 s11, s89, 0
	s_add_u32 s10, s10, s20
	s_addc_u32 s11, s11, 0
	s_add_u32 s12, s44, 0x8000
	s_addc_u32 s13, s45, 0
	s_mul_i32 s21, s19, 0x12000
	s_add_u32 s14, s88, 0x14e000
	s_addc_u32 s15, s89, 0
	s_add_u32 s14, s14, s21
	s_addc_u32 s15, s15, 0
	s_add_u32 s16, s88, 0x150000
	s_addc_u32 s17, s89, 0
	s_add_u32 s16, s16, s21
	s_addc_u32 s17, s17, 0
	global_load_dwordx4 v[72:75], v2, s[12:13] offset:0
	global_load_dwordx4 v[76:79], v2, s[12:13] offset:16
	global_load_dwordx4 v[80:83], v2, s[12:13] offset:2048
	global_load_dwordx4 v[84:87], v2, s[12:13] offset:2064
	global_load_dwordx4 v[88:91], v3, s[12:13] offset:0
	global_load_dwordx4 v[92:95], v3, s[12:13] offset:16
	global_load_dwordx4 v[96:99], v3, s[12:13] offset:2048
	global_load_dwordx4 v[100:103], v3, s[12:13] offset:2064
	global_load_dwordx4 v[8:11], v2, s[16:17] offset:0
	global_load_dwordx4 v[12:15], v2, s[16:17] offset:16
	global_load_dwordx4 v[16:19], v2, s[16:17] offset:2048
	global_load_dwordx4 v[20:23], v2, s[16:17] offset:2064
	global_load_dwordx4 v[24:27], v3, s[16:17] offset:0
	global_load_dwordx4 v[28:31], v3, s[16:17] offset:16
	global_load_dwordx4 v[32:35], v3, s[16:17] offset:2048
	global_load_dwordx4 v[36:39], v3, s[16:17] offset:2064
	global_load_dwordx4 v[40:43], v2, s[14:15] offset:0
	global_load_dwordx4 v[44:47], v2, s[14:15] offset:16
	global_load_dwordx4 v[48:51], v2, s[14:15] offset:2048
	global_load_dwordx4 v[52:55], v2, s[14:15] offset:2064
	global_load_dwordx4 v[56:59], v3, s[14:15] offset:0
	global_load_dwordx4 v[60:63], v3, s[14:15] offset:16
	global_load_dwordx4 v[64:67], v3, s[14:15] offset:2048
	global_load_dwordx4 v[68:71], v3, s[14:15] offset:2064
	s_add_u32 s8, s6, 0x0
	s_addc_u32 s9, s7, 0
	global_load_dwordx4 v[104:107], v1, s[8:9] offset:0 nt
	global_load_dwordx4 v[108:111], v1, s[8:9] offset:1024 nt
	global_load_dwordx4 v[112:115], v1, s[8:9] offset:2048 nt
	global_load_dwordx4 v[116:119], v1, s[8:9] offset:3072 nt
	s_add_u32 s8, s6, 0x20000
	s_addc_u32 s9, s7, 0
	global_load_dwordx4 v[120:123], v1, s[8:9] offset:0 nt
	global_load_dwordx4 v[124:127], v1, s[8:9] offset:1024 nt
	global_load_dwordx4 v[128:131], v1, s[8:9] offset:2048 nt
	global_load_dwordx4 v[132:135], v1, s[8:9] offset:3072 nt
	s_add_u32 s8, s6, 0x40000
	s_addc_u32 s9, s7, 0
	global_load_dwordx4 v[136:139], v1, s[8:9] offset:0 nt
	global_load_dwordx4 v[140:143], v1, s[8:9] offset:1024 nt
	global_load_dwordx4 v[144:147], v1, s[8:9] offset:2048 nt
	global_load_dwordx4 v[148:151], v1, s[8:9] offset:3072 nt
	s_add_u32 s8, s6, 0x60000
	s_addc_u32 s9, s7, 0
	global_load_dwordx4 v[152:155], v1, s[8:9] offset:0 nt
	global_load_dwordx4 v[156:159], v1, s[8:9] offset:1024 nt
	global_load_dwordx4 v[160:163], v1, s[8:9] offset:2048 nt
	global_load_dwordx4 v[164:167], v1, s[8:9] offset:3072 nt
	s_add_u32 s8, s6, 0x80000
	s_addc_u32 s9, s7, 0
	global_load_dwordx4 v[168:171], v1, s[8:9] offset:0 nt
	global_load_dwordx4 v[172:175], v1, s[8:9] offset:1024 nt
	global_load_dwordx4 v[176:179], v1, s[8:9] offset:2048 nt
	global_load_dwordx4 v[180:183], v1, s[8:9] offset:3072 nt
	s_add_u32 s8, s6, 0xa0000
	s_addc_u32 s9, s7, 0
	global_load_dwordx4 v[184:187], v1, s[8:9] offset:0 nt
	global_load_dwordx4 v[188:191], v1, s[8:9] offset:1024 nt
	global_load_dwordx4 v[192:195], v1, s[8:9] offset:2048 nt
	global_load_dwordx4 v[196:199], v1, s[8:9] offset:3072 nt
	s_add_u32 s8, s6, 0xc0000
	s_addc_u32 s9, s7, 0
	global_load_dwordx4 v[200:203], v1, s[8:9] offset:0 nt
	global_load_dwordx4 v[204:207], v1, s[8:9] offset:1024 nt
	global_load_dwordx4 v[208:211], v1, s[8:9] offset:2048 nt
	global_load_dwordx4 v[212:215], v1, s[8:9] offset:3072 nt
	s_add_u32 s8, s6, 0xe0000
	s_addc_u32 s9, s7, 0
	global_load_dwordx4 v[216:219], v1, s[8:9] offset:0 nt
	global_load_dwordx4 v[220:223], v1, s[8:9] offset:1024 nt
	global_load_dwordx4 v[224:227], v1, s[8:9] offset:2048 nt
	global_load_dwordx4 v[228:231], v1, s[8:9] offset:3072 nt
	s_waitcnt vmcnt(32)
	v_pk_add_f32 v[8:9], v[8:9], 1.0 op_sel_hi:[1,0]
	v_pk_add_f32 v[10:11], v[10:11], 1.0 op_sel_hi:[1,0]
	v_pk_add_f32 v[12:13], v[12:13], 1.0 op_sel_hi:[1,0]
	v_pk_add_f32 v[14:15], v[14:15], 1.0 op_sel_hi:[1,0]
	v_pk_add_f32 v[16:17], v[16:17], 1.0 op_sel_hi:[1,0]
	v_pk_add_f32 v[18:19], v[18:19], 1.0 op_sel_hi:[1,0]
	v_pk_add_f32 v[20:21], v[20:21], 1.0 op_sel_hi:[1,0]
	v_pk_add_f32 v[22:23], v[22:23], 1.0 op_sel_hi:[1,0]
	v_pk_add_f32 v[24:25], v[24:25], 1.0 op_sel_hi:[1,0]
	v_pk_add_f32 v[26:27], v[26:27], 1.0 op_sel_hi:[1,0]
	v_pk_add_f32 v[28:29], v[28:29], 1.0 op_sel_hi:[1,0]
	v_pk_add_f32 v[30:31], v[30:31], 1.0 op_sel_hi:[1,0]
	v_pk_add_f32 v[32:33], v[32:33], 1.0 op_sel_hi:[1,0]
	v_pk_add_f32 v[34:35], v[34:35], 1.0 op_sel_hi:[1,0]
	v_pk_add_f32 v[36:37], v[36:37], 1.0 op_sel_hi:[1,0]
	v_pk_add_f32 v[38:39], v[38:39], 1.0 op_sel_hi:[1,0]
	v_pk_mul_f32 v[8:9], v[72:73], v[8:9]
	v_pk_mul_f32 v[10:11], v[74:75], v[10:11]
	v_pk_mul_f32 v[12:13], v[76:77], v[12:13]
	v_pk_mul_f32 v[14:15], v[78:79], v[14:15]
	v_pk_mul_f32 v[16:17], v[80:81], v[16:17]
	v_pk_mul_f32 v[18:19], v[82:83], v[18:19]
	v_pk_mul_f32 v[20:21], v[84:85], v[20:21]
	v_pk_mul_f32 v[22:23], v[86:87], v[22:23]
	v_pk_mul_f32 v[24:25], v[88:89], v[24:25]
	v_pk_mul_f32 v[26:27], v[90:91], v[26:27]
	v_pk_mul_f32 v[28:29], v[92:93], v[28:29]
	v_pk_mul_f32 v[30:31], v[94:95], v[30:31]
	v_pk_mul_f32 v[32:33], v[96:97], v[32:33]
	v_pk_mul_f32 v[34:35], v[98:99], v[34:35]
	v_pk_mul_f32 v[36:37], v[100:101], v[36:37]
	v_pk_mul_f32 v[38:39], v[102:103], v[38:39]
	v_mov_b32_e32 v248, 0x260
	s_waitcnt vmcnt(28)
	v_cvt_f32_f16_e32 v72, v104
	v_cvt_f32_f16_sdwa v73, v104 dst_sel:DWORD dst_unused:UNUSED_PAD src0_sel:WORD_1
	v_cvt_f32_f16_e32 v74, v105
	v_cvt_f32_f16_sdwa v75, v105 dst_sel:DWORD dst_unused:UNUSED_PAD src0_sel:WORD_1
	v_cvt_f32_f16_e32 v76, v106
	v_cvt_f32_f16_sdwa v77, v106 dst_sel:DWORD dst_unused:UNUSED_PAD src0_sel:WORD_1
	v_cvt_f32_f16_e32 v78, v107
	v_cvt_f32_f16_sdwa v79, v107 dst_sel:DWORD dst_unused:UNUSED_PAD src0_sel:WORD_1
	v_cvt_f32_f16_e32 v80, v108
	v_cvt_f32_f16_sdwa v81, v108 dst_sel:DWORD dst_unused:UNUSED_PAD src0_sel:WORD_1
	v_cvt_f32_f16_e32 v82, v109
	v_cvt_f32_f16_sdwa v83, v109 dst_sel:DWORD dst_unused:UNUSED_PAD src0_sel:WORD_1
	v_cvt_f32_f16_e32 v84, v110
	v_cvt_f32_f16_sdwa v85, v110 dst_sel:DWORD dst_unused:UNUSED_PAD src0_sel:WORD_1
	v_cvt_f32_f16_e32 v86, v111
	v_cvt_f32_f16_sdwa v87, v111 dst_sel:DWORD dst_unused:UNUSED_PAD src0_sel:WORD_1
	v_cvt_f32_f16_e32 v88, v112
	v_cvt_f32_f16_sdwa v89, v112 dst_sel:DWORD dst_unused:UNUSED_PAD src0_sel:WORD_1
	v_cvt_f32_f16_e32 v90, v113
	v_cvt_f32_f16_sdwa v91, v113 dst_sel:DWORD dst_unused:UNUSED_PAD src0_sel:WORD_1
	v_cvt_f32_f16_e32 v92, v114
	v_cvt_f32_f16_sdwa v93, v114 dst_sel:DWORD dst_unused:UNUSED_PAD src0_sel:WORD_1
	v_cvt_f32_f16_e32 v94, v115
	v_cvt_f32_f16_sdwa v95, v115 dst_sel:DWORD dst_unused:UNUSED_PAD src0_sel:WORD_1
	v_cvt_f32_f16_e32 v96, v116
	v_cvt_f32_f16_sdwa v97, v116 dst_sel:DWORD dst_unused:UNUSED_PAD src0_sel:WORD_1
	v_cvt_f32_f16_e32 v98, v117
	v_cvt_f32_f16_sdwa v99, v117 dst_sel:DWORD dst_unused:UNUSED_PAD src0_sel:WORD_1
	v_cvt_f32_f16_e32 v100, v118
	v_cvt_f32_f16_sdwa v101, v118 dst_sel:DWORD dst_unused:UNUSED_PAD src0_sel:WORD_1
	v_cvt_f32_f16_e32 v102, v119
	v_cvt_f32_f16_sdwa v103, v119 dst_sel:DWORD dst_unused:UNUSED_PAD src0_sel:WORD_1
	v_pk_mul_f32 v[232:233], v[72:73], v[72:73]
	v_pk_mul_f32 v[234:235], v[74:75], v[74:75]
	v_pk_mul_f32 v[236:237], v[76:77], v[76:77]
	v_pk_mul_f32 v[238:239], v[78:79], v[78:79]
	v_pk_fma_f32 v[232:233], v[80:81], v[80:81], v[232:233]
	v_pk_fma_f32 v[234:235], v[82:83], v[82:83], v[234:235]
	v_pk_fma_f32 v[236:237], v[84:85], v[84:85], v[236:237]
	v_pk_fma_f32 v[238:239], v[86:87], v[86:87], v[238:239]
	v_pk_fma_f32 v[232:233], v[88:89], v[88:89], v[232:233]
	v_pk_fma_f32 v[234:235], v[90:91], v[90:91], v[234:235]
	v_pk_fma_f32 v[236:237], v[92:93], v[92:93], v[236:237]
	v_pk_fma_f32 v[238:239], v[94:95], v[94:95], v[238:239]
	v_pk_fma_f32 v[232:233], v[96:97], v[96:97], v[232:233]
	v_pk_fma_f32 v[234:235], v[98:99], v[98:99], v[234:235]
	v_pk_fma_f32 v[236:237], v[100:101], v[100:101], v[236:237]
	v_pk_fma_f32 v[238:239], v[102:103], v[102:103], v[238:239]
	v_pk_add_f32 v[232:233], v[232:233], v[234:235]
	v_pk_add_f32 v[236:237], v[236:237], v[238:239]
	v_pk_add_f32 v[232:233], v[232:233], v[236:237]
	v_add_f32_e32 v240, v232, v233
	s_nop 1
	v_add_f32_dpp v240, v240, v240 quad_perm:[1,0,3,2] row_mask:0xf bank_mask:0xf
	s_nop 1
	v_add_f32_dpp v240, v240, v240 quad_perm:[2,3,0,1] row_mask:0xf bank_mask:0xf
	s_nop 1
	v_add_f32_dpp v240, v240, v240 row_half_mirror row_mask:0xf bank_mask:0xf
	s_nop 1
	v_add_f32_dpp v240, v240, v240 row_mirror row_mask:0xf bank_mask:0xf
	s_nop 1
	v_readlane_b32 s0, v240, 0
	v_readlane_b32 s1, v240, 16
	v_readlane_b32 s4, v240, 32
	v_readlane_b32 s5, v240, 48
	v_mov_b32_e32 v249, 0x358637bd
	s_nop 1
	v_mov_b32_e32 v240, s0
	v_add_f32_e32 v240, s1, v240
	v_add_f32_e32 v240, s4, v240
	v_add_f32_e32 v240, s5, v240
	v_fmamk_f32 v240, v240, 0x3a000000, v249
	s_mov_b32 s0, 0xf800000
	v_mul_f32_e32 v241, 0x4f800000, v240
	v_cmp_gt_f32_e32 vcc, s0, v240
	s_nop 1
	v_cndmask_b32_e32 v240, v240, v241, vcc
	v_sqrt_f32_e32 v241, v240
	s_nop 0
	v_add_u32_e32 v242, -1, v241
	v_fma_f32 v243, -v242, v241, v240
	v_cmp_ge_f32_e64 s[0:1], 0, v243
	v_add_u32_e32 v243, 1, v241
	s_nop 0
	v_cndmask_b32_e64 v242, v241, v242, s[0:1]
	v_fma_f32 v241, -v243, v241, v240
	v_cmp_lt_f32_e64 s[0:1], 0, v241
	s_nop 1
	v_cndmask_b32_e64 v241, v242, v243, s[0:1]
	v_mul_f32_e32 v242, 0x37800000, v241
	v_cndmask_b32_e32 v241, v241, v242, vcc
	v_cmp_class_f32_e32 vcc, v240, v248
	s_nop 1
	v_cndmask_b32_e32 v240, v241, v240, vcc
	v_div_scale_f32 v241, s[0:1], v240, v240, 1.0
	v_rcp_f32_e32 v242, v241
	s_nop 0
	v_fma_f32 v243, -v241, v242, 1.0
	v_fmac_f32_e32 v242, v243, v242
	v_div_scale_f32 v243, vcc, 1.0, v240, 1.0
	v_mul_f32_e32 v244, v243, v242
	v_fma_f32 v247, -v241, v244, v243
	v_fmac_f32_e32 v244, v247, v242
	v_fma_f32 v241, -v241, v244, v243
	s_nop 1
	v_div_fmas_f32 v241, v241, v242, v244
	v_div_fixup_f32 v246, v241, v240, 1.0
	v_pk_mul_f32 v[72:73], v[72:73], v[246:247] op_sel_hi:[1,0]
	v_pk_mul_f32 v[74:75], v[74:75], v[246:247] op_sel_hi:[1,0]
	v_pk_mul_f32 v[76:77], v[76:77], v[246:247] op_sel_hi:[1,0]
	v_pk_mul_f32 v[78:79], v[78:79], v[246:247] op_sel_hi:[1,0]
	v_pk_mul_f32 v[80:81], v[80:81], v[246:247] op_sel_hi:[1,0]
	v_pk_mul_f32 v[82:83], v[82:83], v[246:247] op_sel_hi:[1,0]
	v_pk_mul_f32 v[84:85], v[84:85], v[246:247] op_sel_hi:[1,0]
	v_pk_mul_f32 v[86:87], v[86:87], v[246:247] op_sel_hi:[1,0]
	v_pk_mul_f32 v[88:89], v[88:89], v[246:247] op_sel_hi:[1,0]
	v_pk_mul_f32 v[90:91], v[90:91], v[246:247] op_sel_hi:[1,0]
	v_pk_mul_f32 v[92:93], v[92:93], v[246:247] op_sel_hi:[1,0]
	v_pk_mul_f32 v[94:95], v[94:95], v[246:247] op_sel_hi:[1,0]
	v_pk_mul_f32 v[96:97], v[96:97], v[246:247] op_sel_hi:[1,0]
	v_pk_mul_f32 v[98:99], v[98:99], v[246:247] op_sel_hi:[1,0]
	v_pk_mul_f32 v[100:101], v[100:101], v[246:247] op_sel_hi:[1,0]
	v_pk_mul_f32 v[102:103], v[102:103], v[246:247] op_sel_hi:[1,0]
	s_add_u32 s8, s10, 0x0
	s_addc_u32 s9, s11, 0
	v_pk_fma_f32 v[72:73], v[8:9], v[72:73], v[40:41]
	v_cvt_pk_bf16_f32 v232, v72, v73
	v_pk_fma_f32 v[74:75], v[10:11], v[74:75], v[42:43]
	v_cvt_pk_bf16_f32 v233, v74, v75
	v_pk_fma_f32 v[76:77], v[12:13], v[76:77], v[44:45]
	v_cvt_pk_bf16_f32 v234, v76, v77
	v_pk_fma_f32 v[78:79], v[14:15], v[78:79], v[46:47]
	v_cvt_pk_bf16_f32 v235, v78, v79
	global_store_dwordx4 v1, v[232:235], s[8:9] offset:0
	v_pk_fma_f32 v[80:81], v[16:17], v[80:81], v[48:49]
	v_cvt_pk_bf16_f32 v236, v80, v81
	v_pk_fma_f32 v[82:83], v[18:19], v[82:83], v[50:51]
	v_cvt_pk_bf16_f32 v237, v82, v83
	v_pk_fma_f32 v[84:85], v[20:21], v[84:85], v[52:53]
	v_cvt_pk_bf16_f32 v238, v84, v85
	v_pk_fma_f32 v[86:87], v[22:23], v[86:87], v[54:55]
	v_cvt_pk_bf16_f32 v239, v86, v87
	global_store_dwordx4 v1, v[236:239], s[8:9] offset:1024
	v_pk_fma_f32 v[88:89], v[24:25], v[88:89], v[56:57]
	v_cvt_pk_bf16_f32 v232, v88, v89
	v_pk_fma_f32 v[90:91], v[26:27], v[90:91], v[58:59]
	v_cvt_pk_bf16_f32 v233, v90, v91
	v_pk_fma_f32 v[92:93], v[28:29], v[92:93], v[60:61]
	v_cvt_pk_bf16_f32 v234, v92, v93
	v_pk_fma_f32 v[94:95], v[30:31], v[94:95], v[62:63]
	v_cvt_pk_bf16_f32 v235, v94, v95
	global_store_dwordx4 v1, v[232:235], s[8:9] offset:2048
	v_pk_fma_f32 v[96:97], v[32:33], v[96:97], v[64:65]
	v_cvt_pk_bf16_f32 v236, v96, v97
	v_pk_fma_f32 v[98:99], v[34:35], v[98:99], v[66:67]
	v_cvt_pk_bf16_f32 v237, v98, v99
	v_pk_fma_f32 v[100:101], v[36:37], v[100:101], v[68:69]
	v_cvt_pk_bf16_f32 v238, v100, v101
	v_pk_fma_f32 v[102:103], v[38:39], v[102:103], v[70:71]
	v_cvt_pk_bf16_f32 v239, v102, v103
	global_store_dwordx4 v1, v[236:239], s[8:9] offset:3072
	s_waitcnt vmcnt(28)
	v_cvt_f32_f16_e32 v72, v120
	v_cvt_f32_f16_sdwa v73, v120 dst_sel:DWORD dst_unused:UNUSED_PAD src0_sel:WORD_1
	v_cvt_f32_f16_e32 v74, v121
	v_cvt_f32_f16_sdwa v75, v121 dst_sel:DWORD dst_unused:UNUSED_PAD src0_sel:WORD_1
	v_cvt_f32_f16_e32 v76, v122
	v_cvt_f32_f16_sdwa v77, v122 dst_sel:DWORD dst_unused:UNUSED_PAD src0_sel:WORD_1
	v_cvt_f32_f16_e32 v78, v123
	v_cvt_f32_f16_sdwa v79, v123 dst_sel:DWORD dst_unused:UNUSED_PAD src0_sel:WORD_1
	v_cvt_f32_f16_e32 v80, v124
	v_cvt_f32_f16_sdwa v81, v124 dst_sel:DWORD dst_unused:UNUSED_PAD src0_sel:WORD_1
	v_cvt_f32_f16_e32 v82, v125
	v_cvt_f32_f16_sdwa v83, v125 dst_sel:DWORD dst_unused:UNUSED_PAD src0_sel:WORD_1
	v_cvt_f32_f16_e32 v84, v126
	v_cvt_f32_f16_sdwa v85, v126 dst_sel:DWORD dst_unused:UNUSED_PAD src0_sel:WORD_1
	v_cvt_f32_f16_e32 v86, v127
	v_cvt_f32_f16_sdwa v87, v127 dst_sel:DWORD dst_unused:UNUSED_PAD src0_sel:WORD_1
	v_cvt_f32_f16_e32 v88, v128
	v_cvt_f32_f16_sdwa v89, v128 dst_sel:DWORD dst_unused:UNUSED_PAD src0_sel:WORD_1
	v_cvt_f32_f16_e32 v90, v129
	v_cvt_f32_f16_sdwa v91, v129 dst_sel:DWORD dst_unused:UNUSED_PAD src0_sel:WORD_1
	v_cvt_f32_f16_e32 v92, v130
	v_cvt_f32_f16_sdwa v93, v130 dst_sel:DWORD dst_unused:UNUSED_PAD src0_sel:WORD_1
	v_cvt_f32_f16_e32 v94, v131
	v_cvt_f32_f16_sdwa v95, v131 dst_sel:DWORD dst_unused:UNUSED_PAD src0_sel:WORD_1
	v_cvt_f32_f16_e32 v96, v132
	v_cvt_f32_f16_sdwa v97, v132 dst_sel:DWORD dst_unused:UNUSED_PAD src0_sel:WORD_1
	v_cvt_f32_f16_e32 v98, v133
	v_cvt_f32_f16_sdwa v99, v133 dst_sel:DWORD dst_unused:UNUSED_PAD src0_sel:WORD_1
	v_cvt_f32_f16_e32 v100, v134
	v_cvt_f32_f16_sdwa v101, v134 dst_sel:DWORD dst_unused:UNUSED_PAD src0_sel:WORD_1
	v_cvt_f32_f16_e32 v102, v135
	v_cvt_f32_f16_sdwa v103, v135 dst_sel:DWORD dst_unused:UNUSED_PAD src0_sel:WORD_1
	v_pk_mul_f32 v[232:233], v[72:73], v[72:73]
	v_pk_mul_f32 v[234:235], v[74:75], v[74:75]
	v_pk_mul_f32 v[236:237], v[76:77], v[76:77]
	v_pk_mul_f32 v[238:239], v[78:79], v[78:79]
	v_pk_fma_f32 v[232:233], v[80:81], v[80:81], v[232:233]
	v_pk_fma_f32 v[234:235], v[82:83], v[82:83], v[234:235]
	v_pk_fma_f32 v[236:237], v[84:85], v[84:85], v[236:237]
	v_pk_fma_f32 v[238:239], v[86:87], v[86:87], v[238:239]
	v_pk_fma_f32 v[232:233], v[88:89], v[88:89], v[232:233]
	v_pk_fma_f32 v[234:235], v[90:91], v[90:91], v[234:235]
	v_pk_fma_f32 v[236:237], v[92:93], v[92:93], v[236:237]
	v_pk_fma_f32 v[238:239], v[94:95], v[94:95], v[238:239]
	v_pk_fma_f32 v[232:233], v[96:97], v[96:97], v[232:233]
	v_pk_fma_f32 v[234:235], v[98:99], v[98:99], v[234:235]
	v_pk_fma_f32 v[236:237], v[100:101], v[100:101], v[236:237]
	v_pk_fma_f32 v[238:239], v[102:103], v[102:103], v[238:239]
	v_pk_add_f32 v[232:233], v[232:233], v[234:235]
	v_pk_add_f32 v[236:237], v[236:237], v[238:239]
	v_pk_add_f32 v[232:233], v[232:233], v[236:237]
	v_add_f32_e32 v240, v232, v233
	s_nop 1
	v_add_f32_dpp v240, v240, v240 quad_perm:[1,0,3,2] row_mask:0xf bank_mask:0xf
	s_nop 1
	v_add_f32_dpp v240, v240, v240 quad_perm:[2,3,0,1] row_mask:0xf bank_mask:0xf
	s_nop 1
	v_add_f32_dpp v240, v240, v240 row_half_mirror row_mask:0xf bank_mask:0xf
	s_nop 1
	v_add_f32_dpp v240, v240, v240 row_mirror row_mask:0xf bank_mask:0xf
	s_nop 1
	v_readlane_b32 s0, v240, 0
	v_readlane_b32 s1, v240, 16
	v_readlane_b32 s4, v240, 32
	v_readlane_b32 s5, v240, 48
	v_mov_b32_e32 v249, 0x358637bd
	s_nop 1
	v_mov_b32_e32 v240, s0
	v_add_f32_e32 v240, s1, v240
	v_add_f32_e32 v240, s4, v240
	v_add_f32_e32 v240, s5, v240
	v_fmamk_f32 v240, v240, 0x3a000000, v249
	s_mov_b32 s0, 0xf800000
	v_mul_f32_e32 v241, 0x4f800000, v240
	v_cmp_gt_f32_e32 vcc, s0, v240
	s_nop 1
	v_cndmask_b32_e32 v240, v240, v241, vcc
	v_sqrt_f32_e32 v241, v240
	s_nop 0
	v_add_u32_e32 v242, -1, v241
	v_fma_f32 v243, -v242, v241, v240
	v_cmp_ge_f32_e64 s[0:1], 0, v243
	v_add_u32_e32 v243, 1, v241
	s_nop 0
	v_cndmask_b32_e64 v242, v241, v242, s[0:1]
	v_fma_f32 v241, -v243, v241, v240
	v_cmp_lt_f32_e64 s[0:1], 0, v241
	s_nop 1
	v_cndmask_b32_e64 v241, v242, v243, s[0:1]
	v_mul_f32_e32 v242, 0x37800000, v241
	v_cndmask_b32_e32 v241, v241, v242, vcc
	v_cmp_class_f32_e32 vcc, v240, v248
	s_nop 1
	v_cndmask_b32_e32 v240, v241, v240, vcc
	v_div_scale_f32 v241, s[0:1], v240, v240, 1.0
	v_rcp_f32_e32 v242, v241
	s_nop 0
	v_fma_f32 v243, -v241, v242, 1.0
	v_fmac_f32_e32 v242, v243, v242
	v_div_scale_f32 v243, vcc, 1.0, v240, 1.0
	v_mul_f32_e32 v244, v243, v242
	v_fma_f32 v247, -v241, v244, v243
	v_fmac_f32_e32 v244, v247, v242
	v_fma_f32 v241, -v241, v244, v243
	s_nop 1
	v_div_fmas_f32 v241, v241, v242, v244
	v_div_fixup_f32 v246, v241, v240, 1.0
	v_pk_mul_f32 v[72:73], v[72:73], v[246:247] op_sel_hi:[1,0]
	v_pk_mul_f32 v[74:75], v[74:75], v[246:247] op_sel_hi:[1,0]
	v_pk_mul_f32 v[76:77], v[76:77], v[246:247] op_sel_hi:[1,0]
	v_pk_mul_f32 v[78:79], v[78:79], v[246:247] op_sel_hi:[1,0]
	v_pk_mul_f32 v[80:81], v[80:81], v[246:247] op_sel_hi:[1,0]
	v_pk_mul_f32 v[82:83], v[82:83], v[246:247] op_sel_hi:[1,0]
	v_pk_mul_f32 v[84:85], v[84:85], v[246:247] op_sel_hi:[1,0]
	v_pk_mul_f32 v[86:87], v[86:87], v[246:247] op_sel_hi:[1,0]
	v_pk_mul_f32 v[88:89], v[88:89], v[246:247] op_sel_hi:[1,0]
	v_pk_mul_f32 v[90:91], v[90:91], v[246:247] op_sel_hi:[1,0]
	v_pk_mul_f32 v[92:93], v[92:93], v[246:247] op_sel_hi:[1,0]
	v_pk_mul_f32 v[94:95], v[94:95], v[246:247] op_sel_hi:[1,0]
	v_pk_mul_f32 v[96:97], v[96:97], v[246:247] op_sel_hi:[1,0]
	v_pk_mul_f32 v[98:99], v[98:99], v[246:247] op_sel_hi:[1,0]
	v_pk_mul_f32 v[100:101], v[100:101], v[246:247] op_sel_hi:[1,0]
	v_pk_mul_f32 v[102:103], v[102:103], v[246:247] op_sel_hi:[1,0]
	s_add_u32 s8, s10, 0x20000
	s_addc_u32 s9, s11, 0
	v_pk_fma_f32 v[72:73], v[8:9], v[72:73], v[40:41]
	v_cvt_pk_bf16_f32 v232, v72, v73
	v_pk_fma_f32 v[74:75], v[10:11], v[74:75], v[42:43]
	v_cvt_pk_bf16_f32 v233, v74, v75
	v_pk_fma_f32 v[76:77], v[12:13], v[76:77], v[44:45]
	v_cvt_pk_bf16_f32 v234, v76, v77
	v_pk_fma_f32 v[78:79], v[14:15], v[78:79], v[46:47]
	v_cvt_pk_bf16_f32 v235, v78, v79
	global_store_dwordx4 v1, v[232:235], s[8:9] offset:0
	v_pk_fma_f32 v[80:81], v[16:17], v[80:81], v[48:49]
	v_cvt_pk_bf16_f32 v236, v80, v81
	v_pk_fma_f32 v[82:83], v[18:19], v[82:83], v[50:51]
	v_cvt_pk_bf16_f32 v237, v82, v83
	v_pk_fma_f32 v[84:85], v[20:21], v[84:85], v[52:53]
	v_cvt_pk_bf16_f32 v238, v84, v85
	v_pk_fma_f32 v[86:87], v[22:23], v[86:87], v[54:55]
	v_cvt_pk_bf16_f32 v239, v86, v87
	global_store_dwordx4 v1, v[236:239], s[8:9] offset:1024
	v_pk_fma_f32 v[88:89], v[24:25], v[88:89], v[56:57]
	v_cvt_pk_bf16_f32 v232, v88, v89
	v_pk_fma_f32 v[90:91], v[26:27], v[90:91], v[58:59]
	v_cvt_pk_bf16_f32 v233, v90, v91
	v_pk_fma_f32 v[92:93], v[28:29], v[92:93], v[60:61]
	v_cvt_pk_bf16_f32 v234, v92, v93
	v_pk_fma_f32 v[94:95], v[30:31], v[94:95], v[62:63]
	v_cvt_pk_bf16_f32 v235, v94, v95
	global_store_dwordx4 v1, v[232:235], s[8:9] offset:2048
	v_pk_fma_f32 v[96:97], v[32:33], v[96:97], v[64:65]
	v_cvt_pk_bf16_f32 v236, v96, v97
	v_pk_fma_f32 v[98:99], v[34:35], v[98:99], v[66:67]
	v_cvt_pk_bf16_f32 v237, v98, v99
	v_pk_fma_f32 v[100:101], v[36:37], v[100:101], v[68:69]
	v_cvt_pk_bf16_f32 v238, v100, v101
	v_pk_fma_f32 v[102:103], v[38:39], v[102:103], v[70:71]
	v_cvt_pk_bf16_f32 v239, v102, v103
	global_store_dwordx4 v1, v[236:239], s[8:9] offset:3072
	s_waitcnt vmcnt(28)
	v_cvt_f32_f16_e32 v72, v136
	v_cvt_f32_f16_sdwa v73, v136 dst_sel:DWORD dst_unused:UNUSED_PAD src0_sel:WORD_1
	v_cvt_f32_f16_e32 v74, v137
	v_cvt_f32_f16_sdwa v75, v137 dst_sel:DWORD dst_unused:UNUSED_PAD src0_sel:WORD_1
	v_cvt_f32_f16_e32 v76, v138
	v_cvt_f32_f16_sdwa v77, v138 dst_sel:DWORD dst_unused:UNUSED_PAD src0_sel:WORD_1
	v_cvt_f32_f16_e32 v78, v139
	v_cvt_f32_f16_sdwa v79, v139 dst_sel:DWORD dst_unused:UNUSED_PAD src0_sel:WORD_1
	v_cvt_f32_f16_e32 v80, v140
	v_cvt_f32_f16_sdwa v81, v140 dst_sel:DWORD dst_unused:UNUSED_PAD src0_sel:WORD_1
	v_cvt_f32_f16_e32 v82, v141
	v_cvt_f32_f16_sdwa v83, v141 dst_sel:DWORD dst_unused:UNUSED_PAD src0_sel:WORD_1
	v_cvt_f32_f16_e32 v84, v142
	v_cvt_f32_f16_sdwa v85, v142 dst_sel:DWORD dst_unused:UNUSED_PAD src0_sel:WORD_1
	v_cvt_f32_f16_e32 v86, v143
	v_cvt_f32_f16_sdwa v87, v143 dst_sel:DWORD dst_unused:UNUSED_PAD src0_sel:WORD_1
	v_cvt_f32_f16_e32 v88, v144
	v_cvt_f32_f16_sdwa v89, v144 dst_sel:DWORD dst_unused:UNUSED_PAD src0_sel:WORD_1
	v_cvt_f32_f16_e32 v90, v145
	v_cvt_f32_f16_sdwa v91, v145 dst_sel:DWORD dst_unused:UNUSED_PAD src0_sel:WORD_1
	v_cvt_f32_f16_e32 v92, v146
	v_cvt_f32_f16_sdwa v93, v146 dst_sel:DWORD dst_unused:UNUSED_PAD src0_sel:WORD_1
	v_cvt_f32_f16_e32 v94, v147
	v_cvt_f32_f16_sdwa v95, v147 dst_sel:DWORD dst_unused:UNUSED_PAD src0_sel:WORD_1
	v_cvt_f32_f16_e32 v96, v148
	v_cvt_f32_f16_sdwa v97, v148 dst_sel:DWORD dst_unused:UNUSED_PAD src0_sel:WORD_1
	v_cvt_f32_f16_e32 v98, v149
	v_cvt_f32_f16_sdwa v99, v149 dst_sel:DWORD dst_unused:UNUSED_PAD src0_sel:WORD_1
	v_cvt_f32_f16_e32 v100, v150
	v_cvt_f32_f16_sdwa v101, v150 dst_sel:DWORD dst_unused:UNUSED_PAD src0_sel:WORD_1
	v_cvt_f32_f16_e32 v102, v151
	v_cvt_f32_f16_sdwa v103, v151 dst_sel:DWORD dst_unused:UNUSED_PAD src0_sel:WORD_1
	v_pk_mul_f32 v[232:233], v[72:73], v[72:73]
	v_pk_mul_f32 v[234:235], v[74:75], v[74:75]
	v_pk_mul_f32 v[236:237], v[76:77], v[76:77]
	v_pk_mul_f32 v[238:239], v[78:79], v[78:79]
	v_pk_fma_f32 v[232:233], v[80:81], v[80:81], v[232:233]
	v_pk_fma_f32 v[234:235], v[82:83], v[82:83], v[234:235]
	v_pk_fma_f32 v[236:237], v[84:85], v[84:85], v[236:237]
	v_pk_fma_f32 v[238:239], v[86:87], v[86:87], v[238:239]
	v_pk_fma_f32 v[232:233], v[88:89], v[88:89], v[232:233]
	v_pk_fma_f32 v[234:235], v[90:91], v[90:91], v[234:235]
	v_pk_fma_f32 v[236:237], v[92:93], v[92:93], v[236:237]
	v_pk_fma_f32 v[238:239], v[94:95], v[94:95], v[238:239]
	v_pk_fma_f32 v[232:233], v[96:97], v[96:97], v[232:233]
	v_pk_fma_f32 v[234:235], v[98:99], v[98:99], v[234:235]
	v_pk_fma_f32 v[236:237], v[100:101], v[100:101], v[236:237]
	v_pk_fma_f32 v[238:239], v[102:103], v[102:103], v[238:239]
	v_pk_add_f32 v[232:233], v[232:233], v[234:235]
	v_pk_add_f32 v[236:237], v[236:237], v[238:239]
	v_pk_add_f32 v[232:233], v[232:233], v[236:237]
	v_add_f32_e32 v240, v232, v233
	s_nop 1
	v_add_f32_dpp v240, v240, v240 quad_perm:[1,0,3,2] row_mask:0xf bank_mask:0xf
	s_nop 1
	v_add_f32_dpp v240, v240, v240 quad_perm:[2,3,0,1] row_mask:0xf bank_mask:0xf
	s_nop 1
	v_add_f32_dpp v240, v240, v240 row_half_mirror row_mask:0xf bank_mask:0xf
	s_nop 1
	v_add_f32_dpp v240, v240, v240 row_mirror row_mask:0xf bank_mask:0xf
	s_nop 1
	v_readlane_b32 s0, v240, 0
	v_readlane_b32 s1, v240, 16
	v_readlane_b32 s4, v240, 32
	v_readlane_b32 s5, v240, 48
	v_mov_b32_e32 v249, 0x358637bd
	s_nop 1
	v_mov_b32_e32 v240, s0
	v_add_f32_e32 v240, s1, v240
	v_add_f32_e32 v240, s4, v240
	v_add_f32_e32 v240, s5, v240
	v_fmamk_f32 v240, v240, 0x3a000000, v249
	s_mov_b32 s0, 0xf800000
	v_mul_f32_e32 v241, 0x4f800000, v240
	v_cmp_gt_f32_e32 vcc, s0, v240
	s_nop 1
	v_cndmask_b32_e32 v240, v240, v241, vcc
	v_sqrt_f32_e32 v241, v240
	s_nop 0
	v_add_u32_e32 v242, -1, v241
	v_fma_f32 v243, -v242, v241, v240
	v_cmp_ge_f32_e64 s[0:1], 0, v243
	v_add_u32_e32 v243, 1, v241
	s_nop 0
	v_cndmask_b32_e64 v242, v241, v242, s[0:1]
	v_fma_f32 v241, -v243, v241, v240
	v_cmp_lt_f32_e64 s[0:1], 0, v241
	s_nop 1
	v_cndmask_b32_e64 v241, v242, v243, s[0:1]
	v_mul_f32_e32 v242, 0x37800000, v241
	v_cndmask_b32_e32 v241, v241, v242, vcc
	v_cmp_class_f32_e32 vcc, v240, v248
	s_nop 1
	v_cndmask_b32_e32 v240, v241, v240, vcc
	v_div_scale_f32 v241, s[0:1], v240, v240, 1.0
	v_rcp_f32_e32 v242, v241
	s_nop 0
	v_fma_f32 v243, -v241, v242, 1.0
	v_fmac_f32_e32 v242, v243, v242
	v_div_scale_f32 v243, vcc, 1.0, v240, 1.0
	v_mul_f32_e32 v244, v243, v242
	v_fma_f32 v247, -v241, v244, v243
	v_fmac_f32_e32 v244, v247, v242
	v_fma_f32 v241, -v241, v244, v243
	s_nop 1
	v_div_fmas_f32 v241, v241, v242, v244
	v_div_fixup_f32 v246, v241, v240, 1.0
	v_pk_mul_f32 v[72:73], v[72:73], v[246:247] op_sel_hi:[1,0]
	v_pk_mul_f32 v[74:75], v[74:75], v[246:247] op_sel_hi:[1,0]
	v_pk_mul_f32 v[76:77], v[76:77], v[246:247] op_sel_hi:[1,0]
	v_pk_mul_f32 v[78:79], v[78:79], v[246:247] op_sel_hi:[1,0]
	v_pk_mul_f32 v[80:81], v[80:81], v[246:247] op_sel_hi:[1,0]
	v_pk_mul_f32 v[82:83], v[82:83], v[246:247] op_sel_hi:[1,0]
	v_pk_mul_f32 v[84:85], v[84:85], v[246:247] op_sel_hi:[1,0]
	v_pk_mul_f32 v[86:87], v[86:87], v[246:247] op_sel_hi:[1,0]
	v_pk_mul_f32 v[88:89], v[88:89], v[246:247] op_sel_hi:[1,0]
	v_pk_mul_f32 v[90:91], v[90:91], v[246:247] op_sel_hi:[1,0]
	v_pk_mul_f32 v[92:93], v[92:93], v[246:247] op_sel_hi:[1,0]
	v_pk_mul_f32 v[94:95], v[94:95], v[246:247] op_sel_hi:[1,0]
	v_pk_mul_f32 v[96:97], v[96:97], v[246:247] op_sel_hi:[1,0]
	v_pk_mul_f32 v[98:99], v[98:99], v[246:247] op_sel_hi:[1,0]
	v_pk_mul_f32 v[100:101], v[100:101], v[246:247] op_sel_hi:[1,0]
	v_pk_mul_f32 v[102:103], v[102:103], v[246:247] op_sel_hi:[1,0]
	s_add_u32 s8, s10, 0x40000
	s_addc_u32 s9, s11, 0
	v_pk_fma_f32 v[72:73], v[8:9], v[72:73], v[40:41]
	v_cvt_pk_bf16_f32 v232, v72, v73
	v_pk_fma_f32 v[74:75], v[10:11], v[74:75], v[42:43]
	v_cvt_pk_bf16_f32 v233, v74, v75
	v_pk_fma_f32 v[76:77], v[12:13], v[76:77], v[44:45]
	v_cvt_pk_bf16_f32 v234, v76, v77
	v_pk_fma_f32 v[78:79], v[14:15], v[78:79], v[46:47]
	v_cvt_pk_bf16_f32 v235, v78, v79
	global_store_dwordx4 v1, v[232:235], s[8:9] offset:0
	v_pk_fma_f32 v[80:81], v[16:17], v[80:81], v[48:49]
	v_cvt_pk_bf16_f32 v236, v80, v81
	v_pk_fma_f32 v[82:83], v[18:19], v[82:83], v[50:51]
	v_cvt_pk_bf16_f32 v237, v82, v83
	v_pk_fma_f32 v[84:85], v[20:21], v[84:85], v[52:53]
	v_cvt_pk_bf16_f32 v238, v84, v85
	v_pk_fma_f32 v[86:87], v[22:23], v[86:87], v[54:55]
	v_cvt_pk_bf16_f32 v239, v86, v87
	global_store_dwordx4 v1, v[236:239], s[8:9] offset:1024
	v_pk_fma_f32 v[88:89], v[24:25], v[88:89], v[56:57]
	v_cvt_pk_bf16_f32 v232, v88, v89
	v_pk_fma_f32 v[90:91], v[26:27], v[90:91], v[58:59]
	v_cvt_pk_bf16_f32 v233, v90, v91
	v_pk_fma_f32 v[92:93], v[28:29], v[92:93], v[60:61]
	v_cvt_pk_bf16_f32 v234, v92, v93
	v_pk_fma_f32 v[94:95], v[30:31], v[94:95], v[62:63]
	v_cvt_pk_bf16_f32 v235, v94, v95
	global_store_dwordx4 v1, v[232:235], s[8:9] offset:2048
	v_pk_fma_f32 v[96:97], v[32:33], v[96:97], v[64:65]
	v_cvt_pk_bf16_f32 v236, v96, v97
	v_pk_fma_f32 v[98:99], v[34:35], v[98:99], v[66:67]
	v_cvt_pk_bf16_f32 v237, v98, v99
	v_pk_fma_f32 v[100:101], v[36:37], v[100:101], v[68:69]
	v_cvt_pk_bf16_f32 v238, v100, v101
	v_pk_fma_f32 v[102:103], v[38:39], v[102:103], v[70:71]
	v_cvt_pk_bf16_f32 v239, v102, v103
	global_store_dwordx4 v1, v[236:239], s[8:9] offset:3072
	s_waitcnt vmcnt(28)
	v_cvt_f32_f16_e32 v72, v152
	v_cvt_f32_f16_sdwa v73, v152 dst_sel:DWORD dst_unused:UNUSED_PAD src0_sel:WORD_1
	v_cvt_f32_f16_e32 v74, v153
	v_cvt_f32_f16_sdwa v75, v153 dst_sel:DWORD dst_unused:UNUSED_PAD src0_sel:WORD_1
	v_cvt_f32_f16_e32 v76, v154
	v_cvt_f32_f16_sdwa v77, v154 dst_sel:DWORD dst_unused:UNUSED_PAD src0_sel:WORD_1
	v_cvt_f32_f16_e32 v78, v155
	v_cvt_f32_f16_sdwa v79, v155 dst_sel:DWORD dst_unused:UNUSED_PAD src0_sel:WORD_1
	v_cvt_f32_f16_e32 v80, v156
	v_cvt_f32_f16_sdwa v81, v156 dst_sel:DWORD dst_unused:UNUSED_PAD src0_sel:WORD_1
	v_cvt_f32_f16_e32 v82, v157
	v_cvt_f32_f16_sdwa v83, v157 dst_sel:DWORD dst_unused:UNUSED_PAD src0_sel:WORD_1
	v_cvt_f32_f16_e32 v84, v158
	v_cvt_f32_f16_sdwa v85, v158 dst_sel:DWORD dst_unused:UNUSED_PAD src0_sel:WORD_1
	v_cvt_f32_f16_e32 v86, v159
	v_cvt_f32_f16_sdwa v87, v159 dst_sel:DWORD dst_unused:UNUSED_PAD src0_sel:WORD_1
	v_cvt_f32_f16_e32 v88, v160
	v_cvt_f32_f16_sdwa v89, v160 dst_sel:DWORD dst_unused:UNUSED_PAD src0_sel:WORD_1
	v_cvt_f32_f16_e32 v90, v161
	v_cvt_f32_f16_sdwa v91, v161 dst_sel:DWORD dst_unused:UNUSED_PAD src0_sel:WORD_1
	v_cvt_f32_f16_e32 v92, v162
	v_cvt_f32_f16_sdwa v93, v162 dst_sel:DWORD dst_unused:UNUSED_PAD src0_sel:WORD_1
	v_cvt_f32_f16_e32 v94, v163
	v_cvt_f32_f16_sdwa v95, v163 dst_sel:DWORD dst_unused:UNUSED_PAD src0_sel:WORD_1
	v_cvt_f32_f16_e32 v96, v164
	v_cvt_f32_f16_sdwa v97, v164 dst_sel:DWORD dst_unused:UNUSED_PAD src0_sel:WORD_1
	v_cvt_f32_f16_e32 v98, v165
	v_cvt_f32_f16_sdwa v99, v165 dst_sel:DWORD dst_unused:UNUSED_PAD src0_sel:WORD_1
	v_cvt_f32_f16_e32 v100, v166
	v_cvt_f32_f16_sdwa v101, v166 dst_sel:DWORD dst_unused:UNUSED_PAD src0_sel:WORD_1
	v_cvt_f32_f16_e32 v102, v167
	v_cvt_f32_f16_sdwa v103, v167 dst_sel:DWORD dst_unused:UNUSED_PAD src0_sel:WORD_1
	v_pk_mul_f32 v[232:233], v[72:73], v[72:73]
	v_pk_mul_f32 v[234:235], v[74:75], v[74:75]
	v_pk_mul_f32 v[236:237], v[76:77], v[76:77]
	v_pk_mul_f32 v[238:239], v[78:79], v[78:79]
	v_pk_fma_f32 v[232:233], v[80:81], v[80:81], v[232:233]
	v_pk_fma_f32 v[234:235], v[82:83], v[82:83], v[234:235]
	v_pk_fma_f32 v[236:237], v[84:85], v[84:85], v[236:237]
	v_pk_fma_f32 v[238:239], v[86:87], v[86:87], v[238:239]
	v_pk_fma_f32 v[232:233], v[88:89], v[88:89], v[232:233]
	v_pk_fma_f32 v[234:235], v[90:91], v[90:91], v[234:235]
	v_pk_fma_f32 v[236:237], v[92:93], v[92:93], v[236:237]
	v_pk_fma_f32 v[238:239], v[94:95], v[94:95], v[238:239]
	v_pk_fma_f32 v[232:233], v[96:97], v[96:97], v[232:233]
	v_pk_fma_f32 v[234:235], v[98:99], v[98:99], v[234:235]
	v_pk_fma_f32 v[236:237], v[100:101], v[100:101], v[236:237]
	v_pk_fma_f32 v[238:239], v[102:103], v[102:103], v[238:239]
	v_pk_add_f32 v[232:233], v[232:233], v[234:235]
	v_pk_add_f32 v[236:237], v[236:237], v[238:239]
	v_pk_add_f32 v[232:233], v[232:233], v[236:237]
	v_add_f32_e32 v240, v232, v233
	s_nop 1
	v_add_f32_dpp v240, v240, v240 quad_perm:[1,0,3,2] row_mask:0xf bank_mask:0xf
	s_nop 1
	v_add_f32_dpp v240, v240, v240 quad_perm:[2,3,0,1] row_mask:0xf bank_mask:0xf
	s_nop 1
	v_add_f32_dpp v240, v240, v240 row_half_mirror row_mask:0xf bank_mask:0xf
	s_nop 1
	v_add_f32_dpp v240, v240, v240 row_mirror row_mask:0xf bank_mask:0xf
	s_nop 1
	v_readlane_b32 s0, v240, 0
	v_readlane_b32 s1, v240, 16
	v_readlane_b32 s4, v240, 32
	v_readlane_b32 s5, v240, 48
	v_mov_b32_e32 v249, 0x358637bd
	s_nop 1
	v_mov_b32_e32 v240, s0
	v_add_f32_e32 v240, s1, v240
	v_add_f32_e32 v240, s4, v240
	v_add_f32_e32 v240, s5, v240
	v_fmamk_f32 v240, v240, 0x3a000000, v249
	s_mov_b32 s0, 0xf800000
	v_mul_f32_e32 v241, 0x4f800000, v240
	v_cmp_gt_f32_e32 vcc, s0, v240
	s_nop 1
	v_cndmask_b32_e32 v240, v240, v241, vcc
	v_sqrt_f32_e32 v241, v240
	s_nop 0
	v_add_u32_e32 v242, -1, v241
	v_fma_f32 v243, -v242, v241, v240
	v_cmp_ge_f32_e64 s[0:1], 0, v243
	v_add_u32_e32 v243, 1, v241
	s_nop 0
	v_cndmask_b32_e64 v242, v241, v242, s[0:1]
	v_fma_f32 v241, -v243, v241, v240
	v_cmp_lt_f32_e64 s[0:1], 0, v241
	s_nop 1
	v_cndmask_b32_e64 v241, v242, v243, s[0:1]
	v_mul_f32_e32 v242, 0x37800000, v241
	v_cndmask_b32_e32 v241, v241, v242, vcc
	v_cmp_class_f32_e32 vcc, v240, v248
	s_nop 1
	v_cndmask_b32_e32 v240, v241, v240, vcc
	v_div_scale_f32 v241, s[0:1], v240, v240, 1.0
	v_rcp_f32_e32 v242, v241
	s_nop 0
	v_fma_f32 v243, -v241, v242, 1.0
	v_fmac_f32_e32 v242, v243, v242
	v_div_scale_f32 v243, vcc, 1.0, v240, 1.0
	v_mul_f32_e32 v244, v243, v242
	v_fma_f32 v247, -v241, v244, v243
	v_fmac_f32_e32 v244, v247, v242
	v_fma_f32 v241, -v241, v244, v243
	s_nop 1
	v_div_fmas_f32 v241, v241, v242, v244
	v_div_fixup_f32 v246, v241, v240, 1.0
	v_pk_mul_f32 v[72:73], v[72:73], v[246:247] op_sel_hi:[1,0]
	v_pk_mul_f32 v[74:75], v[74:75], v[246:247] op_sel_hi:[1,0]
	v_pk_mul_f32 v[76:77], v[76:77], v[246:247] op_sel_hi:[1,0]
	v_pk_mul_f32 v[78:79], v[78:79], v[246:247] op_sel_hi:[1,0]
	v_pk_mul_f32 v[80:81], v[80:81], v[246:247] op_sel_hi:[1,0]
	v_pk_mul_f32 v[82:83], v[82:83], v[246:247] op_sel_hi:[1,0]
	v_pk_mul_f32 v[84:85], v[84:85], v[246:247] op_sel_hi:[1,0]
	v_pk_mul_f32 v[86:87], v[86:87], v[246:247] op_sel_hi:[1,0]
	v_pk_mul_f32 v[88:89], v[88:89], v[246:247] op_sel_hi:[1,0]
	v_pk_mul_f32 v[90:91], v[90:91], v[246:247] op_sel_hi:[1,0]
	v_pk_mul_f32 v[92:93], v[92:93], v[246:247] op_sel_hi:[1,0]
	v_pk_mul_f32 v[94:95], v[94:95], v[246:247] op_sel_hi:[1,0]
	v_pk_mul_f32 v[96:97], v[96:97], v[246:247] op_sel_hi:[1,0]
	v_pk_mul_f32 v[98:99], v[98:99], v[246:247] op_sel_hi:[1,0]
	v_pk_mul_f32 v[100:101], v[100:101], v[246:247] op_sel_hi:[1,0]
	v_pk_mul_f32 v[102:103], v[102:103], v[246:247] op_sel_hi:[1,0]
	s_add_u32 s8, s10, 0x60000
	s_addc_u32 s9, s11, 0
	v_pk_fma_f32 v[72:73], v[8:9], v[72:73], v[40:41]
	v_cvt_pk_bf16_f32 v232, v72, v73
	v_pk_fma_f32 v[74:75], v[10:11], v[74:75], v[42:43]
	v_cvt_pk_bf16_f32 v233, v74, v75
	v_pk_fma_f32 v[76:77], v[12:13], v[76:77], v[44:45]
	v_cvt_pk_bf16_f32 v234, v76, v77
	v_pk_fma_f32 v[78:79], v[14:15], v[78:79], v[46:47]
	v_cvt_pk_bf16_f32 v235, v78, v79
	global_store_dwordx4 v1, v[232:235], s[8:9] offset:0
	v_pk_fma_f32 v[80:81], v[16:17], v[80:81], v[48:49]
	v_cvt_pk_bf16_f32 v236, v80, v81
	v_pk_fma_f32 v[82:83], v[18:19], v[82:83], v[50:51]
	v_cvt_pk_bf16_f32 v237, v82, v83
	v_pk_fma_f32 v[84:85], v[20:21], v[84:85], v[52:53]
	v_cvt_pk_bf16_f32 v238, v84, v85
	v_pk_fma_f32 v[86:87], v[22:23], v[86:87], v[54:55]
	v_cvt_pk_bf16_f32 v239, v86, v87
	global_store_dwordx4 v1, v[236:239], s[8:9] offset:1024
	v_pk_fma_f32 v[88:89], v[24:25], v[88:89], v[56:57]
	v_cvt_pk_bf16_f32 v232, v88, v89
	v_pk_fma_f32 v[90:91], v[26:27], v[90:91], v[58:59]
	v_cvt_pk_bf16_f32 v233, v90, v91
	v_pk_fma_f32 v[92:93], v[28:29], v[92:93], v[60:61]
	v_cvt_pk_bf16_f32 v234, v92, v93
	v_pk_fma_f32 v[94:95], v[30:31], v[94:95], v[62:63]
	v_cvt_pk_bf16_f32 v235, v94, v95
	global_store_dwordx4 v1, v[232:235], s[8:9] offset:2048
	v_pk_fma_f32 v[96:97], v[32:33], v[96:97], v[64:65]
	v_cvt_pk_bf16_f32 v236, v96, v97
	v_pk_fma_f32 v[98:99], v[34:35], v[98:99], v[66:67]
	v_cvt_pk_bf16_f32 v237, v98, v99
	v_pk_fma_f32 v[100:101], v[36:37], v[100:101], v[68:69]
	v_cvt_pk_bf16_f32 v238, v100, v101
	v_pk_fma_f32 v[102:103], v[38:39], v[102:103], v[70:71]
	v_cvt_pk_bf16_f32 v239, v102, v103
	global_store_dwordx4 v1, v[236:239], s[8:9] offset:3072
	s_waitcnt vmcnt(28)
	v_cvt_f32_f16_e32 v72, v168
	v_cvt_f32_f16_sdwa v73, v168 dst_sel:DWORD dst_unused:UNUSED_PAD src0_sel:WORD_1
	v_cvt_f32_f16_e32 v74, v169
	v_cvt_f32_f16_sdwa v75, v169 dst_sel:DWORD dst_unused:UNUSED_PAD src0_sel:WORD_1
	v_cvt_f32_f16_e32 v76, v170
	v_cvt_f32_f16_sdwa v77, v170 dst_sel:DWORD dst_unused:UNUSED_PAD src0_sel:WORD_1
	v_cvt_f32_f16_e32 v78, v171
	v_cvt_f32_f16_sdwa v79, v171 dst_sel:DWORD dst_unused:UNUSED_PAD src0_sel:WORD_1
	v_cvt_f32_f16_e32 v80, v172
	v_cvt_f32_f16_sdwa v81, v172 dst_sel:DWORD dst_unused:UNUSED_PAD src0_sel:WORD_1
	v_cvt_f32_f16_e32 v82, v173
	v_cvt_f32_f16_sdwa v83, v173 dst_sel:DWORD dst_unused:UNUSED_PAD src0_sel:WORD_1
	v_cvt_f32_f16_e32 v84, v174
	v_cvt_f32_f16_sdwa v85, v174 dst_sel:DWORD dst_unused:UNUSED_PAD src0_sel:WORD_1
	v_cvt_f32_f16_e32 v86, v175
	v_cvt_f32_f16_sdwa v87, v175 dst_sel:DWORD dst_unused:UNUSED_PAD src0_sel:WORD_1
	v_cvt_f32_f16_e32 v88, v176
	v_cvt_f32_f16_sdwa v89, v176 dst_sel:DWORD dst_unused:UNUSED_PAD src0_sel:WORD_1
	v_cvt_f32_f16_e32 v90, v177
	v_cvt_f32_f16_sdwa v91, v177 dst_sel:DWORD dst_unused:UNUSED_PAD src0_sel:WORD_1
	v_cvt_f32_f16_e32 v92, v178
	v_cvt_f32_f16_sdwa v93, v178 dst_sel:DWORD dst_unused:UNUSED_PAD src0_sel:WORD_1
	v_cvt_f32_f16_e32 v94, v179
	v_cvt_f32_f16_sdwa v95, v179 dst_sel:DWORD dst_unused:UNUSED_PAD src0_sel:WORD_1
	v_cvt_f32_f16_e32 v96, v180
	v_cvt_f32_f16_sdwa v97, v180 dst_sel:DWORD dst_unused:UNUSED_PAD src0_sel:WORD_1
	v_cvt_f32_f16_e32 v98, v181
	v_cvt_f32_f16_sdwa v99, v181 dst_sel:DWORD dst_unused:UNUSED_PAD src0_sel:WORD_1
	v_cvt_f32_f16_e32 v100, v182
	v_cvt_f32_f16_sdwa v101, v182 dst_sel:DWORD dst_unused:UNUSED_PAD src0_sel:WORD_1
	v_cvt_f32_f16_e32 v102, v183
	v_cvt_f32_f16_sdwa v103, v183 dst_sel:DWORD dst_unused:UNUSED_PAD src0_sel:WORD_1
	v_pk_mul_f32 v[232:233], v[72:73], v[72:73]
	v_pk_mul_f32 v[234:235], v[74:75], v[74:75]
	v_pk_mul_f32 v[236:237], v[76:77], v[76:77]
	v_pk_mul_f32 v[238:239], v[78:79], v[78:79]
	v_pk_fma_f32 v[232:233], v[80:81], v[80:81], v[232:233]
	v_pk_fma_f32 v[234:235], v[82:83], v[82:83], v[234:235]
	v_pk_fma_f32 v[236:237], v[84:85], v[84:85], v[236:237]
	v_pk_fma_f32 v[238:239], v[86:87], v[86:87], v[238:239]
	v_pk_fma_f32 v[232:233], v[88:89], v[88:89], v[232:233]
	v_pk_fma_f32 v[234:235], v[90:91], v[90:91], v[234:235]
	v_pk_fma_f32 v[236:237], v[92:93], v[92:93], v[236:237]
	v_pk_fma_f32 v[238:239], v[94:95], v[94:95], v[238:239]
	v_pk_fma_f32 v[232:233], v[96:97], v[96:97], v[232:233]
	v_pk_fma_f32 v[234:235], v[98:99], v[98:99], v[234:235]
	v_pk_fma_f32 v[236:237], v[100:101], v[100:101], v[236:237]
	v_pk_fma_f32 v[238:239], v[102:103], v[102:103], v[238:239]
	v_pk_add_f32 v[232:233], v[232:233], v[234:235]
	v_pk_add_f32 v[236:237], v[236:237], v[238:239]
	v_pk_add_f32 v[232:233], v[232:233], v[236:237]
	v_add_f32_e32 v240, v232, v233
	s_nop 1
	v_add_f32_dpp v240, v240, v240 quad_perm:[1,0,3,2] row_mask:0xf bank_mask:0xf
	s_nop 1
	v_add_f32_dpp v240, v240, v240 quad_perm:[2,3,0,1] row_mask:0xf bank_mask:0xf
	s_nop 1
	v_add_f32_dpp v240, v240, v240 row_half_mirror row_mask:0xf bank_mask:0xf
	s_nop 1
	v_add_f32_dpp v240, v240, v240 row_mirror row_mask:0xf bank_mask:0xf
	s_nop 1
	v_readlane_b32 s0, v240, 0
	v_readlane_b32 s1, v240, 16
	v_readlane_b32 s4, v240, 32
	v_readlane_b32 s5, v240, 48
	v_mov_b32_e32 v249, 0x358637bd
	s_nop 1
	v_mov_b32_e32 v240, s0
	v_add_f32_e32 v240, s1, v240
	v_add_f32_e32 v240, s4, v240
	v_add_f32_e32 v240, s5, v240
	v_fmamk_f32 v240, v240, 0x3a000000, v249
	s_mov_b32 s0, 0xf800000
	v_mul_f32_e32 v241, 0x4f800000, v240
	v_cmp_gt_f32_e32 vcc, s0, v240
	s_nop 1
	v_cndmask_b32_e32 v240, v240, v241, vcc
	v_sqrt_f32_e32 v241, v240
	s_nop 0
	v_add_u32_e32 v242, -1, v241
	v_fma_f32 v243, -v242, v241, v240
	v_cmp_ge_f32_e64 s[0:1], 0, v243
	v_add_u32_e32 v243, 1, v241
	s_nop 0
	v_cndmask_b32_e64 v242, v241, v242, s[0:1]
	v_fma_f32 v241, -v243, v241, v240
	v_cmp_lt_f32_e64 s[0:1], 0, v241
	s_nop 1
	v_cndmask_b32_e64 v241, v242, v243, s[0:1]
	v_mul_f32_e32 v242, 0x37800000, v241
	v_cndmask_b32_e32 v241, v241, v242, vcc
	v_cmp_class_f32_e32 vcc, v240, v248
	s_nop 1
	v_cndmask_b32_e32 v240, v241, v240, vcc
	v_div_scale_f32 v241, s[0:1], v240, v240, 1.0
	v_rcp_f32_e32 v242, v241
	s_nop 0
	v_fma_f32 v243, -v241, v242, 1.0
	v_fmac_f32_e32 v242, v243, v242
	v_div_scale_f32 v243, vcc, 1.0, v240, 1.0
	v_mul_f32_e32 v244, v243, v242
	v_fma_f32 v247, -v241, v244, v243
	v_fmac_f32_e32 v244, v247, v242
	v_fma_f32 v241, -v241, v244, v243
	s_nop 1
	v_div_fmas_f32 v241, v241, v242, v244
	v_div_fixup_f32 v246, v241, v240, 1.0
	v_pk_mul_f32 v[72:73], v[72:73], v[246:247] op_sel_hi:[1,0]
	v_pk_mul_f32 v[74:75], v[74:75], v[246:247] op_sel_hi:[1,0]
	v_pk_mul_f32 v[76:77], v[76:77], v[246:247] op_sel_hi:[1,0]
	v_pk_mul_f32 v[78:79], v[78:79], v[246:247] op_sel_hi:[1,0]
	v_pk_mul_f32 v[80:81], v[80:81], v[246:247] op_sel_hi:[1,0]
	v_pk_mul_f32 v[82:83], v[82:83], v[246:247] op_sel_hi:[1,0]
	v_pk_mul_f32 v[84:85], v[84:85], v[246:247] op_sel_hi:[1,0]
	v_pk_mul_f32 v[86:87], v[86:87], v[246:247] op_sel_hi:[1,0]
	v_pk_mul_f32 v[88:89], v[88:89], v[246:247] op_sel_hi:[1,0]
	v_pk_mul_f32 v[90:91], v[90:91], v[246:247] op_sel_hi:[1,0]
	v_pk_mul_f32 v[92:93], v[92:93], v[246:247] op_sel_hi:[1,0]
	v_pk_mul_f32 v[94:95], v[94:95], v[246:247] op_sel_hi:[1,0]
	v_pk_mul_f32 v[96:97], v[96:97], v[246:247] op_sel_hi:[1,0]
	v_pk_mul_f32 v[98:99], v[98:99], v[246:247] op_sel_hi:[1,0]
	v_pk_mul_f32 v[100:101], v[100:101], v[246:247] op_sel_hi:[1,0]
	v_pk_mul_f32 v[102:103], v[102:103], v[246:247] op_sel_hi:[1,0]
	s_add_u32 s8, s10, 0x80000
	s_addc_u32 s9, s11, 0
	v_pk_fma_f32 v[72:73], v[8:9], v[72:73], v[40:41]
	v_cvt_pk_bf16_f32 v232, v72, v73
	v_pk_fma_f32 v[74:75], v[10:11], v[74:75], v[42:43]
	v_cvt_pk_bf16_f32 v233, v74, v75
	v_pk_fma_f32 v[76:77], v[12:13], v[76:77], v[44:45]
	v_cvt_pk_bf16_f32 v234, v76, v77
	v_pk_fma_f32 v[78:79], v[14:15], v[78:79], v[46:47]
	v_cvt_pk_bf16_f32 v235, v78, v79
	global_store_dwordx4 v1, v[232:235], s[8:9] offset:0
	v_pk_fma_f32 v[80:81], v[16:17], v[80:81], v[48:49]
	v_cvt_pk_bf16_f32 v236, v80, v81
	v_pk_fma_f32 v[82:83], v[18:19], v[82:83], v[50:51]
	v_cvt_pk_bf16_f32 v237, v82, v83
	v_pk_fma_f32 v[84:85], v[20:21], v[84:85], v[52:53]
	v_cvt_pk_bf16_f32 v238, v84, v85
	v_pk_fma_f32 v[86:87], v[22:23], v[86:87], v[54:55]
	v_cvt_pk_bf16_f32 v239, v86, v87
	global_store_dwordx4 v1, v[236:239], s[8:9] offset:1024
	v_pk_fma_f32 v[88:89], v[24:25], v[88:89], v[56:57]
	v_cvt_pk_bf16_f32 v232, v88, v89
	v_pk_fma_f32 v[90:91], v[26:27], v[90:91], v[58:59]
	v_cvt_pk_bf16_f32 v233, v90, v91
	v_pk_fma_f32 v[92:93], v[28:29], v[92:93], v[60:61]
	v_cvt_pk_bf16_f32 v234, v92, v93
	v_pk_fma_f32 v[94:95], v[30:31], v[94:95], v[62:63]
	v_cvt_pk_bf16_f32 v235, v94, v95
	global_store_dwordx4 v1, v[232:235], s[8:9] offset:2048
	v_pk_fma_f32 v[96:97], v[32:33], v[96:97], v[64:65]
	v_cvt_pk_bf16_f32 v236, v96, v97
	v_pk_fma_f32 v[98:99], v[34:35], v[98:99], v[66:67]
	v_cvt_pk_bf16_f32 v237, v98, v99
	v_pk_fma_f32 v[100:101], v[36:37], v[100:101], v[68:69]
	v_cvt_pk_bf16_f32 v238, v100, v101
	v_pk_fma_f32 v[102:103], v[38:39], v[102:103], v[70:71]
	v_cvt_pk_bf16_f32 v239, v102, v103
	global_store_dwordx4 v1, v[236:239], s[8:9] offset:3072
	s_waitcnt vmcnt(28)
	v_cvt_f32_f16_e32 v72, v184
	v_cvt_f32_f16_sdwa v73, v184 dst_sel:DWORD dst_unused:UNUSED_PAD src0_sel:WORD_1
	v_cvt_f32_f16_e32 v74, v185
	v_cvt_f32_f16_sdwa v75, v185 dst_sel:DWORD dst_unused:UNUSED_PAD src0_sel:WORD_1
	v_cvt_f32_f16_e32 v76, v186
	v_cvt_f32_f16_sdwa v77, v186 dst_sel:DWORD dst_unused:UNUSED_PAD src0_sel:WORD_1
	v_cvt_f32_f16_e32 v78, v187
	v_cvt_f32_f16_sdwa v79, v187 dst_sel:DWORD dst_unused:UNUSED_PAD src0_sel:WORD_1
	v_cvt_f32_f16_e32 v80, v188
	v_cvt_f32_f16_sdwa v81, v188 dst_sel:DWORD dst_unused:UNUSED_PAD src0_sel:WORD_1
	v_cvt_f32_f16_e32 v82, v189
	v_cvt_f32_f16_sdwa v83, v189 dst_sel:DWORD dst_unused:UNUSED_PAD src0_sel:WORD_1
	v_cvt_f32_f16_e32 v84, v190
	v_cvt_f32_f16_sdwa v85, v190 dst_sel:DWORD dst_unused:UNUSED_PAD src0_sel:WORD_1
	v_cvt_f32_f16_e32 v86, v191
	v_cvt_f32_f16_sdwa v87, v191 dst_sel:DWORD dst_unused:UNUSED_PAD src0_sel:WORD_1
	v_cvt_f32_f16_e32 v88, v192
	v_cvt_f32_f16_sdwa v89, v192 dst_sel:DWORD dst_unused:UNUSED_PAD src0_sel:WORD_1
	v_cvt_f32_f16_e32 v90, v193
	v_cvt_f32_f16_sdwa v91, v193 dst_sel:DWORD dst_unused:UNUSED_PAD src0_sel:WORD_1
	v_cvt_f32_f16_e32 v92, v194
	v_cvt_f32_f16_sdwa v93, v194 dst_sel:DWORD dst_unused:UNUSED_PAD src0_sel:WORD_1
	v_cvt_f32_f16_e32 v94, v195
	v_cvt_f32_f16_sdwa v95, v195 dst_sel:DWORD dst_unused:UNUSED_PAD src0_sel:WORD_1
	v_cvt_f32_f16_e32 v96, v196
	v_cvt_f32_f16_sdwa v97, v196 dst_sel:DWORD dst_unused:UNUSED_PAD src0_sel:WORD_1
	v_cvt_f32_f16_e32 v98, v197
	v_cvt_f32_f16_sdwa v99, v197 dst_sel:DWORD dst_unused:UNUSED_PAD src0_sel:WORD_1
	v_cvt_f32_f16_e32 v100, v198
	v_cvt_f32_f16_sdwa v101, v198 dst_sel:DWORD dst_unused:UNUSED_PAD src0_sel:WORD_1
	v_cvt_f32_f16_e32 v102, v199
	v_cvt_f32_f16_sdwa v103, v199 dst_sel:DWORD dst_unused:UNUSED_PAD src0_sel:WORD_1
	v_pk_mul_f32 v[232:233], v[72:73], v[72:73]
	v_pk_mul_f32 v[234:235], v[74:75], v[74:75]
	v_pk_mul_f32 v[236:237], v[76:77], v[76:77]
	v_pk_mul_f32 v[238:239], v[78:79], v[78:79]
	v_pk_fma_f32 v[232:233], v[80:81], v[80:81], v[232:233]
	v_pk_fma_f32 v[234:235], v[82:83], v[82:83], v[234:235]
	v_pk_fma_f32 v[236:237], v[84:85], v[84:85], v[236:237]
	v_pk_fma_f32 v[238:239], v[86:87], v[86:87], v[238:239]
	v_pk_fma_f32 v[232:233], v[88:89], v[88:89], v[232:233]
	v_pk_fma_f32 v[234:235], v[90:91], v[90:91], v[234:235]
	v_pk_fma_f32 v[236:237], v[92:93], v[92:93], v[236:237]
	v_pk_fma_f32 v[238:239], v[94:95], v[94:95], v[238:239]
	v_pk_fma_f32 v[232:233], v[96:97], v[96:97], v[232:233]
	v_pk_fma_f32 v[234:235], v[98:99], v[98:99], v[234:235]
	v_pk_fma_f32 v[236:237], v[100:101], v[100:101], v[236:237]
	v_pk_fma_f32 v[238:239], v[102:103], v[102:103], v[238:239]
	v_pk_add_f32 v[232:233], v[232:233], v[234:235]
	v_pk_add_f32 v[236:237], v[236:237], v[238:239]
	v_pk_add_f32 v[232:233], v[232:233], v[236:237]
	v_add_f32_e32 v240, v232, v233
	s_nop 1
	v_add_f32_dpp v240, v240, v240 quad_perm:[1,0,3,2] row_mask:0xf bank_mask:0xf
	s_nop 1
	v_add_f32_dpp v240, v240, v240 quad_perm:[2,3,0,1] row_mask:0xf bank_mask:0xf
	s_nop 1
	v_add_f32_dpp v240, v240, v240 row_half_mirror row_mask:0xf bank_mask:0xf
	s_nop 1
	v_add_f32_dpp v240, v240, v240 row_mirror row_mask:0xf bank_mask:0xf
	s_nop 1
	v_readlane_b32 s0, v240, 0
	v_readlane_b32 s1, v240, 16
	v_readlane_b32 s4, v240, 32
	v_readlane_b32 s5, v240, 48
	v_mov_b32_e32 v249, 0x358637bd
	s_nop 1
	v_mov_b32_e32 v240, s0
	v_add_f32_e32 v240, s1, v240
	v_add_f32_e32 v240, s4, v240
	v_add_f32_e32 v240, s5, v240
	v_fmamk_f32 v240, v240, 0x3a000000, v249
	s_mov_b32 s0, 0xf800000
	v_mul_f32_e32 v241, 0x4f800000, v240
	v_cmp_gt_f32_e32 vcc, s0, v240
	s_nop 1
	v_cndmask_b32_e32 v240, v240, v241, vcc
	v_sqrt_f32_e32 v241, v240
	s_nop 0
	v_add_u32_e32 v242, -1, v241
	v_fma_f32 v243, -v242, v241, v240
	v_cmp_ge_f32_e64 s[0:1], 0, v243
	v_add_u32_e32 v243, 1, v241
	s_nop 0
	v_cndmask_b32_e64 v242, v241, v242, s[0:1]
	v_fma_f32 v241, -v243, v241, v240
	v_cmp_lt_f32_e64 s[0:1], 0, v241
	s_nop 1
	v_cndmask_b32_e64 v241, v242, v243, s[0:1]
	v_mul_f32_e32 v242, 0x37800000, v241
	v_cndmask_b32_e32 v241, v241, v242, vcc
	v_cmp_class_f32_e32 vcc, v240, v248
	s_nop 1
	v_cndmask_b32_e32 v240, v241, v240, vcc
	v_div_scale_f32 v241, s[0:1], v240, v240, 1.0
	v_rcp_f32_e32 v242, v241
	s_nop 0
	v_fma_f32 v243, -v241, v242, 1.0
	v_fmac_f32_e32 v242, v243, v242
	v_div_scale_f32 v243, vcc, 1.0, v240, 1.0
	v_mul_f32_e32 v244, v243, v242
	v_fma_f32 v247, -v241, v244, v243
	v_fmac_f32_e32 v244, v247, v242
	v_fma_f32 v241, -v241, v244, v243
	s_nop 1
	v_div_fmas_f32 v241, v241, v242, v244
	v_div_fixup_f32 v246, v241, v240, 1.0
	v_pk_mul_f32 v[72:73], v[72:73], v[246:247] op_sel_hi:[1,0]
	v_pk_mul_f32 v[74:75], v[74:75], v[246:247] op_sel_hi:[1,0]
	v_pk_mul_f32 v[76:77], v[76:77], v[246:247] op_sel_hi:[1,0]
	v_pk_mul_f32 v[78:79], v[78:79], v[246:247] op_sel_hi:[1,0]
	v_pk_mul_f32 v[80:81], v[80:81], v[246:247] op_sel_hi:[1,0]
	v_pk_mul_f32 v[82:83], v[82:83], v[246:247] op_sel_hi:[1,0]
	v_pk_mul_f32 v[84:85], v[84:85], v[246:247] op_sel_hi:[1,0]
	v_pk_mul_f32 v[86:87], v[86:87], v[246:247] op_sel_hi:[1,0]
	v_pk_mul_f32 v[88:89], v[88:89], v[246:247] op_sel_hi:[1,0]
	v_pk_mul_f32 v[90:91], v[90:91], v[246:247] op_sel_hi:[1,0]
	v_pk_mul_f32 v[92:93], v[92:93], v[246:247] op_sel_hi:[1,0]
	v_pk_mul_f32 v[94:95], v[94:95], v[246:247] op_sel_hi:[1,0]
	v_pk_mul_f32 v[96:97], v[96:97], v[246:247] op_sel_hi:[1,0]
	v_pk_mul_f32 v[98:99], v[98:99], v[246:247] op_sel_hi:[1,0]
	v_pk_mul_f32 v[100:101], v[100:101], v[246:247] op_sel_hi:[1,0]
	v_pk_mul_f32 v[102:103], v[102:103], v[246:247] op_sel_hi:[1,0]
	s_add_u32 s8, s10, 0xa0000
	s_addc_u32 s9, s11, 0
	v_pk_fma_f32 v[72:73], v[8:9], v[72:73], v[40:41]
	v_cvt_pk_bf16_f32 v232, v72, v73
	v_pk_fma_f32 v[74:75], v[10:11], v[74:75], v[42:43]
	v_cvt_pk_bf16_f32 v233, v74, v75
	v_pk_fma_f32 v[76:77], v[12:13], v[76:77], v[44:45]
	v_cvt_pk_bf16_f32 v234, v76, v77
	v_pk_fma_f32 v[78:79], v[14:15], v[78:79], v[46:47]
	v_cvt_pk_bf16_f32 v235, v78, v79
	global_store_dwordx4 v1, v[232:235], s[8:9] offset:0
	v_pk_fma_f32 v[80:81], v[16:17], v[80:81], v[48:49]
	v_cvt_pk_bf16_f32 v236, v80, v81
	v_pk_fma_f32 v[82:83], v[18:19], v[82:83], v[50:51]
	v_cvt_pk_bf16_f32 v237, v82, v83
	v_pk_fma_f32 v[84:85], v[20:21], v[84:85], v[52:53]
	v_cvt_pk_bf16_f32 v238, v84, v85
	v_pk_fma_f32 v[86:87], v[22:23], v[86:87], v[54:55]
	v_cvt_pk_bf16_f32 v239, v86, v87
	global_store_dwordx4 v1, v[236:239], s[8:9] offset:1024
	v_pk_fma_f32 v[88:89], v[24:25], v[88:89], v[56:57]
	v_cvt_pk_bf16_f32 v232, v88, v89
	v_pk_fma_f32 v[90:91], v[26:27], v[90:91], v[58:59]
	v_cvt_pk_bf16_f32 v233, v90, v91
	v_pk_fma_f32 v[92:93], v[28:29], v[92:93], v[60:61]
	v_cvt_pk_bf16_f32 v234, v92, v93
	v_pk_fma_f32 v[94:95], v[30:31], v[94:95], v[62:63]
	v_cvt_pk_bf16_f32 v235, v94, v95
	global_store_dwordx4 v1, v[232:235], s[8:9] offset:2048
	v_pk_fma_f32 v[96:97], v[32:33], v[96:97], v[64:65]
	v_cvt_pk_bf16_f32 v236, v96, v97
	v_pk_fma_f32 v[98:99], v[34:35], v[98:99], v[66:67]
	v_cvt_pk_bf16_f32 v237, v98, v99
	v_pk_fma_f32 v[100:101], v[36:37], v[100:101], v[68:69]
	v_cvt_pk_bf16_f32 v238, v100, v101
	v_pk_fma_f32 v[102:103], v[38:39], v[102:103], v[70:71]
	v_cvt_pk_bf16_f32 v239, v102, v103
	global_store_dwordx4 v1, v[236:239], s[8:9] offset:3072
	s_waitcnt vmcnt(28)
	v_cvt_f32_f16_e32 v72, v200
	v_cvt_f32_f16_sdwa v73, v200 dst_sel:DWORD dst_unused:UNUSED_PAD src0_sel:WORD_1
	v_cvt_f32_f16_e32 v74, v201
	v_cvt_f32_f16_sdwa v75, v201 dst_sel:DWORD dst_unused:UNUSED_PAD src0_sel:WORD_1
	v_cvt_f32_f16_e32 v76, v202
	v_cvt_f32_f16_sdwa v77, v202 dst_sel:DWORD dst_unused:UNUSED_PAD src0_sel:WORD_1
	v_cvt_f32_f16_e32 v78, v203
	v_cvt_f32_f16_sdwa v79, v203 dst_sel:DWORD dst_unused:UNUSED_PAD src0_sel:WORD_1
	v_cvt_f32_f16_e32 v80, v204
	v_cvt_f32_f16_sdwa v81, v204 dst_sel:DWORD dst_unused:UNUSED_PAD src0_sel:WORD_1
	v_cvt_f32_f16_e32 v82, v205
	v_cvt_f32_f16_sdwa v83, v205 dst_sel:DWORD dst_unused:UNUSED_PAD src0_sel:WORD_1
	v_cvt_f32_f16_e32 v84, v206
	v_cvt_f32_f16_sdwa v85, v206 dst_sel:DWORD dst_unused:UNUSED_PAD src0_sel:WORD_1
	v_cvt_f32_f16_e32 v86, v207
	v_cvt_f32_f16_sdwa v87, v207 dst_sel:DWORD dst_unused:UNUSED_PAD src0_sel:WORD_1
	v_cvt_f32_f16_e32 v88, v208
	v_cvt_f32_f16_sdwa v89, v208 dst_sel:DWORD dst_unused:UNUSED_PAD src0_sel:WORD_1
	v_cvt_f32_f16_e32 v90, v209
	v_cvt_f32_f16_sdwa v91, v209 dst_sel:DWORD dst_unused:UNUSED_PAD src0_sel:WORD_1
	v_cvt_f32_f16_e32 v92, v210
	v_cvt_f32_f16_sdwa v93, v210 dst_sel:DWORD dst_unused:UNUSED_PAD src0_sel:WORD_1
	v_cvt_f32_f16_e32 v94, v211
	v_cvt_f32_f16_sdwa v95, v211 dst_sel:DWORD dst_unused:UNUSED_PAD src0_sel:WORD_1
	v_cvt_f32_f16_e32 v96, v212
	v_cvt_f32_f16_sdwa v97, v212 dst_sel:DWORD dst_unused:UNUSED_PAD src0_sel:WORD_1
	v_cvt_f32_f16_e32 v98, v213
	v_cvt_f32_f16_sdwa v99, v213 dst_sel:DWORD dst_unused:UNUSED_PAD src0_sel:WORD_1
	v_cvt_f32_f16_e32 v100, v214
	v_cvt_f32_f16_sdwa v101, v214 dst_sel:DWORD dst_unused:UNUSED_PAD src0_sel:WORD_1
	v_cvt_f32_f16_e32 v102, v215
	v_cvt_f32_f16_sdwa v103, v215 dst_sel:DWORD dst_unused:UNUSED_PAD src0_sel:WORD_1
	v_pk_mul_f32 v[232:233], v[72:73], v[72:73]
	v_pk_mul_f32 v[234:235], v[74:75], v[74:75]
	v_pk_mul_f32 v[236:237], v[76:77], v[76:77]
	v_pk_mul_f32 v[238:239], v[78:79], v[78:79]
	v_pk_fma_f32 v[232:233], v[80:81], v[80:81], v[232:233]
	v_pk_fma_f32 v[234:235], v[82:83], v[82:83], v[234:235]
	v_pk_fma_f32 v[236:237], v[84:85], v[84:85], v[236:237]
	v_pk_fma_f32 v[238:239], v[86:87], v[86:87], v[238:239]
	v_pk_fma_f32 v[232:233], v[88:89], v[88:89], v[232:233]
	v_pk_fma_f32 v[234:235], v[90:91], v[90:91], v[234:235]
	v_pk_fma_f32 v[236:237], v[92:93], v[92:93], v[236:237]
	v_pk_fma_f32 v[238:239], v[94:95], v[94:95], v[238:239]
	v_pk_fma_f32 v[232:233], v[96:97], v[96:97], v[232:233]
	v_pk_fma_f32 v[234:235], v[98:99], v[98:99], v[234:235]
	v_pk_fma_f32 v[236:237], v[100:101], v[100:101], v[236:237]
	v_pk_fma_f32 v[238:239], v[102:103], v[102:103], v[238:239]
	v_pk_add_f32 v[232:233], v[232:233], v[234:235]
	v_pk_add_f32 v[236:237], v[236:237], v[238:239]
	v_pk_add_f32 v[232:233], v[232:233], v[236:237]
	v_add_f32_e32 v240, v232, v233
	s_nop 1
	v_add_f32_dpp v240, v240, v240 quad_perm:[1,0,3,2] row_mask:0xf bank_mask:0xf
	s_nop 1
	v_add_f32_dpp v240, v240, v240 quad_perm:[2,3,0,1] row_mask:0xf bank_mask:0xf
	s_nop 1
	v_add_f32_dpp v240, v240, v240 row_half_mirror row_mask:0xf bank_mask:0xf
	s_nop 1
	v_add_f32_dpp v240, v240, v240 row_mirror row_mask:0xf bank_mask:0xf
	s_nop 1
	v_readlane_b32 s0, v240, 0
	v_readlane_b32 s1, v240, 16
	v_readlane_b32 s4, v240, 32
	v_readlane_b32 s5, v240, 48
	v_mov_b32_e32 v249, 0x358637bd
	s_nop 1
	v_mov_b32_e32 v240, s0
	v_add_f32_e32 v240, s1, v240
	v_add_f32_e32 v240, s4, v240
	v_add_f32_e32 v240, s5, v240
	v_fmamk_f32 v240, v240, 0x3a000000, v249
	s_mov_b32 s0, 0xf800000
	v_mul_f32_e32 v241, 0x4f800000, v240
	v_cmp_gt_f32_e32 vcc, s0, v240
	s_nop 1
	v_cndmask_b32_e32 v240, v240, v241, vcc
	v_sqrt_f32_e32 v241, v240
	s_nop 0
	v_add_u32_e32 v242, -1, v241
	v_fma_f32 v243, -v242, v241, v240
	v_cmp_ge_f32_e64 s[0:1], 0, v243
	v_add_u32_e32 v243, 1, v241
	s_nop 0
	v_cndmask_b32_e64 v242, v241, v242, s[0:1]
	v_fma_f32 v241, -v243, v241, v240
	v_cmp_lt_f32_e64 s[0:1], 0, v241
	s_nop 1
	v_cndmask_b32_e64 v241, v242, v243, s[0:1]
	v_mul_f32_e32 v242, 0x37800000, v241
	v_cndmask_b32_e32 v241, v241, v242, vcc
	v_cmp_class_f32_e32 vcc, v240, v248
	s_nop 1
	v_cndmask_b32_e32 v240, v241, v240, vcc
	v_div_scale_f32 v241, s[0:1], v240, v240, 1.0
	v_rcp_f32_e32 v242, v241
	s_nop 0
	v_fma_f32 v243, -v241, v242, 1.0
	v_fmac_f32_e32 v242, v243, v242
	v_div_scale_f32 v243, vcc, 1.0, v240, 1.0
	v_mul_f32_e32 v244, v243, v242
	v_fma_f32 v247, -v241, v244, v243
	v_fmac_f32_e32 v244, v247, v242
	v_fma_f32 v241, -v241, v244, v243
	s_nop 1
	v_div_fmas_f32 v241, v241, v242, v244
	v_div_fixup_f32 v246, v241, v240, 1.0
	v_pk_mul_f32 v[72:73], v[72:73], v[246:247] op_sel_hi:[1,0]
	v_pk_mul_f32 v[74:75], v[74:75], v[246:247] op_sel_hi:[1,0]
	v_pk_mul_f32 v[76:77], v[76:77], v[246:247] op_sel_hi:[1,0]
	v_pk_mul_f32 v[78:79], v[78:79], v[246:247] op_sel_hi:[1,0]
	v_pk_mul_f32 v[80:81], v[80:81], v[246:247] op_sel_hi:[1,0]
	v_pk_mul_f32 v[82:83], v[82:83], v[246:247] op_sel_hi:[1,0]
	v_pk_mul_f32 v[84:85], v[84:85], v[246:247] op_sel_hi:[1,0]
	v_pk_mul_f32 v[86:87], v[86:87], v[246:247] op_sel_hi:[1,0]
	v_pk_mul_f32 v[88:89], v[88:89], v[246:247] op_sel_hi:[1,0]
	v_pk_mul_f32 v[90:91], v[90:91], v[246:247] op_sel_hi:[1,0]
	v_pk_mul_f32 v[92:93], v[92:93], v[246:247] op_sel_hi:[1,0]
	v_pk_mul_f32 v[94:95], v[94:95], v[246:247] op_sel_hi:[1,0]
	v_pk_mul_f32 v[96:97], v[96:97], v[246:247] op_sel_hi:[1,0]
	v_pk_mul_f32 v[98:99], v[98:99], v[246:247] op_sel_hi:[1,0]
	v_pk_mul_f32 v[100:101], v[100:101], v[246:247] op_sel_hi:[1,0]
	v_pk_mul_f32 v[102:103], v[102:103], v[246:247] op_sel_hi:[1,0]
	s_add_u32 s8, s10, 0xc0000
	s_addc_u32 s9, s11, 0
	v_pk_fma_f32 v[72:73], v[8:9], v[72:73], v[40:41]
	v_cvt_pk_bf16_f32 v232, v72, v73
	v_pk_fma_f32 v[74:75], v[10:11], v[74:75], v[42:43]
	v_cvt_pk_bf16_f32 v233, v74, v75
	v_pk_fma_f32 v[76:77], v[12:13], v[76:77], v[44:45]
	v_cvt_pk_bf16_f32 v234, v76, v77
	v_pk_fma_f32 v[78:79], v[14:15], v[78:79], v[46:47]
	v_cvt_pk_bf16_f32 v235, v78, v79
	global_store_dwordx4 v1, v[232:235], s[8:9] offset:0
	v_pk_fma_f32 v[80:81], v[16:17], v[80:81], v[48:49]
	v_cvt_pk_bf16_f32 v236, v80, v81
	v_pk_fma_f32 v[82:83], v[18:19], v[82:83], v[50:51]
	v_cvt_pk_bf16_f32 v237, v82, v83
	v_pk_fma_f32 v[84:85], v[20:21], v[84:85], v[52:53]
	v_cvt_pk_bf16_f32 v238, v84, v85
	v_pk_fma_f32 v[86:87], v[22:23], v[86:87], v[54:55]
	v_cvt_pk_bf16_f32 v239, v86, v87
	global_store_dwordx4 v1, v[236:239], s[8:9] offset:1024
	v_pk_fma_f32 v[88:89], v[24:25], v[88:89], v[56:57]
	v_cvt_pk_bf16_f32 v232, v88, v89
	v_pk_fma_f32 v[90:91], v[26:27], v[90:91], v[58:59]
	v_cvt_pk_bf16_f32 v233, v90, v91
	v_pk_fma_f32 v[92:93], v[28:29], v[92:93], v[60:61]
	v_cvt_pk_bf16_f32 v234, v92, v93
	v_pk_fma_f32 v[94:95], v[30:31], v[94:95], v[62:63]
	v_cvt_pk_bf16_f32 v235, v94, v95
	global_store_dwordx4 v1, v[232:235], s[8:9] offset:2048
	v_pk_fma_f32 v[96:97], v[32:33], v[96:97], v[64:65]
	v_cvt_pk_bf16_f32 v236, v96, v97
	v_pk_fma_f32 v[98:99], v[34:35], v[98:99], v[66:67]
	v_cvt_pk_bf16_f32 v237, v98, v99
	v_pk_fma_f32 v[100:101], v[36:37], v[100:101], v[68:69]
	v_cvt_pk_bf16_f32 v238, v100, v101
	v_pk_fma_f32 v[102:103], v[38:39], v[102:103], v[70:71]
	v_cvt_pk_bf16_f32 v239, v102, v103
	global_store_dwordx4 v1, v[236:239], s[8:9] offset:3072
	s_waitcnt vmcnt(28)
	v_cvt_f32_f16_e32 v72, v216
	v_cvt_f32_f16_sdwa v73, v216 dst_sel:DWORD dst_unused:UNUSED_PAD src0_sel:WORD_1
	v_cvt_f32_f16_e32 v74, v217
	v_cvt_f32_f16_sdwa v75, v217 dst_sel:DWORD dst_unused:UNUSED_PAD src0_sel:WORD_1
	v_cvt_f32_f16_e32 v76, v218
	v_cvt_f32_f16_sdwa v77, v218 dst_sel:DWORD dst_unused:UNUSED_PAD src0_sel:WORD_1
	v_cvt_f32_f16_e32 v78, v219
	v_cvt_f32_f16_sdwa v79, v219 dst_sel:DWORD dst_unused:UNUSED_PAD src0_sel:WORD_1
	v_cvt_f32_f16_e32 v80, v220
	v_cvt_f32_f16_sdwa v81, v220 dst_sel:DWORD dst_unused:UNUSED_PAD src0_sel:WORD_1
	v_cvt_f32_f16_e32 v82, v221
	v_cvt_f32_f16_sdwa v83, v221 dst_sel:DWORD dst_unused:UNUSED_PAD src0_sel:WORD_1
	v_cvt_f32_f16_e32 v84, v222
	v_cvt_f32_f16_sdwa v85, v222 dst_sel:DWORD dst_unused:UNUSED_PAD src0_sel:WORD_1
	v_cvt_f32_f16_e32 v86, v223
	v_cvt_f32_f16_sdwa v87, v223 dst_sel:DWORD dst_unused:UNUSED_PAD src0_sel:WORD_1
	v_cvt_f32_f16_e32 v88, v224
	v_cvt_f32_f16_sdwa v89, v224 dst_sel:DWORD dst_unused:UNUSED_PAD src0_sel:WORD_1
	v_cvt_f32_f16_e32 v90, v225
	v_cvt_f32_f16_sdwa v91, v225 dst_sel:DWORD dst_unused:UNUSED_PAD src0_sel:WORD_1
	v_cvt_f32_f16_e32 v92, v226
	v_cvt_f32_f16_sdwa v93, v226 dst_sel:DWORD dst_unused:UNUSED_PAD src0_sel:WORD_1
	v_cvt_f32_f16_e32 v94, v227
	v_cvt_f32_f16_sdwa v95, v227 dst_sel:DWORD dst_unused:UNUSED_PAD src0_sel:WORD_1
	v_cvt_f32_f16_e32 v96, v228
	v_cvt_f32_f16_sdwa v97, v228 dst_sel:DWORD dst_unused:UNUSED_PAD src0_sel:WORD_1
	v_cvt_f32_f16_e32 v98, v229
	v_cvt_f32_f16_sdwa v99, v229 dst_sel:DWORD dst_unused:UNUSED_PAD src0_sel:WORD_1
	v_cvt_f32_f16_e32 v100, v230
	v_cvt_f32_f16_sdwa v101, v230 dst_sel:DWORD dst_unused:UNUSED_PAD src0_sel:WORD_1
	v_cvt_f32_f16_e32 v102, v231
	v_cvt_f32_f16_sdwa v103, v231 dst_sel:DWORD dst_unused:UNUSED_PAD src0_sel:WORD_1
	v_pk_mul_f32 v[232:233], v[72:73], v[72:73]
	v_pk_mul_f32 v[234:235], v[74:75], v[74:75]
	v_pk_mul_f32 v[236:237], v[76:77], v[76:77]
	v_pk_mul_f32 v[238:239], v[78:79], v[78:79]
	v_pk_fma_f32 v[232:233], v[80:81], v[80:81], v[232:233]
	v_pk_fma_f32 v[234:235], v[82:83], v[82:83], v[234:235]
	v_pk_fma_f32 v[236:237], v[84:85], v[84:85], v[236:237]
	v_pk_fma_f32 v[238:239], v[86:87], v[86:87], v[238:239]
	v_pk_fma_f32 v[232:233], v[88:89], v[88:89], v[232:233]
	v_pk_fma_f32 v[234:235], v[90:91], v[90:91], v[234:235]
	v_pk_fma_f32 v[236:237], v[92:93], v[92:93], v[236:237]
	v_pk_fma_f32 v[238:239], v[94:95], v[94:95], v[238:239]
	v_pk_fma_f32 v[232:233], v[96:97], v[96:97], v[232:233]
	v_pk_fma_f32 v[234:235], v[98:99], v[98:99], v[234:235]
	v_pk_fma_f32 v[236:237], v[100:101], v[100:101], v[236:237]
	v_pk_fma_f32 v[238:239], v[102:103], v[102:103], v[238:239]
	v_pk_add_f32 v[232:233], v[232:233], v[234:235]
	v_pk_add_f32 v[236:237], v[236:237], v[238:239]
	v_pk_add_f32 v[232:233], v[232:233], v[236:237]
	v_add_f32_e32 v240, v232, v233
	s_nop 1
	v_add_f32_dpp v240, v240, v240 quad_perm:[1,0,3,2] row_mask:0xf bank_mask:0xf
	s_nop 1
	v_add_f32_dpp v240, v240, v240 quad_perm:[2,3,0,1] row_mask:0xf bank_mask:0xf
	s_nop 1
	v_add_f32_dpp v240, v240, v240 row_half_mirror row_mask:0xf bank_mask:0xf
	s_nop 1
	v_add_f32_dpp v240, v240, v240 row_mirror row_mask:0xf bank_mask:0xf
	s_nop 1
	v_readlane_b32 s0, v240, 0
	v_readlane_b32 s1, v240, 16
	v_readlane_b32 s4, v240, 32
	v_readlane_b32 s5, v240, 48
	v_mov_b32_e32 v249, 0x358637bd
	s_nop 1
	v_mov_b32_e32 v240, s0
	v_add_f32_e32 v240, s1, v240
	v_add_f32_e32 v240, s4, v240
	v_add_f32_e32 v240, s5, v240
	v_fmamk_f32 v240, v240, 0x3a000000, v249
	s_mov_b32 s0, 0xf800000
	v_mul_f32_e32 v241, 0x4f800000, v240
	v_cmp_gt_f32_e32 vcc, s0, v240
	s_nop 1
	v_cndmask_b32_e32 v240, v240, v241, vcc
	v_sqrt_f32_e32 v241, v240
	s_nop 0
	v_add_u32_e32 v242, -1, v241
	v_fma_f32 v243, -v242, v241, v240
	v_cmp_ge_f32_e64 s[0:1], 0, v243
	v_add_u32_e32 v243, 1, v241
	s_nop 0
	v_cndmask_b32_e64 v242, v241, v242, s[0:1]
	v_fma_f32 v241, -v243, v241, v240
	v_cmp_lt_f32_e64 s[0:1], 0, v241
	s_nop 1
	v_cndmask_b32_e64 v241, v242, v243, s[0:1]
	v_mul_f32_e32 v242, 0x37800000, v241
	v_cndmask_b32_e32 v241, v241, v242, vcc
	v_cmp_class_f32_e32 vcc, v240, v248
	s_nop 1
	v_cndmask_b32_e32 v240, v241, v240, vcc
	v_div_scale_f32 v241, s[0:1], v240, v240, 1.0
	v_rcp_f32_e32 v242, v241
	s_nop 0
	v_fma_f32 v243, -v241, v242, 1.0
	v_fmac_f32_e32 v242, v243, v242
	v_div_scale_f32 v243, vcc, 1.0, v240, 1.0
	v_mul_f32_e32 v244, v243, v242
	v_fma_f32 v247, -v241, v244, v243
	v_fmac_f32_e32 v244, v247, v242
	v_fma_f32 v241, -v241, v244, v243
	s_nop 1
	v_div_fmas_f32 v241, v241, v242, v244
	v_div_fixup_f32 v246, v241, v240, 1.0
	v_pk_mul_f32 v[72:73], v[72:73], v[246:247] op_sel_hi:[1,0]
	v_pk_mul_f32 v[74:75], v[74:75], v[246:247] op_sel_hi:[1,0]
	v_pk_mul_f32 v[76:77], v[76:77], v[246:247] op_sel_hi:[1,0]
	v_pk_mul_f32 v[78:79], v[78:79], v[246:247] op_sel_hi:[1,0]
	v_pk_mul_f32 v[80:81], v[80:81], v[246:247] op_sel_hi:[1,0]
	v_pk_mul_f32 v[82:83], v[82:83], v[246:247] op_sel_hi:[1,0]
	v_pk_mul_f32 v[84:85], v[84:85], v[246:247] op_sel_hi:[1,0]
	v_pk_mul_f32 v[86:87], v[86:87], v[246:247] op_sel_hi:[1,0]
	v_pk_mul_f32 v[88:89], v[88:89], v[246:247] op_sel_hi:[1,0]
	v_pk_mul_f32 v[90:91], v[90:91], v[246:247] op_sel_hi:[1,0]
	v_pk_mul_f32 v[92:93], v[92:93], v[246:247] op_sel_hi:[1,0]
	v_pk_mul_f32 v[94:95], v[94:95], v[246:247] op_sel_hi:[1,0]
	v_pk_mul_f32 v[96:97], v[96:97], v[246:247] op_sel_hi:[1,0]
	v_pk_mul_f32 v[98:99], v[98:99], v[246:247] op_sel_hi:[1,0]
	v_pk_mul_f32 v[100:101], v[100:101], v[246:247] op_sel_hi:[1,0]
	v_pk_mul_f32 v[102:103], v[102:103], v[246:247] op_sel_hi:[1,0]
	s_add_u32 s8, s10, 0xe0000
	s_addc_u32 s9, s11, 0
	v_pk_fma_f32 v[72:73], v[8:9], v[72:73], v[40:41]
	v_cvt_pk_bf16_f32 v232, v72, v73
	v_pk_fma_f32 v[74:75], v[10:11], v[74:75], v[42:43]
	v_cvt_pk_bf16_f32 v233, v74, v75
	v_pk_fma_f32 v[76:77], v[12:13], v[76:77], v[44:45]
	v_cvt_pk_bf16_f32 v234, v76, v77
	v_pk_fma_f32 v[78:79], v[14:15], v[78:79], v[46:47]
	v_cvt_pk_bf16_f32 v235, v78, v79
	global_store_dwordx4 v1, v[232:235], s[8:9] offset:0
	v_pk_fma_f32 v[80:81], v[16:17], v[80:81], v[48:49]
	v_cvt_pk_bf16_f32 v236, v80, v81
	v_pk_fma_f32 v[82:83], v[18:19], v[82:83], v[50:51]
	v_cvt_pk_bf16_f32 v237, v82, v83
	v_pk_fma_f32 v[84:85], v[20:21], v[84:85], v[52:53]
	v_cvt_pk_bf16_f32 v238, v84, v85
	v_pk_fma_f32 v[86:87], v[22:23], v[86:87], v[54:55]
	v_cvt_pk_bf16_f32 v239, v86, v87
	global_store_dwordx4 v1, v[236:239], s[8:9] offset:1024
	v_pk_fma_f32 v[88:89], v[24:25], v[88:89], v[56:57]
	v_cvt_pk_bf16_f32 v232, v88, v89
	v_pk_fma_f32 v[90:91], v[26:27], v[90:91], v[58:59]
	v_cvt_pk_bf16_f32 v233, v90, v91
	v_pk_fma_f32 v[92:93], v[28:29], v[92:93], v[60:61]
	v_cvt_pk_bf16_f32 v234, v92, v93
	v_pk_fma_f32 v[94:95], v[30:31], v[94:95], v[62:63]
	v_cvt_pk_bf16_f32 v235, v94, v95
	global_store_dwordx4 v1, v[232:235], s[8:9] offset:2048
	v_pk_fma_f32 v[96:97], v[32:33], v[96:97], v[64:65]
	v_cvt_pk_bf16_f32 v236, v96, v97
	v_pk_fma_f32 v[98:99], v[34:35], v[98:99], v[66:67]
	v_cvt_pk_bf16_f32 v237, v98, v99
	v_pk_fma_f32 v[100:101], v[36:37], v[100:101], v[68:69]
	v_cvt_pk_bf16_f32 v238, v100, v101
	v_pk_fma_f32 v[102:103], v[38:39], v[102:103], v[70:71]
	v_cvt_pk_bf16_f32 v239, v102, v103
	global_store_dwordx4 v1, v[236:239], s[8:9] offset:3072
	s_branch .LBB0_2042
.Lnorm_fb_3:
	s_mov_b64 s[6:7], s[88:89]
	v_mov_b32_e32 v1, v0
	s_mov_b32 s0, s72
	s_add_i32 s0, 0, 0x2416c
	s_waitcnt vmcnt(31)
	v_mov_b32_e32 v2, s0
	s_add_i32 s0, 0, 0x24170
	ds_read_b32 v2, v2
	s_waitcnt vmcnt(30)
	v_mov_b32_e32 v3, s0
	ds_read_b32 v3, v3
	v_readfirstlane_b32 s0, v1
	s_ashr_i32 s1, s0, 6
	s_waitcnt lgkmcnt(1)
	v_readfirstlane_b32 s5, v2
	s_cmp_lt_i32 s5, 1
	s_waitcnt lgkmcnt(0)
	v_readfirstlane_b32 s10, v3
	s_cbranch_scc0 .LBB0_2033
	s_lshl_b32 s0, s72, 3
	s_add_i32 s0, s1, s0
	s_lshl_b32 s4, s38, 3
	s_movk_i32 s14, 0x4000
	s_cbranch_execz .LBB0_2034
	s_branch .LBB0_2035

.LBB0_2488:
	v_readlane_b32 s4, v250, 12
	s_cmp_lt_i32 s4, 21
	s_cselect_b64 s[0:1], -1, 0
	s_and_b64 s[2:3], s[0:1], s[2:3]
	s_andn2_b64 vcc, exec, s[2:3]
	v_readlane_b32 s5, v250, 13
	v_readlane_b32 s6, v250, 14
	v_readlane_b32 s7, v250, 15
	s_cbranch_vccnz .LBB0_2500
	v_and_b32_e32 v1, 63, v0
	v_lshlrev_b32_e32 v2, 5, v1
	v_add_u32_e32 v3, 0x1000, v2
	v_lshlrev_b32_e32 v1, 4, v1
	v_mov_b32_e32 v4, 0x2416c
	ds_read_b32 v5, v4
	ds_read_b32 v6, v4 offset:4
	v_readfirstlane_b32 s0, v0
	s_lshr_b32 s1, s0, 6
	s_waitcnt lgkmcnt(0)
	v_readfirstlane_b32 s4, v5
	v_readfirstlane_b32 s5, v6
	s_cmp_lt_i32 s4, 1
	s_cbranch_scc1 .Lnorm_fb_4
	s_add_i32 s4, s4, -1
	s_lshl_b32 s18, s4, 8
	s_lshl_b32 s19, s5, 3
	s_add_i32 s18, s18, s19
	s_add_i32 s18, s18, s1
	s_lshr_b32 s19, s4, 4
	s_lshl_b32 s20, s18, 12
	s_add_u32 s6, s88, 0x45c00000
	s_addc_u32 s7, s89, 0
	s_add_u32 s6, s6, s20
	s_addc_u32 s7, s7, 0
	s_add_u32 s10, s88, 0x13e00000
	s_addc_u32 s11, s89, 0
	s_add_u32 s10, s10, s20
	s_addc_u32 s11, s11, 0
	s_add_u32 s12, s44, 0xa000
	s_addc_u32 s13, s45, 0
	s_mul_i32 s21, s19, 0x12000
	s_add_u32 s14, s88, 0x154000
	s_addc_u32 s15, s89, 0
	s_add_u32 s14, s14, s21
	s_addc_u32 s15, s15, 0
	s_add_u32 s16, s88, 0x156000
	s_addc_u32 s17, s89, 0
	s_add_u32 s16, s16, s21
	s_addc_u32 s17, s17, 0
	global_load_dwordx4 v[72:75], v2, s[12:13] offset:0
	global_load_dwordx4 v[76:79], v2, s[12:13] offset:16
	global_load_dwordx4 v[80:83], v2, s[12:13] offset:2048
	global_load_dwordx4 v[84:87], v2, s[12:13] offset:2064
	global_load_dwordx4 v[88:91], v3, s[12:13] offset:0
	global_load_dwordx4 v[92:95], v3, s[12:13] offset:16
	global_load_dwordx4 v[96:99], v3, s[12:13] offset:2048
	global_load_dwordx4 v[100:103], v3, s[12:13] offset:2064
	global_load_dwordx4 v[8:11], v2, s[16:17] offset:0
	global_load_dwordx4 v[12:15], v2, s[16:17] offset:16
	global_load_dwordx4 v[16:19], v2, s[16:17] offset:2048
	global_load_dwordx4 v[20:23], v2, s[16:17] offset:2064
	global_load_dwordx4 v[24:27], v3, s[16:17] offset:0
	global_load_dwordx4 v[28:31], v3, s[16:17] offset:16
	global_load_dwordx4 v[32:35], v3, s[16:17] offset:2048
	global_load_dwordx4 v[36:39], v3, s[16:17] offset:2064
	global_load_dwordx4 v[40:43], v2, s[14:15] offset:0
	global_load_dwordx4 v[44:47], v2, s[14:15] offset:16
	global_load_dwordx4 v[48:51], v2, s[14:15] offset:2048
	global_load_dwordx4 v[52:55], v2, s[14:15] offset:2064
	global_load_dwordx4 v[56:59], v3, s[14:15] offset:0
	global_load_dwordx4 v[60:63], v3, s[14:15] offset:16
	global_load_dwordx4 v[64:67], v3, s[14:15] offset:2048
	global_load_dwordx4 v[68:71], v3, s[14:15] offset:2064
	s_add_u32 s8, s6, 0x0
	s_addc_u32 s9, s7, 0
	global_load_dwordx4 v[104:107], v1, s[8:9] offset:0 nt
	global_load_dwordx4 v[108:111], v1, s[8:9] offset:1024 nt
	global_load_dwordx4 v[112:115], v1, s[8:9] offset:2048 nt
	global_load_dwordx4 v[116:119], v1, s[8:9] offset:3072 nt
	s_add_u32 s8, s6, 0x20000
	s_addc_u32 s9, s7, 0
	global_load_dwordx4 v[120:123], v1, s[8:9] offset:0 nt
	global_load_dwordx4 v[124:127], v1, s[8:9] offset:1024 nt
	global_load_dwordx4 v[128:131], v1, s[8:9] offset:2048 nt
	global_load_dwordx4 v[132:135], v1, s[8:9] offset:3072 nt
	s_add_u32 s8, s6, 0x40000
	s_addc_u32 s9, s7, 0
	global_load_dwordx4 v[136:139], v1, s[8:9] offset:0 nt
	global_load_dwordx4 v[140:143], v1, s[8:9] offset:1024 nt
	global_load_dwordx4 v[144:147], v1, s[8:9] offset:2048 nt
	global_load_dwordx4 v[148:151], v1, s[8:9] offset:3072 nt
	s_add_u32 s8, s6, 0x60000
	s_addc_u32 s9, s7, 0
	global_load_dwordx4 v[152:155], v1, s[8:9] offset:0 nt
	global_load_dwordx4 v[156:159], v1, s[8:9] offset:1024 nt
	global_load_dwordx4 v[160:163], v1, s[8:9] offset:2048 nt
	global_load_dwordx4 v[164:167], v1, s[8:9] offset:3072 nt
	s_add_u32 s8, s6, 0x80000
	s_addc_u32 s9, s7, 0
	global_load_dwordx4 v[168:171], v1, s[8:9] offset:0 nt
	global_load_dwordx4 v[172:175], v1, s[8:9] offset:1024 nt
	global_load_dwordx4 v[176:179], v1, s[8:9] offset:2048 nt
	global_load_dwordx4 v[180:183], v1, s[8:9] offset:3072 nt
	s_add_u32 s8, s6, 0xa0000
	s_addc_u32 s9, s7, 0
	global_load_dwordx4 v[184:187], v1, s[8:9] offset:0 nt
	global_load_dwordx4 v[188:191], v1, s[8:9] offset:1024 nt
	global_load_dwordx4 v[192:195], v1, s[8:9] offset:2048 nt
	global_load_dwordx4 v[196:199], v1, s[8:9] offset:3072 nt
	s_add_u32 s8, s6, 0xc0000
	s_addc_u32 s9, s7, 0
	global_load_dwordx4 v[200:203], v1, s[8:9] offset:0 nt
	global_load_dwordx4 v[204:207], v1, s[8:9] offset:1024 nt
	global_load_dwordx4 v[208:211], v1, s[8:9] offset:2048 nt
	global_load_dwordx4 v[212:215], v1, s[8:9] offset:3072 nt
	s_add_u32 s8, s6, 0xe0000
	s_addc_u32 s9, s7, 0
	global_load_dwordx4 v[216:219], v1, s[8:9] offset:0 nt
	global_load_dwordx4 v[220:223], v1, s[8:9] offset:1024 nt
	global_load_dwordx4 v[224:227], v1, s[8:9] offset:2048 nt
	global_load_dwordx4 v[228:231], v1, s[8:9] offset:3072 nt
	s_waitcnt vmcnt(32)
	v_pk_add_f32 v[8:9], v[8:9], 1.0 op_sel_hi:[1,0]
	v_pk_add_f32 v[10:11], v[10:11], 1.0 op_sel_hi:[1,0]
	v_pk_add_f32 v[12:13], v[12:13], 1.0 op_sel_hi:[1,0]
	v_pk_add_f32 v[14:15], v[14:15], 1.0 op_sel_hi:[1,0]
	v_pk_add_f32 v[16:17], v[16:17], 1.0 op_sel_hi:[1,0]
	v_pk_add_f32 v[18:19], v[18:19], 1.0 op_sel_hi:[1,0]
	v_pk_add_f32 v[20:21], v[20:21], 1.0 op_sel_hi:[1,0]
	v_pk_add_f32 v[22:23], v[22:23], 1.0 op_sel_hi:[1,0]
	v_pk_add_f32 v[24:25], v[24:25], 1.0 op_sel_hi:[1,0]
	v_pk_add_f32 v[26:27], v[26:27], 1.0 op_sel_hi:[1,0]
	v_pk_add_f32 v[28:29], v[28:29], 1.0 op_sel_hi:[1,0]
	v_pk_add_f32 v[30:31], v[30:31], 1.0 op_sel_hi:[1,0]
	v_pk_add_f32 v[32:33], v[32:33], 1.0 op_sel_hi:[1,0]
	v_pk_add_f32 v[34:35], v[34:35], 1.0 op_sel_hi:[1,0]
	v_pk_add_f32 v[36:37], v[36:37], 1.0 op_sel_hi:[1,0]
	v_pk_add_f32 v[38:39], v[38:39], 1.0 op_sel_hi:[1,0]
	v_pk_mul_f32 v[8:9], v[72:73], v[8:9]
	v_pk_mul_f32 v[10:11], v[74:75], v[10:11]
	v_pk_mul_f32 v[12:13], v[76:77], v[12:13]
	v_pk_mul_f32 v[14:15], v[78:79], v[14:15]
	v_pk_mul_f32 v[16:17], v[80:81], v[16:17]
	v_pk_mul_f32 v[18:19], v[82:83], v[18:19]
	v_pk_mul_f32 v[20:21], v[84:85], v[20:21]
	v_pk_mul_f32 v[22:23], v[86:87], v[22:23]
	v_pk_mul_f32 v[24:25], v[88:89], v[24:25]
	v_pk_mul_f32 v[26:27], v[90:91], v[26:27]
	v_pk_mul_f32 v[28:29], v[92:93], v[28:29]
	v_pk_mul_f32 v[30:31], v[94:95], v[30:31]
	v_pk_mul_f32 v[32:33], v[96:97], v[32:33]
	v_pk_mul_f32 v[34:35], v[98:99], v[34:35]
	v_pk_mul_f32 v[36:37], v[100:101], v[36:37]
	v_pk_mul_f32 v[38:39], v[102:103], v[38:39]
	v_mov_b32_e32 v248, 0x260
	s_waitcnt vmcnt(28)
	v_cvt_f32_f16_e32 v72, v104
	v_cvt_f32_f16_sdwa v73, v104 dst_sel:DWORD dst_unused:UNUSED_PAD src0_sel:WORD_1
	v_cvt_f32_f16_e32 v74, v105
	v_cvt_f32_f16_sdwa v75, v105 dst_sel:DWORD dst_unused:UNUSED_PAD src0_sel:WORD_1
	v_cvt_f32_f16_e32 v76, v106
	v_cvt_f32_f16_sdwa v77, v106 dst_sel:DWORD dst_unused:UNUSED_PAD src0_sel:WORD_1
	v_cvt_f32_f16_e32 v78, v107
	v_cvt_f32_f16_sdwa v79, v107 dst_sel:DWORD dst_unused:UNUSED_PAD src0_sel:WORD_1
	v_cvt_f32_f16_e32 v80, v108
	v_cvt_f32_f16_sdwa v81, v108 dst_sel:DWORD dst_unused:UNUSED_PAD src0_sel:WORD_1
	v_cvt_f32_f16_e32 v82, v109
	v_cvt_f32_f16_sdwa v83, v109 dst_sel:DWORD dst_unused:UNUSED_PAD src0_sel:WORD_1
	v_cvt_f32_f16_e32 v84, v110
	v_cvt_f32_f16_sdwa v85, v110 dst_sel:DWORD dst_unused:UNUSED_PAD src0_sel:WORD_1
	v_cvt_f32_f16_e32 v86, v111
	v_cvt_f32_f16_sdwa v87, v111 dst_sel:DWORD dst_unused:UNUSED_PAD src0_sel:WORD_1
	v_cvt_f32_f16_e32 v88, v112
	v_cvt_f32_f16_sdwa v89, v112 dst_sel:DWORD dst_unused:UNUSED_PAD src0_sel:WORD_1
	v_cvt_f32_f16_e32 v90, v113
	v_cvt_f32_f16_sdwa v91, v113 dst_sel:DWORD dst_unused:UNUSED_PAD src0_sel:WORD_1
	v_cvt_f32_f16_e32 v92, v114
	v_cvt_f32_f16_sdwa v93, v114 dst_sel:DWORD dst_unused:UNUSED_PAD src0_sel:WORD_1
	v_cvt_f32_f16_e32 v94, v115
	v_cvt_f32_f16_sdwa v95, v115 dst_sel:DWORD dst_unused:UNUSED_PAD src0_sel:WORD_1
	v_cvt_f32_f16_e32 v96, v116
	v_cvt_f32_f16_sdwa v97, v116 dst_sel:DWORD dst_unused:UNUSED_PAD src0_sel:WORD_1
	v_cvt_f32_f16_e32 v98, v117
	v_cvt_f32_f16_sdwa v99, v117 dst_sel:DWORD dst_unused:UNUSED_PAD src0_sel:WORD_1
	v_cvt_f32_f16_e32 v100, v118
	v_cvt_f32_f16_sdwa v101, v118 dst_sel:DWORD dst_unused:UNUSED_PAD src0_sel:WORD_1
	v_cvt_f32_f16_e32 v102, v119
	v_cvt_f32_f16_sdwa v103, v119 dst_sel:DWORD dst_unused:UNUSED_PAD src0_sel:WORD_1
	v_pk_mul_f32 v[232:233], v[72:73], v[72:73]
	v_pk_mul_f32 v[234:235], v[74:75], v[74:75]
	v_pk_mul_f32 v[236:237], v[76:77], v[76:77]
	v_pk_mul_f32 v[238:239], v[78:79], v[78:79]
	v_pk_fma_f32 v[232:233], v[80:81], v[80:81], v[232:233]
	v_pk_fma_f32 v[234:235], v[82:83], v[82:83], v[234:235]
	v_pk_fma_f32 v[236:237], v[84:85], v[84:85], v[236:237]
	v_pk_fma_f32 v[238:239], v[86:87], v[86:87], v[238:239]
	v_pk_fma_f32 v[232:233], v[88:89], v[88:89], v[232:233]
	v_pk_fma_f32 v[234:235], v[90:91], v[90:91], v[234:235]
	v_pk_fma_f32 v[236:237], v[92:93], v[92:93], v[236:237]
	v_pk_fma_f32 v[238:239], v[94:95], v[94:95], v[238:239]
	v_pk_fma_f32 v[232:233], v[96:97], v[96:97], v[232:233]
	v_pk_fma_f32 v[234:235], v[98:99], v[98:99], v[234:235]
	v_pk_fma_f32 v[236:237], v[100:101], v[100:101], v[236:237]
	v_pk_fma_f32 v[238:239], v[102:103], v[102:103], v[238:239]
	v_pk_add_f32 v[232:233], v[232:233], v[234:235]
	v_pk_add_f32 v[236:237], v[236:237], v[238:239]
	v_pk_add_f32 v[232:233], v[232:233], v[236:237]
	v_add_f32_e32 v240, v232, v233
	s_nop 1
	v_add_f32_dpp v240, v240, v240 quad_perm:[1,0,3,2] row_mask:0xf bank_mask:0xf
	s_nop 1
	v_add_f32_dpp v240, v240, v240 quad_perm:[2,3,0,1] row_mask:0xf bank_mask:0xf
	s_nop 1
	v_add_f32_dpp v240, v240, v240 row_half_mirror row_mask:0xf bank_mask:0xf
	s_nop 1
	v_add_f32_dpp v240, v240, v240 row_mirror row_mask:0xf bank_mask:0xf
	s_nop 1
	v_readlane_b32 s0, v240, 0
	v_readlane_b32 s1, v240, 16
	v_readlane_b32 s4, v240, 32
	v_readlane_b32 s5, v240, 48
	v_mov_b32_e32 v249, 0x358637bd
	s_nop 1
	v_mov_b32_e32 v240, s0
	v_add_f32_e32 v240, s1, v240
	v_add_f32_e32 v240, s4, v240
	v_add_f32_e32 v240, s5, v240
	v_fmamk_f32 v240, v240, 0x3a000000, v249
	s_mov_b32 s0, 0xf800000
	v_mul_f32_e32 v241, 0x4f800000, v240
	v_cmp_gt_f32_e32 vcc, s0, v240
	s_nop 1
	v_cndmask_b32_e32 v240, v240, v241, vcc
	v_sqrt_f32_e32 v241, v240
	s_nop 0
	v_add_u32_e32 v242, -1, v241
	v_fma_f32 v243, -v242, v241, v240
	v_cmp_ge_f32_e64 s[0:1], 0, v243
	v_add_u32_e32 v243, 1, v241
	s_nop 0
	v_cndmask_b32_e64 v242, v241, v242, s[0:1]
	v_fma_f32 v241, -v243, v241, v240
	v_cmp_lt_f32_e64 s[0:1], 0, v241
	s_nop 1
	v_cndmask_b32_e64 v241, v242, v243, s[0:1]
	v_mul_f32_e32 v242, 0x37800000, v241
	v_cndmask_b32_e32 v241, v241, v242, vcc
	v_cmp_class_f32_e32 vcc, v240, v248
	s_nop 1
	v_cndmask_b32_e32 v240, v241, v240, vcc
	v_div_scale_f32 v241, s[0:1], v240, v240, 1.0
	v_rcp_f32_e32 v242, v241
	s_nop 0
	v_fma_f32 v243, -v241, v242, 1.0
	v_fmac_f32_e32 v242, v243, v242
	v_div_scale_f32 v243, vcc, 1.0, v240, 1.0
	v_mul_f32_e32 v244, v243, v242
	v_fma_f32 v247, -v241, v244, v243
	v_fmac_f32_e32 v244, v247, v242
	v_fma_f32 v241, -v241, v244, v243
	s_nop 1
	v_div_fmas_f32 v241, v241, v242, v244
	v_div_fixup_f32 v246, v241, v240, 1.0
	v_pk_mul_f32 v[72:73], v[72:73], v[246:247] op_sel_hi:[1,0]
	v_pk_mul_f32 v[74:75], v[74:75], v[246:247] op_sel_hi:[1,0]
	v_pk_mul_f32 v[76:77], v[76:77], v[246:247] op_sel_hi:[1,0]
	v_pk_mul_f32 v[78:79], v[78:79], v[246:247] op_sel_hi:[1,0]
	v_pk_mul_f32 v[80:81], v[80:81], v[246:247] op_sel_hi:[1,0]
	v_pk_mul_f32 v[82:83], v[82:83], v[246:247] op_sel_hi:[1,0]
	v_pk_mul_f32 v[84:85], v[84:85], v[246:247] op_sel_hi:[1,0]
	v_pk_mul_f32 v[86:87], v[86:87], v[246:247] op_sel_hi:[1,0]
	v_pk_mul_f32 v[88:89], v[88:89], v[246:247] op_sel_hi:[1,0]
	v_pk_mul_f32 v[90:91], v[90:91], v[246:247] op_sel_hi:[1,0]
	v_pk_mul_f32 v[92:93], v[92:93], v[246:247] op_sel_hi:[1,0]
	v_pk_mul_f32 v[94:95], v[94:95], v[246:247] op_sel_hi:[1,0]
	v_pk_mul_f32 v[96:97], v[96:97], v[246:247] op_sel_hi:[1,0]
	v_pk_mul_f32 v[98:99], v[98:99], v[246:247] op_sel_hi:[1,0]
	v_pk_mul_f32 v[100:101], v[100:101], v[246:247] op_sel_hi:[1,0]
	v_pk_mul_f32 v[102:103], v[102:103], v[246:247] op_sel_hi:[1,0]
	s_add_u32 s8, s10, 0x0
	s_addc_u32 s9, s11, 0
	v_pk_fma_f32 v[72:73], v[8:9], v[72:73], v[40:41]
	v_cvt_pk_bf16_f32 v232, v72, v73
	v_pk_fma_f32 v[74:75], v[10:11], v[74:75], v[42:43]
	v_cvt_pk_bf16_f32 v233, v74, v75
	v_pk_fma_f32 v[76:77], v[12:13], v[76:77], v[44:45]
	v_cvt_pk_bf16_f32 v234, v76, v77
	v_pk_fma_f32 v[78:79], v[14:15], v[78:79], v[46:47]
	v_cvt_pk_bf16_f32 v235, v78, v79
	global_store_dwordx4 v1, v[232:235], s[8:9] offset:0
	v_pk_fma_f32 v[80:81], v[16:17], v[80:81], v[48:49]
	v_cvt_pk_bf16_f32 v236, v80, v81
	v_pk_fma_f32 v[82:83], v[18:19], v[82:83], v[50:51]
	v_cvt_pk_bf16_f32 v237, v82, v83
	v_pk_fma_f32 v[84:85], v[20:21], v[84:85], v[52:53]
	v_cvt_pk_bf16_f32 v238, v84, v85
	v_pk_fma_f32 v[86:87], v[22:23], v[86:87], v[54:55]
	v_cvt_pk_bf16_f32 v239, v86, v87
	global_store_dwordx4 v1, v[236:239], s[8:9] offset:1024
	v_pk_fma_f32 v[88:89], v[24:25], v[88:89], v[56:57]
	v_cvt_pk_bf16_f32 v232, v88, v89
	v_pk_fma_f32 v[90:91], v[26:27], v[90:91], v[58:59]
	v_cvt_pk_bf16_f32 v233, v90, v91
	v_pk_fma_f32 v[92:93], v[28:29], v[92:93], v[60:61]
	v_cvt_pk_bf16_f32 v234, v92, v93
	v_pk_fma_f32 v[94:95], v[30:31], v[94:95], v[62:63]
	v_cvt_pk_bf16_f32 v235, v94, v95
	global_store_dwordx4 v1, v[232:235], s[8:9] offset:2048
	v_pk_fma_f32 v[96:97], v[32:33], v[96:97], v[64:65]
	v_cvt_pk_bf16_f32 v236, v96, v97
	v_pk_fma_f32 v[98:99], v[34:35], v[98:99], v[66:67]
	v_cvt_pk_bf16_f32 v237, v98, v99
	v_pk_fma_f32 v[100:101], v[36:37], v[100:101], v[68:69]
	v_cvt_pk_bf16_f32 v238, v100, v101
	v_pk_fma_f32 v[102:103], v[38:39], v[102:103], v[70:71]
	v_cvt_pk_bf16_f32 v239, v102, v103
	global_store_dwordx4 v1, v[236:239], s[8:9] offset:3072
	s_waitcnt vmcnt(28)
	v_cvt_f32_f16_e32 v72, v120
	v_cvt_f32_f16_sdwa v73, v120 dst_sel:DWORD dst_unused:UNUSED_PAD src0_sel:WORD_1
	v_cvt_f32_f16_e32 v74, v121
	v_cvt_f32_f16_sdwa v75, v121 dst_sel:DWORD dst_unused:UNUSED_PAD src0_sel:WORD_1
	v_cvt_f32_f16_e32 v76, v122
	v_cvt_f32_f16_sdwa v77, v122 dst_sel:DWORD dst_unused:UNUSED_PAD src0_sel:WORD_1
	v_cvt_f32_f16_e32 v78, v123
	v_cvt_f32_f16_sdwa v79, v123 dst_sel:DWORD dst_unused:UNUSED_PAD src0_sel:WORD_1
	v_cvt_f32_f16_e32 v80, v124
	v_cvt_f32_f16_sdwa v81, v124 dst_sel:DWORD dst_unused:UNUSED_PAD src0_sel:WORD_1
	v_cvt_f32_f16_e32 v82, v125
	v_cvt_f32_f16_sdwa v83, v125 dst_sel:DWORD dst_unused:UNUSED_PAD src0_sel:WORD_1
	v_cvt_f32_f16_e32 v84, v126
	v_cvt_f32_f16_sdwa v85, v126 dst_sel:DWORD dst_unused:UNUSED_PAD src0_sel:WORD_1
	v_cvt_f32_f16_e32 v86, v127
	v_cvt_f32_f16_sdwa v87, v127 dst_sel:DWORD dst_unused:UNUSED_PAD src0_sel:WORD_1
	v_cvt_f32_f16_e32 v88, v128
	v_cvt_f32_f16_sdwa v89, v128 dst_sel:DWORD dst_unused:UNUSED_PAD src0_sel:WORD_1
	v_cvt_f32_f16_e32 v90, v129
	v_cvt_f32_f16_sdwa v91, v129 dst_sel:DWORD dst_unused:UNUSED_PAD src0_sel:WORD_1
	v_cvt_f32_f16_e32 v92, v130
	v_cvt_f32_f16_sdwa v93, v130 dst_sel:DWORD dst_unused:UNUSED_PAD src0_sel:WORD_1
	v_cvt_f32_f16_e32 v94, v131
	v_cvt_f32_f16_sdwa v95, v131 dst_sel:DWORD dst_unused:UNUSED_PAD src0_sel:WORD_1
	v_cvt_f32_f16_e32 v96, v132
	v_cvt_f32_f16_sdwa v97, v132 dst_sel:DWORD dst_unused:UNUSED_PAD src0_sel:WORD_1
	v_cvt_f32_f16_e32 v98, v133
	v_cvt_f32_f16_sdwa v99, v133 dst_sel:DWORD dst_unused:UNUSED_PAD src0_sel:WORD_1
	v_cvt_f32_f16_e32 v100, v134
	v_cvt_f32_f16_sdwa v101, v134 dst_sel:DWORD dst_unused:UNUSED_PAD src0_sel:WORD_1
	v_cvt_f32_f16_e32 v102, v135
	v_cvt_f32_f16_sdwa v103, v135 dst_sel:DWORD dst_unused:UNUSED_PAD src0_sel:WORD_1
	v_pk_mul_f32 v[232:233], v[72:73], v[72:73]
	v_pk_mul_f32 v[234:235], v[74:75], v[74:75]
	v_pk_mul_f32 v[236:237], v[76:77], v[76:77]
	v_pk_mul_f32 v[238:239], v[78:79], v[78:79]
	v_pk_fma_f32 v[232:233], v[80:81], v[80:81], v[232:233]
	v_pk_fma_f32 v[234:235], v[82:83], v[82:83], v[234:235]
	v_pk_fma_f32 v[236:237], v[84:85], v[84:85], v[236:237]
	v_pk_fma_f32 v[238:239], v[86:87], v[86:87], v[238:239]
	v_pk_fma_f32 v[232:233], v[88:89], v[88:89], v[232:233]
	v_pk_fma_f32 v[234:235], v[90:91], v[90:91], v[234:235]
	v_pk_fma_f32 v[236:237], v[92:93], v[92:93], v[236:237]
	v_pk_fma_f32 v[238:239], v[94:95], v[94:95], v[238:239]
	v_pk_fma_f32 v[232:233], v[96:97], v[96:97], v[232:233]
	v_pk_fma_f32 v[234:235], v[98:99], v[98:99], v[234:235]
	v_pk_fma_f32 v[236:237], v[100:101], v[100:101], v[236:237]
	v_pk_fma_f32 v[238:239], v[102:103], v[102:103], v[238:239]
	v_pk_add_f32 v[232:233], v[232:233], v[234:235]
	v_pk_add_f32 v[236:237], v[236:237], v[238:239]
	v_pk_add_f32 v[232:233], v[232:233], v[236:237]
	v_add_f32_e32 v240, v232, v233
	s_nop 1
	v_add_f32_dpp v240, v240, v240 quad_perm:[1,0,3,2] row_mask:0xf bank_mask:0xf
	s_nop 1
	v_add_f32_dpp v240, v240, v240 quad_perm:[2,3,0,1] row_mask:0xf bank_mask:0xf
	s_nop 1
	v_add_f32_dpp v240, v240, v240 row_half_mirror row_mask:0xf bank_mask:0xf
	s_nop 1
	v_add_f32_dpp v240, v240, v240 row_mirror row_mask:0xf bank_mask:0xf
	s_nop 1
	v_readlane_b32 s0, v240, 0
	v_readlane_b32 s1, v240, 16
	v_readlane_b32 s4, v240, 32
	v_readlane_b32 s5, v240, 48
	v_mov_b32_e32 v249, 0x358637bd
	s_nop 1
	v_mov_b32_e32 v240, s0
	v_add_f32_e32 v240, s1, v240
	v_add_f32_e32 v240, s4, v240
	v_add_f32_e32 v240, s5, v240
	v_fmamk_f32 v240, v240, 0x3a000000, v249
	s_mov_b32 s0, 0xf800000
	v_mul_f32_e32 v241, 0x4f800000, v240
	v_cmp_gt_f32_e32 vcc, s0, v240
	s_nop 1
	v_cndmask_b32_e32 v240, v240, v241, vcc
	v_sqrt_f32_e32 v241, v240
	s_nop 0
	v_add_u32_e32 v242, -1, v241
	v_fma_f32 v243, -v242, v241, v240
	v_cmp_ge_f32_e64 s[0:1], 0, v243
	v_add_u32_e32 v243, 1, v241
	s_nop 0
	v_cndmask_b32_e64 v242, v241, v242, s[0:1]
	v_fma_f32 v241, -v243, v241, v240
	v_cmp_lt_f32_e64 s[0:1], 0, v241
	s_nop 1
	v_cndmask_b32_e64 v241, v242, v243, s[0:1]
	v_mul_f32_e32 v242, 0x37800000, v241
	v_cndmask_b32_e32 v241, v241, v242, vcc
	v_cmp_class_f32_e32 vcc, v240, v248
	s_nop 1
	v_cndmask_b32_e32 v240, v241, v240, vcc
	v_div_scale_f32 v241, s[0:1], v240, v240, 1.0
	v_rcp_f32_e32 v242, v241
	s_nop 0
	v_fma_f32 v243, -v241, v242, 1.0
	v_fmac_f32_e32 v242, v243, v242
	v_div_scale_f32 v243, vcc, 1.0, v240, 1.0
	v_mul_f32_e32 v244, v243, v242
	v_fma_f32 v247, -v241, v244, v243
	v_fmac_f32_e32 v244, v247, v242
	v_fma_f32 v241, -v241, v244, v243
	s_nop 1
	v_div_fmas_f32 v241, v241, v242, v244
	v_div_fixup_f32 v246, v241, v240, 1.0
	v_pk_mul_f32 v[72:73], v[72:73], v[246:247] op_sel_hi:[1,0]
	v_pk_mul_f32 v[74:75], v[74:75], v[246:247] op_sel_hi:[1,0]
	v_pk_mul_f32 v[76:77], v[76:77], v[246:247] op_sel_hi:[1,0]
	v_pk_mul_f32 v[78:79], v[78:79], v[246:247] op_sel_hi:[1,0]
	v_pk_mul_f32 v[80:81], v[80:81], v[246:247] op_sel_hi:[1,0]
	v_pk_mul_f32 v[82:83], v[82:83], v[246:247] op_sel_hi:[1,0]
	v_pk_mul_f32 v[84:85], v[84:85], v[246:247] op_sel_hi:[1,0]
	v_pk_mul_f32 v[86:87], v[86:87], v[246:247] op_sel_hi:[1,0]
	v_pk_mul_f32 v[88:89], v[88:89], v[246:247] op_sel_hi:[1,0]
	v_pk_mul_f32 v[90:91], v[90:91], v[246:247] op_sel_hi:[1,0]
	v_pk_mul_f32 v[92:93], v[92:93], v[246:247] op_sel_hi:[1,0]
	v_pk_mul_f32 v[94:95], v[94:95], v[246:247] op_sel_hi:[1,0]
	v_pk_mul_f32 v[96:97], v[96:97], v[246:247] op_sel_hi:[1,0]
	v_pk_mul_f32 v[98:99], v[98:99], v[246:247] op_sel_hi:[1,0]
	v_pk_mul_f32 v[100:101], v[100:101], v[246:247] op_sel_hi:[1,0]
	v_pk_mul_f32 v[102:103], v[102:103], v[246:247] op_sel_hi:[1,0]
	s_add_u32 s8, s10, 0x20000
	s_addc_u32 s9, s11, 0
	v_pk_fma_f32 v[72:73], v[8:9], v[72:73], v[40:41]
	v_cvt_pk_bf16_f32 v232, v72, v73
	v_pk_fma_f32 v[74:75], v[10:11], v[74:75], v[42:43]
	v_cvt_pk_bf16_f32 v233, v74, v75
	v_pk_fma_f32 v[76:77], v[12:13], v[76:77], v[44:45]
	v_cvt_pk_bf16_f32 v234, v76, v77
	v_pk_fma_f32 v[78:79], v[14:15], v[78:79], v[46:47]
	v_cvt_pk_bf16_f32 v235, v78, v79
	global_store_dwordx4 v1, v[232:235], s[8:9] offset:0
	v_pk_fma_f32 v[80:81], v[16:17], v[80:81], v[48:49]
	v_cvt_pk_bf16_f32 v236, v80, v81
	v_pk_fma_f32 v[82:83], v[18:19], v[82:83], v[50:51]
	v_cvt_pk_bf16_f32 v237, v82, v83
	v_pk_fma_f32 v[84:85], v[20:21], v[84:85], v[52:53]
	v_cvt_pk_bf16_f32 v238, v84, v85
	v_pk_fma_f32 v[86:87], v[22:23], v[86:87], v[54:55]
	v_cvt_pk_bf16_f32 v239, v86, v87
	global_store_dwordx4 v1, v[236:239], s[8:9] offset:1024
	v_pk_fma_f32 v[88:89], v[24:25], v[88:89], v[56:57]
	v_cvt_pk_bf16_f32 v232, v88, v89
	v_pk_fma_f32 v[90:91], v[26:27], v[90:91], v[58:59]
	v_cvt_pk_bf16_f32 v233, v90, v91
	v_pk_fma_f32 v[92:93], v[28:29], v[92:93], v[60:61]
	v_cvt_pk_bf16_f32 v234, v92, v93
	v_pk_fma_f32 v[94:95], v[30:31], v[94:95], v[62:63]
	v_cvt_pk_bf16_f32 v235, v94, v95
	global_store_dwordx4 v1, v[232:235], s[8:9] offset:2048
	v_pk_fma_f32 v[96:97], v[32:33], v[96:97], v[64:65]
	v_cvt_pk_bf16_f32 v236, v96, v97
	v_pk_fma_f32 v[98:99], v[34:35], v[98:99], v[66:67]
	v_cvt_pk_bf16_f32 v237, v98, v99
	v_pk_fma_f32 v[100:101], v[36:37], v[100:101], v[68:69]
	v_cvt_pk_bf16_f32 v238, v100, v101
	v_pk_fma_f32 v[102:103], v[38:39], v[102:103], v[70:71]
	v_cvt_pk_bf16_f32 v239, v102, v103
	global_store_dwordx4 v1, v[236:239], s[8:9] offset:3072
	s_waitcnt vmcnt(28)
	v_cvt_f32_f16_e32 v72, v136
	v_cvt_f32_f16_sdwa v73, v136 dst_sel:DWORD dst_unused:UNUSED_PAD src0_sel:WORD_1
	v_cvt_f32_f16_e32 v74, v137
	v_cvt_f32_f16_sdwa v75, v137 dst_sel:DWORD dst_unused:UNUSED_PAD src0_sel:WORD_1
	v_cvt_f32_f16_e32 v76, v138
	v_cvt_f32_f16_sdwa v77, v138 dst_sel:DWORD dst_unused:UNUSED_PAD src0_sel:WORD_1
	v_cvt_f32_f16_e32 v78, v139
	v_cvt_f32_f16_sdwa v79, v139 dst_sel:DWORD dst_unused:UNUSED_PAD src0_sel:WORD_1
	v_cvt_f32_f16_e32 v80, v140
	v_cvt_f32_f16_sdwa v81, v140 dst_sel:DWORD dst_unused:UNUSED_PAD src0_sel:WORD_1
	v_cvt_f32_f16_e32 v82, v141
	v_cvt_f32_f16_sdwa v83, v141 dst_sel:DWORD dst_unused:UNUSED_PAD src0_sel:WORD_1
	v_cvt_f32_f16_e32 v84, v142
	v_cvt_f32_f16_sdwa v85, v142 dst_sel:DWORD dst_unused:UNUSED_PAD src0_sel:WORD_1
	v_cvt_f32_f16_e32 v86, v143
	v_cvt_f32_f16_sdwa v87, v143 dst_sel:DWORD dst_unused:UNUSED_PAD src0_sel:WORD_1
	v_cvt_f32_f16_e32 v88, v144
	v_cvt_f32_f16_sdwa v89, v144 dst_sel:DWORD dst_unused:UNUSED_PAD src0_sel:WORD_1
	v_cvt_f32_f16_e32 v90, v145
	v_cvt_f32_f16_sdwa v91, v145 dst_sel:DWORD dst_unused:UNUSED_PAD src0_sel:WORD_1
	v_cvt_f32_f16_e32 v92, v146
	v_cvt_f32_f16_sdwa v93, v146 dst_sel:DWORD dst_unused:UNUSED_PAD src0_sel:WORD_1
	v_cvt_f32_f16_e32 v94, v147
	v_cvt_f32_f16_sdwa v95, v147 dst_sel:DWORD dst_unused:UNUSED_PAD src0_sel:WORD_1
	v_cvt_f32_f16_e32 v96, v148
	v_cvt_f32_f16_sdwa v97, v148 dst_sel:DWORD dst_unused:UNUSED_PAD src0_sel:WORD_1
	v_cvt_f32_f16_e32 v98, v149
	v_cvt_f32_f16_sdwa v99, v149 dst_sel:DWORD dst_unused:UNUSED_PAD src0_sel:WORD_1
	v_cvt_f32_f16_e32 v100, v150
	v_cvt_f32_f16_sdwa v101, v150 dst_sel:DWORD dst_unused:UNUSED_PAD src0_sel:WORD_1
	v_cvt_f32_f16_e32 v102, v151
	v_cvt_f32_f16_sdwa v103, v151 dst_sel:DWORD dst_unused:UNUSED_PAD src0_sel:WORD_1
	v_pk_mul_f32 v[232:233], v[72:73], v[72:73]
	v_pk_mul_f32 v[234:235], v[74:75], v[74:75]
	v_pk_mul_f32 v[236:237], v[76:77], v[76:77]
	v_pk_mul_f32 v[238:239], v[78:79], v[78:79]
	v_pk_fma_f32 v[232:233], v[80:81], v[80:81], v[232:233]
	v_pk_fma_f32 v[234:235], v[82:83], v[82:83], v[234:235]
	v_pk_fma_f32 v[236:237], v[84:85], v[84:85], v[236:237]
	v_pk_fma_f32 v[238:239], v[86:87], v[86:87], v[238:239]
	v_pk_fma_f32 v[232:233], v[88:89], v[88:89], v[232:233]
	v_pk_fma_f32 v[234:235], v[90:91], v[90:91], v[234:235]
	v_pk_fma_f32 v[236:237], v[92:93], v[92:93], v[236:237]
	v_pk_fma_f32 v[238:239], v[94:95], v[94:95], v[238:239]
	v_pk_fma_f32 v[232:233], v[96:97], v[96:97], v[232:233]
	v_pk_fma_f32 v[234:235], v[98:99], v[98:99], v[234:235]
	v_pk_fma_f32 v[236:237], v[100:101], v[100:101], v[236:237]
	v_pk_fma_f32 v[238:239], v[102:103], v[102:103], v[238:239]
	v_pk_add_f32 v[232:233], v[232:233], v[234:235]
	v_pk_add_f32 v[236:237], v[236:237], v[238:239]
	v_pk_add_f32 v[232:233], v[232:233], v[236:237]
	v_add_f32_e32 v240, v232, v233
	s_nop 1
	v_add_f32_dpp v240, v240, v240 quad_perm:[1,0,3,2] row_mask:0xf bank_mask:0xf
	s_nop 1
	v_add_f32_dpp v240, v240, v240 quad_perm:[2,3,0,1] row_mask:0xf bank_mask:0xf
	s_nop 1
	v_add_f32_dpp v240, v240, v240 row_half_mirror row_mask:0xf bank_mask:0xf
	s_nop 1
	v_add_f32_dpp v240, v240, v240 row_mirror row_mask:0xf bank_mask:0xf
	s_nop 1
	v_readlane_b32 s0, v240, 0
	v_readlane_b32 s1, v240, 16
	v_readlane_b32 s4, v240, 32
	v_readlane_b32 s5, v240, 48
	v_mov_b32_e32 v249, 0x358637bd
	s_nop 1
	v_mov_b32_e32 v240, s0
	v_add_f32_e32 v240, s1, v240
	v_add_f32_e32 v240, s4, v240
	v_add_f32_e32 v240, s5, v240
	v_fmamk_f32 v240, v240, 0x3a000000, v249
	s_mov_b32 s0, 0xf800000
	v_mul_f32_e32 v241, 0x4f800000, v240
	v_cmp_gt_f32_e32 vcc, s0, v240
	s_nop 1
	v_cndmask_b32_e32 v240, v240, v241, vcc
	v_sqrt_f32_e32 v241, v240
	s_nop 0
	v_add_u32_e32 v242, -1, v241
	v_fma_f32 v243, -v242, v241, v240
	v_cmp_ge_f32_e64 s[0:1], 0, v243
	v_add_u32_e32 v243, 1, v241
	s_nop 0
	v_cndmask_b32_e64 v242, v241, v242, s[0:1]
	v_fma_f32 v241, -v243, v241, v240
	v_cmp_lt_f32_e64 s[0:1], 0, v241
	s_nop 1
	v_cndmask_b32_e64 v241, v242, v243, s[0:1]
	v_mul_f32_e32 v242, 0x37800000, v241
	v_cndmask_b32_e32 v241, v241, v242, vcc
	v_cmp_class_f32_e32 vcc, v240, v248
	s_nop 1
	v_cndmask_b32_e32 v240, v241, v240, vcc
	v_div_scale_f32 v241, s[0:1], v240, v240, 1.0
	v_rcp_f32_e32 v242, v241
	s_nop 0
	v_fma_f32 v243, -v241, v242, 1.0
	v_fmac_f32_e32 v242, v243, v242
	v_div_scale_f32 v243, vcc, 1.0, v240, 1.0
	v_mul_f32_e32 v244, v243, v242
	v_fma_f32 v247, -v241, v244, v243
	v_fmac_f32_e32 v244, v247, v242
	v_fma_f32 v241, -v241, v244, v243
	s_nop 1
	v_div_fmas_f32 v241, v241, v242, v244
	v_div_fixup_f32 v246, v241, v240, 1.0
	v_pk_mul_f32 v[72:73], v[72:73], v[246:247] op_sel_hi:[1,0]
	v_pk_mul_f32 v[74:75], v[74:75], v[246:247] op_sel_hi:[1,0]
	v_pk_mul_f32 v[76:77], v[76:77], v[246:247] op_sel_hi:[1,0]
	v_pk_mul_f32 v[78:79], v[78:79], v[246:247] op_sel_hi:[1,0]
	v_pk_mul_f32 v[80:81], v[80:81], v[246:247] op_sel_hi:[1,0]
	v_pk_mul_f32 v[82:83], v[82:83], v[246:247] op_sel_hi:[1,0]
	v_pk_mul_f32 v[84:85], v[84:85], v[246:247] op_sel_hi:[1,0]
	v_pk_mul_f32 v[86:87], v[86:87], v[246:247] op_sel_hi:[1,0]
	v_pk_mul_f32 v[88:89], v[88:89], v[246:247] op_sel_hi:[1,0]
	v_pk_mul_f32 v[90:91], v[90:91], v[246:247] op_sel_hi:[1,0]
	v_pk_mul_f32 v[92:93], v[92:93], v[246:247] op_sel_hi:[1,0]
	v_pk_mul_f32 v[94:95], v[94:95], v[246:247] op_sel_hi:[1,0]
	v_pk_mul_f32 v[96:97], v[96:97], v[246:247] op_sel_hi:[1,0]
	v_pk_mul_f32 v[98:99], v[98:99], v[246:247] op_sel_hi:[1,0]
	v_pk_mul_f32 v[100:101], v[100:101], v[246:247] op_sel_hi:[1,0]
	v_pk_mul_f32 v[102:103], v[102:103], v[246:247] op_sel_hi:[1,0]
	s_add_u32 s8, s10, 0x40000
	s_addc_u32 s9, s11, 0
	v_pk_fma_f32 v[72:73], v[8:9], v[72:73], v[40:41]
	v_cvt_pk_bf16_f32 v232, v72, v73
	v_pk_fma_f32 v[74:75], v[10:11], v[74:75], v[42:43]
	v_cvt_pk_bf16_f32 v233, v74, v75
	v_pk_fma_f32 v[76:77], v[12:13], v[76:77], v[44:45]
	v_cvt_pk_bf16_f32 v234, v76, v77
	v_pk_fma_f32 v[78:79], v[14:15], v[78:79], v[46:47]
	v_cvt_pk_bf16_f32 v235, v78, v79
	global_store_dwordx4 v1, v[232:235], s[8:9] offset:0
	v_pk_fma_f32 v[80:81], v[16:17], v[80:81], v[48:49]
	v_cvt_pk_bf16_f32 v236, v80, v81
	v_pk_fma_f32 v[82:83], v[18:19], v[82:83], v[50:51]
	v_cvt_pk_bf16_f32 v237, v82, v83
	v_pk_fma_f32 v[84:85], v[20:21], v[84:85], v[52:53]
	v_cvt_pk_bf16_f32 v238, v84, v85
	v_pk_fma_f32 v[86:87], v[22:23], v[86:87], v[54:55]
	v_cvt_pk_bf16_f32 v239, v86, v87
	global_store_dwordx4 v1, v[236:239], s[8:9] offset:1024
	v_pk_fma_f32 v[88:89], v[24:25], v[88:89], v[56:57]
	v_cvt_pk_bf16_f32 v232, v88, v89
	v_pk_fma_f32 v[90:91], v[26:27], v[90:91], v[58:59]
	v_cvt_pk_bf16_f32 v233, v90, v91
	v_pk_fma_f32 v[92:93], v[28:29], v[92:93], v[60:61]
	v_cvt_pk_bf16_f32 v234, v92, v93
	v_pk_fma_f32 v[94:95], v[30:31], v[94:95], v[62:63]
	v_cvt_pk_bf16_f32 v235, v94, v95
	global_store_dwordx4 v1, v[232:235], s[8:9] offset:2048
	v_pk_fma_f32 v[96:97], v[32:33], v[96:97], v[64:65]
	v_cvt_pk_bf16_f32 v236, v96, v97
	v_pk_fma_f32 v[98:99], v[34:35], v[98:99], v[66:67]
	v_cvt_pk_bf16_f32 v237, v98, v99
	v_pk_fma_f32 v[100:101], v[36:37], v[100:101], v[68:69]
	v_cvt_pk_bf16_f32 v238, v100, v101
	v_pk_fma_f32 v[102:103], v[38:39], v[102:103], v[70:71]
	v_cvt_pk_bf16_f32 v239, v102, v103
	global_store_dwordx4 v1, v[236:239], s[8:9] offset:3072
	s_waitcnt vmcnt(28)
	v_cvt_f32_f16_e32 v72, v152
	v_cvt_f32_f16_sdwa v73, v152 dst_sel:DWORD dst_unused:UNUSED_PAD src0_sel:WORD_1
	v_cvt_f32_f16_e32 v74, v153
	v_cvt_f32_f16_sdwa v75, v153 dst_sel:DWORD dst_unused:UNUSED_PAD src0_sel:WORD_1
	v_cvt_f32_f16_e32 v76, v154
	v_cvt_f32_f16_sdwa v77, v154 dst_sel:DWORD dst_unused:UNUSED_PAD src0_sel:WORD_1
	v_cvt_f32_f16_e32 v78, v155
	v_cvt_f32_f16_sdwa v79, v155 dst_sel:DWORD dst_unused:UNUSED_PAD src0_sel:WORD_1
	v_cvt_f32_f16_e32 v80, v156
	v_cvt_f32_f16_sdwa v81, v156 dst_sel:DWORD dst_unused:UNUSED_PAD src0_sel:WORD_1
	v_cvt_f32_f16_e32 v82, v157
	v_cvt_f32_f16_sdwa v83, v157 dst_sel:DWORD dst_unused:UNUSED_PAD src0_sel:WORD_1
	v_cvt_f32_f16_e32 v84, v158
	v_cvt_f32_f16_sdwa v85, v158 dst_sel:DWORD dst_unused:UNUSED_PAD src0_sel:WORD_1
	v_cvt_f32_f16_e32 v86, v159
	v_cvt_f32_f16_sdwa v87, v159 dst_sel:DWORD dst_unused:UNUSED_PAD src0_sel:WORD_1
	v_cvt_f32_f16_e32 v88, v160
	v_cvt_f32_f16_sdwa v89, v160 dst_sel:DWORD dst_unused:UNUSED_PAD src0_sel:WORD_1
	v_cvt_f32_f16_e32 v90, v161
	v_cvt_f32_f16_sdwa v91, v161 dst_sel:DWORD dst_unused:UNUSED_PAD src0_sel:WORD_1
	v_cvt_f32_f16_e32 v92, v162
	v_cvt_f32_f16_sdwa v93, v162 dst_sel:DWORD dst_unused:UNUSED_PAD src0_sel:WORD_1
	v_cvt_f32_f16_e32 v94, v163
	v_cvt_f32_f16_sdwa v95, v163 dst_sel:DWORD dst_unused:UNUSED_PAD src0_sel:WORD_1
	v_cvt_f32_f16_e32 v96, v164
	v_cvt_f32_f16_sdwa v97, v164 dst_sel:DWORD dst_unused:UNUSED_PAD src0_sel:WORD_1
	v_cvt_f32_f16_e32 v98, v165
	v_cvt_f32_f16_sdwa v99, v165 dst_sel:DWORD dst_unused:UNUSED_PAD src0_sel:WORD_1
	v_cvt_f32_f16_e32 v100, v166
	v_cvt_f32_f16_sdwa v101, v166 dst_sel:DWORD dst_unused:UNUSED_PAD src0_sel:WORD_1
	v_cvt_f32_f16_e32 v102, v167
	v_cvt_f32_f16_sdwa v103, v167 dst_sel:DWORD dst_unused:UNUSED_PAD src0_sel:WORD_1
	v_pk_mul_f32 v[232:233], v[72:73], v[72:73]
	v_pk_mul_f32 v[234:235], v[74:75], v[74:75]
	v_pk_mul_f32 v[236:237], v[76:77], v[76:77]
	v_pk_mul_f32 v[238:239], v[78:79], v[78:79]
	v_pk_fma_f32 v[232:233], v[80:81], v[80:81], v[232:233]
	v_pk_fma_f32 v[234:235], v[82:83], v[82:83], v[234:235]
	v_pk_fma_f32 v[236:237], v[84:85], v[84:85], v[236:237]
	v_pk_fma_f32 v[238:239], v[86:87], v[86:87], v[238:239]
	v_pk_fma_f32 v[232:233], v[88:89], v[88:89], v[232:233]
	v_pk_fma_f32 v[234:235], v[90:91], v[90:91], v[234:235]
	v_pk_fma_f32 v[236:237], v[92:93], v[92:93], v[236:237]
	v_pk_fma_f32 v[238:239], v[94:95], v[94:95], v[238:239]
	v_pk_fma_f32 v[232:233], v[96:97], v[96:97], v[232:233]
	v_pk_fma_f32 v[234:235], v[98:99], v[98:99], v[234:235]
	v_pk_fma_f32 v[236:237], v[100:101], v[100:101], v[236:237]
	v_pk_fma_f32 v[238:239], v[102:103], v[102:103], v[238:239]
	v_pk_add_f32 v[232:233], v[232:233], v[234:235]
	v_pk_add_f32 v[236:237], v[236:237], v[238:239]
	v_pk_add_f32 v[232:233], v[232:233], v[236:237]
	v_add_f32_e32 v240, v232, v233
	s_nop 1
	v_add_f32_dpp v240, v240, v240 quad_perm:[1,0,3,2] row_mask:0xf bank_mask:0xf
	s_nop 1
	v_add_f32_dpp v240, v240, v240 quad_perm:[2,3,0,1] row_mask:0xf bank_mask:0xf
	s_nop 1
	v_add_f32_dpp v240, v240, v240 row_half_mirror row_mask:0xf bank_mask:0xf
	s_nop 1
	v_add_f32_dpp v240, v240, v240 row_mirror row_mask:0xf bank_mask:0xf
	s_nop 1
	v_readlane_b32 s0, v240, 0
	v_readlane_b32 s1, v240, 16
	v_readlane_b32 s4, v240, 32
	v_readlane_b32 s5, v240, 48
	v_mov_b32_e32 v249, 0x358637bd
	s_nop 1
	v_mov_b32_e32 v240, s0
	v_add_f32_e32 v240, s1, v240
	v_add_f32_e32 v240, s4, v240
	v_add_f32_e32 v240, s5, v240
	v_fmamk_f32 v240, v240, 0x3a000000, v249
	s_mov_b32 s0, 0xf800000
	v_mul_f32_e32 v241, 0x4f800000, v240
	v_cmp_gt_f32_e32 vcc, s0, v240
	s_nop 1
	v_cndmask_b32_e32 v240, v240, v241, vcc
	v_sqrt_f32_e32 v241, v240
	s_nop 0
	v_add_u32_e32 v242, -1, v241
	v_fma_f32 v243, -v242, v241, v240
	v_cmp_ge_f32_e64 s[0:1], 0, v243
	v_add_u32_e32 v243, 1, v241
	s_nop 0
	v_cndmask_b32_e64 v242, v241, v242, s[0:1]
	v_fma_f32 v241, -v243, v241, v240
	v_cmp_lt_f32_e64 s[0:1], 0, v241
	s_nop 1
	v_cndmask_b32_e64 v241, v242, v243, s[0:1]
	v_mul_f32_e32 v242, 0x37800000, v241
	v_cndmask_b32_e32 v241, v241, v242, vcc
	v_cmp_class_f32_e32 vcc, v240, v248
	s_nop 1
	v_cndmask_b32_e32 v240, v241, v240, vcc
	v_div_scale_f32 v241, s[0:1], v240, v240, 1.0
	v_rcp_f32_e32 v242, v241
	s_nop 0
	v_fma_f32 v243, -v241, v242, 1.0
	v_fmac_f32_e32 v242, v243, v242
	v_div_scale_f32 v243, vcc, 1.0, v240, 1.0
	v_mul_f32_e32 v244, v243, v242
	v_fma_f32 v247, -v241, v244, v243
	v_fmac_f32_e32 v244, v247, v242
	v_fma_f32 v241, -v241, v244, v243
	s_nop 1
	v_div_fmas_f32 v241, v241, v242, v244
	v_div_fixup_f32 v246, v241, v240, 1.0
	v_pk_mul_f32 v[72:73], v[72:73], v[246:247] op_sel_hi:[1,0]
	v_pk_mul_f32 v[74:75], v[74:75], v[246:247] op_sel_hi:[1,0]
	v_pk_mul_f32 v[76:77], v[76:77], v[246:247] op_sel_hi:[1,0]
	v_pk_mul_f32 v[78:79], v[78:79], v[246:247] op_sel_hi:[1,0]
	v_pk_mul_f32 v[80:81], v[80:81], v[246:247] op_sel_hi:[1,0]
	v_pk_mul_f32 v[82:83], v[82:83], v[246:247] op_sel_hi:[1,0]
	v_pk_mul_f32 v[84:85], v[84:85], v[246:247] op_sel_hi:[1,0]
	v_pk_mul_f32 v[86:87], v[86:87], v[246:247] op_sel_hi:[1,0]
	v_pk_mul_f32 v[88:89], v[88:89], v[246:247] op_sel_hi:[1,0]
	v_pk_mul_f32 v[90:91], v[90:91], v[246:247] op_sel_hi:[1,0]
	v_pk_mul_f32 v[92:93], v[92:93], v[246:247] op_sel_hi:[1,0]
	v_pk_mul_f32 v[94:95], v[94:95], v[246:247] op_sel_hi:[1,0]
	v_pk_mul_f32 v[96:97], v[96:97], v[246:247] op_sel_hi:[1,0]
	v_pk_mul_f32 v[98:99], v[98:99], v[246:247] op_sel_hi:[1,0]
	v_pk_mul_f32 v[100:101], v[100:101], v[246:247] op_sel_hi:[1,0]
	v_pk_mul_f32 v[102:103], v[102:103], v[246:247] op_sel_hi:[1,0]
	s_add_u32 s8, s10, 0x60000
	s_addc_u32 s9, s11, 0
	v_pk_fma_f32 v[72:73], v[8:9], v[72:73], v[40:41]
	v_cvt_pk_bf16_f32 v232, v72, v73
	v_pk_fma_f32 v[74:75], v[10:11], v[74:75], v[42:43]
	v_cvt_pk_bf16_f32 v233, v74, v75
	v_pk_fma_f32 v[76:77], v[12:13], v[76:77], v[44:45]
	v_cvt_pk_bf16_f32 v234, v76, v77
	v_pk_fma_f32 v[78:79], v[14:15], v[78:79], v[46:47]
	v_cvt_pk_bf16_f32 v235, v78, v79
	global_store_dwordx4 v1, v[232:235], s[8:9] offset:0
	v_pk_fma_f32 v[80:81], v[16:17], v[80:81], v[48:49]
	v_cvt_pk_bf16_f32 v236, v80, v81
	v_pk_fma_f32 v[82:83], v[18:19], v[82:83], v[50:51]
	v_cvt_pk_bf16_f32 v237, v82, v83
	v_pk_fma_f32 v[84:85], v[20:21], v[84:85], v[52:53]
	v_cvt_pk_bf16_f32 v238, v84, v85
	v_pk_fma_f32 v[86:87], v[22:23], v[86:87], v[54:55]
	v_cvt_pk_bf16_f32 v239, v86, v87
	global_store_dwordx4 v1, v[236:239], s[8:9] offset:1024
	v_pk_fma_f32 v[88:89], v[24:25], v[88:89], v[56:57]
	v_cvt_pk_bf16_f32 v232, v88, v89
	v_pk_fma_f32 v[90:91], v[26:27], v[90:91], v[58:59]
	v_cvt_pk_bf16_f32 v233, v90, v91
	v_pk_fma_f32 v[92:93], v[28:29], v[92:93], v[60:61]
	v_cvt_pk_bf16_f32 v234, v92, v93
	v_pk_fma_f32 v[94:95], v[30:31], v[94:95], v[62:63]
	v_cvt_pk_bf16_f32 v235, v94, v95
	global_store_dwordx4 v1, v[232:235], s[8:9] offset:2048
	v_pk_fma_f32 v[96:97], v[32:33], v[96:97], v[64:65]
	v_cvt_pk_bf16_f32 v236, v96, v97
	v_pk_fma_f32 v[98:99], v[34:35], v[98:99], v[66:67]
	v_cvt_pk_bf16_f32 v237, v98, v99
	v_pk_fma_f32 v[100:101], v[36:37], v[100:101], v[68:69]
	v_cvt_pk_bf16_f32 v238, v100, v101
	v_pk_fma_f32 v[102:103], v[38:39], v[102:103], v[70:71]
	v_cvt_pk_bf16_f32 v239, v102, v103
	global_store_dwordx4 v1, v[236:239], s[8:9] offset:3072
	s_waitcnt vmcnt(28)
	v_cvt_f32_f16_e32 v72, v168
	v_cvt_f32_f16_sdwa v73, v168 dst_sel:DWORD dst_unused:UNUSED_PAD src0_sel:WORD_1
	v_cvt_f32_f16_e32 v74, v169
	v_cvt_f32_f16_sdwa v75, v169 dst_sel:DWORD dst_unused:UNUSED_PAD src0_sel:WORD_1
	v_cvt_f32_f16_e32 v76, v170
	v_cvt_f32_f16_sdwa v77, v170 dst_sel:DWORD dst_unused:UNUSED_PAD src0_sel:WORD_1
	v_cvt_f32_f16_e32 v78, v171
	v_cvt_f32_f16_sdwa v79, v171 dst_sel:DWORD dst_unused:UNUSED_PAD src0_sel:WORD_1
	v_cvt_f32_f16_e32 v80, v172
	v_cvt_f32_f16_sdwa v81, v172 dst_sel:DWORD dst_unused:UNUSED_PAD src0_sel:WORD_1
	v_cvt_f32_f16_e32 v82, v173
	v_cvt_f32_f16_sdwa v83, v173 dst_sel:DWORD dst_unused:UNUSED_PAD src0_sel:WORD_1
	v_cvt_f32_f16_e32 v84, v174
	v_cvt_f32_f16_sdwa v85, v174 dst_sel:DWORD dst_unused:UNUSED_PAD src0_sel:WORD_1
	v_cvt_f32_f16_e32 v86, v175
	v_cvt_f32_f16_sdwa v87, v175 dst_sel:DWORD dst_unused:UNUSED_PAD src0_sel:WORD_1
	v_cvt_f32_f16_e32 v88, v176
	v_cvt_f32_f16_sdwa v89, v176 dst_sel:DWORD dst_unused:UNUSED_PAD src0_sel:WORD_1
	v_cvt_f32_f16_e32 v90, v177
	v_cvt_f32_f16_sdwa v91, v177 dst_sel:DWORD dst_unused:UNUSED_PAD src0_sel:WORD_1
	v_cvt_f32_f16_e32 v92, v178
	v_cvt_f32_f16_sdwa v93, v178 dst_sel:DWORD dst_unused:UNUSED_PAD src0_sel:WORD_1
	v_cvt_f32_f16_e32 v94, v179
	v_cvt_f32_f16_sdwa v95, v179 dst_sel:DWORD dst_unused:UNUSED_PAD src0_sel:WORD_1
	v_cvt_f32_f16_e32 v96, v180
	v_cvt_f32_f16_sdwa v97, v180 dst_sel:DWORD dst_unused:UNUSED_PAD src0_sel:WORD_1
	v_cvt_f32_f16_e32 v98, v181
	v_cvt_f32_f16_sdwa v99, v181 dst_sel:DWORD dst_unused:UNUSED_PAD src0_sel:WORD_1
	v_cvt_f32_f16_e32 v100, v182
	v_cvt_f32_f16_sdwa v101, v182 dst_sel:DWORD dst_unused:UNUSED_PAD src0_sel:WORD_1
	v_cvt_f32_f16_e32 v102, v183
	v_cvt_f32_f16_sdwa v103, v183 dst_sel:DWORD dst_unused:UNUSED_PAD src0_sel:WORD_1
	v_pk_mul_f32 v[232:233], v[72:73], v[72:73]
	v_pk_mul_f32 v[234:235], v[74:75], v[74:75]
	v_pk_mul_f32 v[236:237], v[76:77], v[76:77]
	v_pk_mul_f32 v[238:239], v[78:79], v[78:79]
	v_pk_fma_f32 v[232:233], v[80:81], v[80:81], v[232:233]
	v_pk_fma_f32 v[234:235], v[82:83], v[82:83], v[234:235]
	v_pk_fma_f32 v[236:237], v[84:85], v[84:85], v[236:237]
	v_pk_fma_f32 v[238:239], v[86:87], v[86:87], v[238:239]
	v_pk_fma_f32 v[232:233], v[88:89], v[88:89], v[232:233]
	v_pk_fma_f32 v[234:235], v[90:91], v[90:91], v[234:235]
	v_pk_fma_f32 v[236:237], v[92:93], v[92:93], v[236:237]
	v_pk_fma_f32 v[238:239], v[94:95], v[94:95], v[238:239]
	v_pk_fma_f32 v[232:233], v[96:97], v[96:97], v[232:233]
	v_pk_fma_f32 v[234:235], v[98:99], v[98:99], v[234:235]
	v_pk_fma_f32 v[236:237], v[100:101], v[100:101], v[236:237]
	v_pk_fma_f32 v[238:239], v[102:103], v[102:103], v[238:239]
	v_pk_add_f32 v[232:233], v[232:233], v[234:235]
	v_pk_add_f32 v[236:237], v[236:237], v[238:239]
	v_pk_add_f32 v[232:233], v[232:233], v[236:237]
	v_add_f32_e32 v240, v232, v233
	s_nop 1
	v_add_f32_dpp v240, v240, v240 quad_perm:[1,0,3,2] row_mask:0xf bank_mask:0xf
	s_nop 1
	v_add_f32_dpp v240, v240, v240 quad_perm:[2,3,0,1] row_mask:0xf bank_mask:0xf
	s_nop 1
	v_add_f32_dpp v240, v240, v240 row_half_mirror row_mask:0xf bank_mask:0xf
	s_nop 1
	v_add_f32_dpp v240, v240, v240 row_mirror row_mask:0xf bank_mask:0xf
	s_nop 1
	v_readlane_b32 s0, v240, 0
	v_readlane_b32 s1, v240, 16
	v_readlane_b32 s4, v240, 32
	v_readlane_b32 s5, v240, 48
	v_mov_b32_e32 v249, 0x358637bd
	s_nop 1
	v_mov_b32_e32 v240, s0
	v_add_f32_e32 v240, s1, v240
	v_add_f32_e32 v240, s4, v240
	v_add_f32_e32 v240, s5, v240
	v_fmamk_f32 v240, v240, 0x3a000000, v249
	s_mov_b32 s0, 0xf800000
	v_mul_f32_e32 v241, 0x4f800000, v240
	v_cmp_gt_f32_e32 vcc, s0, v240
	s_nop 1
	v_cndmask_b32_e32 v240, v240, v241, vcc
	v_sqrt_f32_e32 v241, v240
	s_nop 0
	v_add_u32_e32 v242, -1, v241
	v_fma_f32 v243, -v242, v241, v240
	v_cmp_ge_f32_e64 s[0:1], 0, v243
	v_add_u32_e32 v243, 1, v241
	s_nop 0
	v_cndmask_b32_e64 v242, v241, v242, s[0:1]
	v_fma_f32 v241, -v243, v241, v240
	v_cmp_lt_f32_e64 s[0:1], 0, v241
	s_nop 1
	v_cndmask_b32_e64 v241, v242, v243, s[0:1]
	v_mul_f32_e32 v242, 0x37800000, v241
	v_cndmask_b32_e32 v241, v241, v242, vcc
	v_cmp_class_f32_e32 vcc, v240, v248
	s_nop 1
	v_cndmask_b32_e32 v240, v241, v240, vcc
	v_div_scale_f32 v241, s[0:1], v240, v240, 1.0
	v_rcp_f32_e32 v242, v241
	s_nop 0
	v_fma_f32 v243, -v241, v242, 1.0
	v_fmac_f32_e32 v242, v243, v242
	v_div_scale_f32 v243, vcc, 1.0, v240, 1.0
	v_mul_f32_e32 v244, v243, v242
	v_fma_f32 v247, -v241, v244, v243
	v_fmac_f32_e32 v244, v247, v242
	v_fma_f32 v241, -v241, v244, v243
	s_nop 1
	v_div_fmas_f32 v241, v241, v242, v244
	v_div_fixup_f32 v246, v241, v240, 1.0
	v_pk_mul_f32 v[72:73], v[72:73], v[246:247] op_sel_hi:[1,0]
	v_pk_mul_f32 v[74:75], v[74:75], v[246:247] op_sel_hi:[1,0]
	v_pk_mul_f32 v[76:77], v[76:77], v[246:247] op_sel_hi:[1,0]
	v_pk_mul_f32 v[78:79], v[78:79], v[246:247] op_sel_hi:[1,0]
	v_pk_mul_f32 v[80:81], v[80:81], v[246:247] op_sel_hi:[1,0]
	v_pk_mul_f32 v[82:83], v[82:83], v[246:247] op_sel_hi:[1,0]
	v_pk_mul_f32 v[84:85], v[84:85], v[246:247] op_sel_hi:[1,0]
	v_pk_mul_f32 v[86:87], v[86:87], v[246:247] op_sel_hi:[1,0]
	v_pk_mul_f32 v[88:89], v[88:89], v[246:247] op_sel_hi:[1,0]
	v_pk_mul_f32 v[90:91], v[90:91], v[246:247] op_sel_hi:[1,0]
	v_pk_mul_f32 v[92:93], v[92:93], v[246:247] op_sel_hi:[1,0]
	v_pk_mul_f32 v[94:95], v[94:95], v[246:247] op_sel_hi:[1,0]
	v_pk_mul_f32 v[96:97], v[96:97], v[246:247] op_sel_hi:[1,0]
	v_pk_mul_f32 v[98:99], v[98:99], v[246:247] op_sel_hi:[1,0]
	v_pk_mul_f32 v[100:101], v[100:101], v[246:247] op_sel_hi:[1,0]
	v_pk_mul_f32 v[102:103], v[102:103], v[246:247] op_sel_hi:[1,0]
	s_add_u32 s8, s10, 0x80000
	s_addc_u32 s9, s11, 0
	v_pk_fma_f32 v[72:73], v[8:9], v[72:73], v[40:41]
	v_cvt_pk_bf16_f32 v232, v72, v73
	v_pk_fma_f32 v[74:75], v[10:11], v[74:75], v[42:43]
	v_cvt_pk_bf16_f32 v233, v74, v75
	v_pk_fma_f32 v[76:77], v[12:13], v[76:77], v[44:45]
	v_cvt_pk_bf16_f32 v234, v76, v77
	v_pk_fma_f32 v[78:79], v[14:15], v[78:79], v[46:47]
	v_cvt_pk_bf16_f32 v235, v78, v79
	global_store_dwordx4 v1, v[232:235], s[8:9] offset:0
	v_pk_fma_f32 v[80:81], v[16:17], v[80:81], v[48:49]
	v_cvt_pk_bf16_f32 v236, v80, v81
	v_pk_fma_f32 v[82:83], v[18:19], v[82:83], v[50:51]
	v_cvt_pk_bf16_f32 v237, v82, v83
	v_pk_fma_f32 v[84:85], v[20:21], v[84:85], v[52:53]
	v_cvt_pk_bf16_f32 v238, v84, v85
	v_pk_fma_f32 v[86:87], v[22:23], v[86:87], v[54:55]
	v_cvt_pk_bf16_f32 v239, v86, v87
	global_store_dwordx4 v1, v[236:239], s[8:9] offset:1024
	v_pk_fma_f32 v[88:89], v[24:25], v[88:89], v[56:57]
	v_cvt_pk_bf16_f32 v232, v88, v89
	v_pk_fma_f32 v[90:91], v[26:27], v[90:91], v[58:59]
	v_cvt_pk_bf16_f32 v233, v90, v91
	v_pk_fma_f32 v[92:93], v[28:29], v[92:93], v[60:61]
	v_cvt_pk_bf16_f32 v234, v92, v93
	v_pk_fma_f32 v[94:95], v[30:31], v[94:95], v[62:63]
	v_cvt_pk_bf16_f32 v235, v94, v95
	global_store_dwordx4 v1, v[232:235], s[8:9] offset:2048
	v_pk_fma_f32 v[96:97], v[32:33], v[96:97], v[64:65]
	v_cvt_pk_bf16_f32 v236, v96, v97
	v_pk_fma_f32 v[98:99], v[34:35], v[98:99], v[66:67]
	v_cvt_pk_bf16_f32 v237, v98, v99
	v_pk_fma_f32 v[100:101], v[36:37], v[100:101], v[68:69]
	v_cvt_pk_bf16_f32 v238, v100, v101
	v_pk_fma_f32 v[102:103], v[38:39], v[102:103], v[70:71]
	v_cvt_pk_bf16_f32 v239, v102, v103
	global_store_dwordx4 v1, v[236:239], s[8:9] offset:3072
	s_waitcnt vmcnt(28)
	v_cvt_f32_f16_e32 v72, v184
	v_cvt_f32_f16_sdwa v73, v184 dst_sel:DWORD dst_unused:UNUSED_PAD src0_sel:WORD_1
	v_cvt_f32_f16_e32 v74, v185
	v_cvt_f32_f16_sdwa v75, v185 dst_sel:DWORD dst_unused:UNUSED_PAD src0_sel:WORD_1
	v_cvt_f32_f16_e32 v76, v186
	v_cvt_f32_f16_sdwa v77, v186 dst_sel:DWORD dst_unused:UNUSED_PAD src0_sel:WORD_1
	v_cvt_f32_f16_e32 v78, v187
	v_cvt_f32_f16_sdwa v79, v187 dst_sel:DWORD dst_unused:UNUSED_PAD src0_sel:WORD_1
	v_cvt_f32_f16_e32 v80, v188
	v_cvt_f32_f16_sdwa v81, v188 dst_sel:DWORD dst_unused:UNUSED_PAD src0_sel:WORD_1
	v_cvt_f32_f16_e32 v82, v189
	v_cvt_f32_f16_sdwa v83, v189 dst_sel:DWORD dst_unused:UNUSED_PAD src0_sel:WORD_1
	v_cvt_f32_f16_e32 v84, v190
	v_cvt_f32_f16_sdwa v85, v190 dst_sel:DWORD dst_unused:UNUSED_PAD src0_sel:WORD_1
	v_cvt_f32_f16_e32 v86, v191
	v_cvt_f32_f16_sdwa v87, v191 dst_sel:DWORD dst_unused:UNUSED_PAD src0_sel:WORD_1
	v_cvt_f32_f16_e32 v88, v192
	v_cvt_f32_f16_sdwa v89, v192 dst_sel:DWORD dst_unused:UNUSED_PAD src0_sel:WORD_1
	v_cvt_f32_f16_e32 v90, v193
	v_cvt_f32_f16_sdwa v91, v193 dst_sel:DWORD dst_unused:UNUSED_PAD src0_sel:WORD_1
	v_cvt_f32_f16_e32 v92, v194
	v_cvt_f32_f16_sdwa v93, v194 dst_sel:DWORD dst_unused:UNUSED_PAD src0_sel:WORD_1
	v_cvt_f32_f16_e32 v94, v195
	v_cvt_f32_f16_sdwa v95, v195 dst_sel:DWORD dst_unused:UNUSED_PAD src0_sel:WORD_1
	v_cvt_f32_f16_e32 v96, v196
	v_cvt_f32_f16_sdwa v97, v196 dst_sel:DWORD dst_unused:UNUSED_PAD src0_sel:WORD_1
	v_cvt_f32_f16_e32 v98, v197
	v_cvt_f32_f16_sdwa v99, v197 dst_sel:DWORD dst_unused:UNUSED_PAD src0_sel:WORD_1
	v_cvt_f32_f16_e32 v100, v198
	v_cvt_f32_f16_sdwa v101, v198 dst_sel:DWORD dst_unused:UNUSED_PAD src0_sel:WORD_1
	v_cvt_f32_f16_e32 v102, v199
	v_cvt_f32_f16_sdwa v103, v199 dst_sel:DWORD dst_unused:UNUSED_PAD src0_sel:WORD_1
	v_pk_mul_f32 v[232:233], v[72:73], v[72:73]
	v_pk_mul_f32 v[234:235], v[74:75], v[74:75]
	v_pk_mul_f32 v[236:237], v[76:77], v[76:77]
	v_pk_mul_f32 v[238:239], v[78:79], v[78:79]
	v_pk_fma_f32 v[232:233], v[80:81], v[80:81], v[232:233]
	v_pk_fma_f32 v[234:235], v[82:83], v[82:83], v[234:235]
	v_pk_fma_f32 v[236:237], v[84:85], v[84:85], v[236:237]
	v_pk_fma_f32 v[238:239], v[86:87], v[86:87], v[238:239]
	v_pk_fma_f32 v[232:233], v[88:89], v[88:89], v[232:233]
	v_pk_fma_f32 v[234:235], v[90:91], v[90:91], v[234:235]
	v_pk_fma_f32 v[236:237], v[92:93], v[92:93], v[236:237]
	v_pk_fma_f32 v[238:239], v[94:95], v[94:95], v[238:239]
	v_pk_fma_f32 v[232:233], v[96:97], v[96:97], v[232:233]
	v_pk_fma_f32 v[234:235], v[98:99], v[98:99], v[234:235]
	v_pk_fma_f32 v[236:237], v[100:101], v[100:101], v[236:237]
	v_pk_fma_f32 v[238:239], v[102:103], v[102:103], v[238:239]
	v_pk_add_f32 v[232:233], v[232:233], v[234:235]
	v_pk_add_f32 v[236:237], v[236:237], v[238:239]
	v_pk_add_f32 v[232:233], v[232:233], v[236:237]
	v_add_f32_e32 v240, v232, v233
	s_nop 1
	v_add_f32_dpp v240, v240, v240 quad_perm:[1,0,3,2] row_mask:0xf bank_mask:0xf
	s_nop 1
	v_add_f32_dpp v240, v240, v240 quad_perm:[2,3,0,1] row_mask:0xf bank_mask:0xf
	s_nop 1
	v_add_f32_dpp v240, v240, v240 row_half_mirror row_mask:0xf bank_mask:0xf
	s_nop 1
	v_add_f32_dpp v240, v240, v240 row_mirror row_mask:0xf bank_mask:0xf
	s_nop 1
	v_readlane_b32 s0, v240, 0
	v_readlane_b32 s1, v240, 16
	v_readlane_b32 s4, v240, 32
	v_readlane_b32 s5, v240, 48
	v_mov_b32_e32 v249, 0x358637bd
	s_nop 1
	v_mov_b32_e32 v240, s0
	v_add_f32_e32 v240, s1, v240
	v_add_f32_e32 v240, s4, v240
	v_add_f32_e32 v240, s5, v240
	v_fmamk_f32 v240, v240, 0x3a000000, v249
	s_mov_b32 s0, 0xf800000
	v_mul_f32_e32 v241, 0x4f800000, v240
	v_cmp_gt_f32_e32 vcc, s0, v240
	s_nop 1
	v_cndmask_b32_e32 v240, v240, v241, vcc
	v_sqrt_f32_e32 v241, v240
	s_nop 0
	v_add_u32_e32 v242, -1, v241
	v_fma_f32 v243, -v242, v241, v240
	v_cmp_ge_f32_e64 s[0:1], 0, v243
	v_add_u32_e32 v243, 1, v241
	s_nop 0
	v_cndmask_b32_e64 v242, v241, v242, s[0:1]
	v_fma_f32 v241, -v243, v241, v240
	v_cmp_lt_f32_e64 s[0:1], 0, v241
	s_nop 1
	v_cndmask_b32_e64 v241, v242, v243, s[0:1]
	v_mul_f32_e32 v242, 0x37800000, v241
	v_cndmask_b32_e32 v241, v241, v242, vcc
	v_cmp_class_f32_e32 vcc, v240, v248
	s_nop 1
	v_cndmask_b32_e32 v240, v241, v240, vcc
	v_div_scale_f32 v241, s[0:1], v240, v240, 1.0
	v_rcp_f32_e32 v242, v241
	s_nop 0
	v_fma_f32 v243, -v241, v242, 1.0
	v_fmac_f32_e32 v242, v243, v242
	v_div_scale_f32 v243, vcc, 1.0, v240, 1.0
	v_mul_f32_e32 v244, v243, v242
	v_fma_f32 v247, -v241, v244, v243
	v_fmac_f32_e32 v244, v247, v242
	v_fma_f32 v241, -v241, v244, v243
	s_nop 1
	v_div_fmas_f32 v241, v241, v242, v244
	v_div_fixup_f32 v246, v241, v240, 1.0
	v_pk_mul_f32 v[72:73], v[72:73], v[246:247] op_sel_hi:[1,0]
	v_pk_mul_f32 v[74:75], v[74:75], v[246:247] op_sel_hi:[1,0]
	v_pk_mul_f32 v[76:77], v[76:77], v[246:247] op_sel_hi:[1,0]
	v_pk_mul_f32 v[78:79], v[78:79], v[246:247] op_sel_hi:[1,0]
	v_pk_mul_f32 v[80:81], v[80:81], v[246:247] op_sel_hi:[1,0]
	v_pk_mul_f32 v[82:83], v[82:83], v[246:247] op_sel_hi:[1,0]
	v_pk_mul_f32 v[84:85], v[84:85], v[246:247] op_sel_hi:[1,0]
	v_pk_mul_f32 v[86:87], v[86:87], v[246:247] op_sel_hi:[1,0]
	v_pk_mul_f32 v[88:89], v[88:89], v[246:247] op_sel_hi:[1,0]
	v_pk_mul_f32 v[90:91], v[90:91], v[246:247] op_sel_hi:[1,0]
	v_pk_mul_f32 v[92:93], v[92:93], v[246:247] op_sel_hi:[1,0]
	v_pk_mul_f32 v[94:95], v[94:95], v[246:247] op_sel_hi:[1,0]
	v_pk_mul_f32 v[96:97], v[96:97], v[246:247] op_sel_hi:[1,0]
	v_pk_mul_f32 v[98:99], v[98:99], v[246:247] op_sel_hi:[1,0]
	v_pk_mul_f32 v[100:101], v[100:101], v[246:247] op_sel_hi:[1,0]
	v_pk_mul_f32 v[102:103], v[102:103], v[246:247] op_sel_hi:[1,0]
	s_add_u32 s8, s10, 0xa0000
	s_addc_u32 s9, s11, 0
	v_pk_fma_f32 v[72:73], v[8:9], v[72:73], v[40:41]
	v_cvt_pk_bf16_f32 v232, v72, v73
	v_pk_fma_f32 v[74:75], v[10:11], v[74:75], v[42:43]
	v_cvt_pk_bf16_f32 v233, v74, v75
	v_pk_fma_f32 v[76:77], v[12:13], v[76:77], v[44:45]
	v_cvt_pk_bf16_f32 v234, v76, v77
	v_pk_fma_f32 v[78:79], v[14:15], v[78:79], v[46:47]
	v_cvt_pk_bf16_f32 v235, v78, v79
	global_store_dwordx4 v1, v[232:235], s[8:9] offset:0
	v_pk_fma_f32 v[80:81], v[16:17], v[80:81], v[48:49]
	v_cvt_pk_bf16_f32 v236, v80, v81
	v_pk_fma_f32 v[82:83], v[18:19], v[82:83], v[50:51]
	v_cvt_pk_bf16_f32 v237, v82, v83
	v_pk_fma_f32 v[84:85], v[20:21], v[84:85], v[52:53]
	v_cvt_pk_bf16_f32 v238, v84, v85
	v_pk_fma_f32 v[86:87], v[22:23], v[86:87], v[54:55]
	v_cvt_pk_bf16_f32 v239, v86, v87
	global_store_dwordx4 v1, v[236:239], s[8:9] offset:1024
	v_pk_fma_f32 v[88:89], v[24:25], v[88:89], v[56:57]
	v_cvt_pk_bf16_f32 v232, v88, v89
	v_pk_fma_f32 v[90:91], v[26:27], v[90:91], v[58:59]
	v_cvt_pk_bf16_f32 v233, v90, v91
	v_pk_fma_f32 v[92:93], v[28:29], v[92:93], v[60:61]
	v_cvt_pk_bf16_f32 v234, v92, v93
	v_pk_fma_f32 v[94:95], v[30:31], v[94:95], v[62:63]
	v_cvt_pk_bf16_f32 v235, v94, v95
	global_store_dwordx4 v1, v[232:235], s[8:9] offset:2048
	v_pk_fma_f32 v[96:97], v[32:33], v[96:97], v[64:65]
	v_cvt_pk_bf16_f32 v236, v96, v97
	v_pk_fma_f32 v[98:99], v[34:35], v[98:99], v[66:67]
	v_cvt_pk_bf16_f32 v237, v98, v99
	v_pk_fma_f32 v[100:101], v[36:37], v[100:101], v[68:69]
	v_cvt_pk_bf16_f32 v238, v100, v101
	v_pk_fma_f32 v[102:103], v[38:39], v[102:103], v[70:71]
	v_cvt_pk_bf16_f32 v239, v102, v103
	global_store_dwordx4 v1, v[236:239], s[8:9] offset:3072
	s_waitcnt vmcnt(28)
	v_cvt_f32_f16_e32 v72, v200
	v_cvt_f32_f16_sdwa v73, v200 dst_sel:DWORD dst_unused:UNUSED_PAD src0_sel:WORD_1
	v_cvt_f32_f16_e32 v74, v201
	v_cvt_f32_f16_sdwa v75, v201 dst_sel:DWORD dst_unused:UNUSED_PAD src0_sel:WORD_1
	v_cvt_f32_f16_e32 v76, v202
	v_cvt_f32_f16_sdwa v77, v202 dst_sel:DWORD dst_unused:UNUSED_PAD src0_sel:WORD_1
	v_cvt_f32_f16_e32 v78, v203
	v_cvt_f32_f16_sdwa v79, v203 dst_sel:DWORD dst_unused:UNUSED_PAD src0_sel:WORD_1
	v_cvt_f32_f16_e32 v80, v204
	v_cvt_f32_f16_sdwa v81, v204 dst_sel:DWORD dst_unused:UNUSED_PAD src0_sel:WORD_1
	v_cvt_f32_f16_e32 v82, v205
	v_cvt_f32_f16_sdwa v83, v205 dst_sel:DWORD dst_unused:UNUSED_PAD src0_sel:WORD_1
	v_cvt_f32_f16_e32 v84, v206
	v_cvt_f32_f16_sdwa v85, v206 dst_sel:DWORD dst_unused:UNUSED_PAD src0_sel:WORD_1
	v_cvt_f32_f16_e32 v86, v207
	v_cvt_f32_f16_sdwa v87, v207 dst_sel:DWORD dst_unused:UNUSED_PAD src0_sel:WORD_1
	v_cvt_f32_f16_e32 v88, v208
	v_cvt_f32_f16_sdwa v89, v208 dst_sel:DWORD dst_unused:UNUSED_PAD src0_sel:WORD_1
	v_cvt_f32_f16_e32 v90, v209
	v_cvt_f32_f16_sdwa v91, v209 dst_sel:DWORD dst_unused:UNUSED_PAD src0_sel:WORD_1
	v_cvt_f32_f16_e32 v92, v210
	v_cvt_f32_f16_sdwa v93, v210 dst_sel:DWORD dst_unused:UNUSED_PAD src0_sel:WORD_1
	v_cvt_f32_f16_e32 v94, v211
	v_cvt_f32_f16_sdwa v95, v211 dst_sel:DWORD dst_unused:UNUSED_PAD src0_sel:WORD_1
	v_cvt_f32_f16_e32 v96, v212
	v_cvt_f32_f16_sdwa v97, v212 dst_sel:DWORD dst_unused:UNUSED_PAD src0_sel:WORD_1
	v_cvt_f32_f16_e32 v98, v213
	v_cvt_f32_f16_sdwa v99, v213 dst_sel:DWORD dst_unused:UNUSED_PAD src0_sel:WORD_1
	v_cvt_f32_f16_e32 v100, v214
	v_cvt_f32_f16_sdwa v101, v214 dst_sel:DWORD dst_unused:UNUSED_PAD src0_sel:WORD_1
	v_cvt_f32_f16_e32 v102, v215
	v_cvt_f32_f16_sdwa v103, v215 dst_sel:DWORD dst_unused:UNUSED_PAD src0_sel:WORD_1
	v_pk_mul_f32 v[232:233], v[72:73], v[72:73]
	v_pk_mul_f32 v[234:235], v[74:75], v[74:75]
	v_pk_mul_f32 v[236:237], v[76:77], v[76:77]
	v_pk_mul_f32 v[238:239], v[78:79], v[78:79]
	v_pk_fma_f32 v[232:233], v[80:81], v[80:81], v[232:233]
	v_pk_fma_f32 v[234:235], v[82:83], v[82:83], v[234:235]
	v_pk_fma_f32 v[236:237], v[84:85], v[84:85], v[236:237]
	v_pk_fma_f32 v[238:239], v[86:87], v[86:87], v[238:239]
	v_pk_fma_f32 v[232:233], v[88:89], v[88:89], v[232:233]
	v_pk_fma_f32 v[234:235], v[90:91], v[90:91], v[234:235]
	v_pk_fma_f32 v[236:237], v[92:93], v[92:93], v[236:237]
	v_pk_fma_f32 v[238:239], v[94:95], v[94:95], v[238:239]
	v_pk_fma_f32 v[232:233], v[96:97], v[96:97], v[232:233]
	v_pk_fma_f32 v[234:235], v[98:99], v[98:99], v[234:235]
	v_pk_fma_f32 v[236:237], v[100:101], v[100:101], v[236:237]
	v_pk_fma_f32 v[238:239], v[102:103], v[102:103], v[238:239]
	v_pk_add_f32 v[232:233], v[232:233], v[234:235]
	v_pk_add_f32 v[236:237], v[236:237], v[238:239]
	v_pk_add_f32 v[232:233], v[232:233], v[236:237]
	v_add_f32_e32 v240, v232, v233
	s_nop 1
	v_add_f32_dpp v240, v240, v240 quad_perm:[1,0,3,2] row_mask:0xf bank_mask:0xf
	s_nop 1
	v_add_f32_dpp v240, v240, v240 quad_perm:[2,3,0,1] row_mask:0xf bank_mask:0xf
	s_nop 1
	v_add_f32_dpp v240, v240, v240 row_half_mirror row_mask:0xf bank_mask:0xf
	s_nop 1
	v_add_f32_dpp v240, v240, v240 row_mirror row_mask:0xf bank_mask:0xf
	s_nop 1
	v_readlane_b32 s0, v240, 0
	v_readlane_b32 s1, v240, 16
	v_readlane_b32 s4, v240, 32
	v_readlane_b32 s5, v240, 48
	v_mov_b32_e32 v249, 0x358637bd
	s_nop 1
	v_mov_b32_e32 v240, s0
	v_add_f32_e32 v240, s1, v240
	v_add_f32_e32 v240, s4, v240
	v_add_f32_e32 v240, s5, v240
	v_fmamk_f32 v240, v240, 0x3a000000, v249
	s_mov_b32 s0, 0xf800000
	v_mul_f32_e32 v241, 0x4f800000, v240
	v_cmp_gt_f32_e32 vcc, s0, v240
	s_nop 1
	v_cndmask_b32_e32 v240, v240, v241, vcc
	v_sqrt_f32_e32 v241, v240
	s_nop 0
	v_add_u32_e32 v242, -1, v241
	v_fma_f32 v243, -v242, v241, v240
	v_cmp_ge_f32_e64 s[0:1], 0, v243
	v_add_u32_e32 v243, 1, v241
	s_nop 0
	v_cndmask_b32_e64 v242, v241, v242, s[0:1]
	v_fma_f32 v241, -v243, v241, v240
	v_cmp_lt_f32_e64 s[0:1], 0, v241
	s_nop 1
	v_cndmask_b32_e64 v241, v242, v243, s[0:1]
	v_mul_f32_e32 v242, 0x37800000, v241
	v_cndmask_b32_e32 v241, v241, v242, vcc
	v_cmp_class_f32_e32 vcc, v240, v248
	s_nop 1
	v_cndmask_b32_e32 v240, v241, v240, vcc
	v_div_scale_f32 v241, s[0:1], v240, v240, 1.0
	v_rcp_f32_e32 v242, v241
	s_nop 0
	v_fma_f32 v243, -v241, v242, 1.0
	v_fmac_f32_e32 v242, v243, v242
	v_div_scale_f32 v243, vcc, 1.0, v240, 1.0
	v_mul_f32_e32 v244, v243, v242
	v_fma_f32 v247, -v241, v244, v243
	v_fmac_f32_e32 v244, v247, v242
	v_fma_f32 v241, -v241, v244, v243
	s_nop 1
	v_div_fmas_f32 v241, v241, v242, v244
	v_div_fixup_f32 v246, v241, v240, 1.0
	v_pk_mul_f32 v[72:73], v[72:73], v[246:247] op_sel_hi:[1,0]
	v_pk_mul_f32 v[74:75], v[74:75], v[246:247] op_sel_hi:[1,0]
	v_pk_mul_f32 v[76:77], v[76:77], v[246:247] op_sel_hi:[1,0]
	v_pk_mul_f32 v[78:79], v[78:79], v[246:247] op_sel_hi:[1,0]
	v_pk_mul_f32 v[80:81], v[80:81], v[246:247] op_sel_hi:[1,0]
	v_pk_mul_f32 v[82:83], v[82:83], v[246:247] op_sel_hi:[1,0]
	v_pk_mul_f32 v[84:85], v[84:85], v[246:247] op_sel_hi:[1,0]
	v_pk_mul_f32 v[86:87], v[86:87], v[246:247] op_sel_hi:[1,0]
	v_pk_mul_f32 v[88:89], v[88:89], v[246:247] op_sel_hi:[1,0]
	v_pk_mul_f32 v[90:91], v[90:91], v[246:247] op_sel_hi:[1,0]
	v_pk_mul_f32 v[92:93], v[92:93], v[246:247] op_sel_hi:[1,0]
	v_pk_mul_f32 v[94:95], v[94:95], v[246:247] op_sel_hi:[1,0]
	v_pk_mul_f32 v[96:97], v[96:97], v[246:247] op_sel_hi:[1,0]
	v_pk_mul_f32 v[98:99], v[98:99], v[246:247] op_sel_hi:[1,0]
	v_pk_mul_f32 v[100:101], v[100:101], v[246:247] op_sel_hi:[1,0]
	v_pk_mul_f32 v[102:103], v[102:103], v[246:247] op_sel_hi:[1,0]
	s_add_u32 s8, s10, 0xc0000
	s_addc_u32 s9, s11, 0
	v_pk_fma_f32 v[72:73], v[8:9], v[72:73], v[40:41]
	v_cvt_pk_bf16_f32 v232, v72, v73
	v_pk_fma_f32 v[74:75], v[10:11], v[74:75], v[42:43]
	v_cvt_pk_bf16_f32 v233, v74, v75
	v_pk_fma_f32 v[76:77], v[12:13], v[76:77], v[44:45]
	v_cvt_pk_bf16_f32 v234, v76, v77
	v_pk_fma_f32 v[78:79], v[14:15], v[78:79], v[46:47]
	v_cvt_pk_bf16_f32 v235, v78, v79
	global_store_dwordx4 v1, v[232:235], s[8:9] offset:0
	v_pk_fma_f32 v[80:81], v[16:17], v[80:81], v[48:49]
	v_cvt_pk_bf16_f32 v236, v80, v81
	v_pk_fma_f32 v[82:83], v[18:19], v[82:83], v[50:51]
	v_cvt_pk_bf16_f32 v237, v82, v83
	v_pk_fma_f32 v[84:85], v[20:21], v[84:85], v[52:53]
	v_cvt_pk_bf16_f32 v238, v84, v85
	v_pk_fma_f32 v[86:87], v[22:23], v[86:87], v[54:55]
	v_cvt_pk_bf16_f32 v239, v86, v87
	global_store_dwordx4 v1, v[236:239], s[8:9] offset:1024
	v_pk_fma_f32 v[88:89], v[24:25], v[88:89], v[56:57]
	v_cvt_pk_bf16_f32 v232, v88, v89
	v_pk_fma_f32 v[90:91], v[26:27], v[90:91], v[58:59]
	v_cvt_pk_bf16_f32 v233, v90, v91
	v_pk_fma_f32 v[92:93], v[28:29], v[92:93], v[60:61]
	v_cvt_pk_bf16_f32 v234, v92, v93
	v_pk_fma_f32 v[94:95], v[30:31], v[94:95], v[62:63]
	v_cvt_pk_bf16_f32 v235, v94, v95
	global_store_dwordx4 v1, v[232:235], s[8:9] offset:2048
	v_pk_fma_f32 v[96:97], v[32:33], v[96:97], v[64:65]
	v_cvt_pk_bf16_f32 v236, v96, v97
	v_pk_fma_f32 v[98:99], v[34:35], v[98:99], v[66:67]
	v_cvt_pk_bf16_f32 v237, v98, v99
	v_pk_fma_f32 v[100:101], v[36:37], v[100:101], v[68:69]
	v_cvt_pk_bf16_f32 v238, v100, v101
	v_pk_fma_f32 v[102:103], v[38:39], v[102:103], v[70:71]
	v_cvt_pk_bf16_f32 v239, v102, v103
	global_store_dwordx4 v1, v[236:239], s[8:9] offset:3072
	s_waitcnt vmcnt(28)
	v_cvt_f32_f16_e32 v72, v216
	v_cvt_f32_f16_sdwa v73, v216 dst_sel:DWORD dst_unused:UNUSED_PAD src0_sel:WORD_1
	v_cvt_f32_f16_e32 v74, v217
	v_cvt_f32_f16_sdwa v75, v217 dst_sel:DWORD dst_unused:UNUSED_PAD src0_sel:WORD_1
	v_cvt_f32_f16_e32 v76, v218
	v_cvt_f32_f16_sdwa v77, v218 dst_sel:DWORD dst_unused:UNUSED_PAD src0_sel:WORD_1
	v_cvt_f32_f16_e32 v78, v219
	v_cvt_f32_f16_sdwa v79, v219 dst_sel:DWORD dst_unused:UNUSED_PAD src0_sel:WORD_1
	v_cvt_f32_f16_e32 v80, v220
	v_cvt_f32_f16_sdwa v81, v220 dst_sel:DWORD dst_unused:UNUSED_PAD src0_sel:WORD_1
	v_cvt_f32_f16_e32 v82, v221
	v_cvt_f32_f16_sdwa v83, v221 dst_sel:DWORD dst_unused:UNUSED_PAD src0_sel:WORD_1
	v_cvt_f32_f16_e32 v84, v222
	v_cvt_f32_f16_sdwa v85, v222 dst_sel:DWORD dst_unused:UNUSED_PAD src0_sel:WORD_1
	v_cvt_f32_f16_e32 v86, v223
	v_cvt_f32_f16_sdwa v87, v223 dst_sel:DWORD dst_unused:UNUSED_PAD src0_sel:WORD_1
	v_cvt_f32_f16_e32 v88, v224
	v_cvt_f32_f16_sdwa v89, v224 dst_sel:DWORD dst_unused:UNUSED_PAD src0_sel:WORD_1
	v_cvt_f32_f16_e32 v90, v225
	v_cvt_f32_f16_sdwa v91, v225 dst_sel:DWORD dst_unused:UNUSED_PAD src0_sel:WORD_1
	v_cvt_f32_f16_e32 v92, v226
	v_cvt_f32_f16_sdwa v93, v226 dst_sel:DWORD dst_unused:UNUSED_PAD src0_sel:WORD_1
	v_cvt_f32_f16_e32 v94, v227
	v_cvt_f32_f16_sdwa v95, v227 dst_sel:DWORD dst_unused:UNUSED_PAD src0_sel:WORD_1
	v_cvt_f32_f16_e32 v96, v228
	v_cvt_f32_f16_sdwa v97, v228 dst_sel:DWORD dst_unused:UNUSED_PAD src0_sel:WORD_1
	v_cvt_f32_f16_e32 v98, v229
	v_cvt_f32_f16_sdwa v99, v229 dst_sel:DWORD dst_unused:UNUSED_PAD src0_sel:WORD_1
	v_cvt_f32_f16_e32 v100, v230
	v_cvt_f32_f16_sdwa v101, v230 dst_sel:DWORD dst_unused:UNUSED_PAD src0_sel:WORD_1
	v_cvt_f32_f16_e32 v102, v231
	v_cvt_f32_f16_sdwa v103, v231 dst_sel:DWORD dst_unused:UNUSED_PAD src0_sel:WORD_1
	v_pk_mul_f32 v[232:233], v[72:73], v[72:73]
	v_pk_mul_f32 v[234:235], v[74:75], v[74:75]
	v_pk_mul_f32 v[236:237], v[76:77], v[76:77]
	v_pk_mul_f32 v[238:239], v[78:79], v[78:79]
	v_pk_fma_f32 v[232:233], v[80:81], v[80:81], v[232:233]
	v_pk_fma_f32 v[234:235], v[82:83], v[82:83], v[234:235]
	v_pk_fma_f32 v[236:237], v[84:85], v[84:85], v[236:237]
	v_pk_fma_f32 v[238:239], v[86:87], v[86:87], v[238:239]
	v_pk_fma_f32 v[232:233], v[88:89], v[88:89], v[232:233]
	v_pk_fma_f32 v[234:235], v[90:91], v[90:91], v[234:235]
	v_pk_fma_f32 v[236:237], v[92:93], v[92:93], v[236:237]
	v_pk_fma_f32 v[238:239], v[94:95], v[94:95], v[238:239]
	v_pk_fma_f32 v[232:233], v[96:97], v[96:97], v[232:233]
	v_pk_fma_f32 v[234:235], v[98:99], v[98:99], v[234:235]
	v_pk_fma_f32 v[236:237], v[100:101], v[100:101], v[236:237]
	v_pk_fma_f32 v[238:239], v[102:103], v[102:103], v[238:239]
	v_pk_add_f32 v[232:233], v[232:233], v[234:235]
	v_pk_add_f32 v[236:237], v[236:237], v[238:239]
	v_pk_add_f32 v[232:233], v[232:233], v[236:237]
	v_add_f32_e32 v240, v232, v233
	s_nop 1
	v_add_f32_dpp v240, v240, v240 quad_perm:[1,0,3,2] row_mask:0xf bank_mask:0xf
	s_nop 1
	v_add_f32_dpp v240, v240, v240 quad_perm:[2,3,0,1] row_mask:0xf bank_mask:0xf
	s_nop 1
	v_add_f32_dpp v240, v240, v240 row_half_mirror row_mask:0xf bank_mask:0xf
	s_nop 1
	v_add_f32_dpp v240, v240, v240 row_mirror row_mask:0xf bank_mask:0xf
	s_nop 1
	v_readlane_b32 s0, v240, 0
	v_readlane_b32 s1, v240, 16
	v_readlane_b32 s4, v240, 32
	v_readlane_b32 s5, v240, 48
	v_mov_b32_e32 v249, 0x358637bd
	s_nop 1
	v_mov_b32_e32 v240, s0
	v_add_f32_e32 v240, s1, v240
	v_add_f32_e32 v240, s4, v240
	v_add_f32_e32 v240, s5, v240
	v_fmamk_f32 v240, v240, 0x3a000000, v249
	s_mov_b32 s0, 0xf800000
	v_mul_f32_e32 v241, 0x4f800000, v240
	v_cmp_gt_f32_e32 vcc, s0, v240
	s_nop 1
	v_cndmask_b32_e32 v240, v240, v241, vcc
	v_sqrt_f32_e32 v241, v240
	s_nop 0
	v_add_u32_e32 v242, -1, v241
	v_fma_f32 v243, -v242, v241, v240
	v_cmp_ge_f32_e64 s[0:1], 0, v243
	v_add_u32_e32 v243, 1, v241
	s_nop 0
	v_cndmask_b32_e64 v242, v241, v242, s[0:1]
	v_fma_f32 v241, -v243, v241, v240
	v_cmp_lt_f32_e64 s[0:1], 0, v241
	s_nop 1
	v_cndmask_b32_e64 v241, v242, v243, s[0:1]
	v_mul_f32_e32 v242, 0x37800000, v241
	v_cndmask_b32_e32 v241, v241, v242, vcc
	v_cmp_class_f32_e32 vcc, v240, v248
	s_nop 1
	v_cndmask_b32_e32 v240, v241, v240, vcc
	v_div_scale_f32 v241, s[0:1], v240, v240, 1.0
	v_rcp_f32_e32 v242, v241
	s_nop 0
	v_fma_f32 v243, -v241, v242, 1.0
	v_fmac_f32_e32 v242, v243, v242
	v_div_scale_f32 v243, vcc, 1.0, v240, 1.0
	v_mul_f32_e32 v244, v243, v242
	v_fma_f32 v247, -v241, v244, v243
	v_fmac_f32_e32 v244, v247, v242
	v_fma_f32 v241, -v241, v244, v243
	s_nop 1
	v_div_fmas_f32 v241, v241, v242, v244
	v_div_fixup_f32 v246, v241, v240, 1.0
	v_pk_mul_f32 v[72:73], v[72:73], v[246:247] op_sel_hi:[1,0]
	v_pk_mul_f32 v[74:75], v[74:75], v[246:247] op_sel_hi:[1,0]
	v_pk_mul_f32 v[76:77], v[76:77], v[246:247] op_sel_hi:[1,0]
	v_pk_mul_f32 v[78:79], v[78:79], v[246:247] op_sel_hi:[1,0]
	v_pk_mul_f32 v[80:81], v[80:81], v[246:247] op_sel_hi:[1,0]
	v_pk_mul_f32 v[82:83], v[82:83], v[246:247] op_sel_hi:[1,0]
	v_pk_mul_f32 v[84:85], v[84:85], v[246:247] op_sel_hi:[1,0]
	v_pk_mul_f32 v[86:87], v[86:87], v[246:247] op_sel_hi:[1,0]
	v_pk_mul_f32 v[88:89], v[88:89], v[246:247] op_sel_hi:[1,0]
	v_pk_mul_f32 v[90:91], v[90:91], v[246:247] op_sel_hi:[1,0]
	v_pk_mul_f32 v[92:93], v[92:93], v[246:247] op_sel_hi:[1,0]
	v_pk_mul_f32 v[94:95], v[94:95], v[246:247] op_sel_hi:[1,0]
	v_pk_mul_f32 v[96:97], v[96:97], v[246:247] op_sel_hi:[1,0]
	v_pk_mul_f32 v[98:99], v[98:99], v[246:247] op_sel_hi:[1,0]
	v_pk_mul_f32 v[100:101], v[100:101], v[246:247] op_sel_hi:[1,0]
	v_pk_mul_f32 v[102:103], v[102:103], v[246:247] op_sel_hi:[1,0]
	s_add_u32 s8, s10, 0xe0000
	s_addc_u32 s9, s11, 0
	v_pk_fma_f32 v[72:73], v[8:9], v[72:73], v[40:41]
	v_cvt_pk_bf16_f32 v232, v72, v73
	v_pk_fma_f32 v[74:75], v[10:11], v[74:75], v[42:43]
	v_cvt_pk_bf16_f32 v233, v74, v75
	v_pk_fma_f32 v[76:77], v[12:13], v[76:77], v[44:45]
	v_cvt_pk_bf16_f32 v234, v76, v77
	v_pk_fma_f32 v[78:79], v[14:15], v[78:79], v[46:47]
	v_cvt_pk_bf16_f32 v235, v78, v79
	global_store_dwordx4 v1, v[232:235], s[8:9] offset:0
	v_pk_fma_f32 v[80:81], v[16:17], v[80:81], v[48:49]
	v_cvt_pk_bf16_f32 v236, v80, v81
	v_pk_fma_f32 v[82:83], v[18:19], v[82:83], v[50:51]
	v_cvt_pk_bf16_f32 v237, v82, v83
	v_pk_fma_f32 v[84:85], v[20:21], v[84:85], v[52:53]
	v_cvt_pk_bf16_f32 v238, v84, v85
	v_pk_fma_f32 v[86:87], v[22:23], v[86:87], v[54:55]
	v_cvt_pk_bf16_f32 v239, v86, v87
	global_store_dwordx4 v1, v[236:239], s[8:9] offset:1024
	v_pk_fma_f32 v[88:89], v[24:25], v[88:89], v[56:57]
	v_cvt_pk_bf16_f32 v232, v88, v89
	v_pk_fma_f32 v[90:91], v[26:27], v[90:91], v[58:59]
	v_cvt_pk_bf16_f32 v233, v90, v91
	v_pk_fma_f32 v[92:93], v[28:29], v[92:93], v[60:61]
	v_cvt_pk_bf16_f32 v234, v92, v93
	v_pk_fma_f32 v[94:95], v[30:31], v[94:95], v[62:63]
	v_cvt_pk_bf16_f32 v235, v94, v95
	global_store_dwordx4 v1, v[232:235], s[8:9] offset:2048
	v_pk_fma_f32 v[96:97], v[32:33], v[96:97], v[64:65]
	v_cvt_pk_bf16_f32 v236, v96, v97
	v_pk_fma_f32 v[98:99], v[34:35], v[98:99], v[66:67]
	v_cvt_pk_bf16_f32 v237, v98, v99
	v_pk_fma_f32 v[100:101], v[36:37], v[100:101], v[68:69]
	v_cvt_pk_bf16_f32 v238, v100, v101
	v_pk_fma_f32 v[102:103], v[38:39], v[102:103], v[70:71]
	v_cvt_pk_bf16_f32 v239, v102, v103
	global_store_dwordx4 v1, v[236:239], s[8:9] offset:3072
	s_branch .LBB0_2500
